# s_setprio 1 around the 10 GEMM K-loops (MFMA waves win issue arbitration over the co-resident WG's epilogue)
# speedup vs baseline: 1.0006x; 1.0006x over previous
.LBB0_187:
	s_lshl_b32 s28, s67, 7
	s_ashr_i32 s29, s28, 31
	s_lshl_b64 s[26:27], s[28:29], 10
	s_lshl_b64 s[6:7], s[28:29], 11
	s_add_u32 s6, s23, s6
	s_addc_u32 s7, s33, s7
	s_ashr_i32 s25, s24, 31
	s_lshl_b64 s[8:9], s[24:25], 18
	s_add_u32 s8, s56, s8
	s_addc_u32 s9, s57, s9
	v_and_b32_e32 v200, 15, v0
	v_bfe_u32 v201, v0, 4, 2
	v_and_b32_e32 v161, 7, v200
	v_xor_b32_e32 v201, v201, v161
	v_lshlrev_b32_e32 v201, 4, v201
	v_lshl_or_b32 v201, v200, 7, v201
	v_bfe_u32 v200, v0, 7, 1
	v_lshl_or_b32 v130, v200, 13, v201
	v_bfe_u32 v200, v0, 6, 1
	v_lshl_or_b32 v194, v200, 13, v201
	v_or_b32_e32 v194, 0x4000, v194
	v_xor_b32_e32 v161, 64, v130
	v_xor_b32_e32 v195, 64, v194
	v_bfe_u32 v200, v0, 3, 3
	v_and_b32_e32 v201, 7, v0
	v_xor_b32_e32 v201, v201, v200
	v_lshlrev_b32_e32 v201, 4, v201
	v_lshl_or_b32 v201, v200, 11, v201
	v_lshrrev_b32_e32 v200, 6, v0
	v_and_b32_e32 v200, 3, v200
	v_lshl_or_b32 v196, v200, 16, v201
	v_add_u32_e32 v197, 0x3c00, v196
	v_add_u32_e32 v198, 0x7800, v196
	v_add_u32_e32 v199, 0xb400, v196
	v_lshlrev_b32_e32 v200, 12, v200
	s_nop 0
	v_readfirstlane_b32 s14, v200
	s_add_u32 s14, s14, 32
	v_mov_b32_e32 v94, 0
	v_mov_b32_e32 v95, 0
	v_mov_b32_e32 v96, 0
	v_mov_b32_e32 v97, 0
	v_mov_b32_e32 v90, 0
	v_mov_b32_e32 v91, 0
	v_mov_b32_e32 v92, 0
	v_mov_b32_e32 v93, 0
	v_mov_b32_e32 v86, 0
	v_mov_b32_e32 v87, 0
	v_mov_b32_e32 v88, 0
	v_mov_b32_e32 v89, 0
	v_mov_b32_e32 v82, 0
	v_mov_b32_e32 v83, 0
	v_mov_b32_e32 v84, 0
	v_mov_b32_e32 v85, 0
	v_mov_b32_e32 v74, 0
	v_mov_b32_e32 v75, 0
	v_mov_b32_e32 v76, 0
	v_mov_b32_e32 v77, 0
	v_mov_b32_e32 v70, 0
	v_mov_b32_e32 v71, 0
	v_mov_b32_e32 v72, 0
	v_mov_b32_e32 v73, 0
	v_mov_b32_e32 v66, 0
	v_mov_b32_e32 v67, 0
	v_mov_b32_e32 v68, 0
	v_mov_b32_e32 v69, 0
	v_mov_b32_e32 v62, 0
	v_mov_b32_e32 v63, 0
	v_mov_b32_e32 v64, 0
	v_mov_b32_e32 v65, 0
	v_mov_b32_e32 v54, 0
	v_mov_b32_e32 v55, 0
	v_mov_b32_e32 v56, 0
	v_mov_b32_e32 v57, 0
	v_mov_b32_e32 v34, 0
	v_mov_b32_e32 v35, 0
	v_mov_b32_e32 v36, 0
	v_mov_b32_e32 v37, 0
	v_mov_b32_e32 v18, 0
	v_mov_b32_e32 v19, 0
	v_mov_b32_e32 v20, 0
	v_mov_b32_e32 v21, 0
	v_mov_b32_e32 v14, 0
	v_mov_b32_e32 v15, 0
	v_mov_b32_e32 v16, 0
	v_mov_b32_e32 v17, 0
	v_mov_b32_e32 v10, 0
	v_mov_b32_e32 v11, 0
	v_mov_b32_e32 v12, 0
	v_mov_b32_e32 v13, 0
	v_mov_b32_e32 v6, 0
	v_mov_b32_e32 v7, 0
	v_mov_b32_e32 v8, 0
	v_mov_b32_e32 v9, 0
	v_mov_b32_e32 v2, 0
	v_mov_b32_e32 v3, 0
	v_mov_b32_e32 v4, 0
	v_mov_b32_e32 v5, 0
	v_mov_b32_e32 v78, 0
	v_mov_b32_e32 v79, 0
	v_mov_b32_e32 v80, 0
	v_mov_b32_e32 v81, 0
	v_mov_b32_e32 v98, 0
	v_mov_b32_e32 v99, 0
	v_mov_b32_e32 v100, 0
	v_mov_b32_e32 v101, 0
	v_mov_b32_e32 v102, 0
	v_mov_b32_e32 v103, 0
	v_mov_b32_e32 v104, 0
	v_mov_b32_e32 v105, 0
	v_mov_b32_e32 v106, 0
	v_mov_b32_e32 v107, 0
	v_mov_b32_e32 v108, 0
	v_mov_b32_e32 v109, 0
	v_mov_b32_e32 v110, 0
	v_mov_b32_e32 v111, 0
	v_mov_b32_e32 v112, 0
	v_mov_b32_e32 v113, 0
	v_mov_b32_e32 v114, 0
	v_mov_b32_e32 v115, 0
	v_mov_b32_e32 v116, 0
	v_mov_b32_e32 v117, 0
	v_mov_b32_e32 v118, 0
	v_mov_b32_e32 v119, 0
	v_mov_b32_e32 v120, 0
	v_mov_b32_e32 v121, 0
	v_mov_b32_e32 v122, 0
	v_mov_b32_e32 v123, 0
	v_mov_b32_e32 v124, 0
	v_mov_b32_e32 v125, 0
	v_mov_b32_e32 v126, 0
	v_mov_b32_e32 v127, 0
	v_mov_b32_e32 v128, 0
	v_mov_b32_e32 v129, 0
	s_waitcnt lgkmcnt(0)
	s_barrier
	v_readlane_b32 s98, v255, 16
	s_and_b32 s98, s98, 7
	s_lshl_b32 s98, s98, 1
	s_lshl_b32 s99, s98, 7
	s_add_u32 s6, s6, s99
	s_addc_u32 s7, s7, 0
	s_add_u32 s8, s8, s99
	s_addc_u32 s9, s9, 0
	s_add_u32 m0, s14, 0
	s_nop 0
	global_load_lds_dwordx4 v196, s[6:7] offset:0
	global_load_lds_dwordx4 v197, s[6:7] offset:1024
	global_load_lds_dwordx4 v198, s[6:7] offset:2048
	global_load_lds_dwordx4 v199, s[6:7] offset:3072
	s_add_u32 m0, s14, 16384
	s_nop 0
	global_load_lds_dwordx4 v196, s[8:9] offset:0
	global_load_lds_dwordx4 v197, s[8:9] offset:1024
	global_load_lds_dwordx4 v198, s[8:9] offset:2048
	global_load_lds_dwordx4 v199, s[8:9] offset:3072
	s_add_u32 s98, s98, 1
	s_and_b32 s98, s98, 15
	s_cmp_eq_u32 s98, 0
	s_cselect_b32 s99, 0x800, 0
	s_add_u32 s6, s6, 0x80
	s_addc_u32 s7, s7, 0
	s_sub_u32 s6, s6, s99
	s_subb_u32 s7, s7, 0
	s_add_u32 s8, s8, 0x80
	s_addc_u32 s9, s9, 0
	s_sub_u32 s8, s8, s99
	s_subb_u32 s9, s9, 0
	s_mov_b32 s25, 0
	s_waitcnt vmcnt(0)
	s_setprio 1
.Lk_g1l0_loop:
	s_barrier
	s_add_u32 m0, s14, 32768
	v_mfma_f32_16x16x32_bf16 v[94:97], v[98:101], v[114:117], v[94:97]
	ds_read_b128 v[22:25], v130 offset:32
	global_load_lds_dwordx4 v196, s[6:7] offset:0
	v_mfma_f32_16x16x32_bf16 v[90:93], v[98:101], v[118:121], v[90:93]
	ds_read_b128 v[42:45], v194 offset:32
	global_load_lds_dwordx4 v197, s[6:7] offset:1024
	v_mfma_f32_16x16x32_bf16 v[86:89], v[98:101], v[122:125], v[86:89]
	ds_read_b128 v[46:49], v194 offset:2080
	global_load_lds_dwordx4 v198, s[6:7] offset:2048
	v_mfma_f32_16x16x32_bf16 v[82:85], v[98:101], v[126:129], v[82:85]
	ds_read_b128 v[26:29], v130 offset:2080
	global_load_lds_dwordx4 v199, s[6:7] offset:3072
	s_add_u32 m0, s14, 49152
	v_mfma_f32_16x16x32_bf16 v[74:77], v[102:105], v[114:117], v[74:77]
	ds_read_b128 v[50:53], v194 offset:4128
	global_load_lds_dwordx4 v196, s[8:9] offset:0
	v_mfma_f32_16x16x32_bf16 v[70:73], v[102:105], v[118:121], v[70:73]
	ds_read_b128 v[58:61], v194 offset:6176
	global_load_lds_dwordx4 v197, s[8:9] offset:1024
	v_mfma_f32_16x16x32_bf16 v[66:69], v[102:105], v[122:125], v[66:69]
	ds_read_b128 v[30:33], v130 offset:4128
	global_load_lds_dwordx4 v198, s[8:9] offset:2048
	v_mfma_f32_16x16x32_bf16 v[62:65], v[102:105], v[126:129], v[62:65]
	ds_read_b128 v[38:41], v130 offset:6176
	global_load_lds_dwordx4 v199, s[8:9] offset:3072
	v_mfma_f32_16x16x32_bf16 v[54:57], v[106:109], v[114:117], v[54:57]
	v_mfma_f32_16x16x32_bf16 v[34:37], v[106:109], v[118:121], v[34:37]
	v_mfma_f32_16x16x32_bf16 v[18:21], v[106:109], v[122:125], v[18:21]
	v_mfma_f32_16x16x32_bf16 v[14:17], v[106:109], v[126:129], v[14:17]
	v_mfma_f32_16x16x32_bf16 v[10:13], v[110:113], v[114:117], v[10:13]
	v_mfma_f32_16x16x32_bf16 v[6:9], v[110:113], v[118:121], v[6:9]
	v_mfma_f32_16x16x32_bf16 v[2:5], v[110:113], v[122:125], v[2:5]
	v_mfma_f32_16x16x32_bf16 v[78:81], v[110:113], v[126:129], v[78:81]
	s_add_u32 s98, s98, 1
	s_and_b32 s98, s98, 15
	s_cmp_eq_u32 s98, 0
	s_cselect_b32 s99, 0x800, 0
	s_add_u32 s6, s6, 0x80
	s_addc_u32 s7, s7, 0
	s_sub_u32 s6, s6, s99
	s_subb_u32 s7, s7, 0
	s_add_u32 s8, s8, 0x80
	s_addc_u32 s9, s9, 0
	s_sub_u32 s8, s8, s99
	s_subb_u32 s9, s9, 0
	s_waitcnt lgkmcnt(0)
	v_mfma_f32_16x16x32_bf16 v[94:97], v[22:25], v[42:45], v[94:97]
	ds_read_b128 v[98:101], v161 offset:32
	v_mfma_f32_16x16x32_bf16 v[90:93], v[22:25], v[46:49], v[90:93]
	ds_read_b128 v[114:117], v195 offset:32
	v_mfma_f32_16x16x32_bf16 v[86:89], v[22:25], v[50:53], v[86:89]
	ds_read_b128 v[118:121], v195 offset:2080
	v_mfma_f32_16x16x32_bf16 v[82:85], v[22:25], v[58:61], v[82:85]
	ds_read_b128 v[102:105], v161 offset:2080
	v_mfma_f32_16x16x32_bf16 v[74:77], v[26:29], v[42:45], v[74:77]
	ds_read_b128 v[122:125], v195 offset:4128
	v_mfma_f32_16x16x32_bf16 v[70:73], v[26:29], v[46:49], v[70:73]
	ds_read_b128 v[126:129], v195 offset:6176
	v_mfma_f32_16x16x32_bf16 v[66:69], v[26:29], v[50:53], v[66:69]
	ds_read_b128 v[106:109], v161 offset:4128
	v_mfma_f32_16x16x32_bf16 v[62:65], v[26:29], v[58:61], v[62:65]
	ds_read_b128 v[110:113], v161 offset:6176
	v_mfma_f32_16x16x32_bf16 v[54:57], v[30:33], v[42:45], v[54:57]
	v_mfma_f32_16x16x32_bf16 v[34:37], v[30:33], v[46:49], v[34:37]
	v_mfma_f32_16x16x32_bf16 v[18:21], v[30:33], v[50:53], v[18:21]
	v_mfma_f32_16x16x32_bf16 v[14:17], v[30:33], v[58:61], v[14:17]
	v_mfma_f32_16x16x32_bf16 v[10:13], v[38:41], v[42:45], v[10:13]
	v_mfma_f32_16x16x32_bf16 v[6:9], v[38:41], v[46:49], v[6:9]
	v_mfma_f32_16x16x32_bf16 v[2:5], v[38:41], v[50:53], v[2:5]
	v_mfma_f32_16x16x32_bf16 v[78:81], v[38:41], v[58:61], v[78:81]
	s_waitcnt lgkmcnt(0)
	s_waitcnt vmcnt(0)
	s_barrier
	s_add_u32 m0, s14, 0
	v_mfma_f32_16x16x32_bf16 v[94:97], v[98:101], v[114:117], v[94:97]
	ds_read_b128 v[22:25], v130 offset:32800
	global_load_lds_dwordx4 v196, s[6:7] offset:0
	v_mfma_f32_16x16x32_bf16 v[90:93], v[98:101], v[118:121], v[90:93]
	ds_read_b128 v[42:45], v194 offset:32800
	global_load_lds_dwordx4 v197, s[6:7] offset:1024
	v_mfma_f32_16x16x32_bf16 v[86:89], v[98:101], v[122:125], v[86:89]
	ds_read_b128 v[46:49], v194 offset:34848
	global_load_lds_dwordx4 v198, s[6:7] offset:2048
	v_mfma_f32_16x16x32_bf16 v[82:85], v[98:101], v[126:129], v[82:85]
	ds_read_b128 v[26:29], v130 offset:34848
	global_load_lds_dwordx4 v199, s[6:7] offset:3072
	s_add_u32 m0, s14, 16384
	v_mfma_f32_16x16x32_bf16 v[74:77], v[102:105], v[114:117], v[74:77]
	ds_read_b128 v[50:53], v194 offset:36896
	global_load_lds_dwordx4 v196, s[8:9] offset:0
	v_mfma_f32_16x16x32_bf16 v[70:73], v[102:105], v[118:121], v[70:73]
	ds_read_b128 v[58:61], v194 offset:38944
	global_load_lds_dwordx4 v197, s[8:9] offset:1024
	v_mfma_f32_16x16x32_bf16 v[66:69], v[102:105], v[122:125], v[66:69]
	ds_read_b128 v[30:33], v130 offset:36896
	global_load_lds_dwordx4 v198, s[8:9] offset:2048
	v_mfma_f32_16x16x32_bf16 v[62:65], v[102:105], v[126:129], v[62:65]
	ds_read_b128 v[38:41], v130 offset:38944
	global_load_lds_dwordx4 v199, s[8:9] offset:3072
	v_mfma_f32_16x16x32_bf16 v[54:57], v[106:109], v[114:117], v[54:57]
	v_mfma_f32_16x16x32_bf16 v[34:37], v[106:109], v[118:121], v[34:37]
	v_mfma_f32_16x16x32_bf16 v[18:21], v[106:109], v[122:125], v[18:21]
	v_mfma_f32_16x16x32_bf16 v[14:17], v[106:109], v[126:129], v[14:17]
	v_mfma_f32_16x16x32_bf16 v[10:13], v[110:113], v[114:117], v[10:13]
	v_mfma_f32_16x16x32_bf16 v[6:9], v[110:113], v[118:121], v[6:9]
	v_mfma_f32_16x16x32_bf16 v[2:5], v[110:113], v[122:125], v[2:5]
	v_mfma_f32_16x16x32_bf16 v[78:81], v[110:113], v[126:129], v[78:81]
	s_add_u32 s98, s98, 1
	s_and_b32 s98, s98, 15
	s_cmp_eq_u32 s98, 0
	s_cselect_b32 s99, 0x800, 0
	s_add_u32 s6, s6, 0x80
	s_addc_u32 s7, s7, 0
	s_sub_u32 s6, s6, s99
	s_subb_u32 s7, s7, 0
	s_add_u32 s8, s8, 0x80
	s_addc_u32 s9, s9, 0
	s_sub_u32 s8, s8, s99
	s_subb_u32 s9, s9, 0
	s_waitcnt lgkmcnt(0)
	v_mfma_f32_16x16x32_bf16 v[94:97], v[22:25], v[42:45], v[94:97]
	ds_read_b128 v[98:101], v161 offset:32800
	v_mfma_f32_16x16x32_bf16 v[90:93], v[22:25], v[46:49], v[90:93]
	ds_read_b128 v[114:117], v195 offset:32800
	v_mfma_f32_16x16x32_bf16 v[86:89], v[22:25], v[50:53], v[86:89]
	ds_read_b128 v[118:121], v195 offset:34848
	v_mfma_f32_16x16x32_bf16 v[82:85], v[22:25], v[58:61], v[82:85]
	ds_read_b128 v[102:105], v161 offset:34848
	v_mfma_f32_16x16x32_bf16 v[74:77], v[26:29], v[42:45], v[74:77]
	ds_read_b128 v[122:125], v195 offset:36896
	v_mfma_f32_16x16x32_bf16 v[70:73], v[26:29], v[46:49], v[70:73]
	ds_read_b128 v[126:129], v195 offset:38944
	v_mfma_f32_16x16x32_bf16 v[66:69], v[26:29], v[50:53], v[66:69]
	ds_read_b128 v[106:109], v161 offset:36896
	v_mfma_f32_16x16x32_bf16 v[62:65], v[26:29], v[58:61], v[62:65]
	ds_read_b128 v[110:113], v161 offset:38944
	v_mfma_f32_16x16x32_bf16 v[54:57], v[30:33], v[42:45], v[54:57]
	v_mfma_f32_16x16x32_bf16 v[34:37], v[30:33], v[46:49], v[34:37]
	v_mfma_f32_16x16x32_bf16 v[18:21], v[30:33], v[50:53], v[18:21]
	v_mfma_f32_16x16x32_bf16 v[14:17], v[30:33], v[58:61], v[14:17]
	v_mfma_f32_16x16x32_bf16 v[10:13], v[38:41], v[42:45], v[10:13]
	v_mfma_f32_16x16x32_bf16 v[6:9], v[38:41], v[46:49], v[6:9]
	v_mfma_f32_16x16x32_bf16 v[2:5], v[38:41], v[50:53], v[2:5]
	v_mfma_f32_16x16x32_bf16 v[78:81], v[38:41], v[58:61], v[78:81]
	s_waitcnt lgkmcnt(0)
	s_waitcnt vmcnt(0)
	s_add_u32 s25, s25, 1
	s_cmp_lt_u32 s25, 7
	s_cbranch_scc1 .Lk_g1l0_loop
	s_barrier
	s_add_u32 m0, s14, 32768
	v_mfma_f32_16x16x32_bf16 v[94:97], v[98:101], v[114:117], v[94:97]
	ds_read_b128 v[22:25], v130 offset:32
	global_load_lds_dwordx4 v196, s[6:7] offset:0
	v_mfma_f32_16x16x32_bf16 v[90:93], v[98:101], v[118:121], v[90:93]
	ds_read_b128 v[42:45], v194 offset:32
	global_load_lds_dwordx4 v197, s[6:7] offset:1024
	v_mfma_f32_16x16x32_bf16 v[86:89], v[98:101], v[122:125], v[86:89]
	ds_read_b128 v[46:49], v194 offset:2080
	global_load_lds_dwordx4 v198, s[6:7] offset:2048
	v_mfma_f32_16x16x32_bf16 v[82:85], v[98:101], v[126:129], v[82:85]
	ds_read_b128 v[26:29], v130 offset:2080
	global_load_lds_dwordx4 v199, s[6:7] offset:3072
	s_add_u32 m0, s14, 49152
	v_mfma_f32_16x16x32_bf16 v[74:77], v[102:105], v[114:117], v[74:77]
	ds_read_b128 v[50:53], v194 offset:4128
	global_load_lds_dwordx4 v196, s[8:9] offset:0
	v_mfma_f32_16x16x32_bf16 v[70:73], v[102:105], v[118:121], v[70:73]
	ds_read_b128 v[58:61], v194 offset:6176
	global_load_lds_dwordx4 v197, s[8:9] offset:1024
	v_mfma_f32_16x16x32_bf16 v[66:69], v[102:105], v[122:125], v[66:69]
	ds_read_b128 v[30:33], v130 offset:4128
	global_load_lds_dwordx4 v198, s[8:9] offset:2048
	v_mfma_f32_16x16x32_bf16 v[62:65], v[102:105], v[126:129], v[62:65]
	ds_read_b128 v[38:41], v130 offset:6176
	global_load_lds_dwordx4 v199, s[8:9] offset:3072
	v_mfma_f32_16x16x32_bf16 v[54:57], v[106:109], v[114:117], v[54:57]
	v_mfma_f32_16x16x32_bf16 v[34:37], v[106:109], v[118:121], v[34:37]
	v_mfma_f32_16x16x32_bf16 v[18:21], v[106:109], v[122:125], v[18:21]
	v_mfma_f32_16x16x32_bf16 v[14:17], v[106:109], v[126:129], v[14:17]
	v_mfma_f32_16x16x32_bf16 v[10:13], v[110:113], v[114:117], v[10:13]
	v_mfma_f32_16x16x32_bf16 v[6:9], v[110:113], v[118:121], v[6:9]
	v_mfma_f32_16x16x32_bf16 v[2:5], v[110:113], v[122:125], v[2:5]
	v_mfma_f32_16x16x32_bf16 v[78:81], v[110:113], v[126:129], v[78:81]
	s_add_u32 s98, s98, 1
	s_and_b32 s98, s98, 15
	s_cmp_eq_u32 s98, 0
	s_cselect_b32 s99, 0x800, 0
	s_add_u32 s6, s6, 0x80
	s_addc_u32 s7, s7, 0
	s_sub_u32 s6, s6, s99
	s_subb_u32 s7, s7, 0
	s_add_u32 s8, s8, 0x80
	s_addc_u32 s9, s9, 0
	s_sub_u32 s8, s8, s99
	s_subb_u32 s9, s9, 0
	s_waitcnt lgkmcnt(0)
	v_mfma_f32_16x16x32_bf16 v[94:97], v[22:25], v[42:45], v[94:97]
	ds_read_b128 v[98:101], v161 offset:32
	v_mfma_f32_16x16x32_bf16 v[90:93], v[22:25], v[46:49], v[90:93]
	ds_read_b128 v[114:117], v195 offset:32
	v_mfma_f32_16x16x32_bf16 v[86:89], v[22:25], v[50:53], v[86:89]
	ds_read_b128 v[118:121], v195 offset:2080
	v_mfma_f32_16x16x32_bf16 v[82:85], v[22:25], v[58:61], v[82:85]
	ds_read_b128 v[102:105], v161 offset:2080
	v_mfma_f32_16x16x32_bf16 v[74:77], v[26:29], v[42:45], v[74:77]
	ds_read_b128 v[122:125], v195 offset:4128
	v_mfma_f32_16x16x32_bf16 v[70:73], v[26:29], v[46:49], v[70:73]
	ds_read_b128 v[126:129], v195 offset:6176
	v_mfma_f32_16x16x32_bf16 v[66:69], v[26:29], v[50:53], v[66:69]
	ds_read_b128 v[106:109], v161 offset:4128
	v_mfma_f32_16x16x32_bf16 v[62:65], v[26:29], v[58:61], v[62:65]
	ds_read_b128 v[110:113], v161 offset:6176
	v_mfma_f32_16x16x32_bf16 v[54:57], v[30:33], v[42:45], v[54:57]
	v_mfma_f32_16x16x32_bf16 v[34:37], v[30:33], v[46:49], v[34:37]
	v_mfma_f32_16x16x32_bf16 v[18:21], v[30:33], v[50:53], v[18:21]
	v_mfma_f32_16x16x32_bf16 v[14:17], v[30:33], v[58:61], v[14:17]
	v_mfma_f32_16x16x32_bf16 v[10:13], v[38:41], v[42:45], v[10:13]
	v_mfma_f32_16x16x32_bf16 v[6:9], v[38:41], v[46:49], v[6:9]
	v_mfma_f32_16x16x32_bf16 v[2:5], v[38:41], v[50:53], v[2:5]
	v_mfma_f32_16x16x32_bf16 v[78:81], v[38:41], v[58:61], v[78:81]
	s_waitcnt lgkmcnt(0)
	s_waitcnt vmcnt(0)
	s_barrier
	v_mfma_f32_16x16x32_bf16 v[94:97], v[98:101], v[114:117], v[94:97]
	ds_read_b128 v[22:25], v130 offset:32800
	v_mfma_f32_16x16x32_bf16 v[90:93], v[98:101], v[118:121], v[90:93]
	ds_read_b128 v[42:45], v194 offset:32800
	v_mfma_f32_16x16x32_bf16 v[86:89], v[98:101], v[122:125], v[86:89]
	ds_read_b128 v[46:49], v194 offset:34848
	v_mfma_f32_16x16x32_bf16 v[82:85], v[98:101], v[126:129], v[82:85]
	ds_read_b128 v[26:29], v130 offset:34848
	v_mfma_f32_16x16x32_bf16 v[74:77], v[102:105], v[114:117], v[74:77]
	ds_read_b128 v[50:53], v194 offset:36896
	v_mfma_f32_16x16x32_bf16 v[70:73], v[102:105], v[118:121], v[70:73]
	ds_read_b128 v[58:61], v194 offset:38944
	v_mfma_f32_16x16x32_bf16 v[66:69], v[102:105], v[122:125], v[66:69]
	ds_read_b128 v[30:33], v130 offset:36896
	v_mfma_f32_16x16x32_bf16 v[62:65], v[102:105], v[126:129], v[62:65]
	ds_read_b128 v[38:41], v130 offset:38944
	v_mfma_f32_16x16x32_bf16 v[54:57], v[106:109], v[114:117], v[54:57]
	v_mfma_f32_16x16x32_bf16 v[34:37], v[106:109], v[118:121], v[34:37]
	v_mfma_f32_16x16x32_bf16 v[18:21], v[106:109], v[122:125], v[18:21]
	v_mfma_f32_16x16x32_bf16 v[14:17], v[106:109], v[126:129], v[14:17]
	v_mfma_f32_16x16x32_bf16 v[10:13], v[110:113], v[114:117], v[10:13]
	v_mfma_f32_16x16x32_bf16 v[6:9], v[110:113], v[118:121], v[6:9]
	v_mfma_f32_16x16x32_bf16 v[2:5], v[110:113], v[122:125], v[2:5]
	v_mfma_f32_16x16x32_bf16 v[78:81], v[110:113], v[126:129], v[78:81]
	s_waitcnt lgkmcnt(0)
	v_mfma_f32_16x16x32_bf16 v[94:97], v[22:25], v[42:45], v[94:97]
	ds_read_b128 v[98:101], v161 offset:32800
	v_mfma_f32_16x16x32_bf16 v[90:93], v[22:25], v[46:49], v[90:93]
	ds_read_b128 v[114:117], v195 offset:32800
	v_mfma_f32_16x16x32_bf16 v[86:89], v[22:25], v[50:53], v[86:89]
	ds_read_b128 v[118:121], v195 offset:34848
	v_mfma_f32_16x16x32_bf16 v[82:85], v[22:25], v[58:61], v[82:85]
	ds_read_b128 v[102:105], v161 offset:34848
	v_mfma_f32_16x16x32_bf16 v[74:77], v[26:29], v[42:45], v[74:77]
	ds_read_b128 v[122:125], v195 offset:36896
	v_mfma_f32_16x16x32_bf16 v[70:73], v[26:29], v[46:49], v[70:73]
	ds_read_b128 v[126:129], v195 offset:38944
	v_mfma_f32_16x16x32_bf16 v[66:69], v[26:29], v[50:53], v[66:69]
	ds_read_b128 v[106:109], v161 offset:36896
	v_mfma_f32_16x16x32_bf16 v[62:65], v[26:29], v[58:61], v[62:65]
	ds_read_b128 v[110:113], v161 offset:38944
	v_mfma_f32_16x16x32_bf16 v[54:57], v[30:33], v[42:45], v[54:57]
	v_mfma_f32_16x16x32_bf16 v[34:37], v[30:33], v[46:49], v[34:37]
	v_mfma_f32_16x16x32_bf16 v[18:21], v[30:33], v[50:53], v[18:21]
	v_mfma_f32_16x16x32_bf16 v[14:17], v[30:33], v[58:61], v[14:17]
	v_mfma_f32_16x16x32_bf16 v[10:13], v[38:41], v[42:45], v[10:13]
	v_mfma_f32_16x16x32_bf16 v[6:9], v[38:41], v[46:49], v[6:9]
	v_mfma_f32_16x16x32_bf16 v[2:5], v[38:41], v[50:53], v[2:5]
	v_mfma_f32_16x16x32_bf16 v[78:81], v[38:41], v[58:61], v[78:81]
	s_waitcnt lgkmcnt(0)
	v_mfma_f32_16x16x32_bf16 v[94:97], v[98:101], v[114:117], v[94:97]
	v_mfma_f32_16x16x32_bf16 v[90:93], v[98:101], v[118:121], v[90:93]
	v_mfma_f32_16x16x32_bf16 v[86:89], v[98:101], v[122:125], v[86:89]
	v_mfma_f32_16x16x32_bf16 v[82:85], v[98:101], v[126:129], v[82:85]
	v_mfma_f32_16x16x32_bf16 v[74:77], v[102:105], v[114:117], v[74:77]
	v_mfma_f32_16x16x32_bf16 v[70:73], v[102:105], v[118:121], v[70:73]
	v_mfma_f32_16x16x32_bf16 v[66:69], v[102:105], v[122:125], v[66:69]
	v_mfma_f32_16x16x32_bf16 v[62:65], v[102:105], v[126:129], v[62:65]
	v_mfma_f32_16x16x32_bf16 v[54:57], v[106:109], v[114:117], v[54:57]
	v_mfma_f32_16x16x32_bf16 v[34:37], v[106:109], v[118:121], v[34:37]
	v_mfma_f32_16x16x32_bf16 v[18:21], v[106:109], v[122:125], v[18:21]
	v_mfma_f32_16x16x32_bf16 v[14:17], v[106:109], v[126:129], v[14:17]
	v_mfma_f32_16x16x32_bf16 v[10:13], v[110:113], v[114:117], v[10:13]
	v_mfma_f32_16x16x32_bf16 v[6:9], v[110:113], v[118:121], v[6:9]
	v_mfma_f32_16x16x32_bf16 v[2:5], v[110:113], v[122:125], v[2:5]
	v_mfma_f32_16x16x32_bf16 v[78:81], v[110:113], v[126:129], v[78:81]
	s_setprio 0
	s_waitcnt vmcnt(7)
	v_add_u32_e32 v22, 0x400, v168
	s_barrier
	ds_write2_b32 v168, v94, v90 offset1:16
	ds_write2_b32 v168, v95, v91 offset0:132 offset1:148
	ds_write2_b32 v22, v96, v92 offset0:8 offset1:24
	ds_write2_b32 v22, v97, v93 offset0:140 offset1:156
	ds_write2_b32 v168, v86, v82 offset0:32 offset1:48
	ds_write2_b32 v168, v87, v83 offset0:164 offset1:180
	ds_write2_b32 v22, v88, v84 offset0:40 offset1:56
	ds_write2_b32 v22, v89, v85 offset0:172 offset1:188
	v_add_u32_e32 v22, 0x2000, v168
	v_add_u32_e32 v23, 0x2400, v168
	s_cmp_gt_i32 s67, 63
	ds_write2_b32 v22, v74, v70 offset0:64 offset1:80
	ds_write2_b32 v22, v75, v71 offset0:196 offset1:212
	ds_write2_b32 v23, v76, v72 offset0:72 offset1:88
	ds_write2_b32 v23, v77, v73 offset0:204 offset1:220
	ds_write2_b32 v22, v66, v62 offset0:96 offset1:112
	ds_write2_b32 v22, v67, v63 offset0:228 offset1:244
	ds_write2_b32 v23, v68, v64 offset0:104 offset1:120
	ds_write2_b32 v23, v69, v65 offset0:236 offset1:252
	v_add_u32_e32 v22, 0x4000, v168
	v_add_u32_e32 v23, 0x4400, v168
	v_add_u32_e32 v24, 0x4800, v168
	s_cselect_b64 s[34:35], -1, 0
	s_cmp_lt_i32 s67, 64
	ds_write2_b32 v22, v54, v34 offset0:128 offset1:144
	ds_write2_b32 v23, v55, v35 offset0:4 offset1:20
	ds_write2_b32 v23, v56, v36 offset0:136 offset1:152
	ds_write2_b32 v24, v57, v37 offset0:12 offset1:28
	ds_write2_b32 v22, v18, v14 offset0:160 offset1:176
	ds_write2_b32 v23, v19, v15 offset0:36 offset1:52
	ds_write2_b32 v23, v20, v16 offset0:168 offset1:184
	ds_write2_b32 v24, v21, v17 offset0:44 offset1:60
	v_add_u32_e32 v14, 0x6000, v168
	s_cselect_b64 s[46:47], -1, 0
	s_add_i32 s6, s28, 0xffffe000
	ds_write2_b32 v14, v10, v6 offset0:192 offset1:208
	v_add_u32_e32 v6, 0x6400, v168
	s_lshr_b32 s68, s6, 10
	s_ashr_i32 s30, s67, 1
	s_and_b32 s69, s28, 0x380
	s_and_b32 s25, s28, 0x80
	ds_write2_b32 v6, v11, v7 offset0:68 offset1:84
	ds_write2_b32 v6, v12, v8 offset0:200 offset1:216
	v_add_u32_e32 v7, 0x6800, v168
	v_add_u32_e32 v162, s28, v165
	s_cmp_gt_i32 s24, 9
	s_mov_b64 s[6:7], -1
	ds_write2_b32 v7, v13, v9 offset0:76 offset1:92
	ds_write2_b32 v14, v2, v78 offset0:224 offset1:240
	ds_write2_b32 v6, v3, v79 offset0:100 offset1:116
	ds_write2_b32 v6, v4, v80 offset0:232 offset1:248
	ds_write2_b32 v7, v5, v81 offset0:108 offset1:124
	s_waitcnt lgkmcnt(0)
	s_barrier
	s_cbranch_scc0 .LBB0_239
	s_cmp_gt_u32 s24, 11
	s_cbranch_scc0 .LBB0_224
	s_cmp_lg_u32 s24, 36
	s_cbranch_scc0 .LBB0_219
	s_sub_i32 s6, s24, 20
	s_cmp_gt_u32 s6, 7
	s_mov_b64 s[6:7], -1
	s_cbranch_scc0 .LBB0_215
	s_cmp_lt_u32 s24, 16
	s_cselect_b64 s[48:49], -1, 0
	s_cmp_gt_u32 s24, 15
	s_mov_b64 s[54:55], -1
	s_cbranch_scc0 .LBB0_202
	s_cmp_gt_u32 s24, 19
	s_cbranch_scc0 .LBB0_199
	s_mov_b64 s[50:51], -1
	s_cmp_gt_u32 s24, 35
	s_mov_b64 s[8:9], -1
	s_cbranch_scc0 .LBB0_197
	s_lshl_b64 s[6:7], s[28:29], 12
	s_add_u32 s6, s42, s6
	s_addc_u32 s7, s43, s7
	s_mov_b64 s[8:9], 0

.LBB0_552:
	s_and_b32 s34, s33, 0xff
	s_mul_i32 s4, s34, 0xab
	s_lshr_b32 s47, s4, 11
	s_mul_i32 s4, s47, 12
	s_sub_i32 s4, s33, s4
	s_and_b32 s4, s4, 0xff
	s_lshl_b32 s4, s4, 10
	s_or_b32 s48, s4, s15
	s_lshl_b32 s35, s48, 10
	s_lshl_b32 s4, s48, 11
	s_add_u32 s10, s16, s4
	s_addc_u32 s11, s17, 0
	s_lshl_b32 s46, s47, 17
	s_lshl_b32 s4, s47, 18
	s_add_u32 s12, s18, s4
	s_addc_u32 s13, s19, 0
	v_and_b32_e32 v164, 15, v0
	v_bfe_u32 v165, v0, 4, 2
	v_and_b32_e32 v111, 7, v164
	v_xor_b32_e32 v165, v165, v111
	v_lshlrev_b32_e32 v165, 4, v165
	v_lshl_or_b32 v165, v164, 7, v165
	v_bfe_u32 v164, v0, 7, 1
	v_lshl_or_b32 v100, v164, 13, v165
	v_bfe_u32 v164, v0, 6, 1
	v_lshl_or_b32 v158, v164, 13, v165
	v_or_b32_e32 v158, 0x4000, v158
	v_xor_b32_e32 v111, 64, v100
	v_xor_b32_e32 v159, 64, v158
	v_bfe_u32 v164, v0, 3, 3
	v_and_b32_e32 v165, 7, v0
	v_xor_b32_e32 v165, v165, v164
	v_lshlrev_b32_e32 v165, 4, v165
	v_lshl_or_b32 v165, v164, 11, v165
	v_lshrrev_b32_e32 v164, 6, v0
	v_and_b32_e32 v164, 3, v164
	v_lshl_or_b32 v160, v164, 16, v165
	v_add_u32_e32 v161, 0x3c00, v160
	v_add_u32_e32 v162, 0x7800, v160
	v_add_u32_e32 v163, 0xb400, v160
	v_lshlrev_b32_e32 v164, 12, v164
	s_nop 0
	v_readfirstlane_b32 s50, v164
	s_add_u32 s50, s50, 32
	v_mov_b32_e32 v94, 0
	v_mov_b32_e32 v95, 0
	v_mov_b32_e32 v96, 0
	v_mov_b32_e32 v97, 0
	v_mov_b32_e32 v90, 0
	v_mov_b32_e32 v91, 0
	v_mov_b32_e32 v92, 0
	v_mov_b32_e32 v93, 0
	v_mov_b32_e32 v82, 0
	v_mov_b32_e32 v83, 0
	v_mov_b32_e32 v84, 0
	v_mov_b32_e32 v85, 0
	v_mov_b32_e32 v78, 0
	v_mov_b32_e32 v79, 0
	v_mov_b32_e32 v80, 0
	v_mov_b32_e32 v81, 0
	v_mov_b32_e32 v74, 0
	v_mov_b32_e32 v75, 0
	v_mov_b32_e32 v76, 0
	v_mov_b32_e32 v77, 0
	v_mov_b32_e32 v70, 0
	v_mov_b32_e32 v71, 0
	v_mov_b32_e32 v72, 0
	v_mov_b32_e32 v73, 0
	v_mov_b32_e32 v66, 0
	v_mov_b32_e32 v67, 0
	v_mov_b32_e32 v68, 0
	v_mov_b32_e32 v69, 0
	v_mov_b32_e32 v58, 0
	v_mov_b32_e32 v59, 0
	v_mov_b32_e32 v60, 0
	v_mov_b32_e32 v61, 0
	v_mov_b32_e32 v26, 0
	v_mov_b32_e32 v27, 0
	v_mov_b32_e32 v28, 0
	v_mov_b32_e32 v29, 0
	v_mov_b32_e32 v22, 0
	v_mov_b32_e32 v23, 0
	v_mov_b32_e32 v24, 0
	v_mov_b32_e32 v25, 0
	v_mov_b32_e32 v18, 0
	v_mov_b32_e32 v19, 0
	v_mov_b32_e32 v20, 0
	v_mov_b32_e32 v21, 0
	v_mov_b32_e32 v14, 0
	v_mov_b32_e32 v15, 0
	v_mov_b32_e32 v16, 0
	v_mov_b32_e32 v17, 0
	v_mov_b32_e32 v10, 0
	v_mov_b32_e32 v11, 0
	v_mov_b32_e32 v12, 0
	v_mov_b32_e32 v13, 0
	v_mov_b32_e32 v6, 0
	v_mov_b32_e32 v7, 0
	v_mov_b32_e32 v8, 0
	v_mov_b32_e32 v9, 0
	v_mov_b32_e32 v2, 0
	v_mov_b32_e32 v3, 0
	v_mov_b32_e32 v4, 0
	v_mov_b32_e32 v5, 0
	v_mov_b32_e32 v86, 0
	v_mov_b32_e32 v87, 0
	v_mov_b32_e32 v88, 0
	v_mov_b32_e32 v89, 0
	v_mov_b32_e32 v114, 0
	v_mov_b32_e32 v115, 0
	v_mov_b32_e32 v116, 0
	v_mov_b32_e32 v117, 0
	v_mov_b32_e32 v118, 0
	v_mov_b32_e32 v119, 0
	v_mov_b32_e32 v120, 0
	v_mov_b32_e32 v121, 0
	v_mov_b32_e32 v122, 0
	v_mov_b32_e32 v123, 0
	v_mov_b32_e32 v124, 0
	v_mov_b32_e32 v125, 0
	v_mov_b32_e32 v138, 0
	v_mov_b32_e32 v139, 0
	v_mov_b32_e32 v140, 0
	v_mov_b32_e32 v141, 0
	v_mov_b32_e32 v142, 0
	v_mov_b32_e32 v143, 0
	v_mov_b32_e32 v144, 0
	v_mov_b32_e32 v145, 0
	v_mov_b32_e32 v146, 0
	v_mov_b32_e32 v147, 0
	v_mov_b32_e32 v148, 0
	v_mov_b32_e32 v149, 0
	v_mov_b32_e32 v150, 0
	v_mov_b32_e32 v151, 0
	v_mov_b32_e32 v152, 0
	v_mov_b32_e32 v153, 0
	v_mov_b32_e32 v154, 0
	v_mov_b32_e32 v155, 0
	v_mov_b32_e32 v156, 0
	v_mov_b32_e32 v157, 0
	s_waitcnt lgkmcnt(0)
	s_barrier
	v_readlane_b32 s98, v255, 16
	s_and_b32 s98, s98, 7
	s_lshl_b32 s98, s98, 1
	s_lshl_b32 s99, s98, 7
	s_add_u32 s10, s10, s99
	s_addc_u32 s11, s11, 0
	s_add_u32 s12, s12, s99
	s_addc_u32 s13, s13, 0
	s_add_u32 m0, s50, 0
	s_nop 0
	global_load_lds_dwordx4 v160, s[10:11] offset:0
	global_load_lds_dwordx4 v161, s[10:11] offset:1024
	global_load_lds_dwordx4 v162, s[10:11] offset:2048
	global_load_lds_dwordx4 v163, s[10:11] offset:3072
	s_add_u32 m0, s50, 16384
	s_nop 0
	global_load_lds_dwordx4 v160, s[12:13] offset:0
	global_load_lds_dwordx4 v161, s[12:13] offset:1024
	global_load_lds_dwordx4 v162, s[12:13] offset:2048
	global_load_lds_dwordx4 v163, s[12:13] offset:3072
	s_add_u32 s98, s98, 1
	s_and_b32 s98, s98, 15
	s_cmp_eq_u32 s98, 0
	s_cselect_b32 s99, 0x800, 0
	s_add_u32 s10, s10, 0x80
	s_addc_u32 s11, s11, 0
	s_sub_u32 s10, s10, s99
	s_subb_u32 s11, s11, 0
	s_add_u32 s12, s12, 0x80
	s_addc_u32 s13, s13, 0
	s_sub_u32 s12, s12, s99
	s_subb_u32 s13, s13, 0
	s_mov_b32 s49, 0
	s_waitcnt vmcnt(0)
	s_setprio 1
.Lk_aol0a_loop:
	s_barrier
	s_add_u32 m0, s50, 32768
	v_mfma_f32_16x16x32_bf16 v[94:97], v[114:117], v[142:145], v[94:97]
	ds_read_b128 v[30:33], v100 offset:32
	global_load_lds_dwordx4 v160, s[10:11] offset:0
	v_mfma_f32_16x16x32_bf16 v[90:93], v[114:117], v[146:149], v[90:93]
	ds_read_b128 v[46:49], v158 offset:32
	global_load_lds_dwordx4 v161, s[10:11] offset:1024
	v_mfma_f32_16x16x32_bf16 v[82:85], v[114:117], v[150:153], v[82:85]
	ds_read_b128 v[50:53], v158 offset:2080
	global_load_lds_dwordx4 v162, s[10:11] offset:2048
	v_mfma_f32_16x16x32_bf16 v[78:81], v[114:117], v[154:157], v[78:81]
	ds_read_b128 v[34:37], v100 offset:2080
	global_load_lds_dwordx4 v163, s[10:11] offset:3072
	s_add_u32 m0, s50, 49152
	v_mfma_f32_16x16x32_bf16 v[74:77], v[118:121], v[142:145], v[74:77]
	ds_read_b128 v[54:57], v158 offset:4128
	global_load_lds_dwordx4 v160, s[12:13] offset:0
	v_mfma_f32_16x16x32_bf16 v[70:73], v[118:121], v[146:149], v[70:73]
	ds_read_b128 v[62:65], v158 offset:6176
	global_load_lds_dwordx4 v161, s[12:13] offset:1024
	v_mfma_f32_16x16x32_bf16 v[66:69], v[118:121], v[150:153], v[66:69]
	ds_read_b128 v[38:41], v100 offset:4128
	global_load_lds_dwordx4 v162, s[12:13] offset:2048
	v_mfma_f32_16x16x32_bf16 v[58:61], v[118:121], v[154:157], v[58:61]
	ds_read_b128 v[42:45], v100 offset:6176
	global_load_lds_dwordx4 v163, s[12:13] offset:3072
	v_mfma_f32_16x16x32_bf16 v[26:29], v[122:125], v[142:145], v[26:29]
	v_mfma_f32_16x16x32_bf16 v[22:25], v[122:125], v[146:149], v[22:25]
	v_mfma_f32_16x16x32_bf16 v[18:21], v[122:125], v[150:153], v[18:21]
	v_mfma_f32_16x16x32_bf16 v[14:17], v[122:125], v[154:157], v[14:17]
	v_mfma_f32_16x16x32_bf16 v[10:13], v[138:141], v[142:145], v[10:13]
	v_mfma_f32_16x16x32_bf16 v[6:9], v[138:141], v[146:149], v[6:9]
	v_mfma_f32_16x16x32_bf16 v[2:5], v[138:141], v[150:153], v[2:5]
	v_mfma_f32_16x16x32_bf16 v[86:89], v[138:141], v[154:157], v[86:89]
	s_add_u32 s98, s98, 1
	s_and_b32 s98, s98, 15
	s_cmp_eq_u32 s98, 0
	s_cselect_b32 s99, 0x800, 0
	s_add_u32 s10, s10, 0x80
	s_addc_u32 s11, s11, 0
	s_sub_u32 s10, s10, s99
	s_subb_u32 s11, s11, 0
	s_add_u32 s12, s12, 0x80
	s_addc_u32 s13, s13, 0
	s_sub_u32 s12, s12, s99
	s_subb_u32 s13, s13, 0
	s_waitcnt lgkmcnt(0)
	v_mfma_f32_16x16x32_bf16 v[94:97], v[30:33], v[46:49], v[94:97]
	ds_read_b128 v[114:117], v111 offset:32
	v_mfma_f32_16x16x32_bf16 v[90:93], v[30:33], v[50:53], v[90:93]
	ds_read_b128 v[142:145], v159 offset:32
	v_mfma_f32_16x16x32_bf16 v[82:85], v[30:33], v[54:57], v[82:85]
	ds_read_b128 v[146:149], v159 offset:2080
	v_mfma_f32_16x16x32_bf16 v[78:81], v[30:33], v[62:65], v[78:81]
	ds_read_b128 v[118:121], v111 offset:2080
	v_mfma_f32_16x16x32_bf16 v[74:77], v[34:37], v[46:49], v[74:77]
	ds_read_b128 v[150:153], v159 offset:4128
	v_mfma_f32_16x16x32_bf16 v[70:73], v[34:37], v[50:53], v[70:73]
	ds_read_b128 v[154:157], v159 offset:6176
	v_mfma_f32_16x16x32_bf16 v[66:69], v[34:37], v[54:57], v[66:69]
	ds_read_b128 v[122:125], v111 offset:4128
	v_mfma_f32_16x16x32_bf16 v[58:61], v[34:37], v[62:65], v[58:61]
	ds_read_b128 v[138:141], v111 offset:6176
	v_mfma_f32_16x16x32_bf16 v[26:29], v[38:41], v[46:49], v[26:29]
	v_mfma_f32_16x16x32_bf16 v[22:25], v[38:41], v[50:53], v[22:25]
	v_mfma_f32_16x16x32_bf16 v[18:21], v[38:41], v[54:57], v[18:21]
	v_mfma_f32_16x16x32_bf16 v[14:17], v[38:41], v[62:65], v[14:17]
	v_mfma_f32_16x16x32_bf16 v[10:13], v[42:45], v[46:49], v[10:13]
	v_mfma_f32_16x16x32_bf16 v[6:9], v[42:45], v[50:53], v[6:9]
	v_mfma_f32_16x16x32_bf16 v[2:5], v[42:45], v[54:57], v[2:5]
	v_mfma_f32_16x16x32_bf16 v[86:89], v[42:45], v[62:65], v[86:89]
	s_waitcnt lgkmcnt(0)
	s_waitcnt vmcnt(0)
	s_barrier
	s_add_u32 m0, s50, 0
	v_mfma_f32_16x16x32_bf16 v[94:97], v[114:117], v[142:145], v[94:97]
	ds_read_b128 v[30:33], v100 offset:32800
	global_load_lds_dwordx4 v160, s[10:11] offset:0
	v_mfma_f32_16x16x32_bf16 v[90:93], v[114:117], v[146:149], v[90:93]
	ds_read_b128 v[46:49], v158 offset:32800
	global_load_lds_dwordx4 v161, s[10:11] offset:1024
	v_mfma_f32_16x16x32_bf16 v[82:85], v[114:117], v[150:153], v[82:85]
	ds_read_b128 v[50:53], v158 offset:34848
	global_load_lds_dwordx4 v162, s[10:11] offset:2048
	v_mfma_f32_16x16x32_bf16 v[78:81], v[114:117], v[154:157], v[78:81]
	ds_read_b128 v[34:37], v100 offset:34848
	global_load_lds_dwordx4 v163, s[10:11] offset:3072
	s_add_u32 m0, s50, 16384
	v_mfma_f32_16x16x32_bf16 v[74:77], v[118:121], v[142:145], v[74:77]
	ds_read_b128 v[54:57], v158 offset:36896
	global_load_lds_dwordx4 v160, s[12:13] offset:0
	v_mfma_f32_16x16x32_bf16 v[70:73], v[118:121], v[146:149], v[70:73]
	ds_read_b128 v[62:65], v158 offset:38944
	global_load_lds_dwordx4 v161, s[12:13] offset:1024
	v_mfma_f32_16x16x32_bf16 v[66:69], v[118:121], v[150:153], v[66:69]
	ds_read_b128 v[38:41], v100 offset:36896
	global_load_lds_dwordx4 v162, s[12:13] offset:2048
	v_mfma_f32_16x16x32_bf16 v[58:61], v[118:121], v[154:157], v[58:61]
	ds_read_b128 v[42:45], v100 offset:38944
	global_load_lds_dwordx4 v163, s[12:13] offset:3072
	v_mfma_f32_16x16x32_bf16 v[26:29], v[122:125], v[142:145], v[26:29]
	v_mfma_f32_16x16x32_bf16 v[22:25], v[122:125], v[146:149], v[22:25]
	v_mfma_f32_16x16x32_bf16 v[18:21], v[122:125], v[150:153], v[18:21]
	v_mfma_f32_16x16x32_bf16 v[14:17], v[122:125], v[154:157], v[14:17]
	v_mfma_f32_16x16x32_bf16 v[10:13], v[138:141], v[142:145], v[10:13]
	v_mfma_f32_16x16x32_bf16 v[6:9], v[138:141], v[146:149], v[6:9]
	v_mfma_f32_16x16x32_bf16 v[2:5], v[138:141], v[150:153], v[2:5]
	v_mfma_f32_16x16x32_bf16 v[86:89], v[138:141], v[154:157], v[86:89]
	s_add_u32 s98, s98, 1
	s_and_b32 s98, s98, 15
	s_cmp_eq_u32 s98, 0
	s_cselect_b32 s99, 0x800, 0
	s_add_u32 s10, s10, 0x80
	s_addc_u32 s11, s11, 0
	s_sub_u32 s10, s10, s99
	s_subb_u32 s11, s11, 0
	s_add_u32 s12, s12, 0x80
	s_addc_u32 s13, s13, 0
	s_sub_u32 s12, s12, s99
	s_subb_u32 s13, s13, 0
	s_waitcnt lgkmcnt(0)
	v_mfma_f32_16x16x32_bf16 v[94:97], v[30:33], v[46:49], v[94:97]
	ds_read_b128 v[114:117], v111 offset:32800
	v_mfma_f32_16x16x32_bf16 v[90:93], v[30:33], v[50:53], v[90:93]
	ds_read_b128 v[142:145], v159 offset:32800
	v_mfma_f32_16x16x32_bf16 v[82:85], v[30:33], v[54:57], v[82:85]
	ds_read_b128 v[146:149], v159 offset:34848
	v_mfma_f32_16x16x32_bf16 v[78:81], v[30:33], v[62:65], v[78:81]
	ds_read_b128 v[118:121], v111 offset:34848
	v_mfma_f32_16x16x32_bf16 v[74:77], v[34:37], v[46:49], v[74:77]
	ds_read_b128 v[150:153], v159 offset:36896
	v_mfma_f32_16x16x32_bf16 v[70:73], v[34:37], v[50:53], v[70:73]
	ds_read_b128 v[154:157], v159 offset:38944
	v_mfma_f32_16x16x32_bf16 v[66:69], v[34:37], v[54:57], v[66:69]
	ds_read_b128 v[122:125], v111 offset:36896
	v_mfma_f32_16x16x32_bf16 v[58:61], v[34:37], v[62:65], v[58:61]
	ds_read_b128 v[138:141], v111 offset:38944
	v_mfma_f32_16x16x32_bf16 v[26:29], v[38:41], v[46:49], v[26:29]
	v_mfma_f32_16x16x32_bf16 v[22:25], v[38:41], v[50:53], v[22:25]
	v_mfma_f32_16x16x32_bf16 v[18:21], v[38:41], v[54:57], v[18:21]
	v_mfma_f32_16x16x32_bf16 v[14:17], v[38:41], v[62:65], v[14:17]
	v_mfma_f32_16x16x32_bf16 v[10:13], v[42:45], v[46:49], v[10:13]
	v_mfma_f32_16x16x32_bf16 v[6:9], v[42:45], v[50:53], v[6:9]
	v_mfma_f32_16x16x32_bf16 v[2:5], v[42:45], v[54:57], v[2:5]
	v_mfma_f32_16x16x32_bf16 v[86:89], v[42:45], v[62:65], v[86:89]
	s_waitcnt lgkmcnt(0)
	s_waitcnt vmcnt(0)
	s_add_u32 s49, s49, 1
	s_cmp_lt_u32 s49, 7
	s_cbranch_scc1 .Lk_aol0a_loop
	s_barrier
	s_add_u32 m0, s50, 32768
	v_mfma_f32_16x16x32_bf16 v[94:97], v[114:117], v[142:145], v[94:97]
	ds_read_b128 v[30:33], v100 offset:32
	global_load_lds_dwordx4 v160, s[10:11] offset:0
	v_mfma_f32_16x16x32_bf16 v[90:93], v[114:117], v[146:149], v[90:93]
	ds_read_b128 v[46:49], v158 offset:32
	global_load_lds_dwordx4 v161, s[10:11] offset:1024
	v_mfma_f32_16x16x32_bf16 v[82:85], v[114:117], v[150:153], v[82:85]
	ds_read_b128 v[50:53], v158 offset:2080
	global_load_lds_dwordx4 v162, s[10:11] offset:2048
	v_mfma_f32_16x16x32_bf16 v[78:81], v[114:117], v[154:157], v[78:81]
	ds_read_b128 v[34:37], v100 offset:2080
	global_load_lds_dwordx4 v163, s[10:11] offset:3072
	s_add_u32 m0, s50, 49152
	v_mfma_f32_16x16x32_bf16 v[74:77], v[118:121], v[142:145], v[74:77]
	ds_read_b128 v[54:57], v158 offset:4128
	global_load_lds_dwordx4 v160, s[12:13] offset:0
	v_mfma_f32_16x16x32_bf16 v[70:73], v[118:121], v[146:149], v[70:73]
	ds_read_b128 v[62:65], v158 offset:6176
	global_load_lds_dwordx4 v161, s[12:13] offset:1024
	v_mfma_f32_16x16x32_bf16 v[66:69], v[118:121], v[150:153], v[66:69]
	ds_read_b128 v[38:41], v100 offset:4128
	global_load_lds_dwordx4 v162, s[12:13] offset:2048
	v_mfma_f32_16x16x32_bf16 v[58:61], v[118:121], v[154:157], v[58:61]
	ds_read_b128 v[42:45], v100 offset:6176
	global_load_lds_dwordx4 v163, s[12:13] offset:3072
	v_mfma_f32_16x16x32_bf16 v[26:29], v[122:125], v[142:145], v[26:29]
	v_mfma_f32_16x16x32_bf16 v[22:25], v[122:125], v[146:149], v[22:25]
	v_mfma_f32_16x16x32_bf16 v[18:21], v[122:125], v[150:153], v[18:21]
	v_mfma_f32_16x16x32_bf16 v[14:17], v[122:125], v[154:157], v[14:17]
	v_mfma_f32_16x16x32_bf16 v[10:13], v[138:141], v[142:145], v[10:13]
	v_mfma_f32_16x16x32_bf16 v[6:9], v[138:141], v[146:149], v[6:9]
	v_mfma_f32_16x16x32_bf16 v[2:5], v[138:141], v[150:153], v[2:5]
	v_mfma_f32_16x16x32_bf16 v[86:89], v[138:141], v[154:157], v[86:89]
	s_add_u32 s98, s98, 1
	s_and_b32 s98, s98, 15
	s_cmp_eq_u32 s98, 0
	s_cselect_b32 s99, 0x800, 0
	s_add_u32 s10, s10, 0x80
	s_addc_u32 s11, s11, 0
	s_sub_u32 s10, s10, s99
	s_subb_u32 s11, s11, 0
	s_add_u32 s12, s12, 0x80
	s_addc_u32 s13, s13, 0
	s_sub_u32 s12, s12, s99
	s_subb_u32 s13, s13, 0
	s_waitcnt lgkmcnt(0)
	v_mfma_f32_16x16x32_bf16 v[94:97], v[30:33], v[46:49], v[94:97]
	ds_read_b128 v[114:117], v111 offset:32
	v_mfma_f32_16x16x32_bf16 v[90:93], v[30:33], v[50:53], v[90:93]
	ds_read_b128 v[142:145], v159 offset:32
	v_mfma_f32_16x16x32_bf16 v[82:85], v[30:33], v[54:57], v[82:85]
	ds_read_b128 v[146:149], v159 offset:2080
	v_mfma_f32_16x16x32_bf16 v[78:81], v[30:33], v[62:65], v[78:81]
	ds_read_b128 v[118:121], v111 offset:2080
	v_mfma_f32_16x16x32_bf16 v[74:77], v[34:37], v[46:49], v[74:77]
	ds_read_b128 v[150:153], v159 offset:4128
	v_mfma_f32_16x16x32_bf16 v[70:73], v[34:37], v[50:53], v[70:73]
	ds_read_b128 v[154:157], v159 offset:6176
	v_mfma_f32_16x16x32_bf16 v[66:69], v[34:37], v[54:57], v[66:69]
	ds_read_b128 v[122:125], v111 offset:4128
	v_mfma_f32_16x16x32_bf16 v[58:61], v[34:37], v[62:65], v[58:61]
	ds_read_b128 v[138:141], v111 offset:6176
	v_mfma_f32_16x16x32_bf16 v[26:29], v[38:41], v[46:49], v[26:29]
	v_mfma_f32_16x16x32_bf16 v[22:25], v[38:41], v[50:53], v[22:25]
	v_mfma_f32_16x16x32_bf16 v[18:21], v[38:41], v[54:57], v[18:21]
	v_mfma_f32_16x16x32_bf16 v[14:17], v[38:41], v[62:65], v[14:17]
	v_mfma_f32_16x16x32_bf16 v[10:13], v[42:45], v[46:49], v[10:13]
	v_mfma_f32_16x16x32_bf16 v[6:9], v[42:45], v[50:53], v[6:9]
	v_mfma_f32_16x16x32_bf16 v[2:5], v[42:45], v[54:57], v[2:5]
	v_mfma_f32_16x16x32_bf16 v[86:89], v[42:45], v[62:65], v[86:89]
	s_waitcnt lgkmcnt(0)
	s_waitcnt vmcnt(0)
	s_barrier
	v_mfma_f32_16x16x32_bf16 v[94:97], v[114:117], v[142:145], v[94:97]
	ds_read_b128 v[30:33], v100 offset:32800
	v_mfma_f32_16x16x32_bf16 v[90:93], v[114:117], v[146:149], v[90:93]
	ds_read_b128 v[46:49], v158 offset:32800
	v_mfma_f32_16x16x32_bf16 v[82:85], v[114:117], v[150:153], v[82:85]
	ds_read_b128 v[50:53], v158 offset:34848
	v_mfma_f32_16x16x32_bf16 v[78:81], v[114:117], v[154:157], v[78:81]
	ds_read_b128 v[34:37], v100 offset:34848
	v_mfma_f32_16x16x32_bf16 v[74:77], v[118:121], v[142:145], v[74:77]
	ds_read_b128 v[54:57], v158 offset:36896
	v_mfma_f32_16x16x32_bf16 v[70:73], v[118:121], v[146:149], v[70:73]
	ds_read_b128 v[62:65], v158 offset:38944
	v_mfma_f32_16x16x32_bf16 v[66:69], v[118:121], v[150:153], v[66:69]
	ds_read_b128 v[38:41], v100 offset:36896
	v_mfma_f32_16x16x32_bf16 v[58:61], v[118:121], v[154:157], v[58:61]
	ds_read_b128 v[42:45], v100 offset:38944
	v_mfma_f32_16x16x32_bf16 v[26:29], v[122:125], v[142:145], v[26:29]
	v_mfma_f32_16x16x32_bf16 v[22:25], v[122:125], v[146:149], v[22:25]
	v_mfma_f32_16x16x32_bf16 v[18:21], v[122:125], v[150:153], v[18:21]
	v_mfma_f32_16x16x32_bf16 v[14:17], v[122:125], v[154:157], v[14:17]
	v_mfma_f32_16x16x32_bf16 v[10:13], v[138:141], v[142:145], v[10:13]
	v_mfma_f32_16x16x32_bf16 v[6:9], v[138:141], v[146:149], v[6:9]
	v_mfma_f32_16x16x32_bf16 v[2:5], v[138:141], v[150:153], v[2:5]
	v_mfma_f32_16x16x32_bf16 v[86:89], v[138:141], v[154:157], v[86:89]
	s_waitcnt lgkmcnt(0)
	v_mfma_f32_16x16x32_bf16 v[94:97], v[30:33], v[46:49], v[94:97]
	ds_read_b128 v[114:117], v111 offset:32800
	v_mfma_f32_16x16x32_bf16 v[90:93], v[30:33], v[50:53], v[90:93]
	ds_read_b128 v[142:145], v159 offset:32800
	v_mfma_f32_16x16x32_bf16 v[82:85], v[30:33], v[54:57], v[82:85]
	ds_read_b128 v[146:149], v159 offset:34848
	v_mfma_f32_16x16x32_bf16 v[78:81], v[30:33], v[62:65], v[78:81]
	ds_read_b128 v[118:121], v111 offset:34848
	v_mfma_f32_16x16x32_bf16 v[74:77], v[34:37], v[46:49], v[74:77]
	ds_read_b128 v[150:153], v159 offset:36896
	v_mfma_f32_16x16x32_bf16 v[70:73], v[34:37], v[50:53], v[70:73]
	ds_read_b128 v[154:157], v159 offset:38944
	v_mfma_f32_16x16x32_bf16 v[66:69], v[34:37], v[54:57], v[66:69]
	ds_read_b128 v[122:125], v111 offset:36896
	v_mfma_f32_16x16x32_bf16 v[58:61], v[34:37], v[62:65], v[58:61]
	ds_read_b128 v[138:141], v111 offset:38944
	v_mfma_f32_16x16x32_bf16 v[26:29], v[38:41], v[46:49], v[26:29]
	v_mfma_f32_16x16x32_bf16 v[22:25], v[38:41], v[50:53], v[22:25]
	v_mfma_f32_16x16x32_bf16 v[18:21], v[38:41], v[54:57], v[18:21]
	v_mfma_f32_16x16x32_bf16 v[14:17], v[38:41], v[62:65], v[14:17]
	v_mfma_f32_16x16x32_bf16 v[10:13], v[42:45], v[46:49], v[10:13]
	v_mfma_f32_16x16x32_bf16 v[6:9], v[42:45], v[50:53], v[6:9]
	v_mfma_f32_16x16x32_bf16 v[2:5], v[42:45], v[54:57], v[2:5]
	v_mfma_f32_16x16x32_bf16 v[86:89], v[42:45], v[62:65], v[86:89]
	s_waitcnt lgkmcnt(0)
	v_mfma_f32_16x16x32_bf16 v[94:97], v[114:117], v[142:145], v[94:97]
	v_mfma_f32_16x16x32_bf16 v[90:93], v[114:117], v[146:149], v[90:93]
	v_mfma_f32_16x16x32_bf16 v[82:85], v[114:117], v[150:153], v[82:85]
	v_mfma_f32_16x16x32_bf16 v[78:81], v[114:117], v[154:157], v[78:81]
	v_mfma_f32_16x16x32_bf16 v[74:77], v[118:121], v[142:145], v[74:77]
	v_mfma_f32_16x16x32_bf16 v[70:73], v[118:121], v[146:149], v[70:73]
	v_mfma_f32_16x16x32_bf16 v[66:69], v[118:121], v[150:153], v[66:69]
	v_mfma_f32_16x16x32_bf16 v[58:61], v[118:121], v[154:157], v[58:61]
	v_mfma_f32_16x16x32_bf16 v[26:29], v[122:125], v[142:145], v[26:29]
	v_mfma_f32_16x16x32_bf16 v[22:25], v[122:125], v[146:149], v[22:25]
	v_mfma_f32_16x16x32_bf16 v[18:21], v[122:125], v[150:153], v[18:21]
	v_mfma_f32_16x16x32_bf16 v[14:17], v[122:125], v[154:157], v[14:17]
	v_mfma_f32_16x16x32_bf16 v[10:13], v[138:141], v[142:145], v[10:13]
	v_mfma_f32_16x16x32_bf16 v[6:9], v[138:141], v[146:149], v[6:9]
	v_mfma_f32_16x16x32_bf16 v[2:5], v[138:141], v[150:153], v[2:5]
	v_mfma_f32_16x16x32_bf16 v[86:89], v[138:141], v[154:157], v[86:89]
	s_setprio 0
	v_lshrrev_b32_e32 v117, 4, v0
	v_and_b32_e32 v117, 15, v117
	v_and_b32_e32 v118, 15, v0
	v_lshlrev_b32_e32 v118, 4, v118
	v_lshl_or_b32 v117, v117, 12, v118
	s_lshl_b32 s100, s48, 12
	s_lshl_b32 s98, s47, 8
	s_add_u32 s100, s100, s98
	s_add_u32 s98, s42, s100
	s_addc_u32 s99, s43, 0
	s_add_u32 s98, s98, 0x12d24000
	s_addc_u32 s99, s99, 0
	global_load_dwordx4 v[148:151], v117, s[98:99]
	global_load_dwordx4 v[152:155], v117, s[98:99] offset:2048
	s_add_u32 s98, s98, 0x10000
	s_addc_u32 s99, s99, 0
	global_load_dwordx4 v[156:159], v117, s[98:99]
	global_load_dwordx4 v[160:163], v117, s[98:99] offset:2048
	s_add_u32 s98, s98, 0x10000
	s_addc_u32 s99, s99, 0
	global_load_dwordx4 v[164:167], v117, s[98:99]
	global_load_dwordx4 v[168:171], v117, s[98:99] offset:2048
	s_add_u32 s98, s98, 0x10000
	s_addc_u32 s99, s99, 0
	global_load_dwordx4 v[172:175], v117, s[98:99]
	global_load_dwordx4 v[188:191], v117, s[98:99] offset:2048
	s_add_u32 s98, s98, 0x10000
	s_addc_u32 s99, s99, 0
	global_load_dwordx4 v[192:195], v117, s[98:99]
	global_load_dwordx4 v[196:199], v117, s[98:99] offset:2048
	s_add_u32 s98, s98, 0x10000
	s_addc_u32 s99, s99, 0
	global_load_dwordx4 v[200:203], v117, s[98:99]
	global_load_dwordx4 v[204:207], v117, s[98:99] offset:2048
	s_add_u32 s98, s98, 0x10000
	s_addc_u32 s99, s99, 0
	global_load_dwordx4 v[208:211], v117, s[98:99]
	global_load_dwordx4 v[34:37], v117, s[98:99] offset:2048
	s_add_u32 s98, s98, 0x10000
	s_addc_u32 s99, s99, 0
	global_load_dwordx4 v[38:41], v117, s[98:99]
	global_load_dwordx4 v[52:55], v117, s[98:99] offset:2048
	s_mul_i32 s4, s31, s25
	s_add_i32 s4, s4, s30
	s_and_b32 s4, s4, 0xff
	v_lshl_or_b32 v30, s4, 10, v132
	s_mul_hi_u32 s4, s4, 0x15555556
	s_mulk_i32 s4, 0xd000
	v_add_u32_e32 v30, s4, v30
	s_lshl_b32 s4, s47, 8
	v_add_u32_e32 v138, 0x400, v129
	v_add_u32_e32 v139, 0x2000, v129
	v_add_u32_e32 v140, 0x2400, v129
	v_add_u32_e32 v141, 0x4000, v129
	v_add_u32_e32 v142, 0x4400, v129
	v_add_u32_e32 v143, 0x4800, v129
	v_add_u32_e32 v144, 0x6000, v129
	v_add_u32_e32 v145, 0x6400, v129
	v_add_u32_e32 v146, 0x6800, v129
	v_lshl_add_u64 v[114:115], v[102:103], 0, s[4:5]
	v_cmp_gt_u32_e32 vcc, s29, v30
	s_barrier
	ds_write2_b32 v129, v94, v90 offset1:16
	ds_write2_b32 v129, v95, v91 offset0:132 offset1:148
	ds_write2_b32 v138, v96, v92 offset0:8 offset1:24
	ds_write2_b32 v138, v97, v93 offset0:140 offset1:156
	ds_write2_b32 v129, v82, v78 offset0:32 offset1:48
	ds_write2_b32 v129, v83, v79 offset0:164 offset1:180
	ds_write2_b32 v138, v84, v80 offset0:40 offset1:56
	ds_write2_b32 v138, v85, v81 offset0:172 offset1:188
	ds_write2_b32 v139, v74, v70 offset0:64 offset1:80
	ds_write2_b32 v139, v75, v71 offset0:196 offset1:212
	ds_write2_b32 v140, v76, v72 offset0:72 offset1:88
	ds_write2_b32 v140, v77, v73 offset0:204 offset1:220
	ds_write2_b32 v139, v66, v58 offset0:96 offset1:112
	ds_write2_b32 v139, v67, v59 offset0:228 offset1:244
	ds_write2_b32 v140, v68, v60 offset0:104 offset1:120
	ds_write2_b32 v140, v69, v61 offset0:236 offset1:252
	ds_write2_b32 v141, v26, v22 offset0:128 offset1:144
	ds_write2_b32 v142, v27, v23 offset0:4 offset1:20
	ds_write2_b32 v142, v28, v24 offset0:136 offset1:152
	ds_write2_b32 v143, v29, v25 offset0:12 offset1:28
	ds_write2_b32 v141, v18, v14 offset0:160 offset1:176
	ds_write2_b32 v142, v19, v15 offset0:36 offset1:52
	ds_write2_b32 v142, v20, v16 offset0:168 offset1:184
	ds_write2_b32 v143, v21, v17 offset0:44 offset1:60
	ds_write2_b32 v144, v10, v6 offset0:192 offset1:208
	ds_write2_b32 v145, v11, v7 offset0:68 offset1:84
	ds_write2_b32 v145, v12, v8 offset0:200 offset1:216
	ds_write2_b32 v146, v13, v9 offset0:76 offset1:92
	ds_write2_b32 v144, v2, v86 offset0:224 offset1:240
	ds_write2_b32 v145, v3, v87 offset0:100 offset1:116
	ds_write2_b32 v145, v4, v88 offset0:232 offset1:248
	ds_write2_b32 v146, v5, v89 offset0:108 offset1:124
	s_waitcnt lgkmcnt(0)
	s_barrier
	v_lshrrev_b32_e32 v50, 4, v0
	v_and_b32_e32 v50, 15, v50
	v_mul_u32_u24_e32 v50, 0x210, v50
	v_and_b32_e32 v2, 15, v0
	v_lshl_add_u32 v50, v2, 5, v50
	ds_read_b128 v[42:45], v50 offset:32
	ds_read_b128 v[46:49], v50 offset:48
	s_waitcnt vmcnt(14)
	v_lshlrev_b32_e32 v2, 16, v148
	v_lshlrev_b32_e32 v3, 16, v152
	v_div_scale_f32 v4, s[4:5], v3, v3, v2
	v_rcp_f32_e32 v5, v4
	s_nop 0
	v_fma_f32 v6, -v4, v5, 1.0
	v_fmac_f32_e32 v5, v6, v5
	v_div_scale_f32 v7, vcc, v2, v3, v2
	v_mul_f32_e32 v8, v7, v5
	v_fma_f32 v6, -v4, v8, v7
	v_fmac_f32_e32 v8, v6, v5
	v_fma_f32 v4, -v4, v8, v7
	v_div_fmas_f32 v4, v4, v5, v8
	v_div_fixup_f32 v10, v4, v3, v2
	v_and_b32_e32 v2, 0xffff0000, v148
	v_and_b32_e32 v3, 0xffff0000, v152
	v_div_scale_f32 v4, s[4:5], v3, v3, v2
	v_rcp_f32_e32 v5, v4
	s_nop 0
	v_fma_f32 v6, -v4, v5, 1.0
	v_fmac_f32_e32 v5, v6, v5
	v_div_scale_f32 v7, vcc, v2, v3, v2
	v_mul_f32_e32 v8, v7, v5
	v_fma_f32 v6, -v4, v8, v7
	v_fmac_f32_e32 v8, v6, v5
	v_fma_f32 v4, -v4, v8, v7
	v_div_fmas_f32 v4, v4, v5, v8
	v_div_fixup_f32 v11, v4, v3, v2
	v_lshlrev_b32_e32 v2, 16, v149
	v_lshlrev_b32_e32 v3, 16, v153
	v_div_scale_f32 v4, s[4:5], v3, v3, v2
	v_rcp_f32_e32 v5, v4
	s_nop 0
	v_fma_f32 v6, -v4, v5, 1.0
	v_fmac_f32_e32 v5, v6, v5
	v_div_scale_f32 v7, vcc, v2, v3, v2
	v_mul_f32_e32 v8, v7, v5
	v_fma_f32 v6, -v4, v8, v7
	v_fmac_f32_e32 v8, v6, v5
	v_fma_f32 v4, -v4, v8, v7
	v_div_fmas_f32 v4, v4, v5, v8
	v_div_fixup_f32 v12, v4, v3, v2
	v_and_b32_e32 v2, 0xffff0000, v149
	v_and_b32_e32 v3, 0xffff0000, v153
	v_div_scale_f32 v4, s[4:5], v3, v3, v2
	v_rcp_f32_e32 v5, v4
	s_nop 0
	v_fma_f32 v6, -v4, v5, 1.0
	v_fmac_f32_e32 v5, v6, v5
	v_div_scale_f32 v7, vcc, v2, v3, v2
	v_mul_f32_e32 v8, v7, v5
	v_fma_f32 v6, -v4, v8, v7
	v_fmac_f32_e32 v8, v6, v5
	v_fma_f32 v4, -v4, v8, v7
	v_div_fmas_f32 v4, v4, v5, v8
	v_div_fixup_f32 v13, v4, v3, v2
	v_lshlrev_b32_e32 v2, 16, v150
	v_lshlrev_b32_e32 v3, 16, v154
	v_div_scale_f32 v4, s[4:5], v3, v3, v2
	v_rcp_f32_e32 v5, v4
	s_nop 0
	v_fma_f32 v6, -v4, v5, 1.0
	v_fmac_f32_e32 v5, v6, v5
	v_div_scale_f32 v7, vcc, v2, v3, v2
	v_mul_f32_e32 v8, v7, v5
	v_fma_f32 v6, -v4, v8, v7
	v_fmac_f32_e32 v8, v6, v5
	v_fma_f32 v4, -v4, v8, v7
	v_div_fmas_f32 v4, v4, v5, v8
	v_div_fixup_f32 v14, v4, v3, v2
	v_and_b32_e32 v2, 0xffff0000, v150
	v_and_b32_e32 v3, 0xffff0000, v154
	v_div_scale_f32 v4, s[4:5], v3, v3, v2
	v_rcp_f32_e32 v5, v4
	s_nop 0
	v_fma_f32 v6, -v4, v5, 1.0
	v_fmac_f32_e32 v5, v6, v5
	v_div_scale_f32 v7, vcc, v2, v3, v2
	v_mul_f32_e32 v8, v7, v5
	v_fma_f32 v6, -v4, v8, v7
	v_fmac_f32_e32 v8, v6, v5
	v_fma_f32 v4, -v4, v8, v7
	v_div_fmas_f32 v4, v4, v5, v8
	v_div_fixup_f32 v15, v4, v3, v2
	v_lshlrev_b32_e32 v2, 16, v151
	v_lshlrev_b32_e32 v3, 16, v155
	v_div_scale_f32 v4, s[4:5], v3, v3, v2
	v_rcp_f32_e32 v5, v4
	s_nop 0
	v_fma_f32 v6, -v4, v5, 1.0
	v_fmac_f32_e32 v5, v6, v5
	v_div_scale_f32 v7, vcc, v2, v3, v2
	v_mul_f32_e32 v8, v7, v5
	v_fma_f32 v6, -v4, v8, v7
	v_fmac_f32_e32 v8, v6, v5
	v_fma_f32 v4, -v4, v8, v7
	v_div_fmas_f32 v4, v4, v5, v8
	v_div_fixup_f32 v16, v4, v3, v2
	v_and_b32_e32 v2, 0xffff0000, v151
	v_and_b32_e32 v3, 0xffff0000, v155
	v_div_scale_f32 v4, s[4:5], v3, v3, v2
	v_rcp_f32_e32 v5, v4
	s_nop 0
	v_fma_f32 v6, -v4, v5, 1.0
	v_fmac_f32_e32 v5, v6, v5
	v_div_scale_f32 v7, vcc, v2, v3, v2
	v_mul_f32_e32 v8, v7, v5
	v_fma_f32 v6, -v4, v8, v7
	v_fmac_f32_e32 v8, v6, v5
	v_fma_f32 v4, -v4, v8, v7
	v_div_fmas_f32 v4, v4, v5, v8
	v_div_fixup_f32 v17, v4, v3, v2
	s_waitcnt lgkmcnt(0)
	v_pk_mul_f32 v[42:43], v[42:43], v[10:11]
	v_pk_mul_f32 v[44:45], v[44:45], v[12:13]
	v_pk_mul_f32 v[46:47], v[46:47], v[14:15]
	v_pk_mul_f32 v[48:49], v[48:49], v[16:17]
	ds_write_b128 v50, v[42:45] offset:32
	ds_write_b128 v50, v[46:49] offset:48
	ds_read_b128 v[42:45], v50 offset:8480
	ds_read_b128 v[46:49], v50 offset:8496
	s_waitcnt vmcnt(12)
	v_lshlrev_b32_e32 v2, 16, v156
	v_lshlrev_b32_e32 v3, 16, v160
	v_div_scale_f32 v4, s[4:5], v3, v3, v2
	v_rcp_f32_e32 v5, v4
	s_nop 0
	v_fma_f32 v6, -v4, v5, 1.0
	v_fmac_f32_e32 v5, v6, v5
	v_div_scale_f32 v7, vcc, v2, v3, v2
	v_mul_f32_e32 v8, v7, v5
	v_fma_f32 v6, -v4, v8, v7
	v_fmac_f32_e32 v8, v6, v5
	v_fma_f32 v4, -v4, v8, v7
	v_div_fmas_f32 v4, v4, v5, v8
	v_div_fixup_f32 v10, v4, v3, v2
	v_and_b32_e32 v2, 0xffff0000, v156
	v_and_b32_e32 v3, 0xffff0000, v160
	v_div_scale_f32 v4, s[4:5], v3, v3, v2
	v_rcp_f32_e32 v5, v4
	s_nop 0
	v_fma_f32 v6, -v4, v5, 1.0
	v_fmac_f32_e32 v5, v6, v5
	v_div_scale_f32 v7, vcc, v2, v3, v2
	v_mul_f32_e32 v8, v7, v5
	v_fma_f32 v6, -v4, v8, v7
	v_fmac_f32_e32 v8, v6, v5
	v_fma_f32 v4, -v4, v8, v7
	v_div_fmas_f32 v4, v4, v5, v8
	v_div_fixup_f32 v11, v4, v3, v2
	v_lshlrev_b32_e32 v2, 16, v157
	v_lshlrev_b32_e32 v3, 16, v161
	v_div_scale_f32 v4, s[4:5], v3, v3, v2
	v_rcp_f32_e32 v5, v4
	s_nop 0
	v_fma_f32 v6, -v4, v5, 1.0
	v_fmac_f32_e32 v5, v6, v5
	v_div_scale_f32 v7, vcc, v2, v3, v2
	v_mul_f32_e32 v8, v7, v5
	v_fma_f32 v6, -v4, v8, v7
	v_fmac_f32_e32 v8, v6, v5
	v_fma_f32 v4, -v4, v8, v7
	v_div_fmas_f32 v4, v4, v5, v8
	v_div_fixup_f32 v12, v4, v3, v2
	v_and_b32_e32 v2, 0xffff0000, v157
	v_and_b32_e32 v3, 0xffff0000, v161
	v_div_scale_f32 v4, s[4:5], v3, v3, v2
	v_rcp_f32_e32 v5, v4
	s_nop 0
	v_fma_f32 v6, -v4, v5, 1.0
	v_fmac_f32_e32 v5, v6, v5
	v_div_scale_f32 v7, vcc, v2, v3, v2
	v_mul_f32_e32 v8, v7, v5
	v_fma_f32 v6, -v4, v8, v7
	v_fmac_f32_e32 v8, v6, v5
	v_fma_f32 v4, -v4, v8, v7
	v_div_fmas_f32 v4, v4, v5, v8
	v_div_fixup_f32 v13, v4, v3, v2
	v_lshlrev_b32_e32 v2, 16, v158
	v_lshlrev_b32_e32 v3, 16, v162
	v_div_scale_f32 v4, s[4:5], v3, v3, v2
	v_rcp_f32_e32 v5, v4
	s_nop 0
	v_fma_f32 v6, -v4, v5, 1.0
	v_fmac_f32_e32 v5, v6, v5
	v_div_scale_f32 v7, vcc, v2, v3, v2
	v_mul_f32_e32 v8, v7, v5
	v_fma_f32 v6, -v4, v8, v7
	v_fmac_f32_e32 v8, v6, v5
	v_fma_f32 v4, -v4, v8, v7
	v_div_fmas_f32 v4, v4, v5, v8
	v_div_fixup_f32 v14, v4, v3, v2
	v_and_b32_e32 v2, 0xffff0000, v158
	v_and_b32_e32 v3, 0xffff0000, v162
	v_div_scale_f32 v4, s[4:5], v3, v3, v2
	v_rcp_f32_e32 v5, v4
	s_nop 0
	v_fma_f32 v6, -v4, v5, 1.0
	v_fmac_f32_e32 v5, v6, v5
	v_div_scale_f32 v7, vcc, v2, v3, v2
	v_mul_f32_e32 v8, v7, v5
	v_fma_f32 v6, -v4, v8, v7
	v_fmac_f32_e32 v8, v6, v5
	v_fma_f32 v4, -v4, v8, v7
	v_div_fmas_f32 v4, v4, v5, v8
	v_div_fixup_f32 v15, v4, v3, v2
	v_lshlrev_b32_e32 v2, 16, v159
	v_lshlrev_b32_e32 v3, 16, v163
	v_div_scale_f32 v4, s[4:5], v3, v3, v2
	v_rcp_f32_e32 v5, v4
	s_nop 0
	v_fma_f32 v6, -v4, v5, 1.0
	v_fmac_f32_e32 v5, v6, v5
	v_div_scale_f32 v7, vcc, v2, v3, v2
	v_mul_f32_e32 v8, v7, v5
	v_fma_f32 v6, -v4, v8, v7
	v_fmac_f32_e32 v8, v6, v5
	v_fma_f32 v4, -v4, v8, v7
	v_div_fmas_f32 v4, v4, v5, v8
	v_div_fixup_f32 v16, v4, v3, v2
	v_and_b32_e32 v2, 0xffff0000, v159
	v_and_b32_e32 v3, 0xffff0000, v163
	v_div_scale_f32 v4, s[4:5], v3, v3, v2
	v_rcp_f32_e32 v5, v4
	s_nop 0
	v_fma_f32 v6, -v4, v5, 1.0
	v_fmac_f32_e32 v5, v6, v5
	v_div_scale_f32 v7, vcc, v2, v3, v2
	v_mul_f32_e32 v8, v7, v5
	v_fma_f32 v6, -v4, v8, v7
	v_fmac_f32_e32 v8, v6, v5
	v_fma_f32 v4, -v4, v8, v7
	v_div_fmas_f32 v4, v4, v5, v8
	v_div_fixup_f32 v17, v4, v3, v2
	s_waitcnt lgkmcnt(0)
	v_pk_mul_f32 v[42:43], v[42:43], v[10:11]
	v_pk_mul_f32 v[44:45], v[44:45], v[12:13]
	v_pk_mul_f32 v[46:47], v[46:47], v[14:15]
	v_pk_mul_f32 v[48:49], v[48:49], v[16:17]
	ds_write_b128 v50, v[42:45] offset:8480
	ds_write_b128 v50, v[46:49] offset:8496
	ds_read_b128 v[42:45], v50 offset:16928
	ds_read_b128 v[46:49], v50 offset:16944
	s_waitcnt vmcnt(10)
	v_lshlrev_b32_e32 v2, 16, v164
	v_lshlrev_b32_e32 v3, 16, v168
	v_div_scale_f32 v4, s[4:5], v3, v3, v2
	v_rcp_f32_e32 v5, v4
	s_nop 0
	v_fma_f32 v6, -v4, v5, 1.0
	v_fmac_f32_e32 v5, v6, v5
	v_div_scale_f32 v7, vcc, v2, v3, v2
	v_mul_f32_e32 v8, v7, v5
	v_fma_f32 v6, -v4, v8, v7
	v_fmac_f32_e32 v8, v6, v5
	v_fma_f32 v4, -v4, v8, v7
	v_div_fmas_f32 v4, v4, v5, v8
	v_div_fixup_f32 v10, v4, v3, v2
	v_and_b32_e32 v2, 0xffff0000, v164
	v_and_b32_e32 v3, 0xffff0000, v168
	v_div_scale_f32 v4, s[4:5], v3, v3, v2
	v_rcp_f32_e32 v5, v4
	s_nop 0
	v_fma_f32 v6, -v4, v5, 1.0
	v_fmac_f32_e32 v5, v6, v5
	v_div_scale_f32 v7, vcc, v2, v3, v2
	v_mul_f32_e32 v8, v7, v5
	v_fma_f32 v6, -v4, v8, v7
	v_fmac_f32_e32 v8, v6, v5
	v_fma_f32 v4, -v4, v8, v7
	v_div_fmas_f32 v4, v4, v5, v8
	v_div_fixup_f32 v11, v4, v3, v2
	v_lshlrev_b32_e32 v2, 16, v165
	v_lshlrev_b32_e32 v3, 16, v169
	v_div_scale_f32 v4, s[4:5], v3, v3, v2
	v_rcp_f32_e32 v5, v4
	s_nop 0
	v_fma_f32 v6, -v4, v5, 1.0
	v_fmac_f32_e32 v5, v6, v5
	v_div_scale_f32 v7, vcc, v2, v3, v2
	v_mul_f32_e32 v8, v7, v5
	v_fma_f32 v6, -v4, v8, v7
	v_fmac_f32_e32 v8, v6, v5
	v_fma_f32 v4, -v4, v8, v7
	v_div_fmas_f32 v4, v4, v5, v8
	v_div_fixup_f32 v12, v4, v3, v2
	v_and_b32_e32 v2, 0xffff0000, v165
	v_and_b32_e32 v3, 0xffff0000, v169
	v_div_scale_f32 v4, s[4:5], v3, v3, v2
	v_rcp_f32_e32 v5, v4
	s_nop 0
	v_fma_f32 v6, -v4, v5, 1.0
	v_fmac_f32_e32 v5, v6, v5
	v_div_scale_f32 v7, vcc, v2, v3, v2
	v_mul_f32_e32 v8, v7, v5
	v_fma_f32 v6, -v4, v8, v7
	v_fmac_f32_e32 v8, v6, v5
	v_fma_f32 v4, -v4, v8, v7
	v_div_fmas_f32 v4, v4, v5, v8
	v_div_fixup_f32 v13, v4, v3, v2
	v_lshlrev_b32_e32 v2, 16, v166
	v_lshlrev_b32_e32 v3, 16, v170
	v_div_scale_f32 v4, s[4:5], v3, v3, v2
	v_rcp_f32_e32 v5, v4
	s_nop 0
	v_fma_f32 v6, -v4, v5, 1.0
	v_fmac_f32_e32 v5, v6, v5
	v_div_scale_f32 v7, vcc, v2, v3, v2
	v_mul_f32_e32 v8, v7, v5
	v_fma_f32 v6, -v4, v8, v7
	v_fmac_f32_e32 v8, v6, v5
	v_fma_f32 v4, -v4, v8, v7
	v_div_fmas_f32 v4, v4, v5, v8
	v_div_fixup_f32 v14, v4, v3, v2
	v_and_b32_e32 v2, 0xffff0000, v166
	v_and_b32_e32 v3, 0xffff0000, v170
	v_div_scale_f32 v4, s[4:5], v3, v3, v2
	v_rcp_f32_e32 v5, v4
	s_nop 0
	v_fma_f32 v6, -v4, v5, 1.0
	v_fmac_f32_e32 v5, v6, v5
	v_div_scale_f32 v7, vcc, v2, v3, v2
	v_mul_f32_e32 v8, v7, v5
	v_fma_f32 v6, -v4, v8, v7
	v_fmac_f32_e32 v8, v6, v5
	v_fma_f32 v4, -v4, v8, v7
	v_div_fmas_f32 v4, v4, v5, v8
	v_div_fixup_f32 v15, v4, v3, v2
	v_lshlrev_b32_e32 v2, 16, v167
	v_lshlrev_b32_e32 v3, 16, v171
	v_div_scale_f32 v4, s[4:5], v3, v3, v2
	v_rcp_f32_e32 v5, v4
	s_nop 0
	v_fma_f32 v6, -v4, v5, 1.0
	v_fmac_f32_e32 v5, v6, v5
	v_div_scale_f32 v7, vcc, v2, v3, v2
	v_mul_f32_e32 v8, v7, v5
	v_fma_f32 v6, -v4, v8, v7
	v_fmac_f32_e32 v8, v6, v5
	v_fma_f32 v4, -v4, v8, v7
	v_div_fmas_f32 v4, v4, v5, v8
	v_div_fixup_f32 v16, v4, v3, v2
	v_and_b32_e32 v2, 0xffff0000, v167
	v_and_b32_e32 v3, 0xffff0000, v171
	v_div_scale_f32 v4, s[4:5], v3, v3, v2
	v_rcp_f32_e32 v5, v4
	s_nop 0
	v_fma_f32 v6, -v4, v5, 1.0
	v_fmac_f32_e32 v5, v6, v5
	v_div_scale_f32 v7, vcc, v2, v3, v2
	v_mul_f32_e32 v8, v7, v5
	v_fma_f32 v6, -v4, v8, v7
	v_fmac_f32_e32 v8, v6, v5
	v_fma_f32 v4, -v4, v8, v7
	v_div_fmas_f32 v4, v4, v5, v8
	v_div_fixup_f32 v17, v4, v3, v2
	s_waitcnt lgkmcnt(0)
	v_pk_mul_f32 v[42:43], v[42:43], v[10:11]
	v_pk_mul_f32 v[44:45], v[44:45], v[12:13]
	v_pk_mul_f32 v[46:47], v[46:47], v[14:15]
	v_pk_mul_f32 v[48:49], v[48:49], v[16:17]
	ds_write_b128 v50, v[42:45] offset:16928
	ds_write_b128 v50, v[46:49] offset:16944
	ds_read_b128 v[42:45], v50 offset:25376
	ds_read_b128 v[46:49], v50 offset:25392
	s_waitcnt vmcnt(8)
	v_lshlrev_b32_e32 v2, 16, v172
	v_lshlrev_b32_e32 v3, 16, v188
	v_div_scale_f32 v4, s[4:5], v3, v3, v2
	v_rcp_f32_e32 v5, v4
	s_nop 0
	v_fma_f32 v6, -v4, v5, 1.0
	v_fmac_f32_e32 v5, v6, v5
	v_div_scale_f32 v7, vcc, v2, v3, v2
	v_mul_f32_e32 v8, v7, v5
	v_fma_f32 v6, -v4, v8, v7
	v_fmac_f32_e32 v8, v6, v5
	v_fma_f32 v4, -v4, v8, v7
	v_div_fmas_f32 v4, v4, v5, v8
	v_div_fixup_f32 v10, v4, v3, v2
	v_and_b32_e32 v2, 0xffff0000, v172
	v_and_b32_e32 v3, 0xffff0000, v188
	v_div_scale_f32 v4, s[4:5], v3, v3, v2
	v_rcp_f32_e32 v5, v4
	s_nop 0
	v_fma_f32 v6, -v4, v5, 1.0
	v_fmac_f32_e32 v5, v6, v5
	v_div_scale_f32 v7, vcc, v2, v3, v2
	v_mul_f32_e32 v8, v7, v5
	v_fma_f32 v6, -v4, v8, v7
	v_fmac_f32_e32 v8, v6, v5
	v_fma_f32 v4, -v4, v8, v7
	v_div_fmas_f32 v4, v4, v5, v8
	v_div_fixup_f32 v11, v4, v3, v2
	v_lshlrev_b32_e32 v2, 16, v173
	v_lshlrev_b32_e32 v3, 16, v189
	v_div_scale_f32 v4, s[4:5], v3, v3, v2
	v_rcp_f32_e32 v5, v4
	s_nop 0
	v_fma_f32 v6, -v4, v5, 1.0
	v_fmac_f32_e32 v5, v6, v5
	v_div_scale_f32 v7, vcc, v2, v3, v2
	v_mul_f32_e32 v8, v7, v5
	v_fma_f32 v6, -v4, v8, v7
	v_fmac_f32_e32 v8, v6, v5
	v_fma_f32 v4, -v4, v8, v7
	v_div_fmas_f32 v4, v4, v5, v8
	v_div_fixup_f32 v12, v4, v3, v2
	v_and_b32_e32 v2, 0xffff0000, v173
	v_and_b32_e32 v3, 0xffff0000, v189
	v_div_scale_f32 v4, s[4:5], v3, v3, v2
	v_rcp_f32_e32 v5, v4
	s_nop 0
	v_fma_f32 v6, -v4, v5, 1.0
	v_fmac_f32_e32 v5, v6, v5
	v_div_scale_f32 v7, vcc, v2, v3, v2
	v_mul_f32_e32 v8, v7, v5
	v_fma_f32 v6, -v4, v8, v7
	v_fmac_f32_e32 v8, v6, v5
	v_fma_f32 v4, -v4, v8, v7
	v_div_fmas_f32 v4, v4, v5, v8
	v_div_fixup_f32 v13, v4, v3, v2
	v_lshlrev_b32_e32 v2, 16, v174
	v_lshlrev_b32_e32 v3, 16, v190
	v_div_scale_f32 v4, s[4:5], v3, v3, v2
	v_rcp_f32_e32 v5, v4
	s_nop 0
	v_fma_f32 v6, -v4, v5, 1.0
	v_fmac_f32_e32 v5, v6, v5
	v_div_scale_f32 v7, vcc, v2, v3, v2
	v_mul_f32_e32 v8, v7, v5
	v_fma_f32 v6, -v4, v8, v7
	v_fmac_f32_e32 v8, v6, v5
	v_fma_f32 v4, -v4, v8, v7
	v_div_fmas_f32 v4, v4, v5, v8
	v_div_fixup_f32 v14, v4, v3, v2
	v_and_b32_e32 v2, 0xffff0000, v174
	v_and_b32_e32 v3, 0xffff0000, v190
	v_div_scale_f32 v4, s[4:5], v3, v3, v2
	v_rcp_f32_e32 v5, v4
	s_nop 0
	v_fma_f32 v6, -v4, v5, 1.0
	v_fmac_f32_e32 v5, v6, v5
	v_div_scale_f32 v7, vcc, v2, v3, v2
	v_mul_f32_e32 v8, v7, v5
	v_fma_f32 v6, -v4, v8, v7
	v_fmac_f32_e32 v8, v6, v5
	v_fma_f32 v4, -v4, v8, v7
	v_div_fmas_f32 v4, v4, v5, v8
	v_div_fixup_f32 v15, v4, v3, v2
	v_lshlrev_b32_e32 v2, 16, v175
	v_lshlrev_b32_e32 v3, 16, v191
	v_div_scale_f32 v4, s[4:5], v3, v3, v2
	v_rcp_f32_e32 v5, v4
	s_nop 0
	v_fma_f32 v6, -v4, v5, 1.0
	v_fmac_f32_e32 v5, v6, v5
	v_div_scale_f32 v7, vcc, v2, v3, v2
	v_mul_f32_e32 v8, v7, v5
	v_fma_f32 v6, -v4, v8, v7
	v_fmac_f32_e32 v8, v6, v5
	v_fma_f32 v4, -v4, v8, v7
	v_div_fmas_f32 v4, v4, v5, v8
	v_div_fixup_f32 v16, v4, v3, v2
	v_and_b32_e32 v2, 0xffff0000, v175
	v_and_b32_e32 v3, 0xffff0000, v191
	v_div_scale_f32 v4, s[4:5], v3, v3, v2
	v_rcp_f32_e32 v5, v4
	s_nop 0
	v_fma_f32 v6, -v4, v5, 1.0
	v_fmac_f32_e32 v5, v6, v5
	v_div_scale_f32 v7, vcc, v2, v3, v2
	v_mul_f32_e32 v8, v7, v5
	v_fma_f32 v6, -v4, v8, v7
	v_fmac_f32_e32 v8, v6, v5
	v_fma_f32 v4, -v4, v8, v7
	v_div_fmas_f32 v4, v4, v5, v8
	v_div_fixup_f32 v17, v4, v3, v2
	s_waitcnt lgkmcnt(0)
	v_pk_mul_f32 v[42:43], v[42:43], v[10:11]
	v_pk_mul_f32 v[44:45], v[44:45], v[12:13]
	v_pk_mul_f32 v[46:47], v[46:47], v[14:15]
	v_pk_mul_f32 v[48:49], v[48:49], v[16:17]
	ds_write_b128 v50, v[42:45] offset:25376
	ds_write_b128 v50, v[46:49] offset:25392
	ds_read_b128 v[42:45], v50 offset:33824
	ds_read_b128 v[46:49], v50 offset:33840
	s_waitcnt vmcnt(6)
	v_lshlrev_b32_e32 v2, 16, v192
	v_lshlrev_b32_e32 v3, 16, v196
	v_div_scale_f32 v4, s[4:5], v3, v3, v2
	v_rcp_f32_e32 v5, v4
	s_nop 0
	v_fma_f32 v6, -v4, v5, 1.0
	v_fmac_f32_e32 v5, v6, v5
	v_div_scale_f32 v7, vcc, v2, v3, v2
	v_mul_f32_e32 v8, v7, v5
	v_fma_f32 v6, -v4, v8, v7
	v_fmac_f32_e32 v8, v6, v5
	v_fma_f32 v4, -v4, v8, v7
	v_div_fmas_f32 v4, v4, v5, v8
	v_div_fixup_f32 v10, v4, v3, v2
	v_and_b32_e32 v2, 0xffff0000, v192
	v_and_b32_e32 v3, 0xffff0000, v196
	v_div_scale_f32 v4, s[4:5], v3, v3, v2
	v_rcp_f32_e32 v5, v4
	s_nop 0
	v_fma_f32 v6, -v4, v5, 1.0
	v_fmac_f32_e32 v5, v6, v5
	v_div_scale_f32 v7, vcc, v2, v3, v2
	v_mul_f32_e32 v8, v7, v5
	v_fma_f32 v6, -v4, v8, v7
	v_fmac_f32_e32 v8, v6, v5
	v_fma_f32 v4, -v4, v8, v7
	v_div_fmas_f32 v4, v4, v5, v8
	v_div_fixup_f32 v11, v4, v3, v2
	v_lshlrev_b32_e32 v2, 16, v193
	v_lshlrev_b32_e32 v3, 16, v197
	v_div_scale_f32 v4, s[4:5], v3, v3, v2
	v_rcp_f32_e32 v5, v4
	s_nop 0
	v_fma_f32 v6, -v4, v5, 1.0
	v_fmac_f32_e32 v5, v6, v5
	v_div_scale_f32 v7, vcc, v2, v3, v2
	v_mul_f32_e32 v8, v7, v5
	v_fma_f32 v6, -v4, v8, v7
	v_fmac_f32_e32 v8, v6, v5
	v_fma_f32 v4, -v4, v8, v7
	v_div_fmas_f32 v4, v4, v5, v8
	v_div_fixup_f32 v12, v4, v3, v2
	v_and_b32_e32 v2, 0xffff0000, v193
	v_and_b32_e32 v3, 0xffff0000, v197
	v_div_scale_f32 v4, s[4:5], v3, v3, v2
	v_rcp_f32_e32 v5, v4
	s_nop 0
	v_fma_f32 v6, -v4, v5, 1.0
	v_fmac_f32_e32 v5, v6, v5
	v_div_scale_f32 v7, vcc, v2, v3, v2
	v_mul_f32_e32 v8, v7, v5
	v_fma_f32 v6, -v4, v8, v7
	v_fmac_f32_e32 v8, v6, v5
	v_fma_f32 v4, -v4, v8, v7
	v_div_fmas_f32 v4, v4, v5, v8
	v_div_fixup_f32 v13, v4, v3, v2
	v_lshlrev_b32_e32 v2, 16, v194
	v_lshlrev_b32_e32 v3, 16, v198
	v_div_scale_f32 v4, s[4:5], v3, v3, v2
	v_rcp_f32_e32 v5, v4
	s_nop 0
	v_fma_f32 v6, -v4, v5, 1.0
	v_fmac_f32_e32 v5, v6, v5
	v_div_scale_f32 v7, vcc, v2, v3, v2
	v_mul_f32_e32 v8, v7, v5
	v_fma_f32 v6, -v4, v8, v7
	v_fmac_f32_e32 v8, v6, v5
	v_fma_f32 v4, -v4, v8, v7
	v_div_fmas_f32 v4, v4, v5, v8
	v_div_fixup_f32 v14, v4, v3, v2
	v_and_b32_e32 v2, 0xffff0000, v194
	v_and_b32_e32 v3, 0xffff0000, v198
	v_div_scale_f32 v4, s[4:5], v3, v3, v2
	v_rcp_f32_e32 v5, v4
	s_nop 0
	v_fma_f32 v6, -v4, v5, 1.0
	v_fmac_f32_e32 v5, v6, v5
	v_div_scale_f32 v7, vcc, v2, v3, v2
	v_mul_f32_e32 v8, v7, v5
	v_fma_f32 v6, -v4, v8, v7
	v_fmac_f32_e32 v8, v6, v5
	v_fma_f32 v4, -v4, v8, v7
	v_div_fmas_f32 v4, v4, v5, v8
	v_div_fixup_f32 v15, v4, v3, v2
	v_lshlrev_b32_e32 v2, 16, v195
	v_lshlrev_b32_e32 v3, 16, v199
	v_div_scale_f32 v4, s[4:5], v3, v3, v2
	v_rcp_f32_e32 v5, v4
	s_nop 0
	v_fma_f32 v6, -v4, v5, 1.0
	v_fmac_f32_e32 v5, v6, v5
	v_div_scale_f32 v7, vcc, v2, v3, v2
	v_mul_f32_e32 v8, v7, v5
	v_fma_f32 v6, -v4, v8, v7
	v_fmac_f32_e32 v8, v6, v5
	v_fma_f32 v4, -v4, v8, v7
	v_div_fmas_f32 v4, v4, v5, v8
	v_div_fixup_f32 v16, v4, v3, v2
	v_and_b32_e32 v2, 0xffff0000, v195
	v_and_b32_e32 v3, 0xffff0000, v199
	v_div_scale_f32 v4, s[4:5], v3, v3, v2
	v_rcp_f32_e32 v5, v4
	s_nop 0
	v_fma_f32 v6, -v4, v5, 1.0
	v_fmac_f32_e32 v5, v6, v5
	v_div_scale_f32 v7, vcc, v2, v3, v2
	v_mul_f32_e32 v8, v7, v5
	v_fma_f32 v6, -v4, v8, v7
	v_fmac_f32_e32 v8, v6, v5
	v_fma_f32 v4, -v4, v8, v7
	v_div_fmas_f32 v4, v4, v5, v8
	v_div_fixup_f32 v17, v4, v3, v2
	s_waitcnt lgkmcnt(0)
	v_pk_mul_f32 v[42:43], v[42:43], v[10:11]
	v_pk_mul_f32 v[44:45], v[44:45], v[12:13]
	v_pk_mul_f32 v[46:47], v[46:47], v[14:15]
	v_pk_mul_f32 v[48:49], v[48:49], v[16:17]
	ds_write_b128 v50, v[42:45] offset:33824
	ds_write_b128 v50, v[46:49] offset:33840
	ds_read_b128 v[42:45], v50 offset:42272
	ds_read_b128 v[46:49], v50 offset:42288
	s_waitcnt vmcnt(4)
	v_lshlrev_b32_e32 v2, 16, v200
	v_lshlrev_b32_e32 v3, 16, v204
	v_div_scale_f32 v4, s[4:5], v3, v3, v2
	v_rcp_f32_e32 v5, v4
	s_nop 0
	v_fma_f32 v6, -v4, v5, 1.0
	v_fmac_f32_e32 v5, v6, v5
	v_div_scale_f32 v7, vcc, v2, v3, v2
	v_mul_f32_e32 v8, v7, v5
	v_fma_f32 v6, -v4, v8, v7
	v_fmac_f32_e32 v8, v6, v5
	v_fma_f32 v4, -v4, v8, v7
	v_div_fmas_f32 v4, v4, v5, v8
	v_div_fixup_f32 v10, v4, v3, v2
	v_and_b32_e32 v2, 0xffff0000, v200
	v_and_b32_e32 v3, 0xffff0000, v204
	v_div_scale_f32 v4, s[4:5], v3, v3, v2
	v_rcp_f32_e32 v5, v4
	s_nop 0
	v_fma_f32 v6, -v4, v5, 1.0
	v_fmac_f32_e32 v5, v6, v5
	v_div_scale_f32 v7, vcc, v2, v3, v2
	v_mul_f32_e32 v8, v7, v5
	v_fma_f32 v6, -v4, v8, v7
	v_fmac_f32_e32 v8, v6, v5
	v_fma_f32 v4, -v4, v8, v7
	v_div_fmas_f32 v4, v4, v5, v8
	v_div_fixup_f32 v11, v4, v3, v2
	v_lshlrev_b32_e32 v2, 16, v201
	v_lshlrev_b32_e32 v3, 16, v205
	v_div_scale_f32 v4, s[4:5], v3, v3, v2
	v_rcp_f32_e32 v5, v4
	s_nop 0
	v_fma_f32 v6, -v4, v5, 1.0
	v_fmac_f32_e32 v5, v6, v5
	v_div_scale_f32 v7, vcc, v2, v3, v2
	v_mul_f32_e32 v8, v7, v5
	v_fma_f32 v6, -v4, v8, v7
	v_fmac_f32_e32 v8, v6, v5
	v_fma_f32 v4, -v4, v8, v7
	v_div_fmas_f32 v4, v4, v5, v8
	v_div_fixup_f32 v12, v4, v3, v2
	v_and_b32_e32 v2, 0xffff0000, v201
	v_and_b32_e32 v3, 0xffff0000, v205
	v_div_scale_f32 v4, s[4:5], v3, v3, v2
	v_rcp_f32_e32 v5, v4
	s_nop 0
	v_fma_f32 v6, -v4, v5, 1.0
	v_fmac_f32_e32 v5, v6, v5
	v_div_scale_f32 v7, vcc, v2, v3, v2
	v_mul_f32_e32 v8, v7, v5
	v_fma_f32 v6, -v4, v8, v7
	v_fmac_f32_e32 v8, v6, v5
	v_fma_f32 v4, -v4, v8, v7
	v_div_fmas_f32 v4, v4, v5, v8
	v_div_fixup_f32 v13, v4, v3, v2
	v_lshlrev_b32_e32 v2, 16, v202
	v_lshlrev_b32_e32 v3, 16, v206
	v_div_scale_f32 v4, s[4:5], v3, v3, v2
	v_rcp_f32_e32 v5, v4
	s_nop 0
	v_fma_f32 v6, -v4, v5, 1.0
	v_fmac_f32_e32 v5, v6, v5
	v_div_scale_f32 v7, vcc, v2, v3, v2
	v_mul_f32_e32 v8, v7, v5
	v_fma_f32 v6, -v4, v8, v7
	v_fmac_f32_e32 v8, v6, v5
	v_fma_f32 v4, -v4, v8, v7
	v_div_fmas_f32 v4, v4, v5, v8
	v_div_fixup_f32 v14, v4, v3, v2
	v_and_b32_e32 v2, 0xffff0000, v202
	v_and_b32_e32 v3, 0xffff0000, v206
	v_div_scale_f32 v4, s[4:5], v3, v3, v2
	v_rcp_f32_e32 v5, v4
	s_nop 0
	v_fma_f32 v6, -v4, v5, 1.0
	v_fmac_f32_e32 v5, v6, v5
	v_div_scale_f32 v7, vcc, v2, v3, v2
	v_mul_f32_e32 v8, v7, v5
	v_fma_f32 v6, -v4, v8, v7
	v_fmac_f32_e32 v8, v6, v5
	v_fma_f32 v4, -v4, v8, v7
	v_div_fmas_f32 v4, v4, v5, v8
	v_div_fixup_f32 v15, v4, v3, v2
	v_lshlrev_b32_e32 v2, 16, v203
	v_lshlrev_b32_e32 v3, 16, v207
	v_div_scale_f32 v4, s[4:5], v3, v3, v2
	v_rcp_f32_e32 v5, v4
	s_nop 0
	v_fma_f32 v6, -v4, v5, 1.0
	v_fmac_f32_e32 v5, v6, v5
	v_div_scale_f32 v7, vcc, v2, v3, v2
	v_mul_f32_e32 v8, v7, v5
	v_fma_f32 v6, -v4, v8, v7
	v_fmac_f32_e32 v8, v6, v5
	v_fma_f32 v4, -v4, v8, v7
	v_div_fmas_f32 v4, v4, v5, v8
	v_div_fixup_f32 v16, v4, v3, v2
	v_and_b32_e32 v2, 0xffff0000, v203
	v_and_b32_e32 v3, 0xffff0000, v207
	v_div_scale_f32 v4, s[4:5], v3, v3, v2
	v_rcp_f32_e32 v5, v4
	s_nop 0
	v_fma_f32 v6, -v4, v5, 1.0
	v_fmac_f32_e32 v5, v6, v5
	v_div_scale_f32 v7, vcc, v2, v3, v2
	v_mul_f32_e32 v8, v7, v5
	v_fma_f32 v6, -v4, v8, v7
	v_fmac_f32_e32 v8, v6, v5
	v_fma_f32 v4, -v4, v8, v7
	v_div_fmas_f32 v4, v4, v5, v8
	v_div_fixup_f32 v17, v4, v3, v2
	s_waitcnt lgkmcnt(0)
	v_pk_mul_f32 v[42:43], v[42:43], v[10:11]
	v_pk_mul_f32 v[44:45], v[44:45], v[12:13]
	v_pk_mul_f32 v[46:47], v[46:47], v[14:15]
	v_pk_mul_f32 v[48:49], v[48:49], v[16:17]
	ds_write_b128 v50, v[42:45] offset:42272
	ds_write_b128 v50, v[46:49] offset:42288
	ds_read_b128 v[42:45], v50 offset:50720
	ds_read_b128 v[46:49], v50 offset:50736
	s_waitcnt vmcnt(2)
	v_lshlrev_b32_e32 v2, 16, v208
	v_lshlrev_b32_e32 v3, 16, v34
	v_div_scale_f32 v4, s[4:5], v3, v3, v2
	v_rcp_f32_e32 v5, v4
	s_nop 0
	v_fma_f32 v6, -v4, v5, 1.0
	v_fmac_f32_e32 v5, v6, v5
	v_div_scale_f32 v7, vcc, v2, v3, v2
	v_mul_f32_e32 v8, v7, v5
	v_fma_f32 v6, -v4, v8, v7
	v_fmac_f32_e32 v8, v6, v5
	v_fma_f32 v4, -v4, v8, v7
	v_div_fmas_f32 v4, v4, v5, v8
	v_div_fixup_f32 v10, v4, v3, v2
	v_and_b32_e32 v2, 0xffff0000, v208
	v_and_b32_e32 v3, 0xffff0000, v34
	v_div_scale_f32 v4, s[4:5], v3, v3, v2
	v_rcp_f32_e32 v5, v4
	s_nop 0
	v_fma_f32 v6, -v4, v5, 1.0
	v_fmac_f32_e32 v5, v6, v5
	v_div_scale_f32 v7, vcc, v2, v3, v2
	v_mul_f32_e32 v8, v7, v5
	v_fma_f32 v6, -v4, v8, v7
	v_fmac_f32_e32 v8, v6, v5
	v_fma_f32 v4, -v4, v8, v7
	v_div_fmas_f32 v4, v4, v5, v8
	v_div_fixup_f32 v11, v4, v3, v2
	v_lshlrev_b32_e32 v2, 16, v209
	v_lshlrev_b32_e32 v3, 16, v35
	v_div_scale_f32 v4, s[4:5], v3, v3, v2
	v_rcp_f32_e32 v5, v4
	s_nop 0
	v_fma_f32 v6, -v4, v5, 1.0
	v_fmac_f32_e32 v5, v6, v5
	v_div_scale_f32 v7, vcc, v2, v3, v2
	v_mul_f32_e32 v8, v7, v5
	v_fma_f32 v6, -v4, v8, v7
	v_fmac_f32_e32 v8, v6, v5
	v_fma_f32 v4, -v4, v8, v7
	v_div_fmas_f32 v4, v4, v5, v8
	v_div_fixup_f32 v12, v4, v3, v2
	v_and_b32_e32 v2, 0xffff0000, v209
	v_and_b32_e32 v3, 0xffff0000, v35
	v_div_scale_f32 v4, s[4:5], v3, v3, v2
	v_rcp_f32_e32 v5, v4
	s_nop 0
	v_fma_f32 v6, -v4, v5, 1.0
	v_fmac_f32_e32 v5, v6, v5
	v_div_scale_f32 v7, vcc, v2, v3, v2
	v_mul_f32_e32 v8, v7, v5
	v_fma_f32 v6, -v4, v8, v7
	v_fmac_f32_e32 v8, v6, v5
	v_fma_f32 v4, -v4, v8, v7
	v_div_fmas_f32 v4, v4, v5, v8
	v_div_fixup_f32 v13, v4, v3, v2
	v_lshlrev_b32_e32 v2, 16, v210
	v_lshlrev_b32_e32 v3, 16, v36
	v_div_scale_f32 v4, s[4:5], v3, v3, v2
	v_rcp_f32_e32 v5, v4
	s_nop 0
	v_fma_f32 v6, -v4, v5, 1.0
	v_fmac_f32_e32 v5, v6, v5
	v_div_scale_f32 v7, vcc, v2, v3, v2
	v_mul_f32_e32 v8, v7, v5
	v_fma_f32 v6, -v4, v8, v7
	v_fmac_f32_e32 v8, v6, v5
	v_fma_f32 v4, -v4, v8, v7
	v_div_fmas_f32 v4, v4, v5, v8
	v_div_fixup_f32 v14, v4, v3, v2
	v_and_b32_e32 v2, 0xffff0000, v210
	v_and_b32_e32 v3, 0xffff0000, v36
	v_div_scale_f32 v4, s[4:5], v3, v3, v2
	v_rcp_f32_e32 v5, v4
	s_nop 0
	v_fma_f32 v6, -v4, v5, 1.0
	v_fmac_f32_e32 v5, v6, v5
	v_div_scale_f32 v7, vcc, v2, v3, v2
	v_mul_f32_e32 v8, v7, v5
	v_fma_f32 v6, -v4, v8, v7
	v_fmac_f32_e32 v8, v6, v5
	v_fma_f32 v4, -v4, v8, v7
	v_div_fmas_f32 v4, v4, v5, v8
	v_div_fixup_f32 v15, v4, v3, v2
	v_lshlrev_b32_e32 v2, 16, v211
	v_lshlrev_b32_e32 v3, 16, v37
	v_div_scale_f32 v4, s[4:5], v3, v3, v2
	v_rcp_f32_e32 v5, v4
	s_nop 0
	v_fma_f32 v6, -v4, v5, 1.0
	v_fmac_f32_e32 v5, v6, v5
	v_div_scale_f32 v7, vcc, v2, v3, v2
	v_mul_f32_e32 v8, v7, v5
	v_fma_f32 v6, -v4, v8, v7
	v_fmac_f32_e32 v8, v6, v5
	v_fma_f32 v4, -v4, v8, v7
	v_div_fmas_f32 v4, v4, v5, v8
	v_div_fixup_f32 v16, v4, v3, v2
	v_and_b32_e32 v2, 0xffff0000, v211
	v_and_b32_e32 v3, 0xffff0000, v37
	v_div_scale_f32 v4, s[4:5], v3, v3, v2
	v_rcp_f32_e32 v5, v4
	s_nop 0
	v_fma_f32 v6, -v4, v5, 1.0
	v_fmac_f32_e32 v5, v6, v5
	v_div_scale_f32 v7, vcc, v2, v3, v2
	v_mul_f32_e32 v8, v7, v5
	v_fma_f32 v6, -v4, v8, v7
	v_fmac_f32_e32 v8, v6, v5
	v_fma_f32 v4, -v4, v8, v7
	v_div_fmas_f32 v4, v4, v5, v8
	v_div_fixup_f32 v17, v4, v3, v2
	s_waitcnt lgkmcnt(0)
	v_pk_mul_f32 v[42:43], v[42:43], v[10:11]
	v_pk_mul_f32 v[44:45], v[44:45], v[12:13]
	v_pk_mul_f32 v[46:47], v[46:47], v[14:15]
	v_pk_mul_f32 v[48:49], v[48:49], v[16:17]
	ds_write_b128 v50, v[42:45] offset:50720
	ds_write_b128 v50, v[46:49] offset:50736
	ds_read_b128 v[42:45], v50 offset:59168
	ds_read_b128 v[46:49], v50 offset:59184
	s_waitcnt vmcnt(0)
	v_lshlrev_b32_e32 v2, 16, v38
	v_lshlrev_b32_e32 v3, 16, v52
	v_div_scale_f32 v4, s[4:5], v3, v3, v2
	v_rcp_f32_e32 v5, v4
	s_nop 0
	v_fma_f32 v6, -v4, v5, 1.0
	v_fmac_f32_e32 v5, v6, v5
	v_div_scale_f32 v7, vcc, v2, v3, v2
	v_mul_f32_e32 v8, v7, v5
	v_fma_f32 v6, -v4, v8, v7
	v_fmac_f32_e32 v8, v6, v5
	v_fma_f32 v4, -v4, v8, v7
	v_div_fmas_f32 v4, v4, v5, v8
	v_div_fixup_f32 v10, v4, v3, v2
	v_and_b32_e32 v2, 0xffff0000, v38
	v_and_b32_e32 v3, 0xffff0000, v52
	v_div_scale_f32 v4, s[4:5], v3, v3, v2
	v_rcp_f32_e32 v5, v4
	s_nop 0
	v_fma_f32 v6, -v4, v5, 1.0
	v_fmac_f32_e32 v5, v6, v5
	v_div_scale_f32 v7, vcc, v2, v3, v2
	v_mul_f32_e32 v8, v7, v5
	v_fma_f32 v6, -v4, v8, v7
	v_fmac_f32_e32 v8, v6, v5
	v_fma_f32 v4, -v4, v8, v7
	v_div_fmas_f32 v4, v4, v5, v8
	v_div_fixup_f32 v11, v4, v3, v2
	v_lshlrev_b32_e32 v2, 16, v39
	v_lshlrev_b32_e32 v3, 16, v53
	v_div_scale_f32 v4, s[4:5], v3, v3, v2
	v_rcp_f32_e32 v5, v4
	s_nop 0
	v_fma_f32 v6, -v4, v5, 1.0
	v_fmac_f32_e32 v5, v6, v5
	v_div_scale_f32 v7, vcc, v2, v3, v2
	v_mul_f32_e32 v8, v7, v5
	v_fma_f32 v6, -v4, v8, v7
	v_fmac_f32_e32 v8, v6, v5
	v_fma_f32 v4, -v4, v8, v7
	v_div_fmas_f32 v4, v4, v5, v8
	v_div_fixup_f32 v12, v4, v3, v2
	v_and_b32_e32 v2, 0xffff0000, v39
	v_and_b32_e32 v3, 0xffff0000, v53
	v_div_scale_f32 v4, s[4:5], v3, v3, v2
	v_rcp_f32_e32 v5, v4
	s_nop 0
	v_fma_f32 v6, -v4, v5, 1.0
	v_fmac_f32_e32 v5, v6, v5
	v_div_scale_f32 v7, vcc, v2, v3, v2
	v_mul_f32_e32 v8, v7, v5
	v_fma_f32 v6, -v4, v8, v7
	v_fmac_f32_e32 v8, v6, v5
	v_fma_f32 v4, -v4, v8, v7
	v_div_fmas_f32 v4, v4, v5, v8
	v_div_fixup_f32 v13, v4, v3, v2
	v_lshlrev_b32_e32 v2, 16, v40
	v_lshlrev_b32_e32 v3, 16, v54
	v_div_scale_f32 v4, s[4:5], v3, v3, v2
	v_rcp_f32_e32 v5, v4
	s_nop 0
	v_fma_f32 v6, -v4, v5, 1.0
	v_fmac_f32_e32 v5, v6, v5
	v_div_scale_f32 v7, vcc, v2, v3, v2
	v_mul_f32_e32 v8, v7, v5
	v_fma_f32 v6, -v4, v8, v7
	v_fmac_f32_e32 v8, v6, v5
	v_fma_f32 v4, -v4, v8, v7
	v_div_fmas_f32 v4, v4, v5, v8
	v_div_fixup_f32 v14, v4, v3, v2
	v_and_b32_e32 v2, 0xffff0000, v40
	v_and_b32_e32 v3, 0xffff0000, v54
	v_div_scale_f32 v4, s[4:5], v3, v3, v2
	v_rcp_f32_e32 v5, v4
	s_nop 0
	v_fma_f32 v6, -v4, v5, 1.0
	v_fmac_f32_e32 v5, v6, v5
	v_div_scale_f32 v7, vcc, v2, v3, v2
	v_mul_f32_e32 v8, v7, v5
	v_fma_f32 v6, -v4, v8, v7
	v_fmac_f32_e32 v8, v6, v5
	v_fma_f32 v4, -v4, v8, v7
	v_div_fmas_f32 v4, v4, v5, v8
	v_div_fixup_f32 v15, v4, v3, v2
	v_lshlrev_b32_e32 v2, 16, v41
	v_lshlrev_b32_e32 v3, 16, v55
	v_div_scale_f32 v4, s[4:5], v3, v3, v2
	v_rcp_f32_e32 v5, v4
	s_nop 0
	v_fma_f32 v6, -v4, v5, 1.0
	v_fmac_f32_e32 v5, v6, v5
	v_div_scale_f32 v7, vcc, v2, v3, v2
	v_mul_f32_e32 v8, v7, v5
	v_fma_f32 v6, -v4, v8, v7
	v_fmac_f32_e32 v8, v6, v5
	v_fma_f32 v4, -v4, v8, v7
	v_div_fmas_f32 v4, v4, v5, v8
	v_div_fixup_f32 v16, v4, v3, v2
	v_and_b32_e32 v2, 0xffff0000, v41
	v_and_b32_e32 v3, 0xffff0000, v55
	v_div_scale_f32 v4, s[4:5], v3, v3, v2
	v_rcp_f32_e32 v5, v4
	s_nop 0
	v_fma_f32 v6, -v4, v5, 1.0
	v_fmac_f32_e32 v5, v6, v5
	v_div_scale_f32 v7, vcc, v2, v3, v2
	v_mul_f32_e32 v8, v7, v5
	v_fma_f32 v6, -v4, v8, v7
	v_fmac_f32_e32 v8, v6, v5
	v_fma_f32 v4, -v4, v8, v7
	v_div_fmas_f32 v4, v4, v5, v8
	v_div_fixup_f32 v17, v4, v3, v2
	s_waitcnt lgkmcnt(0)
	v_pk_mul_f32 v[42:43], v[42:43], v[10:11]
	v_pk_mul_f32 v[44:45], v[44:45], v[12:13]
	v_pk_mul_f32 v[46:47], v[46:47], v[14:15]
	v_pk_mul_f32 v[48:49], v[48:49], v[16:17]
	ds_write_b128 v50, v[42:45] offset:59168
	ds_write_b128 v50, v[46:49] offset:59184
.LBB0_560:
	s_or_b64 exec, exec, s[10:11]
	s_lshl_b32 s10, s47, 7
	s_lshl_b32 s4, s35, 1
	s_add_u32 s12, s21, s4
	s_addc_u32 s13, s22, 0
	s_lshl_b32 s4, s46, 1
	v_mov_b32_e32 v111, v101
	s_add_u32 s46, s23, s4
	s_addc_u32 s47, s24, 0
	s_waitcnt lgkmcnt(0)
	s_barrier
	ds_read2_b32 v[26:27], v129 offset1:16
	ds_read2_b32 v[148:149], v129 offset0:132 offset1:148
	ds_read2_b32 v[28:29], v138 offset0:8 offset1:24
	ds_read2_b32 v[150:151], v138 offset0:140 offset1:156
	ds_read2_b32 v[22:23], v129 offset0:32 offset1:48
	ds_read2_b32 v[152:153], v129 offset0:164 offset1:180
	ds_read2_b32 v[24:25], v138 offset0:40 offset1:56
	ds_read2_b32 v[154:155], v138 offset0:172 offset1:188
	ds_read2_b32 v[18:19], v139 offset0:64 offset1:80
	ds_read2_b32 v[156:157], v139 offset0:196 offset1:212
	ds_read2_b32 v[20:21], v140 offset0:72 offset1:88
	ds_read2_b32 v[158:159], v140 offset0:204 offset1:220
	ds_read2_b32 v[14:15], v139 offset0:96 offset1:112
	ds_read2_b32 v[160:161], v139 offset0:228 offset1:244
	ds_read2_b32 v[16:17], v140 offset0:104 offset1:120
	ds_read2_b32 v[162:163], v140 offset0:236 offset1:252
	ds_read2_b32 v[10:11], v141 offset0:128 offset1:144
	ds_read2_b32 v[164:165], v142 offset0:4 offset1:20
	ds_read2_b32 v[12:13], v142 offset0:136 offset1:152
	ds_read2_b32 v[166:167], v143 offset0:12 offset1:28
	ds_read2_b32 v[6:7], v141 offset0:160 offset1:176
	ds_read2_b32 v[168:169], v142 offset0:36 offset1:52
	ds_read2_b32 v[8:9], v142 offset0:168 offset1:184
	ds_read2_b32 v[170:171], v143 offset0:44 offset1:60
	ds_read2_b32 v[2:3], v144 offset0:192 offset1:208
	ds_read2_b32 v[172:173], v145 offset0:68 offset1:84
	ds_read2_b32 v[4:5], v145 offset0:200 offset1:216
	ds_read2_b32 v[174:175], v146 offset0:76 offset1:92
	ds_read2_b32 v[30:31], v144 offset0:224 offset1:240
	ds_read2_b32 v[176:177], v145 offset0:100 offset1:116
	ds_read2_b32 v[32:33], v145 offset0:232 offset1:248
	ds_read2_b32 v[180:181], v146 offset0:108 offset1:124
	s_waitcnt lgkmcnt(0)
	s_barrier
	v_mov_b32_e32 v94, v31
	v_mov_b32_e32 v95, v177
	v_mov_b32_e32 v96, v33
	v_mov_b32_e32 v97, v181
	v_mov_b32_e32 v31, v176
	v_mov_b32_e32 v33, v180
	v_mov_b32_e32 v66, v3
	v_mov_b32_e32 v67, v173
	v_mov_b32_e32 v68, v5
	v_mov_b32_e32 v69, v175
	v_mov_b32_e32 v3, v172
	v_mov_b32_e32 v5, v174
	v_mov_b32_e32 v70, v7
	v_mov_b32_e32 v71, v169
	v_mov_b32_e32 v72, v9
	v_mov_b32_e32 v73, v171
	v_mov_b32_e32 v7, v168
	v_mov_b32_e32 v9, v170
	v_mov_b32_e32 v74, v11
	v_mov_b32_e32 v75, v165
	v_mov_b32_e32 v76, v13
	v_mov_b32_e32 v77, v167
	v_mov_b32_e32 v11, v164
	v_mov_b32_e32 v13, v166
	v_mov_b32_e32 v78, v15
	v_mov_b32_e32 v79, v161
	v_mov_b32_e32 v80, v17
	v_mov_b32_e32 v81, v163
	v_mov_b32_e32 v15, v160
	v_mov_b32_e32 v17, v162
	v_mov_b32_e32 v82, v19
	v_mov_b32_e32 v83, v157
	v_mov_b32_e32 v84, v21
	v_mov_b32_e32 v85, v159
	v_mov_b32_e32 v19, v156
	v_mov_b32_e32 v21, v158
	v_mov_b32_e32 v86, v23
	v_mov_b32_e32 v87, v153
	v_mov_b32_e32 v88, v25
	v_mov_b32_e32 v89, v155
	v_mov_b32_e32 v23, v152
	v_mov_b32_e32 v25, v154
	v_mov_b32_e32 v90, v27
	v_mov_b32_e32 v91, v149
	v_mov_b32_e32 v92, v29
	v_mov_b32_e32 v93, v151
	v_mov_b32_e32 v27, v148
	v_mov_b32_e32 v29, v150
	s_waitcnt lgkmcnt(0)
	s_barrier
	v_and_b32_e32 v174, 15, v0
	v_bfe_u32 v175, v0, 4, 2
	v_and_b32_e32 v111, 7, v174
	v_xor_b32_e32 v175, v175, v111
	v_lshlrev_b32_e32 v175, 4, v175
	v_lshl_or_b32 v175, v174, 7, v175
	v_bfe_u32 v174, v0, 7, 1
	v_lshl_or_b32 v100, v174, 13, v175
	v_bfe_u32 v174, v0, 6, 1
	v_lshl_or_b32 v168, v174, 13, v175
	v_or_b32_e32 v168, 0x4000, v168
	v_xor_b32_e32 v111, 64, v100
	v_xor_b32_e32 v169, 64, v168
	v_bfe_u32 v174, v0, 3, 3
	v_and_b32_e32 v175, 7, v0
	v_xor_b32_e32 v175, v175, v174
	v_lshlrev_b32_e32 v175, 4, v175
	v_lshl_or_b32 v175, v174, 11, v175
	v_lshrrev_b32_e32 v174, 6, v0
	v_and_b32_e32 v174, 3, v174
	v_lshl_or_b32 v170, v174, 16, v175
	v_add_u32_e32 v171, 0x3c00, v170
	v_add_u32_e32 v172, 0x7800, v170
	v_add_u32_e32 v173, 0xb400, v170
	v_lshlrev_b32_e32 v174, 12, v174
	s_nop 0
	v_readfirstlane_b32 s4, v174
	s_add_u32 s4, s4, 32
	v_mov_b32_e32 v116, 0
	v_mov_b32_e32 v117, 0
	v_mov_b32_e32 v118, 0
	v_mov_b32_e32 v119, 0
	v_mov_b32_e32 v120, 0
	v_mov_b32_e32 v121, 0
	v_mov_b32_e32 v122, 0
	v_mov_b32_e32 v123, 0
	v_mov_b32_e32 v124, 0
	v_mov_b32_e32 v125, 0
	v_mov_b32_e32 v126, 0
	v_mov_b32_e32 v127, 0
	v_mov_b32_e32 v148, 0
	v_mov_b32_e32 v149, 0
	v_mov_b32_e32 v150, 0
	v_mov_b32_e32 v151, 0
	v_mov_b32_e32 v152, 0
	v_mov_b32_e32 v153, 0
	v_mov_b32_e32 v154, 0
	v_mov_b32_e32 v155, 0
	v_mov_b32_e32 v156, 0
	v_mov_b32_e32 v157, 0
	v_mov_b32_e32 v158, 0
	v_mov_b32_e32 v159, 0
	v_mov_b32_e32 v160, 0
	v_mov_b32_e32 v161, 0
	v_mov_b32_e32 v162, 0
	v_mov_b32_e32 v163, 0
	v_mov_b32_e32 v164, 0
	v_mov_b32_e32 v165, 0
	v_mov_b32_e32 v166, 0
	v_mov_b32_e32 v167, 0
	s_waitcnt lgkmcnt(0)
	s_barrier
	v_readlane_b32 s98, v255, 16
	s_and_b32 s98, s98, 7
	s_lshl_b32 s98, s98, 1
	s_lshl_b32 s99, s98, 7
	s_add_u32 s12, s12, s99
	s_addc_u32 s13, s13, 0
	s_add_u32 s46, s46, s99
	s_addc_u32 s47, s47, 0
	s_add_u32 m0, s4, 0
	s_nop 0
	global_load_lds_dwordx4 v170, s[12:13] offset:0
	global_load_lds_dwordx4 v171, s[12:13] offset:1024
	global_load_lds_dwordx4 v172, s[12:13] offset:2048
	global_load_lds_dwordx4 v173, s[12:13] offset:3072
	s_add_u32 m0, s4, 16384
	s_nop 0
	global_load_lds_dwordx4 v170, s[46:47] offset:0
	global_load_lds_dwordx4 v171, s[46:47] offset:1024
	global_load_lds_dwordx4 v172, s[46:47] offset:2048
	global_load_lds_dwordx4 v173, s[46:47] offset:3072
	s_add_u32 s98, s98, 1
	s_and_b32 s98, s98, 15
	s_cmp_eq_u32 s98, 0
	s_cselect_b32 s99, 0x800, 0
	s_add_u32 s12, s12, 0x80
	s_addc_u32 s13, s13, 0
	s_sub_u32 s12, s12, s99
	s_subb_u32 s13, s13, 0
	s_add_u32 s46, s46, 0x80
	s_addc_u32 s47, s47, 0
	s_sub_u32 s46, s46, s99
	s_subb_u32 s47, s47, 0
	s_mov_b32 s11, 0
	s_waitcnt vmcnt(0)
	s_setprio 1
.Lk_aol0b_loop:
	s_barrier
	s_add_u32 m0, s4, 32768
	v_mfma_f32_16x16x32_bf16 v[26:29], v[116:119], v[152:155], v[26:29]
	ds_read_b128 v[34:37], v100 offset:32
	global_load_lds_dwordx4 v170, s[12:13] offset:0
	v_mfma_f32_16x16x32_bf16 v[90:93], v[116:119], v[156:159], v[90:93]
	ds_read_b128 v[50:53], v168 offset:32
	global_load_lds_dwordx4 v171, s[12:13] offset:1024
	v_mfma_f32_16x16x32_bf16 v[22:25], v[116:119], v[160:163], v[22:25]
	ds_read_b128 v[54:57], v168 offset:2080
	global_load_lds_dwordx4 v172, s[12:13] offset:2048
	v_mfma_f32_16x16x32_bf16 v[86:89], v[116:119], v[164:167], v[86:89]
	ds_read_b128 v[38:41], v100 offset:2080
	global_load_lds_dwordx4 v173, s[12:13] offset:3072
	s_add_u32 m0, s4, 49152
	v_mfma_f32_16x16x32_bf16 v[18:21], v[120:123], v[152:155], v[18:21]
	ds_read_b128 v[58:61], v168 offset:4128
	global_load_lds_dwordx4 v170, s[46:47] offset:0
	v_mfma_f32_16x16x32_bf16 v[82:85], v[120:123], v[156:159], v[82:85]
	ds_read_b128 v[62:65], v168 offset:6176
	global_load_lds_dwordx4 v171, s[46:47] offset:1024
	v_mfma_f32_16x16x32_bf16 v[14:17], v[120:123], v[160:163], v[14:17]
	ds_read_b128 v[42:45], v100 offset:4128
	global_load_lds_dwordx4 v172, s[46:47] offset:2048
	v_mfma_f32_16x16x32_bf16 v[78:81], v[120:123], v[164:167], v[78:81]
	ds_read_b128 v[46:49], v100 offset:6176
	global_load_lds_dwordx4 v173, s[46:47] offset:3072
	v_mfma_f32_16x16x32_bf16 v[10:13], v[124:127], v[152:155], v[10:13]
	v_mfma_f32_16x16x32_bf16 v[74:77], v[124:127], v[156:159], v[74:77]
	v_mfma_f32_16x16x32_bf16 v[6:9], v[124:127], v[160:163], v[6:9]
	v_mfma_f32_16x16x32_bf16 v[70:73], v[124:127], v[164:167], v[70:73]
	v_mfma_f32_16x16x32_bf16 v[2:5], v[148:151], v[152:155], v[2:5]
	v_mfma_f32_16x16x32_bf16 v[66:69], v[148:151], v[156:159], v[66:69]
	v_mfma_f32_16x16x32_bf16 v[30:33], v[148:151], v[160:163], v[30:33]
	v_mfma_f32_16x16x32_bf16 v[94:97], v[148:151], v[164:167], v[94:97]
	s_add_u32 s98, s98, 1
	s_and_b32 s98, s98, 15
	s_cmp_eq_u32 s98, 0
	s_cselect_b32 s99, 0x800, 0
	s_add_u32 s12, s12, 0x80
	s_addc_u32 s13, s13, 0
	s_sub_u32 s12, s12, s99
	s_subb_u32 s13, s13, 0
	s_add_u32 s46, s46, 0x80
	s_addc_u32 s47, s47, 0
	s_sub_u32 s46, s46, s99
	s_subb_u32 s47, s47, 0
	s_waitcnt lgkmcnt(0)
	v_mfma_f32_16x16x32_bf16 v[26:29], v[34:37], v[50:53], v[26:29]
	ds_read_b128 v[116:119], v111 offset:32
	v_mfma_f32_16x16x32_bf16 v[90:93], v[34:37], v[54:57], v[90:93]
	ds_read_b128 v[152:155], v169 offset:32
	v_mfma_f32_16x16x32_bf16 v[22:25], v[34:37], v[58:61], v[22:25]
	ds_read_b128 v[156:159], v169 offset:2080
	v_mfma_f32_16x16x32_bf16 v[86:89], v[34:37], v[62:65], v[86:89]
	ds_read_b128 v[120:123], v111 offset:2080
	v_mfma_f32_16x16x32_bf16 v[18:21], v[38:41], v[50:53], v[18:21]
	ds_read_b128 v[160:163], v169 offset:4128
	v_mfma_f32_16x16x32_bf16 v[82:85], v[38:41], v[54:57], v[82:85]
	ds_read_b128 v[164:167], v169 offset:6176
	v_mfma_f32_16x16x32_bf16 v[14:17], v[38:41], v[58:61], v[14:17]
	ds_read_b128 v[124:127], v111 offset:4128
	v_mfma_f32_16x16x32_bf16 v[78:81], v[38:41], v[62:65], v[78:81]
	ds_read_b128 v[148:151], v111 offset:6176
	v_mfma_f32_16x16x32_bf16 v[10:13], v[42:45], v[50:53], v[10:13]
	v_mfma_f32_16x16x32_bf16 v[74:77], v[42:45], v[54:57], v[74:77]
	v_mfma_f32_16x16x32_bf16 v[6:9], v[42:45], v[58:61], v[6:9]
	v_mfma_f32_16x16x32_bf16 v[70:73], v[42:45], v[62:65], v[70:73]
	v_mfma_f32_16x16x32_bf16 v[2:5], v[46:49], v[50:53], v[2:5]
	v_mfma_f32_16x16x32_bf16 v[66:69], v[46:49], v[54:57], v[66:69]
	v_mfma_f32_16x16x32_bf16 v[30:33], v[46:49], v[58:61], v[30:33]
	v_mfma_f32_16x16x32_bf16 v[94:97], v[46:49], v[62:65], v[94:97]
	s_waitcnt lgkmcnt(0)
	s_waitcnt vmcnt(0)
	s_barrier
	s_add_u32 m0, s4, 0
	v_mfma_f32_16x16x32_bf16 v[26:29], v[116:119], v[152:155], v[26:29]
	ds_read_b128 v[34:37], v100 offset:32800
	global_load_lds_dwordx4 v170, s[12:13] offset:0
	v_mfma_f32_16x16x32_bf16 v[90:93], v[116:119], v[156:159], v[90:93]
	ds_read_b128 v[50:53], v168 offset:32800
	global_load_lds_dwordx4 v171, s[12:13] offset:1024
	v_mfma_f32_16x16x32_bf16 v[22:25], v[116:119], v[160:163], v[22:25]
	ds_read_b128 v[54:57], v168 offset:34848
	global_load_lds_dwordx4 v172, s[12:13] offset:2048
	v_mfma_f32_16x16x32_bf16 v[86:89], v[116:119], v[164:167], v[86:89]
	ds_read_b128 v[38:41], v100 offset:34848
	global_load_lds_dwordx4 v173, s[12:13] offset:3072
	s_add_u32 m0, s4, 16384
	v_mfma_f32_16x16x32_bf16 v[18:21], v[120:123], v[152:155], v[18:21]
	ds_read_b128 v[58:61], v168 offset:36896
	global_load_lds_dwordx4 v170, s[46:47] offset:0
	v_mfma_f32_16x16x32_bf16 v[82:85], v[120:123], v[156:159], v[82:85]
	ds_read_b128 v[62:65], v168 offset:38944
	global_load_lds_dwordx4 v171, s[46:47] offset:1024
	v_mfma_f32_16x16x32_bf16 v[14:17], v[120:123], v[160:163], v[14:17]
	ds_read_b128 v[42:45], v100 offset:36896
	global_load_lds_dwordx4 v172, s[46:47] offset:2048
	v_mfma_f32_16x16x32_bf16 v[78:81], v[120:123], v[164:167], v[78:81]
	ds_read_b128 v[46:49], v100 offset:38944
	global_load_lds_dwordx4 v173, s[46:47] offset:3072
	v_mfma_f32_16x16x32_bf16 v[10:13], v[124:127], v[152:155], v[10:13]
	v_mfma_f32_16x16x32_bf16 v[74:77], v[124:127], v[156:159], v[74:77]
	v_mfma_f32_16x16x32_bf16 v[6:9], v[124:127], v[160:163], v[6:9]
	v_mfma_f32_16x16x32_bf16 v[70:73], v[124:127], v[164:167], v[70:73]
	v_mfma_f32_16x16x32_bf16 v[2:5], v[148:151], v[152:155], v[2:5]
	v_mfma_f32_16x16x32_bf16 v[66:69], v[148:151], v[156:159], v[66:69]
	v_mfma_f32_16x16x32_bf16 v[30:33], v[148:151], v[160:163], v[30:33]
	v_mfma_f32_16x16x32_bf16 v[94:97], v[148:151], v[164:167], v[94:97]
	s_add_u32 s98, s98, 1
	s_and_b32 s98, s98, 15
	s_cmp_eq_u32 s98, 0
	s_cselect_b32 s99, 0x800, 0
	s_add_u32 s12, s12, 0x80
	s_addc_u32 s13, s13, 0
	s_sub_u32 s12, s12, s99
	s_subb_u32 s13, s13, 0
	s_add_u32 s46, s46, 0x80
	s_addc_u32 s47, s47, 0
	s_sub_u32 s46, s46, s99
	s_subb_u32 s47, s47, 0
	s_waitcnt lgkmcnt(0)
	v_mfma_f32_16x16x32_bf16 v[26:29], v[34:37], v[50:53], v[26:29]
	ds_read_b128 v[116:119], v111 offset:32800
	v_mfma_f32_16x16x32_bf16 v[90:93], v[34:37], v[54:57], v[90:93]
	ds_read_b128 v[152:155], v169 offset:32800
	v_mfma_f32_16x16x32_bf16 v[22:25], v[34:37], v[58:61], v[22:25]
	ds_read_b128 v[156:159], v169 offset:34848
	v_mfma_f32_16x16x32_bf16 v[86:89], v[34:37], v[62:65], v[86:89]
	ds_read_b128 v[120:123], v111 offset:34848
	v_mfma_f32_16x16x32_bf16 v[18:21], v[38:41], v[50:53], v[18:21]
	ds_read_b128 v[160:163], v169 offset:36896
	v_mfma_f32_16x16x32_bf16 v[82:85], v[38:41], v[54:57], v[82:85]
	ds_read_b128 v[164:167], v169 offset:38944
	v_mfma_f32_16x16x32_bf16 v[14:17], v[38:41], v[58:61], v[14:17]
	ds_read_b128 v[124:127], v111 offset:36896
	v_mfma_f32_16x16x32_bf16 v[78:81], v[38:41], v[62:65], v[78:81]
	ds_read_b128 v[148:151], v111 offset:38944
	v_mfma_f32_16x16x32_bf16 v[10:13], v[42:45], v[50:53], v[10:13]
	v_mfma_f32_16x16x32_bf16 v[74:77], v[42:45], v[54:57], v[74:77]
	v_mfma_f32_16x16x32_bf16 v[6:9], v[42:45], v[58:61], v[6:9]
	v_mfma_f32_16x16x32_bf16 v[70:73], v[42:45], v[62:65], v[70:73]
	v_mfma_f32_16x16x32_bf16 v[2:5], v[46:49], v[50:53], v[2:5]
	v_mfma_f32_16x16x32_bf16 v[66:69], v[46:49], v[54:57], v[66:69]
	v_mfma_f32_16x16x32_bf16 v[30:33], v[46:49], v[58:61], v[30:33]
	v_mfma_f32_16x16x32_bf16 v[94:97], v[46:49], v[62:65], v[94:97]
	s_waitcnt lgkmcnt(0)
	s_waitcnt vmcnt(0)
	s_add_u32 s11, s11, 1
	s_cmp_lt_u32 s11, 7
	s_cbranch_scc1 .Lk_aol0b_loop
	s_barrier
	s_add_u32 m0, s4, 32768
	v_mfma_f32_16x16x32_bf16 v[26:29], v[116:119], v[152:155], v[26:29]
	ds_read_b128 v[34:37], v100 offset:32
	global_load_lds_dwordx4 v170, s[12:13] offset:0
	v_mfma_f32_16x16x32_bf16 v[90:93], v[116:119], v[156:159], v[90:93]
	ds_read_b128 v[50:53], v168 offset:32
	global_load_lds_dwordx4 v171, s[12:13] offset:1024
	v_mfma_f32_16x16x32_bf16 v[22:25], v[116:119], v[160:163], v[22:25]
	ds_read_b128 v[54:57], v168 offset:2080
	global_load_lds_dwordx4 v172, s[12:13] offset:2048
	v_mfma_f32_16x16x32_bf16 v[86:89], v[116:119], v[164:167], v[86:89]
	ds_read_b128 v[38:41], v100 offset:2080
	global_load_lds_dwordx4 v173, s[12:13] offset:3072
	s_add_u32 m0, s4, 49152
	v_mfma_f32_16x16x32_bf16 v[18:21], v[120:123], v[152:155], v[18:21]
	ds_read_b128 v[58:61], v168 offset:4128
	global_load_lds_dwordx4 v170, s[46:47] offset:0
	v_mfma_f32_16x16x32_bf16 v[82:85], v[120:123], v[156:159], v[82:85]
	ds_read_b128 v[62:65], v168 offset:6176
	global_load_lds_dwordx4 v171, s[46:47] offset:1024
	v_mfma_f32_16x16x32_bf16 v[14:17], v[120:123], v[160:163], v[14:17]
	ds_read_b128 v[42:45], v100 offset:4128
	global_load_lds_dwordx4 v172, s[46:47] offset:2048
	v_mfma_f32_16x16x32_bf16 v[78:81], v[120:123], v[164:167], v[78:81]
	ds_read_b128 v[46:49], v100 offset:6176
	global_load_lds_dwordx4 v173, s[46:47] offset:3072
	v_mfma_f32_16x16x32_bf16 v[10:13], v[124:127], v[152:155], v[10:13]
	v_mfma_f32_16x16x32_bf16 v[74:77], v[124:127], v[156:159], v[74:77]
	v_mfma_f32_16x16x32_bf16 v[6:9], v[124:127], v[160:163], v[6:9]
	v_mfma_f32_16x16x32_bf16 v[70:73], v[124:127], v[164:167], v[70:73]
	v_mfma_f32_16x16x32_bf16 v[2:5], v[148:151], v[152:155], v[2:5]
	v_mfma_f32_16x16x32_bf16 v[66:69], v[148:151], v[156:159], v[66:69]
	v_mfma_f32_16x16x32_bf16 v[30:33], v[148:151], v[160:163], v[30:33]
	v_mfma_f32_16x16x32_bf16 v[94:97], v[148:151], v[164:167], v[94:97]
	s_add_u32 s98, s98, 1
	s_and_b32 s98, s98, 15
	s_cmp_eq_u32 s98, 0
	s_cselect_b32 s99, 0x800, 0
	s_add_u32 s12, s12, 0x80
	s_addc_u32 s13, s13, 0
	s_sub_u32 s12, s12, s99
	s_subb_u32 s13, s13, 0
	s_add_u32 s46, s46, 0x80
	s_addc_u32 s47, s47, 0
	s_sub_u32 s46, s46, s99
	s_subb_u32 s47, s47, 0
	s_waitcnt lgkmcnt(0)
	v_mfma_f32_16x16x32_bf16 v[26:29], v[34:37], v[50:53], v[26:29]
	ds_read_b128 v[116:119], v111 offset:32
	v_mfma_f32_16x16x32_bf16 v[90:93], v[34:37], v[54:57], v[90:93]
	ds_read_b128 v[152:155], v169 offset:32
	v_mfma_f32_16x16x32_bf16 v[22:25], v[34:37], v[58:61], v[22:25]
	ds_read_b128 v[156:159], v169 offset:2080
	v_mfma_f32_16x16x32_bf16 v[86:89], v[34:37], v[62:65], v[86:89]
	ds_read_b128 v[120:123], v111 offset:2080
	v_mfma_f32_16x16x32_bf16 v[18:21], v[38:41], v[50:53], v[18:21]
	ds_read_b128 v[160:163], v169 offset:4128
	v_mfma_f32_16x16x32_bf16 v[82:85], v[38:41], v[54:57], v[82:85]
	ds_read_b128 v[164:167], v169 offset:6176
	v_mfma_f32_16x16x32_bf16 v[14:17], v[38:41], v[58:61], v[14:17]
	ds_read_b128 v[124:127], v111 offset:4128
	v_mfma_f32_16x16x32_bf16 v[78:81], v[38:41], v[62:65], v[78:81]
	ds_read_b128 v[148:151], v111 offset:6176
	v_mfma_f32_16x16x32_bf16 v[10:13], v[42:45], v[50:53], v[10:13]
	v_mfma_f32_16x16x32_bf16 v[74:77], v[42:45], v[54:57], v[74:77]
	v_mfma_f32_16x16x32_bf16 v[6:9], v[42:45], v[58:61], v[6:9]
	v_mfma_f32_16x16x32_bf16 v[70:73], v[42:45], v[62:65], v[70:73]
	v_mfma_f32_16x16x32_bf16 v[2:5], v[46:49], v[50:53], v[2:5]
	v_mfma_f32_16x16x32_bf16 v[66:69], v[46:49], v[54:57], v[66:69]
	v_mfma_f32_16x16x32_bf16 v[30:33], v[46:49], v[58:61], v[30:33]
	v_mfma_f32_16x16x32_bf16 v[94:97], v[46:49], v[62:65], v[94:97]
	s_waitcnt lgkmcnt(0)
	s_waitcnt vmcnt(0)
	s_barrier
	v_mfma_f32_16x16x32_bf16 v[26:29], v[116:119], v[152:155], v[26:29]
	ds_read_b128 v[34:37], v100 offset:32800
	v_mfma_f32_16x16x32_bf16 v[90:93], v[116:119], v[156:159], v[90:93]
	ds_read_b128 v[50:53], v168 offset:32800
	v_mfma_f32_16x16x32_bf16 v[22:25], v[116:119], v[160:163], v[22:25]
	ds_read_b128 v[54:57], v168 offset:34848
	v_mfma_f32_16x16x32_bf16 v[86:89], v[116:119], v[164:167], v[86:89]
	ds_read_b128 v[38:41], v100 offset:34848
	v_mfma_f32_16x16x32_bf16 v[18:21], v[120:123], v[152:155], v[18:21]
	ds_read_b128 v[58:61], v168 offset:36896
	v_mfma_f32_16x16x32_bf16 v[82:85], v[120:123], v[156:159], v[82:85]
	ds_read_b128 v[62:65], v168 offset:38944
	v_mfma_f32_16x16x32_bf16 v[14:17], v[120:123], v[160:163], v[14:17]
	ds_read_b128 v[42:45], v100 offset:36896
	v_mfma_f32_16x16x32_bf16 v[78:81], v[120:123], v[164:167], v[78:81]
	ds_read_b128 v[46:49], v100 offset:38944
	v_mfma_f32_16x16x32_bf16 v[10:13], v[124:127], v[152:155], v[10:13]
	v_mfma_f32_16x16x32_bf16 v[74:77], v[124:127], v[156:159], v[74:77]
	v_mfma_f32_16x16x32_bf16 v[6:9], v[124:127], v[160:163], v[6:9]
	v_mfma_f32_16x16x32_bf16 v[70:73], v[124:127], v[164:167], v[70:73]
	v_mfma_f32_16x16x32_bf16 v[2:5], v[148:151], v[152:155], v[2:5]
	v_mfma_f32_16x16x32_bf16 v[66:69], v[148:151], v[156:159], v[66:69]
	v_mfma_f32_16x16x32_bf16 v[30:33], v[148:151], v[160:163], v[30:33]
	v_mfma_f32_16x16x32_bf16 v[94:97], v[148:151], v[164:167], v[94:97]
	s_waitcnt lgkmcnt(0)
	v_mfma_f32_16x16x32_bf16 v[26:29], v[34:37], v[50:53], v[26:29]
	ds_read_b128 v[116:119], v111 offset:32800
	v_mfma_f32_16x16x32_bf16 v[90:93], v[34:37], v[54:57], v[90:93]
	ds_read_b128 v[152:155], v169 offset:32800
	v_mfma_f32_16x16x32_bf16 v[22:25], v[34:37], v[58:61], v[22:25]
	ds_read_b128 v[156:159], v169 offset:34848
	v_mfma_f32_16x16x32_bf16 v[86:89], v[34:37], v[62:65], v[86:89]
	ds_read_b128 v[120:123], v111 offset:34848
	v_mfma_f32_16x16x32_bf16 v[18:21], v[38:41], v[50:53], v[18:21]
	ds_read_b128 v[160:163], v169 offset:36896
	v_mfma_f32_16x16x32_bf16 v[82:85], v[38:41], v[54:57], v[82:85]
	ds_read_b128 v[164:167], v169 offset:38944
	v_mfma_f32_16x16x32_bf16 v[14:17], v[38:41], v[58:61], v[14:17]
	ds_read_b128 v[124:127], v111 offset:36896
	v_mfma_f32_16x16x32_bf16 v[78:81], v[38:41], v[62:65], v[78:81]
	ds_read_b128 v[148:151], v111 offset:38944
	v_mfma_f32_16x16x32_bf16 v[10:13], v[42:45], v[50:53], v[10:13]
	v_mfma_f32_16x16x32_bf16 v[74:77], v[42:45], v[54:57], v[74:77]
	v_mfma_f32_16x16x32_bf16 v[6:9], v[42:45], v[58:61], v[6:9]
	v_mfma_f32_16x16x32_bf16 v[70:73], v[42:45], v[62:65], v[70:73]
	v_mfma_f32_16x16x32_bf16 v[2:5], v[46:49], v[50:53], v[2:5]
	v_mfma_f32_16x16x32_bf16 v[66:69], v[46:49], v[54:57], v[66:69]
	v_mfma_f32_16x16x32_bf16 v[30:33], v[46:49], v[58:61], v[30:33]
	v_mfma_f32_16x16x32_bf16 v[94:97], v[46:49], v[62:65], v[94:97]
	s_waitcnt lgkmcnt(0)
	v_mfma_f32_16x16x32_bf16 v[26:29], v[116:119], v[152:155], v[26:29]
	v_mfma_f32_16x16x32_bf16 v[90:93], v[116:119], v[156:159], v[90:93]
	v_mfma_f32_16x16x32_bf16 v[22:25], v[116:119], v[160:163], v[22:25]
	v_mfma_f32_16x16x32_bf16 v[86:89], v[116:119], v[164:167], v[86:89]
	v_mfma_f32_16x16x32_bf16 v[18:21], v[120:123], v[152:155], v[18:21]
	v_mfma_f32_16x16x32_bf16 v[82:85], v[120:123], v[156:159], v[82:85]
	v_mfma_f32_16x16x32_bf16 v[14:17], v[120:123], v[160:163], v[14:17]
	v_mfma_f32_16x16x32_bf16 v[78:81], v[120:123], v[164:167], v[78:81]
	v_mfma_f32_16x16x32_bf16 v[10:13], v[124:127], v[152:155], v[10:13]
	v_mfma_f32_16x16x32_bf16 v[74:77], v[124:127], v[156:159], v[74:77]
	v_mfma_f32_16x16x32_bf16 v[6:9], v[124:127], v[160:163], v[6:9]
	v_mfma_f32_16x16x32_bf16 v[70:73], v[124:127], v[164:167], v[70:73]
	v_mfma_f32_16x16x32_bf16 v[2:5], v[148:151], v[152:155], v[2:5]
	v_mfma_f32_16x16x32_bf16 v[66:69], v[148:151], v[156:159], v[66:69]
	v_mfma_f32_16x16x32_bf16 v[30:33], v[148:151], v[160:163], v[30:33]
	v_mfma_f32_16x16x32_bf16 v[94:97], v[148:151], v[164:167], v[94:97]
	s_setprio 0
	s_lshr_b32 s101, s10, 7
	v_lshrrev_b32_e32 v117, 4, v0
	v_and_b32_e32 v117, 15, v117
	v_and_b32_e32 v118, 15, v0
	v_lshlrev_b32_e32 v118, 4, v118
	v_lshl_or_b32 v117, v117, 12, v118
	s_lshl_b32 s100, s48, 12
	s_lshl_b32 s98, s101, 8
	s_add_u32 s100, s100, s98
	s_add_u32 s98, s42, s100
	s_addc_u32 s99, s43, 0
	s_add_u32 s98, s98, 0x12d24800
	s_addc_u32 s99, s99, 0
	global_load_dwordx4 v[148:151], v117, s[98:99]
	s_add_u32 s98, s98, 0x10000
	s_addc_u32 s99, s99, 0
	global_load_dwordx4 v[152:155], v117, s[98:99]
	s_add_u32 s98, s98, 0x10000
	s_addc_u32 s99, s99, 0
	global_load_dwordx4 v[156:159], v117, s[98:99]
	s_add_u32 s98, s98, 0x10000
	s_addc_u32 s99, s99, 0
	global_load_dwordx4 v[160:163], v117, s[98:99]
	s_add_u32 s98, s98, 0x10000
	s_addc_u32 s99, s99, 0
	global_load_dwordx4 v[164:167], v117, s[98:99]
	s_add_u32 s98, s98, 0x10000
	s_addc_u32 s99, s99, 0
	global_load_dwordx4 v[168:171], v117, s[98:99]
	s_add_u32 s98, s98, 0x10000
	s_addc_u32 s99, s99, 0
	global_load_dwordx4 v[172:175], v117, s[98:99]
	s_add_u32 s98, s98, 0x10000
	s_addc_u32 s99, s99, 0
	global_load_dwordx4 v[188:191], v117, s[98:99]
	s_lshl_b32 s4, s10, 1
	s_barrier
	ds_write2_b32 v129, v26, v90 offset1:16
	ds_write2_b32 v129, v27, v91 offset0:132 offset1:148
	ds_write2_b32 v138, v28, v92 offset0:8 offset1:24
	ds_write2_b32 v138, v29, v93 offset0:140 offset1:156
	ds_write2_b32 v129, v22, v86 offset0:32 offset1:48
	ds_write2_b32 v129, v23, v87 offset0:164 offset1:180
	ds_write2_b32 v138, v24, v88 offset0:40 offset1:56
	ds_write2_b32 v138, v25, v89 offset0:172 offset1:188
	ds_write2_b32 v139, v18, v82 offset0:64 offset1:80
	ds_write2_b32 v139, v19, v83 offset0:196 offset1:212
	ds_write2_b32 v140, v20, v84 offset0:72 offset1:88
	ds_write2_b32 v140, v21, v85 offset0:204 offset1:220
	ds_write2_b32 v139, v14, v78 offset0:96 offset1:112
	ds_write2_b32 v139, v15, v79 offset0:228 offset1:244
	ds_write2_b32 v140, v16, v80 offset0:104 offset1:120
	ds_write2_b32 v140, v17, v81 offset0:236 offset1:252
	ds_write2_b32 v141, v10, v74 offset0:128 offset1:144
	ds_write2_b32 v142, v11, v75 offset0:4 offset1:20
	ds_write2_b32 v142, v12, v76 offset0:136 offset1:152
	ds_write2_b32 v143, v13, v77 offset0:12 offset1:28
	ds_write2_b32 v141, v6, v70 offset0:160 offset1:176
	ds_write2_b32 v142, v7, v71 offset0:36 offset1:52
	ds_write2_b32 v142, v8, v72 offset0:168 offset1:184
	ds_write2_b32 v143, v9, v73 offset0:44 offset1:60
	ds_write2_b32 v144, v2, v66 offset0:192 offset1:208
	ds_write2_b32 v145, v3, v67 offset0:68 offset1:84
	ds_write2_b32 v145, v4, v68 offset0:200 offset1:216
	ds_write2_b32 v146, v5, v69 offset0:76 offset1:92
	ds_write2_b32 v144, v30, v94 offset0:224 offset1:240
	ds_write2_b32 v145, v31, v95 offset0:100 offset1:116
	ds_write2_b32 v145, v32, v96 offset0:232 offset1:248
	ds_write2_b32 v146, v33, v97 offset0:108 offset1:124
	v_lshl_add_u64 v[2:3], v[106:107], 0, s[4:5]
	s_lshl_b32 s4, s34, 10
	s_mul_hi_u32 s10, s34, 0x15555556
	v_or_b32_e32 v4, s4, v134
	s_mulk_i32 s10, 0x3000
	v_or_b32_e32 v5, s4, v132
	v_subrev_u32_e32 v4, s10, v4
	v_subrev_u32_e32 v100, s10, v5
	s_mov_b32 s4, 0
	s_waitcnt lgkmcnt(0)
	s_barrier
	v_lshrrev_b32_e32 v52, 4, v0
	v_and_b32_e32 v52, 15, v52
	v_and_b32_e32 v50, 15, v0
	v_lshlrev_b32_e32 v53, 4, v50
	v_lshl_or_b32 v53, v52, 11, v53
	v_mul_u32_u24_e32 v52, 0x210, v52
	v_lshl_add_u32 v52, v50, 5, v52
	s_lshl_b32 s100, s48, 11
	s_lshl_b32 s98, s101, 8
	s_add_u32 s100, s100, s98
	s_add_u32 s98, s42, s100
	s_addc_u32 s99, s43, 0
	s_add_u32 s98, s98, 0xb724000
	s_addc_u32 s99, s99, 0
	ds_read_b128 v[34:37], v52 offset:32
	ds_read_b128 v[38:41], v52 offset:48
	ds_read_b128 v[42:45], v52 offset:8480
	ds_read_b128 v[46:49], v52 offset:8496
	s_waitcnt vmcnt(7) lgkmcnt(2)
	v_lshlrev_b32_e32 v51, 16, v148
	v_mul_f32_e32 v34, v34, v51
	v_and_b32_e32 v51, 0xffff0000, v148
	v_mul_f32_e32 v35, v35, v51
	v_lshlrev_b32_e32 v51, 16, v149
	v_mul_f32_e32 v36, v36, v51
	v_and_b32_e32 v51, 0xffff0000, v149
	v_mul_f32_e32 v37, v37, v51
	v_lshlrev_b32_e32 v51, 16, v150
	v_mul_f32_e32 v38, v38, v51
	v_and_b32_e32 v51, 0xffff0000, v150
	v_mul_f32_e32 v39, v39, v51
	v_lshlrev_b32_e32 v51, 16, v151
	v_mul_f32_e32 v40, v40, v51
	v_and_b32_e32 v51, 0xffff0000, v151
	v_mul_f32_e32 v41, v41, v51
	v_cvt_pk_bf16_f32 v34, v34, v35
	v_cvt_pk_bf16_f32 v35, v36, v37
	v_cvt_pk_bf16_f32 v36, v38, v39
	v_cvt_pk_bf16_f32 v37, v40, v41
	global_store_dwordx4 v53, v[34:37], s[98:99]
	s_add_u32 s98, s98, 0x8000
	s_addc_u32 s99, s99, 0
	s_nop 1
	ds_read_b128 v[34:37], v52 offset:16928
	ds_read_b128 v[38:41], v52 offset:16944
	s_waitcnt vmcnt(7) lgkmcnt(2)
	v_lshlrev_b32_e32 v51, 16, v152
	v_mul_f32_e32 v42, v42, v51
	v_and_b32_e32 v51, 0xffff0000, v152
	v_mul_f32_e32 v43, v43, v51
	v_lshlrev_b32_e32 v51, 16, v153
	v_mul_f32_e32 v44, v44, v51
	v_and_b32_e32 v51, 0xffff0000, v153
	v_mul_f32_e32 v45, v45, v51
	v_lshlrev_b32_e32 v51, 16, v154
	v_mul_f32_e32 v46, v46, v51
	v_and_b32_e32 v51, 0xffff0000, v154
	v_mul_f32_e32 v47, v47, v51
	v_lshlrev_b32_e32 v51, 16, v155
	v_mul_f32_e32 v48, v48, v51
	v_and_b32_e32 v51, 0xffff0000, v155
	v_mul_f32_e32 v49, v49, v51
	v_cvt_pk_bf16_f32 v42, v42, v43
	v_cvt_pk_bf16_f32 v43, v44, v45
	v_cvt_pk_bf16_f32 v44, v46, v47
	v_cvt_pk_bf16_f32 v45, v48, v49
	global_store_dwordx4 v53, v[42:45], s[98:99]
	s_add_u32 s98, s98, 0x8000
	s_addc_u32 s99, s99, 0
	s_nop 1
	ds_read_b128 v[42:45], v52 offset:25376
	ds_read_b128 v[46:49], v52 offset:25392
	s_waitcnt vmcnt(7) lgkmcnt(2)
	v_lshlrev_b32_e32 v51, 16, v156
	v_mul_f32_e32 v34, v34, v51
	v_and_b32_e32 v51, 0xffff0000, v156
	v_mul_f32_e32 v35, v35, v51
	v_lshlrev_b32_e32 v51, 16, v157
	v_mul_f32_e32 v36, v36, v51
	v_and_b32_e32 v51, 0xffff0000, v157
	v_mul_f32_e32 v37, v37, v51
	v_lshlrev_b32_e32 v51, 16, v158
	v_mul_f32_e32 v38, v38, v51
	v_and_b32_e32 v51, 0xffff0000, v158
	v_mul_f32_e32 v39, v39, v51
	v_lshlrev_b32_e32 v51, 16, v159
	v_mul_f32_e32 v40, v40, v51
	v_and_b32_e32 v51, 0xffff0000, v159
	v_mul_f32_e32 v41, v41, v51
	v_cvt_pk_bf16_f32 v34, v34, v35
	v_cvt_pk_bf16_f32 v35, v36, v37
	v_cvt_pk_bf16_f32 v36, v38, v39
	v_cvt_pk_bf16_f32 v37, v40, v41
	global_store_dwordx4 v53, v[34:37], s[98:99]
	s_add_u32 s98, s98, 0x8000
	s_addc_u32 s99, s99, 0
	s_nop 1
	ds_read_b128 v[34:37], v52 offset:33824
	ds_read_b128 v[38:41], v52 offset:33840
	s_waitcnt vmcnt(7) lgkmcnt(2)
	v_lshlrev_b32_e32 v51, 16, v160
	v_mul_f32_e32 v42, v42, v51
	v_and_b32_e32 v51, 0xffff0000, v160
	v_mul_f32_e32 v43, v43, v51
	v_lshlrev_b32_e32 v51, 16, v161
	v_mul_f32_e32 v44, v44, v51
	v_and_b32_e32 v51, 0xffff0000, v161
	v_mul_f32_e32 v45, v45, v51
	v_lshlrev_b32_e32 v51, 16, v162
	v_mul_f32_e32 v46, v46, v51
	v_and_b32_e32 v51, 0xffff0000, v162
	v_mul_f32_e32 v47, v47, v51
	v_lshlrev_b32_e32 v51, 16, v163
	v_mul_f32_e32 v48, v48, v51
	v_and_b32_e32 v51, 0xffff0000, v163
	v_mul_f32_e32 v49, v49, v51
	v_cvt_pk_bf16_f32 v42, v42, v43
	v_cvt_pk_bf16_f32 v43, v44, v45
	v_cvt_pk_bf16_f32 v44, v46, v47
	v_cvt_pk_bf16_f32 v45, v48, v49
	global_store_dwordx4 v53, v[42:45], s[98:99]
	s_add_u32 s98, s98, 0x8000
	s_addc_u32 s99, s99, 0
	s_nop 1
	ds_read_b128 v[42:45], v52 offset:42272
	ds_read_b128 v[46:49], v52 offset:42288
	s_waitcnt vmcnt(7) lgkmcnt(2)
	v_lshlrev_b32_e32 v51, 16, v164
	v_mul_f32_e32 v34, v34, v51
	v_and_b32_e32 v51, 0xffff0000, v164
	v_mul_f32_e32 v35, v35, v51
	v_lshlrev_b32_e32 v51, 16, v165
	v_mul_f32_e32 v36, v36, v51
	v_and_b32_e32 v51, 0xffff0000, v165
	v_mul_f32_e32 v37, v37, v51
	v_lshlrev_b32_e32 v51, 16, v166
	v_mul_f32_e32 v38, v38, v51
	v_and_b32_e32 v51, 0xffff0000, v166
	v_mul_f32_e32 v39, v39, v51
	v_lshlrev_b32_e32 v51, 16, v167
	v_mul_f32_e32 v40, v40, v51
	v_and_b32_e32 v51, 0xffff0000, v167
	v_mul_f32_e32 v41, v41, v51
	v_cvt_pk_bf16_f32 v34, v34, v35
	v_cvt_pk_bf16_f32 v35, v36, v37
	v_cvt_pk_bf16_f32 v36, v38, v39
	v_cvt_pk_bf16_f32 v37, v40, v41
	global_store_dwordx4 v53, v[34:37], s[98:99]
	s_add_u32 s98, s98, 0x8000
	s_addc_u32 s99, s99, 0
	s_nop 1
	ds_read_b128 v[34:37], v52 offset:50720
	ds_read_b128 v[38:41], v52 offset:50736
	s_waitcnt vmcnt(7) lgkmcnt(2)
	v_lshlrev_b32_e32 v51, 16, v168
	v_mul_f32_e32 v42, v42, v51
	v_and_b32_e32 v51, 0xffff0000, v168
	v_mul_f32_e32 v43, v43, v51
	v_lshlrev_b32_e32 v51, 16, v169
	v_mul_f32_e32 v44, v44, v51
	v_and_b32_e32 v51, 0xffff0000, v169
	v_mul_f32_e32 v45, v45, v51
	v_lshlrev_b32_e32 v51, 16, v170
	v_mul_f32_e32 v46, v46, v51
	v_and_b32_e32 v51, 0xffff0000, v170
	v_mul_f32_e32 v47, v47, v51
	v_lshlrev_b32_e32 v51, 16, v171
	v_mul_f32_e32 v48, v48, v51
	v_and_b32_e32 v51, 0xffff0000, v171
	v_mul_f32_e32 v49, v49, v51
	v_cvt_pk_bf16_f32 v42, v42, v43
	v_cvt_pk_bf16_f32 v43, v44, v45
	v_cvt_pk_bf16_f32 v44, v46, v47
	v_cvt_pk_bf16_f32 v45, v48, v49
	global_store_dwordx4 v53, v[42:45], s[98:99]
	s_add_u32 s98, s98, 0x8000
	s_addc_u32 s99, s99, 0
	s_nop 1
	ds_read_b128 v[42:45], v52 offset:59168
	ds_read_b128 v[46:49], v52 offset:59184
	s_waitcnt vmcnt(7) lgkmcnt(2)
	v_lshlrev_b32_e32 v51, 16, v172
	v_mul_f32_e32 v34, v34, v51
	v_and_b32_e32 v51, 0xffff0000, v172
	v_mul_f32_e32 v35, v35, v51
	v_lshlrev_b32_e32 v51, 16, v173
	v_mul_f32_e32 v36, v36, v51
	v_and_b32_e32 v51, 0xffff0000, v173
	v_mul_f32_e32 v37, v37, v51
	v_lshlrev_b32_e32 v51, 16, v174
	v_mul_f32_e32 v38, v38, v51
	v_and_b32_e32 v51, 0xffff0000, v174
	v_mul_f32_e32 v39, v39, v51
	v_lshlrev_b32_e32 v51, 16, v175
	v_mul_f32_e32 v40, v40, v51
	v_and_b32_e32 v51, 0xffff0000, v175
	v_mul_f32_e32 v41, v41, v51
	v_cvt_pk_bf16_f32 v34, v34, v35
	v_cvt_pk_bf16_f32 v35, v36, v37
	v_cvt_pk_bf16_f32 v36, v38, v39
	v_cvt_pk_bf16_f32 v37, v40, v41
	global_store_dwordx4 v53, v[34:37], s[98:99]
	s_add_u32 s98, s98, 0x8000
	s_addc_u32 s99, s99, 0
	s_waitcnt vmcnt(7) lgkmcnt(0)
	v_lshlrev_b32_e32 v51, 16, v188
	v_mul_f32_e32 v42, v42, v51
	v_and_b32_e32 v51, 0xffff0000, v188
	v_mul_f32_e32 v43, v43, v51
	v_lshlrev_b32_e32 v51, 16, v189
	v_mul_f32_e32 v44, v44, v51
	v_and_b32_e32 v51, 0xffff0000, v189
	v_mul_f32_e32 v45, v45, v51
	v_lshlrev_b32_e32 v51, 16, v190
	v_mul_f32_e32 v46, v46, v51
	v_and_b32_e32 v51, 0xffff0000, v190
	v_mul_f32_e32 v47, v47, v51
	v_lshlrev_b32_e32 v51, 16, v191
	v_mul_f32_e32 v48, v48, v51
	v_and_b32_e32 v51, 0xffff0000, v191
	v_mul_f32_e32 v49, v49, v51
	v_cvt_pk_bf16_f32 v42, v42, v43
	v_cvt_pk_bf16_f32 v43, v44, v45
	v_cvt_pk_bf16_f32 v44, v46, v47
	v_cvt_pk_bf16_f32 v45, v48, v49
	global_store_dwordx4 v53, v[42:45], s[98:99]
	s_add_i32 s33, s33, s25
	s_add_i32 s31, s31, 1
	s_cmpk_gt_u32 s33, 0x5f
	s_cbranch_scc0 .LBB0_552
	s_load_dwordx16 s[48:63], s[0:1], 0x0

.LBB0_634:
	s_and_b32 s31, s30, 0xff
	s_mul_i32 s4, s31, 0xab
	s_lshr_b32 s33, s4, 11
	s_mul_i32 s4, s33, 12
	s_sub_i32 s4, s30, s4
	s_and_b32 s4, s4, 0xff
	s_lshl_b32 s4, s4, 21
	s_or_b32 s4, s4, s23
	s_add_u32 s14, s18, s4
	s_addc_u32 s15, s19, 0
	s_lshl_b32 s4, s33, 18
	s_add_u32 s16, s20, s4
	s_addc_u32 s17, s21, 0
	v_and_b32_e32 v162, 15, v0
	v_bfe_u32 v163, v0, 4, 2
	v_and_b32_e32 v109, 7, v162
	v_xor_b32_e32 v163, v163, v109
	v_lshlrev_b32_e32 v163, 4, v163
	v_lshl_or_b32 v163, v162, 7, v163
	v_bfe_u32 v162, v0, 7, 1
	v_lshl_or_b32 v100, v162, 13, v163
	v_bfe_u32 v162, v0, 6, 1
	v_lshl_or_b32 v156, v162, 13, v163
	v_or_b32_e32 v156, 0x4000, v156
	v_xor_b32_e32 v109, 64, v100
	v_xor_b32_e32 v157, 64, v156
	v_bfe_u32 v162, v0, 3, 3
	v_and_b32_e32 v163, 7, v0
	v_xor_b32_e32 v163, v163, v162
	v_lshlrev_b32_e32 v163, 4, v163
	v_lshl_or_b32 v163, v162, 11, v163
	v_lshrrev_b32_e32 v162, 6, v0
	v_and_b32_e32 v162, 3, v162
	v_lshl_or_b32 v158, v162, 16, v163
	v_add_u32_e32 v159, 0x3c00, v158
	v_add_u32_e32 v160, 0x7800, v158
	v_add_u32_e32 v161, 0xb400, v158
	v_lshlrev_b32_e32 v162, 12, v162
	s_nop 0
	v_readfirstlane_b32 s35, v162
	s_add_u32 s35, s35, 32
	v_mov_b32_e32 v94, 0
	v_mov_b32_e32 v95, 0
	v_mov_b32_e32 v96, 0
	v_mov_b32_e32 v97, 0
	v_mov_b32_e32 v90, 0
	v_mov_b32_e32 v91, 0
	v_mov_b32_e32 v92, 0
	v_mov_b32_e32 v93, 0
	v_mov_b32_e32 v82, 0
	v_mov_b32_e32 v83, 0
	v_mov_b32_e32 v84, 0
	v_mov_b32_e32 v85, 0
	v_mov_b32_e32 v78, 0
	v_mov_b32_e32 v79, 0
	v_mov_b32_e32 v80, 0
	v_mov_b32_e32 v81, 0
	v_mov_b32_e32 v74, 0
	v_mov_b32_e32 v75, 0
	v_mov_b32_e32 v76, 0
	v_mov_b32_e32 v77, 0
	v_mov_b32_e32 v70, 0
	v_mov_b32_e32 v71, 0
	v_mov_b32_e32 v72, 0
	v_mov_b32_e32 v73, 0
	v_mov_b32_e32 v66, 0
	v_mov_b32_e32 v67, 0
	v_mov_b32_e32 v68, 0
	v_mov_b32_e32 v69, 0
	v_mov_b32_e32 v62, 0
	v_mov_b32_e32 v63, 0
	v_mov_b32_e32 v64, 0
	v_mov_b32_e32 v65, 0
	v_mov_b32_e32 v34, 0
	v_mov_b32_e32 v35, 0
	v_mov_b32_e32 v36, 0
	v_mov_b32_e32 v37, 0
	v_mov_b32_e32 v26, 0
	v_mov_b32_e32 v27, 0
	v_mov_b32_e32 v28, 0
	v_mov_b32_e32 v29, 0
	v_mov_b32_e32 v18, 0
	v_mov_b32_e32 v19, 0
	v_mov_b32_e32 v20, 0
	v_mov_b32_e32 v21, 0
	v_mov_b32_e32 v14, 0
	v_mov_b32_e32 v15, 0
	v_mov_b32_e32 v16, 0
	v_mov_b32_e32 v17, 0
	v_mov_b32_e32 v10, 0
	v_mov_b32_e32 v11, 0
	v_mov_b32_e32 v12, 0
	v_mov_b32_e32 v13, 0
	v_mov_b32_e32 v6, 0
	v_mov_b32_e32 v7, 0
	v_mov_b32_e32 v8, 0
	v_mov_b32_e32 v9, 0
	v_mov_b32_e32 v2, 0
	v_mov_b32_e32 v3, 0
	v_mov_b32_e32 v4, 0
	v_mov_b32_e32 v5, 0
	v_mov_b32_e32 v86, 0
	v_mov_b32_e32 v87, 0
	v_mov_b32_e32 v88, 0
	v_mov_b32_e32 v89, 0
	v_mov_b32_e32 v110, 0
	v_mov_b32_e32 v111, 0
	v_mov_b32_e32 v112, 0
	v_mov_b32_e32 v113, 0
	v_mov_b32_e32 v114, 0
	v_mov_b32_e32 v115, 0
	v_mov_b32_e32 v116, 0
	v_mov_b32_e32 v117, 0
	v_mov_b32_e32 v118, 0
	v_mov_b32_e32 v119, 0
	v_mov_b32_e32 v120, 0
	v_mov_b32_e32 v121, 0
	v_mov_b32_e32 v136, 0
	v_mov_b32_e32 v137, 0
	v_mov_b32_e32 v138, 0
	v_mov_b32_e32 v139, 0
	v_mov_b32_e32 v140, 0
	v_mov_b32_e32 v141, 0
	v_mov_b32_e32 v142, 0
	v_mov_b32_e32 v143, 0
	v_mov_b32_e32 v144, 0
	v_mov_b32_e32 v145, 0
	v_mov_b32_e32 v146, 0
	v_mov_b32_e32 v147, 0
	v_mov_b32_e32 v148, 0
	v_mov_b32_e32 v149, 0
	v_mov_b32_e32 v150, 0
	v_mov_b32_e32 v151, 0
	v_mov_b32_e32 v152, 0
	v_mov_b32_e32 v153, 0
	v_mov_b32_e32 v154, 0
	v_mov_b32_e32 v155, 0
	s_waitcnt lgkmcnt(0)
	s_barrier
	v_readlane_b32 s98, v255, 16
	s_and_b32 s98, s98, 7
	s_lshl_b32 s98, s98, 1
	s_lshl_b32 s99, s98, 7
	s_add_u32 s14, s14, s99
	s_addc_u32 s15, s15, 0
	s_add_u32 s16, s16, s99
	s_addc_u32 s17, s17, 0
	s_add_u32 m0, s35, 0
	s_nop 0
	global_load_lds_dwordx4 v158, s[14:15] offset:0
	global_load_lds_dwordx4 v159, s[14:15] offset:1024
	global_load_lds_dwordx4 v160, s[14:15] offset:2048
	global_load_lds_dwordx4 v161, s[14:15] offset:3072
	s_add_u32 m0, s35, 16384
	s_nop 0
	global_load_lds_dwordx4 v158, s[16:17] offset:0
	global_load_lds_dwordx4 v159, s[16:17] offset:1024
	global_load_lds_dwordx4 v160, s[16:17] offset:2048
	global_load_lds_dwordx4 v161, s[16:17] offset:3072
	s_add_u32 s98, s98, 1
	s_and_b32 s98, s98, 15
	s_cmp_eq_u32 s98, 0
	s_cselect_b32 s99, 0x800, 0
	s_add_u32 s14, s14, 0x80
	s_addc_u32 s15, s15, 0
	s_sub_u32 s14, s14, s99
	s_subb_u32 s15, s15, 0
	s_add_u32 s16, s16, 0x80
	s_addc_u32 s17, s17, 0
	s_sub_u32 s16, s16, s99
	s_subb_u32 s17, s17, 0
	s_mov_b32 s34, 0
	s_waitcnt vmcnt(0)
	s_setprio 1
.Lk_outl0_loop:
	s_barrier
	s_add_u32 m0, s35, 32768
	v_mfma_f32_16x16x32_bf16 v[94:97], v[110:113], v[140:143], v[94:97]
	ds_read_b128 v[22:25], v100 offset:32
	global_load_lds_dwordx4 v158, s[14:15] offset:0
	v_mfma_f32_16x16x32_bf16 v[90:93], v[110:113], v[144:147], v[90:93]
	ds_read_b128 v[46:49], v156 offset:32
	global_load_lds_dwordx4 v159, s[14:15] offset:1024
	v_mfma_f32_16x16x32_bf16 v[82:85], v[110:113], v[148:151], v[82:85]
	ds_read_b128 v[50:53], v156 offset:2080
	global_load_lds_dwordx4 v160, s[14:15] offset:2048
	v_mfma_f32_16x16x32_bf16 v[78:81], v[110:113], v[152:155], v[78:81]
	ds_read_b128 v[30:33], v100 offset:2080
	global_load_lds_dwordx4 v161, s[14:15] offset:3072
	s_add_u32 m0, s35, 49152
	v_mfma_f32_16x16x32_bf16 v[74:77], v[114:117], v[140:143], v[74:77]
	ds_read_b128 v[54:57], v156 offset:4128
	global_load_lds_dwordx4 v158, s[16:17] offset:0
	v_mfma_f32_16x16x32_bf16 v[70:73], v[114:117], v[144:147], v[70:73]
	ds_read_b128 v[58:61], v156 offset:6176
	global_load_lds_dwordx4 v159, s[16:17] offset:1024
	v_mfma_f32_16x16x32_bf16 v[66:69], v[114:117], v[148:151], v[66:69]
	ds_read_b128 v[38:41], v100 offset:4128
	global_load_lds_dwordx4 v160, s[16:17] offset:2048
	v_mfma_f32_16x16x32_bf16 v[62:65], v[114:117], v[152:155], v[62:65]
	ds_read_b128 v[42:45], v100 offset:6176
	global_load_lds_dwordx4 v161, s[16:17] offset:3072
	v_mfma_f32_16x16x32_bf16 v[34:37], v[118:121], v[140:143], v[34:37]
	v_mfma_f32_16x16x32_bf16 v[26:29], v[118:121], v[144:147], v[26:29]
	v_mfma_f32_16x16x32_bf16 v[18:21], v[118:121], v[148:151], v[18:21]
	v_mfma_f32_16x16x32_bf16 v[14:17], v[118:121], v[152:155], v[14:17]
	v_mfma_f32_16x16x32_bf16 v[10:13], v[136:139], v[140:143], v[10:13]
	v_mfma_f32_16x16x32_bf16 v[6:9], v[136:139], v[144:147], v[6:9]
	v_mfma_f32_16x16x32_bf16 v[2:5], v[136:139], v[148:151], v[2:5]
	v_mfma_f32_16x16x32_bf16 v[86:89], v[136:139], v[152:155], v[86:89]
	s_add_u32 s98, s98, 1
	s_and_b32 s98, s98, 15
	s_cmp_eq_u32 s98, 0
	s_cselect_b32 s99, 0x800, 0
	s_add_u32 s14, s14, 0x80
	s_addc_u32 s15, s15, 0
	s_sub_u32 s14, s14, s99
	s_subb_u32 s15, s15, 0
	s_add_u32 s16, s16, 0x80
	s_addc_u32 s17, s17, 0
	s_sub_u32 s16, s16, s99
	s_subb_u32 s17, s17, 0
	s_waitcnt lgkmcnt(0)
	v_mfma_f32_16x16x32_bf16 v[94:97], v[22:25], v[46:49], v[94:97]
	ds_read_b128 v[110:113], v109 offset:32
	v_mfma_f32_16x16x32_bf16 v[90:93], v[22:25], v[50:53], v[90:93]
	ds_read_b128 v[140:143], v157 offset:32
	v_mfma_f32_16x16x32_bf16 v[82:85], v[22:25], v[54:57], v[82:85]
	ds_read_b128 v[144:147], v157 offset:2080
	v_mfma_f32_16x16x32_bf16 v[78:81], v[22:25], v[58:61], v[78:81]
	ds_read_b128 v[114:117], v109 offset:2080
	v_mfma_f32_16x16x32_bf16 v[74:77], v[30:33], v[46:49], v[74:77]
	ds_read_b128 v[148:151], v157 offset:4128
	v_mfma_f32_16x16x32_bf16 v[70:73], v[30:33], v[50:53], v[70:73]
	ds_read_b128 v[152:155], v157 offset:6176
	v_mfma_f32_16x16x32_bf16 v[66:69], v[30:33], v[54:57], v[66:69]
	ds_read_b128 v[118:121], v109 offset:4128
	v_mfma_f32_16x16x32_bf16 v[62:65], v[30:33], v[58:61], v[62:65]
	ds_read_b128 v[136:139], v109 offset:6176
	v_mfma_f32_16x16x32_bf16 v[34:37], v[38:41], v[46:49], v[34:37]
	v_mfma_f32_16x16x32_bf16 v[26:29], v[38:41], v[50:53], v[26:29]
	v_mfma_f32_16x16x32_bf16 v[18:21], v[38:41], v[54:57], v[18:21]
	v_mfma_f32_16x16x32_bf16 v[14:17], v[38:41], v[58:61], v[14:17]
	v_mfma_f32_16x16x32_bf16 v[10:13], v[42:45], v[46:49], v[10:13]
	v_mfma_f32_16x16x32_bf16 v[6:9], v[42:45], v[50:53], v[6:9]
	v_mfma_f32_16x16x32_bf16 v[2:5], v[42:45], v[54:57], v[2:5]
	v_mfma_f32_16x16x32_bf16 v[86:89], v[42:45], v[58:61], v[86:89]
	s_waitcnt lgkmcnt(0)
	s_waitcnt vmcnt(0)
	s_barrier
	s_add_u32 m0, s35, 0
	v_mfma_f32_16x16x32_bf16 v[94:97], v[110:113], v[140:143], v[94:97]
	ds_read_b128 v[22:25], v100 offset:32800
	global_load_lds_dwordx4 v158, s[14:15] offset:0
	v_mfma_f32_16x16x32_bf16 v[90:93], v[110:113], v[144:147], v[90:93]
	ds_read_b128 v[46:49], v156 offset:32800
	global_load_lds_dwordx4 v159, s[14:15] offset:1024
	v_mfma_f32_16x16x32_bf16 v[82:85], v[110:113], v[148:151], v[82:85]
	ds_read_b128 v[50:53], v156 offset:34848
	global_load_lds_dwordx4 v160, s[14:15] offset:2048
	v_mfma_f32_16x16x32_bf16 v[78:81], v[110:113], v[152:155], v[78:81]
	ds_read_b128 v[30:33], v100 offset:34848
	global_load_lds_dwordx4 v161, s[14:15] offset:3072
	s_add_u32 m0, s35, 16384
	v_mfma_f32_16x16x32_bf16 v[74:77], v[114:117], v[140:143], v[74:77]
	ds_read_b128 v[54:57], v156 offset:36896
	global_load_lds_dwordx4 v158, s[16:17] offset:0
	v_mfma_f32_16x16x32_bf16 v[70:73], v[114:117], v[144:147], v[70:73]
	ds_read_b128 v[58:61], v156 offset:38944
	global_load_lds_dwordx4 v159, s[16:17] offset:1024
	v_mfma_f32_16x16x32_bf16 v[66:69], v[114:117], v[148:151], v[66:69]
	ds_read_b128 v[38:41], v100 offset:36896
	global_load_lds_dwordx4 v160, s[16:17] offset:2048
	v_mfma_f32_16x16x32_bf16 v[62:65], v[114:117], v[152:155], v[62:65]
	ds_read_b128 v[42:45], v100 offset:38944
	global_load_lds_dwordx4 v161, s[16:17] offset:3072
	v_mfma_f32_16x16x32_bf16 v[34:37], v[118:121], v[140:143], v[34:37]
	v_mfma_f32_16x16x32_bf16 v[26:29], v[118:121], v[144:147], v[26:29]
	v_mfma_f32_16x16x32_bf16 v[18:21], v[118:121], v[148:151], v[18:21]
	v_mfma_f32_16x16x32_bf16 v[14:17], v[118:121], v[152:155], v[14:17]
	v_mfma_f32_16x16x32_bf16 v[10:13], v[136:139], v[140:143], v[10:13]
	v_mfma_f32_16x16x32_bf16 v[6:9], v[136:139], v[144:147], v[6:9]
	v_mfma_f32_16x16x32_bf16 v[2:5], v[136:139], v[148:151], v[2:5]
	v_mfma_f32_16x16x32_bf16 v[86:89], v[136:139], v[152:155], v[86:89]
	s_add_u32 s98, s98, 1
	s_and_b32 s98, s98, 15
	s_cmp_eq_u32 s98, 0
	s_cselect_b32 s99, 0x800, 0
	s_add_u32 s14, s14, 0x80
	s_addc_u32 s15, s15, 0
	s_sub_u32 s14, s14, s99
	s_subb_u32 s15, s15, 0
	s_add_u32 s16, s16, 0x80
	s_addc_u32 s17, s17, 0
	s_sub_u32 s16, s16, s99
	s_subb_u32 s17, s17, 0
	s_waitcnt lgkmcnt(0)
	v_mfma_f32_16x16x32_bf16 v[94:97], v[22:25], v[46:49], v[94:97]
	ds_read_b128 v[110:113], v109 offset:32800
	v_mfma_f32_16x16x32_bf16 v[90:93], v[22:25], v[50:53], v[90:93]
	ds_read_b128 v[140:143], v157 offset:32800
	v_mfma_f32_16x16x32_bf16 v[82:85], v[22:25], v[54:57], v[82:85]
	ds_read_b128 v[144:147], v157 offset:34848
	v_mfma_f32_16x16x32_bf16 v[78:81], v[22:25], v[58:61], v[78:81]
	ds_read_b128 v[114:117], v109 offset:34848
	v_mfma_f32_16x16x32_bf16 v[74:77], v[30:33], v[46:49], v[74:77]
	ds_read_b128 v[148:151], v157 offset:36896
	v_mfma_f32_16x16x32_bf16 v[70:73], v[30:33], v[50:53], v[70:73]
	ds_read_b128 v[152:155], v157 offset:38944
	v_mfma_f32_16x16x32_bf16 v[66:69], v[30:33], v[54:57], v[66:69]
	ds_read_b128 v[118:121], v109 offset:36896
	v_mfma_f32_16x16x32_bf16 v[62:65], v[30:33], v[58:61], v[62:65]
	ds_read_b128 v[136:139], v109 offset:38944
	v_mfma_f32_16x16x32_bf16 v[34:37], v[38:41], v[46:49], v[34:37]
	v_mfma_f32_16x16x32_bf16 v[26:29], v[38:41], v[50:53], v[26:29]
	v_mfma_f32_16x16x32_bf16 v[18:21], v[38:41], v[54:57], v[18:21]
	v_mfma_f32_16x16x32_bf16 v[14:17], v[38:41], v[58:61], v[14:17]
	v_mfma_f32_16x16x32_bf16 v[10:13], v[42:45], v[46:49], v[10:13]
	v_mfma_f32_16x16x32_bf16 v[6:9], v[42:45], v[50:53], v[6:9]
	v_mfma_f32_16x16x32_bf16 v[2:5], v[42:45], v[54:57], v[2:5]
	v_mfma_f32_16x16x32_bf16 v[86:89], v[42:45], v[58:61], v[86:89]
	s_waitcnt lgkmcnt(0)
	s_waitcnt vmcnt(0)
	s_add_u32 s34, s34, 1
	s_cmp_lt_u32 s34, 7
	s_cbranch_scc1 .Lk_outl0_loop
	s_barrier
	s_add_u32 m0, s35, 32768
	v_mfma_f32_16x16x32_bf16 v[94:97], v[110:113], v[140:143], v[94:97]
	ds_read_b128 v[22:25], v100 offset:32
	global_load_lds_dwordx4 v158, s[14:15] offset:0
	v_mfma_f32_16x16x32_bf16 v[90:93], v[110:113], v[144:147], v[90:93]
	ds_read_b128 v[46:49], v156 offset:32
	global_load_lds_dwordx4 v159, s[14:15] offset:1024
	v_mfma_f32_16x16x32_bf16 v[82:85], v[110:113], v[148:151], v[82:85]
	ds_read_b128 v[50:53], v156 offset:2080
	global_load_lds_dwordx4 v160, s[14:15] offset:2048
	v_mfma_f32_16x16x32_bf16 v[78:81], v[110:113], v[152:155], v[78:81]
	ds_read_b128 v[30:33], v100 offset:2080
	global_load_lds_dwordx4 v161, s[14:15] offset:3072
	s_add_u32 m0, s35, 49152
	v_mfma_f32_16x16x32_bf16 v[74:77], v[114:117], v[140:143], v[74:77]
	ds_read_b128 v[54:57], v156 offset:4128
	global_load_lds_dwordx4 v158, s[16:17] offset:0
	v_mfma_f32_16x16x32_bf16 v[70:73], v[114:117], v[144:147], v[70:73]
	ds_read_b128 v[58:61], v156 offset:6176
	global_load_lds_dwordx4 v159, s[16:17] offset:1024
	v_mfma_f32_16x16x32_bf16 v[66:69], v[114:117], v[148:151], v[66:69]
	ds_read_b128 v[38:41], v100 offset:4128
	global_load_lds_dwordx4 v160, s[16:17] offset:2048
	v_mfma_f32_16x16x32_bf16 v[62:65], v[114:117], v[152:155], v[62:65]
	ds_read_b128 v[42:45], v100 offset:6176
	global_load_lds_dwordx4 v161, s[16:17] offset:3072
	v_mfma_f32_16x16x32_bf16 v[34:37], v[118:121], v[140:143], v[34:37]
	v_mfma_f32_16x16x32_bf16 v[26:29], v[118:121], v[144:147], v[26:29]
	v_mfma_f32_16x16x32_bf16 v[18:21], v[118:121], v[148:151], v[18:21]
	v_mfma_f32_16x16x32_bf16 v[14:17], v[118:121], v[152:155], v[14:17]
	v_mfma_f32_16x16x32_bf16 v[10:13], v[136:139], v[140:143], v[10:13]
	v_mfma_f32_16x16x32_bf16 v[6:9], v[136:139], v[144:147], v[6:9]
	v_mfma_f32_16x16x32_bf16 v[2:5], v[136:139], v[148:151], v[2:5]
	v_mfma_f32_16x16x32_bf16 v[86:89], v[136:139], v[152:155], v[86:89]
	s_add_u32 s98, s98, 1
	s_and_b32 s98, s98, 15
	s_cmp_eq_u32 s98, 0
	s_cselect_b32 s99, 0x800, 0
	s_add_u32 s14, s14, 0x80
	s_addc_u32 s15, s15, 0
	s_sub_u32 s14, s14, s99
	s_subb_u32 s15, s15, 0
	s_add_u32 s16, s16, 0x80
	s_addc_u32 s17, s17, 0
	s_sub_u32 s16, s16, s99
	s_subb_u32 s17, s17, 0
	s_waitcnt lgkmcnt(0)
	v_mfma_f32_16x16x32_bf16 v[94:97], v[22:25], v[46:49], v[94:97]
	ds_read_b128 v[110:113], v109 offset:32
	v_mfma_f32_16x16x32_bf16 v[90:93], v[22:25], v[50:53], v[90:93]
	ds_read_b128 v[140:143], v157 offset:32
	v_mfma_f32_16x16x32_bf16 v[82:85], v[22:25], v[54:57], v[82:85]
	ds_read_b128 v[144:147], v157 offset:2080
	v_mfma_f32_16x16x32_bf16 v[78:81], v[22:25], v[58:61], v[78:81]
	ds_read_b128 v[114:117], v109 offset:2080
	v_mfma_f32_16x16x32_bf16 v[74:77], v[30:33], v[46:49], v[74:77]
	ds_read_b128 v[148:151], v157 offset:4128
	v_mfma_f32_16x16x32_bf16 v[70:73], v[30:33], v[50:53], v[70:73]
	ds_read_b128 v[152:155], v157 offset:6176
	v_mfma_f32_16x16x32_bf16 v[66:69], v[30:33], v[54:57], v[66:69]
	ds_read_b128 v[118:121], v109 offset:4128
	v_mfma_f32_16x16x32_bf16 v[62:65], v[30:33], v[58:61], v[62:65]
	ds_read_b128 v[136:139], v109 offset:6176
	v_mfma_f32_16x16x32_bf16 v[34:37], v[38:41], v[46:49], v[34:37]
	v_mfma_f32_16x16x32_bf16 v[26:29], v[38:41], v[50:53], v[26:29]
	v_mfma_f32_16x16x32_bf16 v[18:21], v[38:41], v[54:57], v[18:21]
	v_mfma_f32_16x16x32_bf16 v[14:17], v[38:41], v[58:61], v[14:17]
	v_mfma_f32_16x16x32_bf16 v[10:13], v[42:45], v[46:49], v[10:13]
	v_mfma_f32_16x16x32_bf16 v[6:9], v[42:45], v[50:53], v[6:9]
	v_mfma_f32_16x16x32_bf16 v[2:5], v[42:45], v[54:57], v[2:5]
	v_mfma_f32_16x16x32_bf16 v[86:89], v[42:45], v[58:61], v[86:89]
	s_waitcnt lgkmcnt(0)
	s_waitcnt vmcnt(0)
	s_barrier
	v_mfma_f32_16x16x32_bf16 v[94:97], v[110:113], v[140:143], v[94:97]
	ds_read_b128 v[22:25], v100 offset:32800
	v_mfma_f32_16x16x32_bf16 v[90:93], v[110:113], v[144:147], v[90:93]
	ds_read_b128 v[46:49], v156 offset:32800
	v_mfma_f32_16x16x32_bf16 v[82:85], v[110:113], v[148:151], v[82:85]
	ds_read_b128 v[50:53], v156 offset:34848
	v_mfma_f32_16x16x32_bf16 v[78:81], v[110:113], v[152:155], v[78:81]
	ds_read_b128 v[30:33], v100 offset:34848
	v_mfma_f32_16x16x32_bf16 v[74:77], v[114:117], v[140:143], v[74:77]
	ds_read_b128 v[54:57], v156 offset:36896
	v_mfma_f32_16x16x32_bf16 v[70:73], v[114:117], v[144:147], v[70:73]
	ds_read_b128 v[58:61], v156 offset:38944
	v_mfma_f32_16x16x32_bf16 v[66:69], v[114:117], v[148:151], v[66:69]
	ds_read_b128 v[38:41], v100 offset:36896
	v_mfma_f32_16x16x32_bf16 v[62:65], v[114:117], v[152:155], v[62:65]
	ds_read_b128 v[42:45], v100 offset:38944
	v_mfma_f32_16x16x32_bf16 v[34:37], v[118:121], v[140:143], v[34:37]
	v_mfma_f32_16x16x32_bf16 v[26:29], v[118:121], v[144:147], v[26:29]
	v_mfma_f32_16x16x32_bf16 v[18:21], v[118:121], v[148:151], v[18:21]
	v_mfma_f32_16x16x32_bf16 v[14:17], v[118:121], v[152:155], v[14:17]
	v_mfma_f32_16x16x32_bf16 v[10:13], v[136:139], v[140:143], v[10:13]
	v_mfma_f32_16x16x32_bf16 v[6:9], v[136:139], v[144:147], v[6:9]
	v_mfma_f32_16x16x32_bf16 v[2:5], v[136:139], v[148:151], v[2:5]
	v_mfma_f32_16x16x32_bf16 v[86:89], v[136:139], v[152:155], v[86:89]
	s_waitcnt lgkmcnt(0)
	v_mfma_f32_16x16x32_bf16 v[94:97], v[22:25], v[46:49], v[94:97]
	ds_read_b128 v[110:113], v109 offset:32800
	v_mfma_f32_16x16x32_bf16 v[90:93], v[22:25], v[50:53], v[90:93]
	ds_read_b128 v[140:143], v157 offset:32800
	v_mfma_f32_16x16x32_bf16 v[82:85], v[22:25], v[54:57], v[82:85]
	ds_read_b128 v[144:147], v157 offset:34848
	v_mfma_f32_16x16x32_bf16 v[78:81], v[22:25], v[58:61], v[78:81]
	ds_read_b128 v[114:117], v109 offset:34848
	v_mfma_f32_16x16x32_bf16 v[74:77], v[30:33], v[46:49], v[74:77]
	ds_read_b128 v[148:151], v157 offset:36896
	v_mfma_f32_16x16x32_bf16 v[70:73], v[30:33], v[50:53], v[70:73]
	ds_read_b128 v[152:155], v157 offset:38944
	v_mfma_f32_16x16x32_bf16 v[66:69], v[30:33], v[54:57], v[66:69]
	ds_read_b128 v[118:121], v109 offset:36896
	v_mfma_f32_16x16x32_bf16 v[62:65], v[30:33], v[58:61], v[62:65]
	ds_read_b128 v[136:139], v109 offset:38944
	v_mfma_f32_16x16x32_bf16 v[34:37], v[38:41], v[46:49], v[34:37]
	v_mfma_f32_16x16x32_bf16 v[26:29], v[38:41], v[50:53], v[26:29]
	v_mfma_f32_16x16x32_bf16 v[18:21], v[38:41], v[54:57], v[18:21]
	v_mfma_f32_16x16x32_bf16 v[14:17], v[38:41], v[58:61], v[14:17]
	v_mfma_f32_16x16x32_bf16 v[10:13], v[42:45], v[46:49], v[10:13]
	v_mfma_f32_16x16x32_bf16 v[6:9], v[42:45], v[50:53], v[6:9]
	v_mfma_f32_16x16x32_bf16 v[2:5], v[42:45], v[54:57], v[2:5]
	v_mfma_f32_16x16x32_bf16 v[86:89], v[42:45], v[58:61], v[86:89]
	s_waitcnt lgkmcnt(0)
	v_mfma_f32_16x16x32_bf16 v[94:97], v[110:113], v[140:143], v[94:97]
	v_mfma_f32_16x16x32_bf16 v[90:93], v[110:113], v[144:147], v[90:93]
	v_mfma_f32_16x16x32_bf16 v[82:85], v[110:113], v[148:151], v[82:85]
	v_mfma_f32_16x16x32_bf16 v[78:81], v[110:113], v[152:155], v[78:81]
	v_mfma_f32_16x16x32_bf16 v[74:77], v[114:117], v[140:143], v[74:77]
	v_mfma_f32_16x16x32_bf16 v[70:73], v[114:117], v[144:147], v[70:73]
	v_mfma_f32_16x16x32_bf16 v[66:69], v[114:117], v[148:151], v[66:69]
	v_mfma_f32_16x16x32_bf16 v[62:65], v[114:117], v[152:155], v[62:65]
	v_mfma_f32_16x16x32_bf16 v[34:37], v[118:121], v[140:143], v[34:37]
	v_mfma_f32_16x16x32_bf16 v[26:29], v[118:121], v[144:147], v[26:29]
	v_mfma_f32_16x16x32_bf16 v[18:21], v[118:121], v[148:151], v[18:21]
	v_mfma_f32_16x16x32_bf16 v[14:17], v[118:121], v[152:155], v[14:17]
	v_mfma_f32_16x16x32_bf16 v[10:13], v[136:139], v[140:143], v[10:13]
	v_mfma_f32_16x16x32_bf16 v[6:9], v[136:139], v[144:147], v[6:9]
	v_mfma_f32_16x16x32_bf16 v[2:5], v[136:139], v[148:151], v[2:5]
	v_mfma_f32_16x16x32_bf16 v[86:89], v[136:139], v[152:155], v[86:89]
	s_setprio 0
	s_mul_i32 s14, s33, 12
	s_sub_u32 s14, s31, s14
	v_readlane_b32 s15, v255, 16
	s_and_b32 s15, s15, 7
	s_lshl_b32 s14, s14, 3
	s_or_b32 s14, s14, s15
	s_lshl_b32 s100, s14, 7
	s_lshl_b32 s101, s33, 9
	v_lshrrev_b32_e32 v114, 5, v0
	v_and_b32_e32 v114, 7, v114
	v_and_b32_e32 v115, 31, v0
	v_lshlrev_b32_e32 v115, 4, v115
	v_lshl_or_b32 v114, v114, 12, v115
	s_sub_u32 s14, s100, 0x2000
	s_lshr_b32 s14, s14, 10
	s_add_u32 s14, s14, 1
	s_cmp_lt_u32 s100, 0x2000
	s_cselect_b32 s14, 0, s14
	s_mul_i32 s14, s14, 0x6000
	s_add_u32 s14, s14, s101
	s_add_u32 s16, s42, s14
	s_addc_u32 s17, s43, 0
	s_add_u32 s16, s16, 0x6ea6000
	s_addc_u32 s17, s17, 0
	global_load_dwordx4 v[110:113], v115, s[16:17]
	s_lshl_b32 s14, s100, 12
	s_add_u32 s14, s14, s101
	s_add_u32 s16, s42, s14
	s_addc_u32 s17, s43, 0
	s_add_u32 s16, s16, 0x6f24000
	s_addc_u32 s17, s17, 0
	global_load_dwordx4 v[136:139], v114, s[16:17] nt
	s_add_u32 s16, s16, 0x8000
	s_addc_u32 s17, s17, 0
	global_load_dwordx4 v[140:143], v114, s[16:17] nt
	s_add_u32 s16, s16, 0x8000
	s_addc_u32 s17, s17, 0
	global_load_dwordx4 v[144:147], v114, s[16:17] nt
	s_add_u32 s16, s16, 0x8000
	s_addc_u32 s17, s17, 0
	global_load_dwordx4 v[148:151], v114, s[16:17] nt
	s_add_u32 s16, s16, 0x8000
	s_addc_u32 s17, s17, 0
	global_load_dwordx4 v[152:155], v114, s[16:17] nt
	s_add_u32 s16, s16, 0x8000
	s_addc_u32 s17, s17, 0
	global_load_dwordx4 v[156:159], v114, s[16:17] nt
	s_add_u32 s16, s16, 0x8000
	s_addc_u32 s17, s17, 0
	global_load_dwordx4 v[160:163], v114, s[16:17] nt
	s_add_u32 s16, s16, 0x8000
	s_addc_u32 s17, s17, 0
	global_load_dwordx4 v[164:167], v114, s[16:17] nt
	s_add_u32 s16, s16, 0x8000
	s_addc_u32 s17, s17, 0
	global_load_dwordx4 v[168:171], v114, s[16:17] nt
	s_add_u32 s16, s16, 0x8000
	s_addc_u32 s17, s17, 0
	global_load_dwordx4 v[172:175], v114, s[16:17] nt
	s_add_u32 s16, s16, 0x8000
	s_addc_u32 s17, s17, 0
	global_load_dwordx4 v[188:191], v114, s[16:17] nt
	s_add_u32 s16, s16, 0x8000
	s_addc_u32 s17, s17, 0
	global_load_dwordx4 v[192:195], v114, s[16:17] nt
	s_add_u32 s16, s16, 0x8000
	s_addc_u32 s17, s17, 0
	global_load_dwordx4 v[196:199], v114, s[16:17] nt
	s_add_u32 s16, s16, 0x8000
	s_addc_u32 s17, s17, 0
	global_load_dwordx4 v[200:203], v114, s[16:17] nt
	s_add_u32 s16, s16, 0x8000
	s_addc_u32 s17, s17, 0
	global_load_dwordx4 v[204:207], v114, s[16:17] nt
	s_add_u32 s16, s16, 0x8000
	s_addc_u32 s17, s17, 0
	global_load_dwordx4 v[208:211], v114, s[16:17] nt
	v_add_u32_e32 v22, 0x400, v123
	s_barrier
	ds_write2_b32 v123, v94, v90 offset1:16
	ds_write2_b32 v123, v95, v91 offset0:132 offset1:148
	ds_write2_b32 v22, v96, v92 offset0:8 offset1:24
	ds_write2_b32 v22, v97, v93 offset0:140 offset1:156
	ds_write2_b32 v123, v82, v78 offset0:32 offset1:48
	ds_write2_b32 v123, v83, v79 offset0:164 offset1:180
	ds_write2_b32 v22, v84, v80 offset0:40 offset1:56
	ds_write2_b32 v22, v85, v81 offset0:172 offset1:188
	v_add_u32_e32 v22, 0x2000, v123
	v_add_u32_e32 v23, 0x2400, v123
	ds_write2_b32 v22, v74, v70 offset0:64 offset1:80
	ds_write2_b32 v22, v75, v71 offset0:196 offset1:212
	ds_write2_b32 v23, v76, v72 offset0:72 offset1:88
	ds_write2_b32 v23, v77, v73 offset0:204 offset1:220
	ds_write2_b32 v22, v66, v62 offset0:96 offset1:112
	ds_write2_b32 v22, v67, v63 offset0:228 offset1:244
	ds_write2_b32 v23, v68, v64 offset0:104 offset1:120
	ds_write2_b32 v23, v69, v65 offset0:236 offset1:252
	v_add_u32_e32 v22, 0x4000, v123
	v_add_u32_e32 v23, 0x4400, v123
	v_add_u32_e32 v24, 0x4800, v123
	ds_write2_b32 v22, v34, v26 offset0:128 offset1:144
	ds_write2_b32 v23, v35, v27 offset0:4 offset1:20
	ds_write2_b32 v23, v36, v28 offset0:136 offset1:152
	ds_write2_b32 v24, v37, v29 offset0:12 offset1:28
	ds_write2_b32 v22, v18, v14 offset0:160 offset1:176
	ds_write2_b32 v23, v19, v15 offset0:36 offset1:52
	ds_write2_b32 v23, v20, v16 offset0:168 offset1:184
	ds_write2_b32 v24, v21, v17 offset0:44 offset1:60
	v_add_u32_e32 v14, 0x6000, v123
	ds_write2_b32 v14, v10, v6 offset0:192 offset1:208
	v_add_u32_e32 v6, 0x6400, v123
	ds_write2_b32 v6, v11, v7 offset0:68 offset1:84
	ds_write2_b32 v6, v12, v8 offset0:200 offset1:216
	v_add_u32_e32 v7, 0x6800, v123
	s_lshl_b32 s4, s33, 9
	ds_write2_b32 v7, v13, v9 offset0:76 offset1:92
	ds_write2_b32 v14, v2, v86 offset0:224 offset1:240
	ds_write2_b32 v6, v3, v87 offset0:100 offset1:116
	ds_write2_b32 v6, v4, v88 offset0:232 offset1:248
	ds_write2_b32 v7, v5, v89 offset0:108 offset1:124
	v_lshl_add_u64 v[2:3], v[102:103], 0, s[4:5]
	v_lshl_add_u64 v[4:5], v[104:105], 0, s[4:5]
	s_lshl_b32 s4, s31, 10
	s_mul_hi_u32 s14, s31, 0x15555556
	s_lshl_b32 s15, s33, 7
	v_or_b32_e32 v6, s4, v125
	s_mulk_i32 s14, 0x3000
	v_or_b32_e32 v7, s4, v127
	v_or_b32_e32 v8, s4, v129
	v_or_b32_e32 v9, s4, v133
	v_subrev_u32_e32 v6, s14, v6
	v_subrev_u32_e32 v7, s14, v7
	v_subrev_u32_e32 v8, s14, v8
	v_subrev_u32_e32 v9, s14, v9
	s_mov_b32 s14, 0
	s_lshl_b32 s4, s15, 2
	v_mov_b32_e32 v10, v132
	v_mov_b32_e32 v11, v128
	v_mov_b32_e32 v12, v126
	v_mov_b32_e32 v13, v124
	s_waitcnt lgkmcnt(0)
	s_barrier
	s_mov_b32 s98, 0x3fb504f3
	v_lshrrev_b32_e32 v116, 5, v0
	v_and_b32_e32 v116, 7, v116
	v_mul_u32_u24_e32 v116, 0x210, v116
	v_and_b32_e32 v38, 31, v0
	v_lshl_add_u32 v116, v38, 4, v116
	s_lshl_b32 s14, s100, 12
	s_add_u32 s14, s14, s101
	s_add_u32 s16, s42, s14
	s_addc_u32 s17, s43, 0
	s_add_u32 s16, s16, 0xfb24000
	s_addc_u32 s17, s17, 0
	ds_read_b128 v[38:41], v116 offset:32
	ds_read_b128 v[42:45], v116 offset:4256
	ds_read_b128 v[46:49], v116 offset:8480
	ds_read_b128 v[50:53], v116 offset:12704
	s_waitcnt vmcnt(15) lgkmcnt(3)
	v_pk_mul_f32 v[38:39], v[38:39], v[110:111]
	v_pk_mul_f32 v[40:41], v[40:41], v[112:113]
	v_pk_fma_f32 v[136:137], v[136:137], s[98:99], v[38:39] op_sel_hi:[1,0,1]
	v_pk_fma_f32 v[138:139], v[138:139], s[98:99], v[40:41] op_sel_hi:[1,0,1]
	ds_read_b128 v[38:41], v116 offset:16928
	global_store_dwordx4 v114, v[136:139], s[16:17]
	s_add_u32 s16, s16, 0x8000
	s_addc_u32 s17, s17, 0
	s_waitcnt vmcnt(15) lgkmcnt(3)
	v_pk_mul_f32 v[42:43], v[42:43], v[110:111]
	v_pk_mul_f32 v[44:45], v[44:45], v[112:113]
	v_pk_fma_f32 v[140:141], v[140:141], s[98:99], v[42:43] op_sel_hi:[1,0,1]
	v_pk_fma_f32 v[142:143], v[142:143], s[98:99], v[44:45] op_sel_hi:[1,0,1]
	ds_read_b128 v[42:45], v116 offset:21152
	global_store_dwordx4 v114, v[140:143], s[16:17]
	s_add_u32 s16, s16, 0x8000
	s_addc_u32 s17, s17, 0
	s_waitcnt vmcnt(15) lgkmcnt(3)
	v_pk_mul_f32 v[46:47], v[46:47], v[110:111]
	v_pk_mul_f32 v[48:49], v[48:49], v[112:113]
	v_pk_fma_f32 v[144:145], v[144:145], s[98:99], v[46:47] op_sel_hi:[1,0,1]
	v_pk_fma_f32 v[146:147], v[146:147], s[98:99], v[48:49] op_sel_hi:[1,0,1]
	ds_read_b128 v[46:49], v116 offset:25376
	global_store_dwordx4 v114, v[144:147], s[16:17]
	s_add_u32 s16, s16, 0x8000
	s_addc_u32 s17, s17, 0
	s_waitcnt vmcnt(15) lgkmcnt(3)
	v_pk_mul_f32 v[50:51], v[50:51], v[110:111]
	v_pk_mul_f32 v[52:53], v[52:53], v[112:113]
	v_pk_fma_f32 v[148:149], v[148:149], s[98:99], v[50:51] op_sel_hi:[1,0,1]
	v_pk_fma_f32 v[150:151], v[150:151], s[98:99], v[52:53] op_sel_hi:[1,0,1]
	ds_read_b128 v[50:53], v116 offset:29600
	global_store_dwordx4 v114, v[148:151], s[16:17]
	s_add_u32 s16, s16, 0x8000
	s_addc_u32 s17, s17, 0
	s_waitcnt vmcnt(15) lgkmcnt(3)
	v_pk_mul_f32 v[38:39], v[38:39], v[110:111]
	v_pk_mul_f32 v[40:41], v[40:41], v[112:113]
	v_pk_fma_f32 v[152:153], v[152:153], s[98:99], v[38:39] op_sel_hi:[1,0,1]
	v_pk_fma_f32 v[154:155], v[154:155], s[98:99], v[40:41] op_sel_hi:[1,0,1]
	ds_read_b128 v[38:41], v116 offset:33824
	global_store_dwordx4 v114, v[152:155], s[16:17]
	s_add_u32 s16, s16, 0x8000
	s_addc_u32 s17, s17, 0
	s_waitcnt vmcnt(15) lgkmcnt(3)
	v_pk_mul_f32 v[42:43], v[42:43], v[110:111]
	v_pk_mul_f32 v[44:45], v[44:45], v[112:113]
	v_pk_fma_f32 v[156:157], v[156:157], s[98:99], v[42:43] op_sel_hi:[1,0,1]
	v_pk_fma_f32 v[158:159], v[158:159], s[98:99], v[44:45] op_sel_hi:[1,0,1]
	ds_read_b128 v[42:45], v116 offset:38048
	global_store_dwordx4 v114, v[156:159], s[16:17]
	s_add_u32 s16, s16, 0x8000
	s_addc_u32 s17, s17, 0
	s_waitcnt vmcnt(15) lgkmcnt(3)
	v_pk_mul_f32 v[46:47], v[46:47], v[110:111]
	v_pk_mul_f32 v[48:49], v[48:49], v[112:113]
	v_pk_fma_f32 v[160:161], v[160:161], s[98:99], v[46:47] op_sel_hi:[1,0,1]
	v_pk_fma_f32 v[162:163], v[162:163], s[98:99], v[48:49] op_sel_hi:[1,0,1]
	ds_read_b128 v[46:49], v116 offset:42272
	global_store_dwordx4 v114, v[160:163], s[16:17]
	s_add_u32 s16, s16, 0x8000
	s_addc_u32 s17, s17, 0
	s_waitcnt vmcnt(15) lgkmcnt(3)
	v_pk_mul_f32 v[50:51], v[50:51], v[110:111]
	v_pk_mul_f32 v[52:53], v[52:53], v[112:113]
	v_pk_fma_f32 v[164:165], v[164:165], s[98:99], v[50:51] op_sel_hi:[1,0,1]
	v_pk_fma_f32 v[166:167], v[166:167], s[98:99], v[52:53] op_sel_hi:[1,0,1]
	ds_read_b128 v[50:53], v116 offset:46496
	global_store_dwordx4 v114, v[164:167], s[16:17]
	s_add_u32 s16, s16, 0x8000
	s_addc_u32 s17, s17, 0
	s_waitcnt vmcnt(15) lgkmcnt(3)
	v_pk_mul_f32 v[38:39], v[38:39], v[110:111]
	v_pk_mul_f32 v[40:41], v[40:41], v[112:113]
	v_pk_fma_f32 v[168:169], v[168:169], s[98:99], v[38:39] op_sel_hi:[1,0,1]
	v_pk_fma_f32 v[170:171], v[170:171], s[98:99], v[40:41] op_sel_hi:[1,0,1]
	ds_read_b128 v[38:41], v116 offset:50720
	global_store_dwordx4 v114, v[168:171], s[16:17]
	s_add_u32 s16, s16, 0x8000
	s_addc_u32 s17, s17, 0
	s_waitcnt vmcnt(15) lgkmcnt(3)
	v_pk_mul_f32 v[42:43], v[42:43], v[110:111]
	v_pk_mul_f32 v[44:45], v[44:45], v[112:113]
	v_pk_fma_f32 v[172:173], v[172:173], s[98:99], v[42:43] op_sel_hi:[1,0,1]
	v_pk_fma_f32 v[174:175], v[174:175], s[98:99], v[44:45] op_sel_hi:[1,0,1]
	ds_read_b128 v[42:45], v116 offset:54944
	global_store_dwordx4 v114, v[172:175], s[16:17]
	s_add_u32 s16, s16, 0x8000
	s_addc_u32 s17, s17, 0
	s_waitcnt vmcnt(15) lgkmcnt(3)
	v_pk_mul_f32 v[46:47], v[46:47], v[110:111]
	v_pk_mul_f32 v[48:49], v[48:49], v[112:113]
	v_pk_fma_f32 v[188:189], v[188:189], s[98:99], v[46:47] op_sel_hi:[1,0,1]
	v_pk_fma_f32 v[190:191], v[190:191], s[98:99], v[48:49] op_sel_hi:[1,0,1]
	ds_read_b128 v[46:49], v116 offset:59168
	global_store_dwordx4 v114, v[188:191], s[16:17]
	s_add_u32 s16, s16, 0x8000
	s_addc_u32 s17, s17, 0
	s_waitcnt vmcnt(15) lgkmcnt(3)
	v_pk_mul_f32 v[50:51], v[50:51], v[110:111]
	v_pk_mul_f32 v[52:53], v[52:53], v[112:113]
	v_pk_fma_f32 v[192:193], v[192:193], s[98:99], v[50:51] op_sel_hi:[1,0,1]
	v_pk_fma_f32 v[194:195], v[194:195], s[98:99], v[52:53] op_sel_hi:[1,0,1]
	ds_read_b128 v[50:53], v116 offset:63392
	global_store_dwordx4 v114, v[192:195], s[16:17]
	s_add_u32 s16, s16, 0x8000
	s_addc_u32 s17, s17, 0
	s_waitcnt vmcnt(15) lgkmcnt(3)
	v_pk_mul_f32 v[38:39], v[38:39], v[110:111]
	v_pk_mul_f32 v[40:41], v[40:41], v[112:113]
	v_pk_fma_f32 v[196:197], v[196:197], s[98:99], v[38:39] op_sel_hi:[1,0,1]
	v_pk_fma_f32 v[198:199], v[198:199], s[98:99], v[40:41] op_sel_hi:[1,0,1]
	global_store_dwordx4 v114, v[196:199], s[16:17]
	s_add_u32 s16, s16, 0x8000
	s_addc_u32 s17, s17, 0
	s_waitcnt vmcnt(15) lgkmcnt(2)
	v_pk_mul_f32 v[42:43], v[42:43], v[110:111]
	v_pk_mul_f32 v[44:45], v[44:45], v[112:113]
	v_pk_fma_f32 v[200:201], v[200:201], s[98:99], v[42:43] op_sel_hi:[1,0,1]
	v_pk_fma_f32 v[202:203], v[202:203], s[98:99], v[44:45] op_sel_hi:[1,0,1]
	global_store_dwordx4 v114, v[200:203], s[16:17]
	s_add_u32 s16, s16, 0x8000
	s_addc_u32 s17, s17, 0
	s_waitcnt vmcnt(15) lgkmcnt(1)
	v_pk_mul_f32 v[46:47], v[46:47], v[110:111]
	v_pk_mul_f32 v[48:49], v[48:49], v[112:113]
	v_pk_fma_f32 v[204:205], v[204:205], s[98:99], v[46:47] op_sel_hi:[1,0,1]
	v_pk_fma_f32 v[206:207], v[206:207], s[98:99], v[48:49] op_sel_hi:[1,0,1]
	global_store_dwordx4 v114, v[204:207], s[16:17]
	s_add_u32 s16, s16, 0x8000
	s_addc_u32 s17, s17, 0
	s_waitcnt vmcnt(15) lgkmcnt(0)
	v_pk_mul_f32 v[50:51], v[50:51], v[110:111]
	v_pk_mul_f32 v[52:53], v[52:53], v[112:113]
	v_pk_fma_f32 v[208:209], v[208:209], s[98:99], v[50:51] op_sel_hi:[1,0,1]
	v_pk_fma_f32 v[210:211], v[210:211], s[98:99], v[52:53] op_sel_hi:[1,0,1]
	global_store_dwordx4 v114, v[208:211], s[16:17]
	s_add_i32 s30, s30, s22
	s_cmpk_lt_u32 s30, 0x60
	s_cbranch_scc1 .LBB0_634

.LBB0_786:
	s_lshl_b32 s10, s48, 7
	s_xor_b64 s[46:47], s[50:51], -1
	s_or_b32 s50, s31, s10
	s_mov_b32 s51, s75
	s_lshl_b64 s[50:51], s[50:51], 11
	s_add_u32 s50, s54, s50
	s_addc_u32 s51, s55, s51
	s_waitcnt lgkmcnt(0)
	s_lshl_b32 s98, s30, 11
	s_add_u32 s98, s52, s98
	s_addc_u32 s99, s53, 0
	v_and_b32_e32 v222, 15, v0
	v_bfe_u32 v223, v0, 4, 2
	v_and_b32_e32 v141, 7, v222
	v_xor_b32_e32 v223, v223, v141
	v_lshlrev_b32_e32 v223, 4, v223
	v_lshl_or_b32 v223, v222, 7, v223
	v_bfe_u32 v222, v0, 7, 1
	v_lshl_or_b32 v140, v222, 13, v223
	v_bfe_u32 v222, v0, 6, 1
	v_lshl_or_b32 v216, v222, 13, v223
	v_or_b32_e32 v216, 0x4000, v216
	v_xor_b32_e32 v141, 64, v140
	v_xor_b32_e32 v217, 64, v216
	v_bfe_u32 v222, v0, 3, 3
	v_and_b32_e32 v223, 7, v0
	v_xor_b32_e32 v223, v223, v222
	v_lshlrev_b32_e32 v223, 4, v223
	v_lshl_or_b32 v223, v222, 11, v223
	v_lshrrev_b32_e32 v222, 6, v0
	v_and_b32_e32 v222, 3, v222
	v_lshl_or_b32 v218, v222, 16, v223
	v_add_u32_e32 v219, 0x3c00, v218
	v_add_u32_e32 v220, 0x7800, v218
	v_add_u32_e32 v221, 0xb400, v218
	v_lshlrev_b32_e32 v222, 12, v222
	s_nop 0
	v_readfirstlane_b32 s101, v222
	s_add_u32 s101, s101, 32
	v_mov_b32_e32 v86, 0
	v_mov_b32_e32 v87, 0
	v_mov_b32_e32 v88, 0
	v_mov_b32_e32 v89, 0
	v_mov_b32_e32 v82, 0
	v_mov_b32_e32 v83, 0
	v_mov_b32_e32 v84, 0
	v_mov_b32_e32 v85, 0
	v_mov_b32_e32 v78, 0
	v_mov_b32_e32 v79, 0
	v_mov_b32_e32 v80, 0
	v_mov_b32_e32 v81, 0
	v_mov_b32_e32 v74, 0
	v_mov_b32_e32 v75, 0
	v_mov_b32_e32 v76, 0
	v_mov_b32_e32 v77, 0
	v_mov_b32_e32 v70, 0
	v_mov_b32_e32 v71, 0
	v_mov_b32_e32 v72, 0
	v_mov_b32_e32 v73, 0
	v_mov_b32_e32 v90, 0
	v_mov_b32_e32 v91, 0
	v_mov_b32_e32 v92, 0
	v_mov_b32_e32 v93, 0
	v_mov_b32_e32 v94, 0
	v_mov_b32_e32 v95, 0
	v_mov_b32_e32 v96, 0
	v_mov_b32_e32 v97, 0
	v_mov_b32_e32 v6, 0
	v_mov_b32_e32 v7, 0
	v_mov_b32_e32 v8, 0
	v_mov_b32_e32 v9, 0
	v_mov_b32_e32 v2, 0
	v_mov_b32_e32 v3, 0
	v_mov_b32_e32 v4, 0
	v_mov_b32_e32 v5, 0
	v_mov_b32_e32 v10, 0
	v_mov_b32_e32 v11, 0
	v_mov_b32_e32 v12, 0
	v_mov_b32_e32 v13, 0
	v_mov_b32_e32 v14, 0
	v_mov_b32_e32 v15, 0
	v_mov_b32_e32 v16, 0
	v_mov_b32_e32 v17, 0
	v_mov_b32_e32 v26, 0
	v_mov_b32_e32 v27, 0
	v_mov_b32_e32 v28, 0
	v_mov_b32_e32 v29, 0
	v_mov_b32_e32 v34, 0
	v_mov_b32_e32 v35, 0
	v_mov_b32_e32 v36, 0
	v_mov_b32_e32 v37, 0
	v_mov_b32_e32 v30, 0
	v_mov_b32_e32 v31, 0
	v_mov_b32_e32 v32, 0
	v_mov_b32_e32 v33, 0
	v_mov_b32_e32 v22, 0
	v_mov_b32_e32 v23, 0
	v_mov_b32_e32 v24, 0
	v_mov_b32_e32 v25, 0
	v_mov_b32_e32 v18, 0
	v_mov_b32_e32 v19, 0
	v_mov_b32_e32 v20, 0
	v_mov_b32_e32 v21, 0
	v_mov_b32_e32 v136, 0
	v_mov_b32_e32 v137, 0
	v_mov_b32_e32 v138, 0
	v_mov_b32_e32 v139, 0
	v_mov_b32_e32 v188, 0
	v_mov_b32_e32 v189, 0
	v_mov_b32_e32 v190, 0
	v_mov_b32_e32 v191, 0
	v_mov_b32_e32 v192, 0
	v_mov_b32_e32 v193, 0
	v_mov_b32_e32 v194, 0
	v_mov_b32_e32 v195, 0
	v_mov_b32_e32 v196, 0
	v_mov_b32_e32 v197, 0
	v_mov_b32_e32 v198, 0
	v_mov_b32_e32 v199, 0
	v_mov_b32_e32 v200, 0
	v_mov_b32_e32 v201, 0
	v_mov_b32_e32 v202, 0
	v_mov_b32_e32 v203, 0
	v_mov_b32_e32 v204, 0
	v_mov_b32_e32 v205, 0
	v_mov_b32_e32 v206, 0
	v_mov_b32_e32 v207, 0
	v_mov_b32_e32 v208, 0
	v_mov_b32_e32 v209, 0
	v_mov_b32_e32 v210, 0
	v_mov_b32_e32 v211, 0
	v_mov_b32_e32 v212, 0
	v_mov_b32_e32 v213, 0
	v_mov_b32_e32 v214, 0
	v_mov_b32_e32 v215, 0
	s_waitcnt lgkmcnt(0)
	s_barrier
	v_readlane_b32 s49, v255, 16
	s_and_b32 s49, s49, 7
	s_lshl_b32 s49, s49, 1
	s_lshl_b32 s10, s49, 7
	s_add_u32 s98, s98, s10
	s_addc_u32 s99, s99, 0
	s_add_u32 s50, s50, s10
	s_addc_u32 s51, s51, 0
	s_add_u32 m0, s101, 0
	s_nop 0
	global_load_lds_dwordx4 v218, s[98:99] offset:0
	global_load_lds_dwordx4 v219, s[98:99] offset:1024
	global_load_lds_dwordx4 v220, s[98:99] offset:2048
	global_load_lds_dwordx4 v221, s[98:99] offset:3072
	s_add_u32 m0, s101, 16384
	s_nop 0
	global_load_lds_dwordx4 v218, s[50:51] offset:0
	global_load_lds_dwordx4 v219, s[50:51] offset:1024
	global_load_lds_dwordx4 v220, s[50:51] offset:2048
	global_load_lds_dwordx4 v221, s[50:51] offset:3072
	s_add_u32 s49, s49, 1
	s_and_b32 s49, s49, 15
	s_cmp_eq_u32 s49, 0
	s_cselect_b32 s10, 0x800, 0
	s_add_u32 s98, s98, 0x80
	s_addc_u32 s99, s99, 0
	s_sub_u32 s98, s98, s10
	s_subb_u32 s99, s99, 0
	s_add_u32 s50, s50, 0x80
	s_addc_u32 s51, s51, 0
	s_sub_u32 s50, s50, s10
	s_subb_u32 s51, s51, 0
	s_mov_b32 s100, 0
	s_waitcnt vmcnt(0)
	s_setprio 1
.Lk_pq0_loop:
	s_barrier
	s_add_u32 m0, s101, 32768
	v_mfma_f32_16x16x32_bf16 v[86:89], v[136:139], v[200:203], v[86:89]
	ds_read_b128 v[38:41], v140 offset:32
	global_load_lds_dwordx4 v218, s[98:99] offset:0
	v_mfma_f32_16x16x32_bf16 v[82:85], v[136:139], v[204:207], v[82:85]
	ds_read_b128 v[54:57], v216 offset:32
	global_load_lds_dwordx4 v219, s[98:99] offset:1024
	v_mfma_f32_16x16x32_bf16 v[78:81], v[136:139], v[208:211], v[78:81]
	ds_read_b128 v[58:61], v216 offset:2080
	global_load_lds_dwordx4 v220, s[98:99] offset:2048
	v_mfma_f32_16x16x32_bf16 v[74:77], v[136:139], v[212:215], v[74:77]
	ds_read_b128 v[42:45], v140 offset:2080
	global_load_lds_dwordx4 v221, s[98:99] offset:3072
	s_add_u32 m0, s101, 49152
	v_mfma_f32_16x16x32_bf16 v[70:73], v[188:191], v[200:203], v[70:73]
	ds_read_b128 v[62:65], v216 offset:4128
	global_load_lds_dwordx4 v218, s[50:51] offset:0
	v_mfma_f32_16x16x32_bf16 v[90:93], v[188:191], v[204:207], v[90:93]
	ds_read_b128 v[66:69], v216 offset:6176
	global_load_lds_dwordx4 v219, s[50:51] offset:1024
	v_mfma_f32_16x16x32_bf16 v[94:97], v[188:191], v[208:211], v[94:97]
	ds_read_b128 v[46:49], v140 offset:4128
	global_load_lds_dwordx4 v220, s[50:51] offset:2048
	v_mfma_f32_16x16x32_bf16 v[6:9], v[188:191], v[212:215], v[6:9]
	ds_read_b128 v[50:53], v140 offset:6176
	global_load_lds_dwordx4 v221, s[50:51] offset:3072
	v_mfma_f32_16x16x32_bf16 v[2:5], v[192:195], v[200:203], v[2:5]
	v_mfma_f32_16x16x32_bf16 v[10:13], v[192:195], v[204:207], v[10:13]
	v_mfma_f32_16x16x32_bf16 v[14:17], v[192:195], v[208:211], v[14:17]
	v_mfma_f32_16x16x32_bf16 v[26:29], v[192:195], v[212:215], v[26:29]
	v_mfma_f32_16x16x32_bf16 v[34:37], v[196:199], v[200:203], v[34:37]
	v_mfma_f32_16x16x32_bf16 v[30:33], v[196:199], v[204:207], v[30:33]
	v_mfma_f32_16x16x32_bf16 v[22:25], v[196:199], v[208:211], v[22:25]
	v_mfma_f32_16x16x32_bf16 v[18:21], v[196:199], v[212:215], v[18:21]
	s_add_u32 s49, s49, 1
	s_and_b32 s49, s49, 15
	s_cmp_eq_u32 s49, 0
	s_cselect_b32 s10, 0x800, 0
	s_add_u32 s98, s98, 0x80
	s_addc_u32 s99, s99, 0
	s_sub_u32 s98, s98, s10
	s_subb_u32 s99, s99, 0
	s_add_u32 s50, s50, 0x80
	s_addc_u32 s51, s51, 0
	s_sub_u32 s50, s50, s10
	s_subb_u32 s51, s51, 0
	s_waitcnt lgkmcnt(0)
	v_mfma_f32_16x16x32_bf16 v[86:89], v[38:41], v[54:57], v[86:89]
	ds_read_b128 v[136:139], v141 offset:32
	v_mfma_f32_16x16x32_bf16 v[82:85], v[38:41], v[58:61], v[82:85]
	ds_read_b128 v[200:203], v217 offset:32
	v_mfma_f32_16x16x32_bf16 v[78:81], v[38:41], v[62:65], v[78:81]
	ds_read_b128 v[204:207], v217 offset:2080
	v_mfma_f32_16x16x32_bf16 v[74:77], v[38:41], v[66:69], v[74:77]
	ds_read_b128 v[188:191], v141 offset:2080
	v_mfma_f32_16x16x32_bf16 v[70:73], v[42:45], v[54:57], v[70:73]
	ds_read_b128 v[208:211], v217 offset:4128
	v_mfma_f32_16x16x32_bf16 v[90:93], v[42:45], v[58:61], v[90:93]
	ds_read_b128 v[212:215], v217 offset:6176
	v_mfma_f32_16x16x32_bf16 v[94:97], v[42:45], v[62:65], v[94:97]
	ds_read_b128 v[192:195], v141 offset:4128
	v_mfma_f32_16x16x32_bf16 v[6:9], v[42:45], v[66:69], v[6:9]
	ds_read_b128 v[196:199], v141 offset:6176
	v_mfma_f32_16x16x32_bf16 v[2:5], v[46:49], v[54:57], v[2:5]
	v_mfma_f32_16x16x32_bf16 v[10:13], v[46:49], v[58:61], v[10:13]
	v_mfma_f32_16x16x32_bf16 v[14:17], v[46:49], v[62:65], v[14:17]
	v_mfma_f32_16x16x32_bf16 v[26:29], v[46:49], v[66:69], v[26:29]
	v_mfma_f32_16x16x32_bf16 v[34:37], v[50:53], v[54:57], v[34:37]
	v_mfma_f32_16x16x32_bf16 v[30:33], v[50:53], v[58:61], v[30:33]
	v_mfma_f32_16x16x32_bf16 v[22:25], v[50:53], v[62:65], v[22:25]
	v_mfma_f32_16x16x32_bf16 v[18:21], v[50:53], v[66:69], v[18:21]
	s_waitcnt lgkmcnt(0)
	s_waitcnt vmcnt(0)
	s_barrier
	s_add_u32 m0, s101, 0
	v_mfma_f32_16x16x32_bf16 v[86:89], v[136:139], v[200:203], v[86:89]
	ds_read_b128 v[38:41], v140 offset:32800
	global_load_lds_dwordx4 v218, s[98:99] offset:0
	v_mfma_f32_16x16x32_bf16 v[82:85], v[136:139], v[204:207], v[82:85]
	ds_read_b128 v[54:57], v216 offset:32800
	global_load_lds_dwordx4 v219, s[98:99] offset:1024
	v_mfma_f32_16x16x32_bf16 v[78:81], v[136:139], v[208:211], v[78:81]
	ds_read_b128 v[58:61], v216 offset:34848
	global_load_lds_dwordx4 v220, s[98:99] offset:2048
	v_mfma_f32_16x16x32_bf16 v[74:77], v[136:139], v[212:215], v[74:77]
	ds_read_b128 v[42:45], v140 offset:34848
	global_load_lds_dwordx4 v221, s[98:99] offset:3072
	s_add_u32 m0, s101, 16384
	v_mfma_f32_16x16x32_bf16 v[70:73], v[188:191], v[200:203], v[70:73]
	ds_read_b128 v[62:65], v216 offset:36896
	global_load_lds_dwordx4 v218, s[50:51] offset:0
	v_mfma_f32_16x16x32_bf16 v[90:93], v[188:191], v[204:207], v[90:93]
	ds_read_b128 v[66:69], v216 offset:38944
	global_load_lds_dwordx4 v219, s[50:51] offset:1024
	v_mfma_f32_16x16x32_bf16 v[94:97], v[188:191], v[208:211], v[94:97]
	ds_read_b128 v[46:49], v140 offset:36896
	global_load_lds_dwordx4 v220, s[50:51] offset:2048
	v_mfma_f32_16x16x32_bf16 v[6:9], v[188:191], v[212:215], v[6:9]
	ds_read_b128 v[50:53], v140 offset:38944
	global_load_lds_dwordx4 v221, s[50:51] offset:3072
	v_mfma_f32_16x16x32_bf16 v[2:5], v[192:195], v[200:203], v[2:5]
	v_mfma_f32_16x16x32_bf16 v[10:13], v[192:195], v[204:207], v[10:13]
	v_mfma_f32_16x16x32_bf16 v[14:17], v[192:195], v[208:211], v[14:17]
	v_mfma_f32_16x16x32_bf16 v[26:29], v[192:195], v[212:215], v[26:29]
	v_mfma_f32_16x16x32_bf16 v[34:37], v[196:199], v[200:203], v[34:37]
	v_mfma_f32_16x16x32_bf16 v[30:33], v[196:199], v[204:207], v[30:33]
	v_mfma_f32_16x16x32_bf16 v[22:25], v[196:199], v[208:211], v[22:25]
	v_mfma_f32_16x16x32_bf16 v[18:21], v[196:199], v[212:215], v[18:21]
	s_add_u32 s49, s49, 1
	s_and_b32 s49, s49, 15
	s_cmp_eq_u32 s49, 0
	s_cselect_b32 s10, 0x800, 0
	s_add_u32 s98, s98, 0x80
	s_addc_u32 s99, s99, 0
	s_sub_u32 s98, s98, s10
	s_subb_u32 s99, s99, 0
	s_add_u32 s50, s50, 0x80
	s_addc_u32 s51, s51, 0
	s_sub_u32 s50, s50, s10
	s_subb_u32 s51, s51, 0
	s_waitcnt lgkmcnt(0)
	v_mfma_f32_16x16x32_bf16 v[86:89], v[38:41], v[54:57], v[86:89]
	ds_read_b128 v[136:139], v141 offset:32800
	v_mfma_f32_16x16x32_bf16 v[82:85], v[38:41], v[58:61], v[82:85]
	ds_read_b128 v[200:203], v217 offset:32800
	v_mfma_f32_16x16x32_bf16 v[78:81], v[38:41], v[62:65], v[78:81]
	ds_read_b128 v[204:207], v217 offset:34848
	v_mfma_f32_16x16x32_bf16 v[74:77], v[38:41], v[66:69], v[74:77]
	ds_read_b128 v[188:191], v141 offset:34848
	v_mfma_f32_16x16x32_bf16 v[70:73], v[42:45], v[54:57], v[70:73]
	ds_read_b128 v[208:211], v217 offset:36896
	v_mfma_f32_16x16x32_bf16 v[90:93], v[42:45], v[58:61], v[90:93]
	ds_read_b128 v[212:215], v217 offset:38944
	v_mfma_f32_16x16x32_bf16 v[94:97], v[42:45], v[62:65], v[94:97]
	ds_read_b128 v[192:195], v141 offset:36896
	v_mfma_f32_16x16x32_bf16 v[6:9], v[42:45], v[66:69], v[6:9]
	ds_read_b128 v[196:199], v141 offset:38944
	v_mfma_f32_16x16x32_bf16 v[2:5], v[46:49], v[54:57], v[2:5]
	v_mfma_f32_16x16x32_bf16 v[10:13], v[46:49], v[58:61], v[10:13]
	v_mfma_f32_16x16x32_bf16 v[14:17], v[46:49], v[62:65], v[14:17]
	v_mfma_f32_16x16x32_bf16 v[26:29], v[46:49], v[66:69], v[26:29]
	v_mfma_f32_16x16x32_bf16 v[34:37], v[50:53], v[54:57], v[34:37]
	v_mfma_f32_16x16x32_bf16 v[30:33], v[50:53], v[58:61], v[30:33]
	v_mfma_f32_16x16x32_bf16 v[22:25], v[50:53], v[62:65], v[22:25]
	v_mfma_f32_16x16x32_bf16 v[18:21], v[50:53], v[66:69], v[18:21]
	s_waitcnt lgkmcnt(0)
	s_waitcnt vmcnt(0)
	s_add_u32 s100, s100, 1
	s_cmp_lt_u32 s100, 7
	s_cbranch_scc1 .Lk_pq0_loop
	s_barrier
	s_add_u32 m0, s101, 32768
	v_mfma_f32_16x16x32_bf16 v[86:89], v[136:139], v[200:203], v[86:89]
	ds_read_b128 v[38:41], v140 offset:32
	global_load_lds_dwordx4 v218, s[98:99] offset:0
	v_mfma_f32_16x16x32_bf16 v[82:85], v[136:139], v[204:207], v[82:85]
	ds_read_b128 v[54:57], v216 offset:32
	global_load_lds_dwordx4 v219, s[98:99] offset:1024
	v_mfma_f32_16x16x32_bf16 v[78:81], v[136:139], v[208:211], v[78:81]
	ds_read_b128 v[58:61], v216 offset:2080
	global_load_lds_dwordx4 v220, s[98:99] offset:2048
	v_mfma_f32_16x16x32_bf16 v[74:77], v[136:139], v[212:215], v[74:77]
	ds_read_b128 v[42:45], v140 offset:2080
	global_load_lds_dwordx4 v221, s[98:99] offset:3072
	s_add_u32 m0, s101, 49152
	v_mfma_f32_16x16x32_bf16 v[70:73], v[188:191], v[200:203], v[70:73]
	ds_read_b128 v[62:65], v216 offset:4128
	global_load_lds_dwordx4 v218, s[50:51] offset:0
	v_mfma_f32_16x16x32_bf16 v[90:93], v[188:191], v[204:207], v[90:93]
	ds_read_b128 v[66:69], v216 offset:6176
	global_load_lds_dwordx4 v219, s[50:51] offset:1024
	v_mfma_f32_16x16x32_bf16 v[94:97], v[188:191], v[208:211], v[94:97]
	ds_read_b128 v[46:49], v140 offset:4128
	global_load_lds_dwordx4 v220, s[50:51] offset:2048
	v_mfma_f32_16x16x32_bf16 v[6:9], v[188:191], v[212:215], v[6:9]
	ds_read_b128 v[50:53], v140 offset:6176
	global_load_lds_dwordx4 v221, s[50:51] offset:3072
	v_mfma_f32_16x16x32_bf16 v[2:5], v[192:195], v[200:203], v[2:5]
	v_mfma_f32_16x16x32_bf16 v[10:13], v[192:195], v[204:207], v[10:13]
	v_mfma_f32_16x16x32_bf16 v[14:17], v[192:195], v[208:211], v[14:17]
	v_mfma_f32_16x16x32_bf16 v[26:29], v[192:195], v[212:215], v[26:29]
	v_mfma_f32_16x16x32_bf16 v[34:37], v[196:199], v[200:203], v[34:37]
	v_mfma_f32_16x16x32_bf16 v[30:33], v[196:199], v[204:207], v[30:33]
	v_mfma_f32_16x16x32_bf16 v[22:25], v[196:199], v[208:211], v[22:25]
	v_mfma_f32_16x16x32_bf16 v[18:21], v[196:199], v[212:215], v[18:21]
	s_add_u32 s49, s49, 1
	s_and_b32 s49, s49, 15
	s_cmp_eq_u32 s49, 0
	s_cselect_b32 s10, 0x800, 0
	s_add_u32 s98, s98, 0x80
	s_addc_u32 s99, s99, 0
	s_sub_u32 s98, s98, s10
	s_subb_u32 s99, s99, 0
	s_add_u32 s50, s50, 0x80
	s_addc_u32 s51, s51, 0
	s_sub_u32 s50, s50, s10
	s_subb_u32 s51, s51, 0
	s_waitcnt lgkmcnt(0)
	v_mfma_f32_16x16x32_bf16 v[86:89], v[38:41], v[54:57], v[86:89]
	ds_read_b128 v[136:139], v141 offset:32
	v_mfma_f32_16x16x32_bf16 v[82:85], v[38:41], v[58:61], v[82:85]
	ds_read_b128 v[200:203], v217 offset:32
	v_mfma_f32_16x16x32_bf16 v[78:81], v[38:41], v[62:65], v[78:81]
	ds_read_b128 v[204:207], v217 offset:2080
	v_mfma_f32_16x16x32_bf16 v[74:77], v[38:41], v[66:69], v[74:77]
	ds_read_b128 v[188:191], v141 offset:2080
	v_mfma_f32_16x16x32_bf16 v[70:73], v[42:45], v[54:57], v[70:73]
	ds_read_b128 v[208:211], v217 offset:4128
	v_mfma_f32_16x16x32_bf16 v[90:93], v[42:45], v[58:61], v[90:93]
	ds_read_b128 v[212:215], v217 offset:6176
	v_mfma_f32_16x16x32_bf16 v[94:97], v[42:45], v[62:65], v[94:97]
	ds_read_b128 v[192:195], v141 offset:4128
	v_mfma_f32_16x16x32_bf16 v[6:9], v[42:45], v[66:69], v[6:9]
	ds_read_b128 v[196:199], v141 offset:6176
	v_mfma_f32_16x16x32_bf16 v[2:5], v[46:49], v[54:57], v[2:5]
	v_mfma_f32_16x16x32_bf16 v[10:13], v[46:49], v[58:61], v[10:13]
	v_mfma_f32_16x16x32_bf16 v[14:17], v[46:49], v[62:65], v[14:17]
	v_mfma_f32_16x16x32_bf16 v[26:29], v[46:49], v[66:69], v[26:29]
	v_mfma_f32_16x16x32_bf16 v[34:37], v[50:53], v[54:57], v[34:37]
	v_mfma_f32_16x16x32_bf16 v[30:33], v[50:53], v[58:61], v[30:33]
	v_mfma_f32_16x16x32_bf16 v[22:25], v[50:53], v[62:65], v[22:25]
	v_mfma_f32_16x16x32_bf16 v[18:21], v[50:53], v[66:69], v[18:21]
	s_waitcnt lgkmcnt(0)
	s_waitcnt vmcnt(0)
	s_barrier
	v_mfma_f32_16x16x32_bf16 v[86:89], v[136:139], v[200:203], v[86:89]
	ds_read_b128 v[38:41], v140 offset:32800
	v_mfma_f32_16x16x32_bf16 v[82:85], v[136:139], v[204:207], v[82:85]
	ds_read_b128 v[54:57], v216 offset:32800
	v_mfma_f32_16x16x32_bf16 v[78:81], v[136:139], v[208:211], v[78:81]
	ds_read_b128 v[58:61], v216 offset:34848
	v_mfma_f32_16x16x32_bf16 v[74:77], v[136:139], v[212:215], v[74:77]
	ds_read_b128 v[42:45], v140 offset:34848
	v_mfma_f32_16x16x32_bf16 v[70:73], v[188:191], v[200:203], v[70:73]
	ds_read_b128 v[62:65], v216 offset:36896
	v_mfma_f32_16x16x32_bf16 v[90:93], v[188:191], v[204:207], v[90:93]
	ds_read_b128 v[66:69], v216 offset:38944
	v_mfma_f32_16x16x32_bf16 v[94:97], v[188:191], v[208:211], v[94:97]
	ds_read_b128 v[46:49], v140 offset:36896
	v_mfma_f32_16x16x32_bf16 v[6:9], v[188:191], v[212:215], v[6:9]
	ds_read_b128 v[50:53], v140 offset:38944
	v_mfma_f32_16x16x32_bf16 v[2:5], v[192:195], v[200:203], v[2:5]
	v_mfma_f32_16x16x32_bf16 v[10:13], v[192:195], v[204:207], v[10:13]
	v_mfma_f32_16x16x32_bf16 v[14:17], v[192:195], v[208:211], v[14:17]
	v_mfma_f32_16x16x32_bf16 v[26:29], v[192:195], v[212:215], v[26:29]
	v_mfma_f32_16x16x32_bf16 v[34:37], v[196:199], v[200:203], v[34:37]
	v_mfma_f32_16x16x32_bf16 v[30:33], v[196:199], v[204:207], v[30:33]
	v_mfma_f32_16x16x32_bf16 v[22:25], v[196:199], v[208:211], v[22:25]
	v_mfma_f32_16x16x32_bf16 v[18:21], v[196:199], v[212:215], v[18:21]
	s_waitcnt lgkmcnt(0)
	v_mfma_f32_16x16x32_bf16 v[86:89], v[38:41], v[54:57], v[86:89]
	ds_read_b128 v[136:139], v141 offset:32800
	v_mfma_f32_16x16x32_bf16 v[82:85], v[38:41], v[58:61], v[82:85]
	ds_read_b128 v[200:203], v217 offset:32800
	v_mfma_f32_16x16x32_bf16 v[78:81], v[38:41], v[62:65], v[78:81]
	ds_read_b128 v[204:207], v217 offset:34848
	v_mfma_f32_16x16x32_bf16 v[74:77], v[38:41], v[66:69], v[74:77]
	ds_read_b128 v[188:191], v141 offset:34848
	v_mfma_f32_16x16x32_bf16 v[70:73], v[42:45], v[54:57], v[70:73]
	ds_read_b128 v[208:211], v217 offset:36896
	v_mfma_f32_16x16x32_bf16 v[90:93], v[42:45], v[58:61], v[90:93]
	ds_read_b128 v[212:215], v217 offset:38944
	v_mfma_f32_16x16x32_bf16 v[94:97], v[42:45], v[62:65], v[94:97]
	ds_read_b128 v[192:195], v141 offset:36896
	v_mfma_f32_16x16x32_bf16 v[6:9], v[42:45], v[66:69], v[6:9]
	ds_read_b128 v[196:199], v141 offset:38944
	v_mfma_f32_16x16x32_bf16 v[2:5], v[46:49], v[54:57], v[2:5]
	v_mfma_f32_16x16x32_bf16 v[10:13], v[46:49], v[58:61], v[10:13]
	v_mfma_f32_16x16x32_bf16 v[14:17], v[46:49], v[62:65], v[14:17]
	v_mfma_f32_16x16x32_bf16 v[26:29], v[46:49], v[66:69], v[26:29]
	v_mfma_f32_16x16x32_bf16 v[34:37], v[50:53], v[54:57], v[34:37]
	v_mfma_f32_16x16x32_bf16 v[30:33], v[50:53], v[58:61], v[30:33]
	v_mfma_f32_16x16x32_bf16 v[22:25], v[50:53], v[62:65], v[22:25]
	v_mfma_f32_16x16x32_bf16 v[18:21], v[50:53], v[66:69], v[18:21]
	s_waitcnt lgkmcnt(0)
	v_mfma_f32_16x16x32_bf16 v[86:89], v[136:139], v[200:203], v[86:89]
	v_mfma_f32_16x16x32_bf16 v[82:85], v[136:139], v[204:207], v[82:85]
	v_mfma_f32_16x16x32_bf16 v[78:81], v[136:139], v[208:211], v[78:81]
	v_mfma_f32_16x16x32_bf16 v[74:77], v[136:139], v[212:215], v[74:77]
	v_mfma_f32_16x16x32_bf16 v[70:73], v[188:191], v[200:203], v[70:73]
	v_mfma_f32_16x16x32_bf16 v[90:93], v[188:191], v[204:207], v[90:93]
	v_mfma_f32_16x16x32_bf16 v[94:97], v[188:191], v[208:211], v[94:97]
	v_mfma_f32_16x16x32_bf16 v[6:9], v[188:191], v[212:215], v[6:9]
	v_mfma_f32_16x16x32_bf16 v[2:5], v[192:195], v[200:203], v[2:5]
	v_mfma_f32_16x16x32_bf16 v[10:13], v[192:195], v[204:207], v[10:13]
	v_mfma_f32_16x16x32_bf16 v[14:17], v[192:195], v[208:211], v[14:17]
	v_mfma_f32_16x16x32_bf16 v[26:29], v[192:195], v[212:215], v[26:29]
	v_mfma_f32_16x16x32_bf16 v[34:37], v[196:199], v[200:203], v[34:37]
	v_mfma_f32_16x16x32_bf16 v[30:33], v[196:199], v[204:207], v[30:33]
	v_mfma_f32_16x16x32_bf16 v[22:25], v[196:199], v[208:211], v[22:25]
	v_mfma_f32_16x16x32_bf16 v[18:21], v[196:199], v[212:215], v[18:21]
	s_setprio 0
	s_waitcnt vmcnt(1)
	v_cvt_pk_bf16_f32 v38, v86, s0
	s_barrier
	ds_write_b16 v147, v38
	v_cvt_pk_bf16_f32 v38, v87, s0
	ds_write_b16 v147, v38 offset:272
	v_cvt_pk_bf16_f32 v38, v88, s0
	ds_write_b16 v147, v38 offset:544
	v_cvt_pk_bf16_f32 v38, v89, s0
	ds_write_b16 v147, v38 offset:816
	v_cvt_pk_bf16_f32 v38, v82, s0
	ds_write_b16 v147, v38 offset:32
	v_cvt_pk_bf16_f32 v38, v83, s0
	ds_write_b16 v147, v38 offset:304
	v_cvt_pk_bf16_f32 v38, v84, s0
	ds_write_b16 v147, v38 offset:576
	v_cvt_pk_bf16_f32 v38, v85, s0
	ds_write_b16 v147, v38 offset:848
	v_cvt_pk_bf16_f32 v38, v78, s0
	ds_write_b16 v147, v38 offset:64
	v_cvt_pk_bf16_f32 v38, v79, s0
	ds_write_b16 v147, v38 offset:336
	v_cvt_pk_bf16_f32 v38, v80, s0
	ds_write_b16 v147, v38 offset:608
	v_cvt_pk_bf16_f32 v38, v81, s0
	ds_write_b16 v147, v38 offset:880
	v_cvt_pk_bf16_f32 v38, v74, s0
	ds_write_b16 v147, v38 offset:96
	v_cvt_pk_bf16_f32 v38, v75, s0
	ds_write_b16 v147, v38 offset:368
	v_cvt_pk_bf16_f32 v38, v76, s0
	ds_write_b16 v147, v38 offset:640
	v_cvt_pk_bf16_f32 v38, v77, s0
	ds_write_b16 v147, v38 offset:912
	v_cvt_pk_bf16_f32 v38, v70, s0
	ds_write_b16 v147, v38 offset:4352
	v_cvt_pk_bf16_f32 v38, v71, s0
	ds_write_b16 v147, v38 offset:4624
	v_cvt_pk_bf16_f32 v38, v72, s0
	ds_write_b16 v147, v38 offset:4896
	v_cvt_pk_bf16_f32 v38, v73, s0
	ds_write_b16 v147, v38 offset:5168
	v_cvt_pk_bf16_f32 v38, v90, s0
	ds_write_b16 v147, v38 offset:4384
	v_cvt_pk_bf16_f32 v38, v91, s0
	ds_write_b16 v147, v38 offset:4656
	v_cvt_pk_bf16_f32 v38, v92, s0
	ds_write_b16 v147, v38 offset:4928
	v_cvt_pk_bf16_f32 v38, v93, s0
	ds_write_b16 v147, v38 offset:5200
	v_cvt_pk_bf16_f32 v38, v94, s0
	ds_write_b16 v147, v38 offset:4416
	v_cvt_pk_bf16_f32 v38, v95, s0
	s_mov_b32 s49, s11
	ds_write_b16 v147, v38 offset:4688
	v_cvt_pk_bf16_f32 v38, v96, s0
	s_lshl_b64 s[50:51], s[48:49], 15
	ds_write_b16 v147, v38 offset:4960
	v_cvt_pk_bf16_f32 v38, v97, s0
	s_waitcnt vmcnt(0)
	v_lshl_add_u64 v[66:67], v[102:103], 0, s[50:51]
	ds_write_b16 v147, v38 offset:5232
	v_lshl_add_u64 v[38:39], v[66:67], 0, v[100:101]
	v_mov_b32_e32 v107, v101
	global_load_dwordx4 v[38:41], v[38:39], off
	v_lshl_add_u64 v[42:43], v[66:67], 0, v[106:107]
	v_mov_b32_e32 v109, v101
	global_load_dwordx4 v[42:45], v[42:43], off
	v_lshl_add_u64 v[46:47], v[66:67], 0, v[108:109]
	v_mov_b32_e32 v111, v101
	global_load_dwordx4 v[46:49], v[46:47], off
	v_lshl_add_u64 v[50:51], v[66:67], 0, v[110:111]
	v_mov_b32_e32 v113, v101
	global_load_dwordx4 v[50:53], v[50:51], off
	v_lshl_add_u64 v[54:55], v[66:67], 0, v[112:113]
	v_mov_b32_e32 v115, v101
	global_load_dwordx4 v[54:57], v[54:55], off
	v_lshl_add_u64 v[58:59], v[66:67], 0, v[114:115]
	v_mov_b32_e32 v117, v101
	global_load_dwordx4 v[58:61], v[58:59], off
	v_lshl_add_u64 v[62:63], v[66:67], 0, v[116:117]
	v_mov_b32_e32 v119, v101
	global_load_dwordx4 v[62:65], v[62:63], off
	v_lshl_add_u64 v[66:67], v[66:67], 0, v[118:119]
	global_load_dwordx4 v[66:69], v[66:67], off
	v_cvt_pk_bf16_f32 v2, v2, s0
	ds_write_b16 v147, v2 offset:8704
	v_cvt_pk_bf16_f32 v2, v3, s0
	ds_write_b16 v147, v2 offset:8976
	v_cvt_pk_bf16_f32 v2, v4, s0
	ds_write_b16 v147, v2 offset:9248
	v_cvt_pk_bf16_f32 v2, v5, s0
	ds_write_b16 v147, v2 offset:9520
	v_cvt_pk_bf16_f32 v2, v10, s0
	ds_write_b16 v147, v2 offset:8736
	v_cvt_pk_bf16_f32 v2, v11, s0
	ds_write_b16 v147, v2 offset:9008
	v_cvt_pk_bf16_f32 v2, v12, s0
	ds_write_b16 v147, v2 offset:9280
	v_cvt_pk_bf16_f32 v2, v13, s0
	ds_write_b16 v147, v2 offset:9552
	v_cvt_pk_bf16_f32 v2, v14, s0
	ds_write_b16 v147, v2 offset:8768
	v_cvt_pk_bf16_f32 v2, v15, s0
	ds_write_b16 v147, v2 offset:9040
	v_cvt_pk_bf16_f32 v2, v16, s0
	ds_write_b16 v147, v2 offset:9312
	v_cvt_pk_bf16_f32 v2, v17, s0
	ds_write_b16 v147, v2 offset:9584
	v_cvt_pk_bf16_f32 v2, v26, s0
	ds_write_b16 v147, v2 offset:8800
	v_cvt_pk_bf16_f32 v2, v27, s0
	ds_write_b16 v147, v2 offset:9072
	v_cvt_pk_bf16_f32 v2, v28, s0
	ds_write_b16 v147, v2 offset:9344
	v_cvt_pk_bf16_f32 v2, v29, s0
	ds_write_b16 v147, v2 offset:9616
	v_cvt_pk_bf16_f32 v2, v34, s0
	ds_write_b16 v147, v2 offset:13056
	v_cvt_pk_bf16_f32 v2, v35, s0
	ds_write_b16 v147, v2 offset:13328
	v_cvt_pk_bf16_f32 v2, v36, s0
	ds_write_b16 v147, v2 offset:13600
	v_cvt_pk_bf16_f32 v2, v37, s0
	ds_write_b16 v147, v2 offset:13872
	v_cvt_pk_bf16_f32 v2, v30, s0
	ds_write_b16 v147, v2 offset:13088
	v_cvt_pk_bf16_f32 v2, v31, s0
	ds_write_b16 v147, v2 offset:13360
	v_cvt_pk_bf16_f32 v2, v32, s0
	ds_write_b16 v147, v2 offset:13632
	v_cvt_pk_bf16_f32 v2, v33, s0
	ds_write_b16 v147, v2 offset:13904
	v_cvt_pk_bf16_f32 v2, v22, s0
	ds_write_b16 v147, v2 offset:13120
	v_cvt_pk_bf16_f32 v2, v23, s0
	ds_write_b16 v147, v2 offset:13392
	v_cvt_pk_bf16_f32 v2, v24, s0
	ds_write_b16 v147, v2 offset:13664
	v_cvt_pk_bf16_f32 v2, v25, s0
	v_cvt_pk_bf16_f32 v6, v6, s0
	ds_write_b16 v147, v2 offset:13936
	v_cvt_pk_bf16_f32 v2, v18, s0
	ds_write_b16 v147, v6 offset:4448
	v_cvt_pk_bf16_f32 v6, v7, s0
	ds_write_b16 v147, v2 offset:13152
	v_cvt_pk_bf16_f32 v2, v19, s0
	ds_write_b16 v147, v6 offset:4720
	v_cvt_pk_bf16_f32 v6, v8, s0
	ds_write_b16 v147, v2 offset:13424
	v_cvt_pk_bf16_f32 v2, v20, s0
	ds_write_b16 v147, v6 offset:4992
	v_cvt_pk_bf16_f32 v6, v9, s0
	ds_write_b16 v147, v2 offset:13696
	v_cvt_pk_bf16_f32 v2, v21, s0
	ds_write_b16 v147, v6 offset:5264
	ds_write_b16 v147, v2 offset:13968
	s_waitcnt vmcnt(7)
	ds_write_b128 v148, v[38:41]
	s_waitcnt vmcnt(6)
	ds_write_b128 v149, v[42:45]
	s_waitcnt vmcnt(5)
	ds_write_b128 v150, v[46:49]
	s_waitcnt vmcnt(4)
	ds_write_b128 v151, v[50:53]
	s_waitcnt vmcnt(3)
	ds_write_b128 v152, v[54:57]
	s_waitcnt vmcnt(2)
	ds_write_b128 v153, v[58:61]
	s_waitcnt vmcnt(1)
	ds_write_b128 v154, v[62:65]
	s_waitcnt vmcnt(0)
	ds_write_b128 v155, v[66:69]
	s_waitcnt lgkmcnt(0)
	s_barrier
	ds_read_b128 v[2:5], v176
	ds_read_b128 v[6:9], v177 offset:34816
	ds_read_b128 v[34:37], v176 offset:4352
	ds_read_b128 v[70:73], v176 offset:64
	ds_read_b128 v[50:53], v176 offset:8704
	ds_read_b128 v[66:69], v176 offset:13056
	ds_read_b128 v[14:17], v177 offset:39168
	ds_read_b128 v[22:25], v177 offset:43520
	ds_read_b128 v[30:33], v177 offset:47872
	ds_read_b128 v[78:81], v177 offset:43584
	s_waitcnt lgkmcnt(8)
	v_mfma_f32_16x16x32_bf16 v[10:13], v[2:5], v[6:9], 0
	ds_read_b128 v[74:77], v177 offset:39232
	ds_read_b128 v[82:85], v177 offset:47936
	s_lshl_b64 s[48:49], s[48:49], 6
	s_waitcnt lgkmcnt(5)
	v_mfma_f32_16x16x32_bf16 v[18:21], v[2:5], v[14:17], 0
	s_add_u32 s48, s29, s48
	s_addc_u32 s49, s76, s49
	s_mov_b32 s10, 0
	s_waitcnt lgkmcnt(4)
	v_mfma_f32_16x16x32_bf16 v[26:29], v[2:5], v[22:25], 0
	s_waitcnt lgkmcnt(3)
	v_mfma_f32_16x16x32_bf16 v[2:5], v[2:5], v[30:33], 0
	v_mfma_f32_16x16x32_bf16 v[38:41], v[34:37], v[6:9], 0
	v_mfma_f32_16x16x32_bf16 v[42:45], v[34:37], v[14:17], 0
	v_mfma_f32_16x16x32_bf16 v[46:49], v[34:37], v[22:25], 0
	v_mfma_f32_16x16x32_bf16 v[34:37], v[34:37], v[30:33], 0
	v_mfma_f32_16x16x32_bf16 v[54:57], v[50:53], v[6:9], 0
	v_mfma_f32_16x16x32_bf16 v[58:61], v[50:53], v[14:17], 0
	v_mfma_f32_16x16x32_bf16 v[62:65], v[50:53], v[22:25], 0
	v_mfma_f32_16x16x32_bf16 v[50:53], v[50:53], v[30:33], 0
	v_mfma_f32_16x16x32_bf16 v[6:9], v[66:69], v[6:9], 0
	v_mfma_f32_16x16x32_bf16 v[14:17], v[66:69], v[14:17], 0
	v_mfma_f32_16x16x32_bf16 v[22:25], v[66:69], v[22:25], 0
	v_mfma_f32_16x16x32_bf16 v[30:33], v[66:69], v[30:33], 0
	ds_read_b128 v[66:69], v177 offset:34880
	s_waitcnt lgkmcnt(0)
	v_mfma_f32_16x16x32_bf16 v[10:13], v[70:73], v[66:69], v[10:13]
	v_mfma_f32_16x16x32_bf16 v[18:21], v[70:73], v[74:77], v[18:21]
	v_mfma_f32_16x16x32_bf16 v[26:29], v[70:73], v[78:81], v[26:29]
	v_mfma_f32_16x16x32_bf16 v[2:5], v[70:73], v[82:85], v[2:5]
	ds_read_b128 v[70:73], v176 offset:4416
	s_waitcnt lgkmcnt(0)
	v_mfma_f32_16x16x32_bf16 v[38:41], v[70:73], v[66:69], v[38:41]
	v_mfma_f32_16x16x32_bf16 v[42:45], v[70:73], v[74:77], v[42:45]
	v_mfma_f32_16x16x32_bf16 v[46:49], v[70:73], v[78:81], v[46:49]
	v_mfma_f32_16x16x32_bf16 v[34:37], v[70:73], v[82:85], v[34:37]
	ds_read_b128 v[70:73], v176 offset:8768
	s_waitcnt lgkmcnt(0)
	v_mfma_f32_16x16x32_bf16 v[54:57], v[70:73], v[66:69], v[54:57]
	v_mfma_f32_16x16x32_bf16 v[58:61], v[70:73], v[74:77], v[58:61]
	v_mfma_f32_16x16x32_bf16 v[62:65], v[70:73], v[78:81], v[62:65]
	v_mfma_f32_16x16x32_bf16 v[50:53], v[70:73], v[82:85], v[50:53]
	ds_read_b128 v[70:73], v176 offset:13120
	s_waitcnt lgkmcnt(0)
	v_mfma_f32_16x16x32_bf16 v[6:9], v[70:73], v[66:69], v[6:9]
	ds_read_b128 v[66:69], v176 offset:128
	v_mfma_f32_16x16x32_bf16 v[14:17], v[70:73], v[74:77], v[14:17]
	ds_read_b128 v[74:77], v177 offset:39296
	v_mfma_f32_16x16x32_bf16 v[22:25], v[70:73], v[78:81], v[22:25]
	ds_read_b128 v[78:81], v177 offset:43648
	v_mfma_f32_16x16x32_bf16 v[30:33], v[70:73], v[82:85], v[30:33]
	ds_read_b128 v[70:73], v177 offset:34944
	ds_read_b128 v[82:85], v177 offset:48000
	s_waitcnt lgkmcnt(1)
	v_mfma_f32_16x16x32_bf16 v[10:13], v[66:69], v[70:73], v[10:13]
	v_mfma_f32_16x16x32_bf16 v[18:21], v[66:69], v[74:77], v[18:21]
	v_mfma_f32_16x16x32_bf16 v[26:29], v[66:69], v[78:81], v[26:29]
	s_waitcnt lgkmcnt(0)
	v_mfma_f32_16x16x32_bf16 v[2:5], v[66:69], v[82:85], v[2:5]
	ds_read_b128 v[66:69], v176 offset:4480
	s_waitcnt lgkmcnt(0)
	v_mfma_f32_16x16x32_bf16 v[38:41], v[66:69], v[70:73], v[38:41]
	v_mfma_f32_16x16x32_bf16 v[42:45], v[66:69], v[74:77], v[42:45]
	v_mfma_f32_16x16x32_bf16 v[46:49], v[66:69], v[78:81], v[46:49]
	v_mfma_f32_16x16x32_bf16 v[34:37], v[66:69], v[82:85], v[34:37]
	ds_read_b128 v[66:69], v176 offset:8832
	s_waitcnt lgkmcnt(0)
	v_mfma_f32_16x16x32_bf16 v[54:57], v[66:69], v[70:73], v[54:57]
	v_mfma_f32_16x16x32_bf16 v[58:61], v[66:69], v[74:77], v[58:61]
	v_mfma_f32_16x16x32_bf16 v[62:65], v[66:69], v[78:81], v[62:65]
	v_mfma_f32_16x16x32_bf16 v[50:53], v[66:69], v[82:85], v[50:53]
	ds_read_b128 v[66:69], v176 offset:13184
	s_waitcnt lgkmcnt(0)
	v_mfma_f32_16x16x32_bf16 v[6:9], v[66:69], v[70:73], v[6:9]
	ds_read_b128 v[70:73], v176 offset:192
	v_mfma_f32_16x16x32_bf16 v[14:17], v[66:69], v[74:77], v[14:17]
	ds_read_b128 v[74:77], v177 offset:39360
	v_mfma_f32_16x16x32_bf16 v[22:25], v[66:69], v[78:81], v[22:25]
	ds_read_b128 v[78:81], v177 offset:43712
	v_mfma_f32_16x16x32_bf16 v[30:33], v[66:69], v[82:85], v[30:33]
	ds_read_b128 v[66:69], v177 offset:35008
	ds_read_b128 v[82:85], v177 offset:48064
	s_waitcnt lgkmcnt(1)
	v_mfma_f32_16x16x32_bf16 v[10:13], v[70:73], v[66:69], v[10:13]
	v_mfma_f32_16x16x32_bf16 v[18:21], v[70:73], v[74:77], v[18:21]
	v_mfma_f32_16x16x32_bf16 v[26:29], v[70:73], v[78:81], v[26:29]
	s_waitcnt lgkmcnt(0)
	v_mfma_f32_16x16x32_bf16 v[2:5], v[70:73], v[82:85], v[2:5]
	ds_read_b128 v[70:73], v176 offset:4544
	s_waitcnt lgkmcnt(0)
	v_mfma_f32_16x16x32_bf16 v[38:41], v[70:73], v[66:69], v[38:41]
	v_mfma_f32_16x16x32_bf16 v[42:45], v[70:73], v[74:77], v[42:45]
	v_mfma_f32_16x16x32_bf16 v[46:49], v[70:73], v[78:81], v[46:49]
	v_mfma_f32_16x16x32_bf16 v[34:37], v[70:73], v[82:85], v[34:37]
	ds_read_b128 v[70:73], v176 offset:8896
	s_waitcnt lgkmcnt(0)
	v_mfma_f32_16x16x32_bf16 v[54:57], v[70:73], v[66:69], v[54:57]
	v_mfma_f32_16x16x32_bf16 v[58:61], v[70:73], v[74:77], v[58:61]
	v_mfma_f32_16x16x32_bf16 v[62:65], v[70:73], v[78:81], v[62:65]
	v_mfma_f32_16x16x32_bf16 v[50:53], v[70:73], v[82:85], v[50:53]
	ds_read_b128 v[70:73], v176 offset:13248
	s_waitcnt lgkmcnt(0)
	s_barrier
	v_mfma_f32_16x16x32_bf16 v[6:9], v[70:73], v[66:69], v[6:9]
	ds_write2_b32 v146, v10, v18 offset1:16
	ds_write2_b32 v146, v11, v19 offset0:132 offset1:148
	v_add_u32_e32 v10, 0x400, v146
	v_mfma_f32_16x16x32_bf16 v[14:17], v[70:73], v[74:77], v[14:17]
	ds_write2_b32 v10, v12, v20 offset0:8 offset1:24
	ds_write2_b32 v10, v13, v21 offset0:140 offset1:156
	ds_write2_b32 v146, v26, v2 offset0:32 offset1:48
	ds_write2_b32 v146, v27, v3 offset0:164 offset1:180
	ds_write2_b32 v10, v28, v4 offset0:40 offset1:56
	ds_write2_b32 v10, v29, v5 offset0:172 offset1:188
	v_add_u32_e32 v2, 0x2000, v146
	v_add_u32_e32 v3, 0x2400, v146
	v_mfma_f32_16x16x32_bf16 v[22:25], v[70:73], v[78:81], v[22:25]
	ds_write2_b32 v2, v38, v42 offset0:64 offset1:80
	ds_write2_b32 v2, v39, v43 offset0:196 offset1:212
	ds_write2_b32 v3, v40, v44 offset0:72 offset1:88
	ds_write2_b32 v3, v41, v45 offset0:204 offset1:220
	ds_write2_b32 v2, v46, v34 offset0:96 offset1:112
	ds_write2_b32 v2, v47, v35 offset0:228 offset1:244
	ds_write2_b32 v3, v48, v36 offset0:104 offset1:120
	ds_write2_b32 v3, v49, v37 offset0:236 offset1:252
	v_add_u32_e32 v2, 0x4000, v146
	v_mfma_f32_16x16x32_bf16 v[30:33], v[70:73], v[82:85], v[30:33]
	v_add_u32_e32 v3, 0x4400, v146
	v_add_u32_e32 v4, 0x4800, v146
	ds_write2_b32 v2, v54, v58 offset0:128 offset1:144
	ds_write2_b32 v3, v55, v59 offset0:4 offset1:20
	ds_write2_b32 v3, v56, v60 offset0:136 offset1:152
	ds_write2_b32 v4, v57, v61 offset0:12 offset1:28
	ds_write2_b32 v2, v62, v50 offset0:160 offset1:176
	ds_write2_b32 v3, v63, v51 offset0:36 offset1:52
	ds_write2_b32 v3, v64, v52 offset0:168 offset1:184
	ds_write2_b32 v4, v65, v53 offset0:44 offset1:60
	v_add_u32_e32 v2, 0x6000, v146
	v_add_u32_e32 v3, 0x6400, v146
	v_add_u32_e32 v4, 0x6800, v146
	ds_write2_b32 v2, v6, v14 offset0:192 offset1:208
	ds_write2_b32 v3, v7, v15 offset0:68 offset1:84
	ds_write2_b32 v3, v8, v16 offset0:200 offset1:216
	ds_write2_b32 v4, v9, v17 offset0:76 offset1:92
	ds_write2_b32 v2, v22, v30 offset0:224 offset1:240
	ds_write2_b32 v3, v23, v31 offset0:100 offset1:116
	ds_write2_b32 v3, v24, v32 offset0:232 offset1:248
	ds_write2_b32 v4, v25, v33 offset0:108 offset1:124
	v_mov_b32_e32 v2, v178
	s_waitcnt lgkmcnt(0)
	s_barrier
	s_branch .LBB0_790

.LBB0_927:
	s_lshl_b32 s28, s66, 7
	s_ashr_i32 s29, s28, 31
	s_lshl_b64 s[26:27], s[28:29], 10
	s_lshl_b64 s[6:7], s[28:29], 11
	s_add_u32 s6, s23, s6
	s_addc_u32 s7, s33, s7
	s_ashr_i32 s25, s24, 31
	s_lshl_b64 s[8:9], s[24:25], 18
	s_add_u32 s8, s54, s8
	s_addc_u32 s9, s55, s9
	v_and_b32_e32 v200, 15, v0
	v_bfe_u32 v201, v0, 4, 2
	v_and_b32_e32 v163, 7, v200
	v_xor_b32_e32 v201, v201, v163
	v_lshlrev_b32_e32 v201, 4, v201
	v_lshl_or_b32 v201, v200, 7, v201
	v_bfe_u32 v200, v0, 7, 1
	v_lshl_or_b32 v132, v200, 13, v201
	v_bfe_u32 v200, v0, 6, 1
	v_lshl_or_b32 v194, v200, 13, v201
	v_or_b32_e32 v194, 0x4000, v194
	v_xor_b32_e32 v163, 64, v132
	v_xor_b32_e32 v195, 64, v194
	v_bfe_u32 v200, v0, 3, 3
	v_and_b32_e32 v201, 7, v0
	v_xor_b32_e32 v201, v201, v200
	v_lshlrev_b32_e32 v201, 4, v201
	v_lshl_or_b32 v201, v200, 11, v201
	v_lshrrev_b32_e32 v200, 6, v0
	v_and_b32_e32 v200, 3, v200
	v_lshl_or_b32 v196, v200, 16, v201
	v_add_u32_e32 v197, 0x3c00, v196
	v_add_u32_e32 v198, 0x7800, v196
	v_add_u32_e32 v199, 0xb400, v196
	v_lshlrev_b32_e32 v200, 12, v200
	s_nop 0
	v_readfirstlane_b32 s14, v200
	s_add_u32 s14, s14, 32
	v_mov_b32_e32 v94, 0
	v_mov_b32_e32 v95, 0
	v_mov_b32_e32 v96, 0
	v_mov_b32_e32 v97, 0
	v_mov_b32_e32 v90, 0
	v_mov_b32_e32 v91, 0
	v_mov_b32_e32 v92, 0
	v_mov_b32_e32 v93, 0
	v_mov_b32_e32 v86, 0
	v_mov_b32_e32 v87, 0
	v_mov_b32_e32 v88, 0
	v_mov_b32_e32 v89, 0
	v_mov_b32_e32 v82, 0
	v_mov_b32_e32 v83, 0
	v_mov_b32_e32 v84, 0
	v_mov_b32_e32 v85, 0
	v_mov_b32_e32 v74, 0
	v_mov_b32_e32 v75, 0
	v_mov_b32_e32 v76, 0
	v_mov_b32_e32 v77, 0
	v_mov_b32_e32 v70, 0
	v_mov_b32_e32 v71, 0
	v_mov_b32_e32 v72, 0
	v_mov_b32_e32 v73, 0
	v_mov_b32_e32 v66, 0
	v_mov_b32_e32 v67, 0
	v_mov_b32_e32 v68, 0
	v_mov_b32_e32 v69, 0
	v_mov_b32_e32 v62, 0
	v_mov_b32_e32 v63, 0
	v_mov_b32_e32 v64, 0
	v_mov_b32_e32 v65, 0
	v_mov_b32_e32 v50, 0
	v_mov_b32_e32 v51, 0
	v_mov_b32_e32 v52, 0
	v_mov_b32_e32 v53, 0
	v_mov_b32_e32 v30, 0
	v_mov_b32_e32 v31, 0
	v_mov_b32_e32 v32, 0
	v_mov_b32_e32 v33, 0
	v_mov_b32_e32 v18, 0
	v_mov_b32_e32 v19, 0
	v_mov_b32_e32 v20, 0
	v_mov_b32_e32 v21, 0
	v_mov_b32_e32 v14, 0
	v_mov_b32_e32 v15, 0
	v_mov_b32_e32 v16, 0
	v_mov_b32_e32 v17, 0
	v_mov_b32_e32 v10, 0
	v_mov_b32_e32 v11, 0
	v_mov_b32_e32 v12, 0
	v_mov_b32_e32 v13, 0
	v_mov_b32_e32 v6, 0
	v_mov_b32_e32 v7, 0
	v_mov_b32_e32 v8, 0
	v_mov_b32_e32 v9, 0
	v_mov_b32_e32 v2, 0
	v_mov_b32_e32 v3, 0
	v_mov_b32_e32 v4, 0
	v_mov_b32_e32 v5, 0
	v_mov_b32_e32 v78, 0
	v_mov_b32_e32 v79, 0
	v_mov_b32_e32 v80, 0
	v_mov_b32_e32 v81, 0
	v_mov_b32_e32 v98, 0
	v_mov_b32_e32 v99, 0
	v_mov_b32_e32 v100, 0
	v_mov_b32_e32 v101, 0
	v_mov_b32_e32 v102, 0
	v_mov_b32_e32 v103, 0
	v_mov_b32_e32 v104, 0
	v_mov_b32_e32 v105, 0
	v_mov_b32_e32 v106, 0
	v_mov_b32_e32 v107, 0
	v_mov_b32_e32 v108, 0
	v_mov_b32_e32 v109, 0
	v_mov_b32_e32 v110, 0
	v_mov_b32_e32 v111, 0
	v_mov_b32_e32 v112, 0
	v_mov_b32_e32 v113, 0
	v_mov_b32_e32 v114, 0
	v_mov_b32_e32 v115, 0
	v_mov_b32_e32 v116, 0
	v_mov_b32_e32 v117, 0
	v_mov_b32_e32 v118, 0
	v_mov_b32_e32 v119, 0
	v_mov_b32_e32 v120, 0
	v_mov_b32_e32 v121, 0
	v_mov_b32_e32 v122, 0
	v_mov_b32_e32 v123, 0
	v_mov_b32_e32 v124, 0
	v_mov_b32_e32 v125, 0
	v_mov_b32_e32 v126, 0
	v_mov_b32_e32 v127, 0
	v_mov_b32_e32 v128, 0
	v_mov_b32_e32 v129, 0
	s_waitcnt lgkmcnt(0)
	s_barrier
	v_readlane_b32 s98, v255, 16
	s_and_b32 s98, s98, 7
	s_lshl_b32 s98, s98, 1
	s_lshl_b32 s99, s98, 7
	s_add_u32 s6, s6, s99
	s_addc_u32 s7, s7, 0
	s_add_u32 s8, s8, s99
	s_addc_u32 s9, s9, 0
	s_add_u32 m0, s14, 0
	s_nop 0
	global_load_lds_dwordx4 v196, s[6:7] offset:0
	global_load_lds_dwordx4 v197, s[6:7] offset:1024
	global_load_lds_dwordx4 v198, s[6:7] offset:2048
	global_load_lds_dwordx4 v199, s[6:7] offset:3072
	s_add_u32 m0, s14, 16384
	s_nop 0
	global_load_lds_dwordx4 v196, s[8:9] offset:0
	global_load_lds_dwordx4 v197, s[8:9] offset:1024
	global_load_lds_dwordx4 v198, s[8:9] offset:2048
	global_load_lds_dwordx4 v199, s[8:9] offset:3072
	s_add_u32 s98, s98, 1
	s_and_b32 s98, s98, 15
	s_cmp_eq_u32 s98, 0
	s_cselect_b32 s99, 0x800, 0
	s_add_u32 s6, s6, 0x80
	s_addc_u32 s7, s7, 0
	s_sub_u32 s6, s6, s99
	s_subb_u32 s7, s7, 0
	s_add_u32 s8, s8, 0x80
	s_addc_u32 s9, s9, 0
	s_sub_u32 s8, s8, s99
	s_subb_u32 s9, s9, 0
	s_mov_b32 s25, 0
	s_waitcnt vmcnt(0)
	s_setprio 1
.Lk_g1l1_loop:
	s_barrier
	s_add_u32 m0, s14, 32768
	v_mfma_f32_16x16x32_bf16 v[94:97], v[98:101], v[114:117], v[94:97]
	ds_read_b128 v[22:25], v132 offset:32
	global_load_lds_dwordx4 v196, s[6:7] offset:0
	v_mfma_f32_16x16x32_bf16 v[90:93], v[98:101], v[118:121], v[90:93]
	ds_read_b128 v[42:45], v194 offset:32
	global_load_lds_dwordx4 v197, s[6:7] offset:1024
	v_mfma_f32_16x16x32_bf16 v[86:89], v[98:101], v[122:125], v[86:89]
	ds_read_b128 v[46:49], v194 offset:2080
	global_load_lds_dwordx4 v198, s[6:7] offset:2048
	v_mfma_f32_16x16x32_bf16 v[82:85], v[98:101], v[126:129], v[82:85]
	ds_read_b128 v[26:29], v132 offset:2080
	global_load_lds_dwordx4 v199, s[6:7] offset:3072
	s_add_u32 m0, s14, 49152
	v_mfma_f32_16x16x32_bf16 v[74:77], v[102:105], v[114:117], v[74:77]
	ds_read_b128 v[54:57], v194 offset:4128
	global_load_lds_dwordx4 v196, s[8:9] offset:0
	v_mfma_f32_16x16x32_bf16 v[70:73], v[102:105], v[118:121], v[70:73]
	ds_read_b128 v[58:61], v194 offset:6176
	global_load_lds_dwordx4 v197, s[8:9] offset:1024
	v_mfma_f32_16x16x32_bf16 v[66:69], v[102:105], v[122:125], v[66:69]
	ds_read_b128 v[34:37], v132 offset:4128
	global_load_lds_dwordx4 v198, s[8:9] offset:2048
	v_mfma_f32_16x16x32_bf16 v[62:65], v[102:105], v[126:129], v[62:65]
	ds_read_b128 v[38:41], v132 offset:6176
	global_load_lds_dwordx4 v199, s[8:9] offset:3072
	v_mfma_f32_16x16x32_bf16 v[50:53], v[106:109], v[114:117], v[50:53]
	v_mfma_f32_16x16x32_bf16 v[30:33], v[106:109], v[118:121], v[30:33]
	v_mfma_f32_16x16x32_bf16 v[18:21], v[106:109], v[122:125], v[18:21]
	v_mfma_f32_16x16x32_bf16 v[14:17], v[106:109], v[126:129], v[14:17]
	v_mfma_f32_16x16x32_bf16 v[10:13], v[110:113], v[114:117], v[10:13]
	v_mfma_f32_16x16x32_bf16 v[6:9], v[110:113], v[118:121], v[6:9]
	v_mfma_f32_16x16x32_bf16 v[2:5], v[110:113], v[122:125], v[2:5]
	v_mfma_f32_16x16x32_bf16 v[78:81], v[110:113], v[126:129], v[78:81]
	s_add_u32 s98, s98, 1
	s_and_b32 s98, s98, 15
	s_cmp_eq_u32 s98, 0
	s_cselect_b32 s99, 0x800, 0
	s_add_u32 s6, s6, 0x80
	s_addc_u32 s7, s7, 0
	s_sub_u32 s6, s6, s99
	s_subb_u32 s7, s7, 0
	s_add_u32 s8, s8, 0x80
	s_addc_u32 s9, s9, 0
	s_sub_u32 s8, s8, s99
	s_subb_u32 s9, s9, 0
	s_waitcnt lgkmcnt(0)
	v_mfma_f32_16x16x32_bf16 v[94:97], v[22:25], v[42:45], v[94:97]
	ds_read_b128 v[98:101], v163 offset:32
	v_mfma_f32_16x16x32_bf16 v[90:93], v[22:25], v[46:49], v[90:93]
	ds_read_b128 v[114:117], v195 offset:32
	v_mfma_f32_16x16x32_bf16 v[86:89], v[22:25], v[54:57], v[86:89]
	ds_read_b128 v[118:121], v195 offset:2080
	v_mfma_f32_16x16x32_bf16 v[82:85], v[22:25], v[58:61], v[82:85]
	ds_read_b128 v[102:105], v163 offset:2080
	v_mfma_f32_16x16x32_bf16 v[74:77], v[26:29], v[42:45], v[74:77]
	ds_read_b128 v[122:125], v195 offset:4128
	v_mfma_f32_16x16x32_bf16 v[70:73], v[26:29], v[46:49], v[70:73]
	ds_read_b128 v[126:129], v195 offset:6176
	v_mfma_f32_16x16x32_bf16 v[66:69], v[26:29], v[54:57], v[66:69]
	ds_read_b128 v[106:109], v163 offset:4128
	v_mfma_f32_16x16x32_bf16 v[62:65], v[26:29], v[58:61], v[62:65]
	ds_read_b128 v[110:113], v163 offset:6176
	v_mfma_f32_16x16x32_bf16 v[50:53], v[34:37], v[42:45], v[50:53]
	v_mfma_f32_16x16x32_bf16 v[30:33], v[34:37], v[46:49], v[30:33]
	v_mfma_f32_16x16x32_bf16 v[18:21], v[34:37], v[54:57], v[18:21]
	v_mfma_f32_16x16x32_bf16 v[14:17], v[34:37], v[58:61], v[14:17]
	v_mfma_f32_16x16x32_bf16 v[10:13], v[38:41], v[42:45], v[10:13]
	v_mfma_f32_16x16x32_bf16 v[6:9], v[38:41], v[46:49], v[6:9]
	v_mfma_f32_16x16x32_bf16 v[2:5], v[38:41], v[54:57], v[2:5]
	v_mfma_f32_16x16x32_bf16 v[78:81], v[38:41], v[58:61], v[78:81]
	s_waitcnt lgkmcnt(0)
	s_waitcnt vmcnt(0)
	s_barrier
	s_add_u32 m0, s14, 0
	v_mfma_f32_16x16x32_bf16 v[94:97], v[98:101], v[114:117], v[94:97]
	ds_read_b128 v[22:25], v132 offset:32800
	global_load_lds_dwordx4 v196, s[6:7] offset:0
	v_mfma_f32_16x16x32_bf16 v[90:93], v[98:101], v[118:121], v[90:93]
	ds_read_b128 v[42:45], v194 offset:32800
	global_load_lds_dwordx4 v197, s[6:7] offset:1024
	v_mfma_f32_16x16x32_bf16 v[86:89], v[98:101], v[122:125], v[86:89]
	ds_read_b128 v[46:49], v194 offset:34848
	global_load_lds_dwordx4 v198, s[6:7] offset:2048
	v_mfma_f32_16x16x32_bf16 v[82:85], v[98:101], v[126:129], v[82:85]
	ds_read_b128 v[26:29], v132 offset:34848
	global_load_lds_dwordx4 v199, s[6:7] offset:3072
	s_add_u32 m0, s14, 16384
	v_mfma_f32_16x16x32_bf16 v[74:77], v[102:105], v[114:117], v[74:77]
	ds_read_b128 v[54:57], v194 offset:36896
	global_load_lds_dwordx4 v196, s[8:9] offset:0
	v_mfma_f32_16x16x32_bf16 v[70:73], v[102:105], v[118:121], v[70:73]
	ds_read_b128 v[58:61], v194 offset:38944
	global_load_lds_dwordx4 v197, s[8:9] offset:1024
	v_mfma_f32_16x16x32_bf16 v[66:69], v[102:105], v[122:125], v[66:69]
	ds_read_b128 v[34:37], v132 offset:36896
	global_load_lds_dwordx4 v198, s[8:9] offset:2048
	v_mfma_f32_16x16x32_bf16 v[62:65], v[102:105], v[126:129], v[62:65]
	ds_read_b128 v[38:41], v132 offset:38944
	global_load_lds_dwordx4 v199, s[8:9] offset:3072
	v_mfma_f32_16x16x32_bf16 v[50:53], v[106:109], v[114:117], v[50:53]
	v_mfma_f32_16x16x32_bf16 v[30:33], v[106:109], v[118:121], v[30:33]
	v_mfma_f32_16x16x32_bf16 v[18:21], v[106:109], v[122:125], v[18:21]
	v_mfma_f32_16x16x32_bf16 v[14:17], v[106:109], v[126:129], v[14:17]
	v_mfma_f32_16x16x32_bf16 v[10:13], v[110:113], v[114:117], v[10:13]
	v_mfma_f32_16x16x32_bf16 v[6:9], v[110:113], v[118:121], v[6:9]
	v_mfma_f32_16x16x32_bf16 v[2:5], v[110:113], v[122:125], v[2:5]
	v_mfma_f32_16x16x32_bf16 v[78:81], v[110:113], v[126:129], v[78:81]
	s_add_u32 s98, s98, 1
	s_and_b32 s98, s98, 15
	s_cmp_eq_u32 s98, 0
	s_cselect_b32 s99, 0x800, 0
	s_add_u32 s6, s6, 0x80
	s_addc_u32 s7, s7, 0
	s_sub_u32 s6, s6, s99
	s_subb_u32 s7, s7, 0
	s_add_u32 s8, s8, 0x80
	s_addc_u32 s9, s9, 0
	s_sub_u32 s8, s8, s99
	s_subb_u32 s9, s9, 0
	s_waitcnt lgkmcnt(0)
	v_mfma_f32_16x16x32_bf16 v[94:97], v[22:25], v[42:45], v[94:97]
	ds_read_b128 v[98:101], v163 offset:32800
	v_mfma_f32_16x16x32_bf16 v[90:93], v[22:25], v[46:49], v[90:93]
	ds_read_b128 v[114:117], v195 offset:32800
	v_mfma_f32_16x16x32_bf16 v[86:89], v[22:25], v[54:57], v[86:89]
	ds_read_b128 v[118:121], v195 offset:34848
	v_mfma_f32_16x16x32_bf16 v[82:85], v[22:25], v[58:61], v[82:85]
	ds_read_b128 v[102:105], v163 offset:34848
	v_mfma_f32_16x16x32_bf16 v[74:77], v[26:29], v[42:45], v[74:77]
	ds_read_b128 v[122:125], v195 offset:36896
	v_mfma_f32_16x16x32_bf16 v[70:73], v[26:29], v[46:49], v[70:73]
	ds_read_b128 v[126:129], v195 offset:38944
	v_mfma_f32_16x16x32_bf16 v[66:69], v[26:29], v[54:57], v[66:69]
	ds_read_b128 v[106:109], v163 offset:36896
	v_mfma_f32_16x16x32_bf16 v[62:65], v[26:29], v[58:61], v[62:65]
	ds_read_b128 v[110:113], v163 offset:38944
	v_mfma_f32_16x16x32_bf16 v[50:53], v[34:37], v[42:45], v[50:53]
	v_mfma_f32_16x16x32_bf16 v[30:33], v[34:37], v[46:49], v[30:33]
	v_mfma_f32_16x16x32_bf16 v[18:21], v[34:37], v[54:57], v[18:21]
	v_mfma_f32_16x16x32_bf16 v[14:17], v[34:37], v[58:61], v[14:17]
	v_mfma_f32_16x16x32_bf16 v[10:13], v[38:41], v[42:45], v[10:13]
	v_mfma_f32_16x16x32_bf16 v[6:9], v[38:41], v[46:49], v[6:9]
	v_mfma_f32_16x16x32_bf16 v[2:5], v[38:41], v[54:57], v[2:5]
	v_mfma_f32_16x16x32_bf16 v[78:81], v[38:41], v[58:61], v[78:81]
	s_waitcnt lgkmcnt(0)
	s_waitcnt vmcnt(0)
	s_add_u32 s25, s25, 1
	s_cmp_lt_u32 s25, 7
	s_cbranch_scc1 .Lk_g1l1_loop
	s_barrier
	s_add_u32 m0, s14, 32768
	v_mfma_f32_16x16x32_bf16 v[94:97], v[98:101], v[114:117], v[94:97]
	ds_read_b128 v[22:25], v132 offset:32
	global_load_lds_dwordx4 v196, s[6:7] offset:0
	v_mfma_f32_16x16x32_bf16 v[90:93], v[98:101], v[118:121], v[90:93]
	ds_read_b128 v[42:45], v194 offset:32
	global_load_lds_dwordx4 v197, s[6:7] offset:1024
	v_mfma_f32_16x16x32_bf16 v[86:89], v[98:101], v[122:125], v[86:89]
	ds_read_b128 v[46:49], v194 offset:2080
	global_load_lds_dwordx4 v198, s[6:7] offset:2048
	v_mfma_f32_16x16x32_bf16 v[82:85], v[98:101], v[126:129], v[82:85]
	ds_read_b128 v[26:29], v132 offset:2080
	global_load_lds_dwordx4 v199, s[6:7] offset:3072
	s_add_u32 m0, s14, 49152
	v_mfma_f32_16x16x32_bf16 v[74:77], v[102:105], v[114:117], v[74:77]
	ds_read_b128 v[54:57], v194 offset:4128
	global_load_lds_dwordx4 v196, s[8:9] offset:0
	v_mfma_f32_16x16x32_bf16 v[70:73], v[102:105], v[118:121], v[70:73]
	ds_read_b128 v[58:61], v194 offset:6176
	global_load_lds_dwordx4 v197, s[8:9] offset:1024
	v_mfma_f32_16x16x32_bf16 v[66:69], v[102:105], v[122:125], v[66:69]
	ds_read_b128 v[34:37], v132 offset:4128
	global_load_lds_dwordx4 v198, s[8:9] offset:2048
	v_mfma_f32_16x16x32_bf16 v[62:65], v[102:105], v[126:129], v[62:65]
	ds_read_b128 v[38:41], v132 offset:6176
	global_load_lds_dwordx4 v199, s[8:9] offset:3072
	v_mfma_f32_16x16x32_bf16 v[50:53], v[106:109], v[114:117], v[50:53]
	v_mfma_f32_16x16x32_bf16 v[30:33], v[106:109], v[118:121], v[30:33]
	v_mfma_f32_16x16x32_bf16 v[18:21], v[106:109], v[122:125], v[18:21]
	v_mfma_f32_16x16x32_bf16 v[14:17], v[106:109], v[126:129], v[14:17]
	v_mfma_f32_16x16x32_bf16 v[10:13], v[110:113], v[114:117], v[10:13]
	v_mfma_f32_16x16x32_bf16 v[6:9], v[110:113], v[118:121], v[6:9]
	v_mfma_f32_16x16x32_bf16 v[2:5], v[110:113], v[122:125], v[2:5]
	v_mfma_f32_16x16x32_bf16 v[78:81], v[110:113], v[126:129], v[78:81]
	s_add_u32 s98, s98, 1
	s_and_b32 s98, s98, 15
	s_cmp_eq_u32 s98, 0
	s_cselect_b32 s99, 0x800, 0
	s_add_u32 s6, s6, 0x80
	s_addc_u32 s7, s7, 0
	s_sub_u32 s6, s6, s99
	s_subb_u32 s7, s7, 0
	s_add_u32 s8, s8, 0x80
	s_addc_u32 s9, s9, 0
	s_sub_u32 s8, s8, s99
	s_subb_u32 s9, s9, 0
	s_waitcnt lgkmcnt(0)
	v_mfma_f32_16x16x32_bf16 v[94:97], v[22:25], v[42:45], v[94:97]
	ds_read_b128 v[98:101], v163 offset:32
	v_mfma_f32_16x16x32_bf16 v[90:93], v[22:25], v[46:49], v[90:93]
	ds_read_b128 v[114:117], v195 offset:32
	v_mfma_f32_16x16x32_bf16 v[86:89], v[22:25], v[54:57], v[86:89]
	ds_read_b128 v[118:121], v195 offset:2080
	v_mfma_f32_16x16x32_bf16 v[82:85], v[22:25], v[58:61], v[82:85]
	ds_read_b128 v[102:105], v163 offset:2080
	v_mfma_f32_16x16x32_bf16 v[74:77], v[26:29], v[42:45], v[74:77]
	ds_read_b128 v[122:125], v195 offset:4128
	v_mfma_f32_16x16x32_bf16 v[70:73], v[26:29], v[46:49], v[70:73]
	ds_read_b128 v[126:129], v195 offset:6176
	v_mfma_f32_16x16x32_bf16 v[66:69], v[26:29], v[54:57], v[66:69]
	ds_read_b128 v[106:109], v163 offset:4128
	v_mfma_f32_16x16x32_bf16 v[62:65], v[26:29], v[58:61], v[62:65]
	ds_read_b128 v[110:113], v163 offset:6176
	v_mfma_f32_16x16x32_bf16 v[50:53], v[34:37], v[42:45], v[50:53]
	v_mfma_f32_16x16x32_bf16 v[30:33], v[34:37], v[46:49], v[30:33]
	v_mfma_f32_16x16x32_bf16 v[18:21], v[34:37], v[54:57], v[18:21]
	v_mfma_f32_16x16x32_bf16 v[14:17], v[34:37], v[58:61], v[14:17]
	v_mfma_f32_16x16x32_bf16 v[10:13], v[38:41], v[42:45], v[10:13]
	v_mfma_f32_16x16x32_bf16 v[6:9], v[38:41], v[46:49], v[6:9]
	v_mfma_f32_16x16x32_bf16 v[2:5], v[38:41], v[54:57], v[2:5]
	v_mfma_f32_16x16x32_bf16 v[78:81], v[38:41], v[58:61], v[78:81]
	s_waitcnt lgkmcnt(0)
	s_waitcnt vmcnt(0)
	s_barrier
	v_mfma_f32_16x16x32_bf16 v[94:97], v[98:101], v[114:117], v[94:97]
	ds_read_b128 v[22:25], v132 offset:32800
	v_mfma_f32_16x16x32_bf16 v[90:93], v[98:101], v[118:121], v[90:93]
	ds_read_b128 v[42:45], v194 offset:32800
	v_mfma_f32_16x16x32_bf16 v[86:89], v[98:101], v[122:125], v[86:89]
	ds_read_b128 v[46:49], v194 offset:34848
	v_mfma_f32_16x16x32_bf16 v[82:85], v[98:101], v[126:129], v[82:85]
	ds_read_b128 v[26:29], v132 offset:34848
	v_mfma_f32_16x16x32_bf16 v[74:77], v[102:105], v[114:117], v[74:77]
	ds_read_b128 v[54:57], v194 offset:36896
	v_mfma_f32_16x16x32_bf16 v[70:73], v[102:105], v[118:121], v[70:73]
	ds_read_b128 v[58:61], v194 offset:38944
	v_mfma_f32_16x16x32_bf16 v[66:69], v[102:105], v[122:125], v[66:69]
	ds_read_b128 v[34:37], v132 offset:36896
	v_mfma_f32_16x16x32_bf16 v[62:65], v[102:105], v[126:129], v[62:65]
	ds_read_b128 v[38:41], v132 offset:38944
	v_mfma_f32_16x16x32_bf16 v[50:53], v[106:109], v[114:117], v[50:53]
	v_mfma_f32_16x16x32_bf16 v[30:33], v[106:109], v[118:121], v[30:33]
	v_mfma_f32_16x16x32_bf16 v[18:21], v[106:109], v[122:125], v[18:21]
	v_mfma_f32_16x16x32_bf16 v[14:17], v[106:109], v[126:129], v[14:17]
	v_mfma_f32_16x16x32_bf16 v[10:13], v[110:113], v[114:117], v[10:13]
	v_mfma_f32_16x16x32_bf16 v[6:9], v[110:113], v[118:121], v[6:9]
	v_mfma_f32_16x16x32_bf16 v[2:5], v[110:113], v[122:125], v[2:5]
	v_mfma_f32_16x16x32_bf16 v[78:81], v[110:113], v[126:129], v[78:81]
	s_waitcnt lgkmcnt(0)
	v_mfma_f32_16x16x32_bf16 v[94:97], v[22:25], v[42:45], v[94:97]
	ds_read_b128 v[98:101], v163 offset:32800
	v_mfma_f32_16x16x32_bf16 v[90:93], v[22:25], v[46:49], v[90:93]
	ds_read_b128 v[114:117], v195 offset:32800
	v_mfma_f32_16x16x32_bf16 v[86:89], v[22:25], v[54:57], v[86:89]
	ds_read_b128 v[118:121], v195 offset:34848
	v_mfma_f32_16x16x32_bf16 v[82:85], v[22:25], v[58:61], v[82:85]
	ds_read_b128 v[102:105], v163 offset:34848
	v_mfma_f32_16x16x32_bf16 v[74:77], v[26:29], v[42:45], v[74:77]
	ds_read_b128 v[122:125], v195 offset:36896
	v_mfma_f32_16x16x32_bf16 v[70:73], v[26:29], v[46:49], v[70:73]
	ds_read_b128 v[126:129], v195 offset:38944
	v_mfma_f32_16x16x32_bf16 v[66:69], v[26:29], v[54:57], v[66:69]
	ds_read_b128 v[106:109], v163 offset:36896
	v_mfma_f32_16x16x32_bf16 v[62:65], v[26:29], v[58:61], v[62:65]
	ds_read_b128 v[110:113], v163 offset:38944
	v_mfma_f32_16x16x32_bf16 v[50:53], v[34:37], v[42:45], v[50:53]
	v_mfma_f32_16x16x32_bf16 v[30:33], v[34:37], v[46:49], v[30:33]
	v_mfma_f32_16x16x32_bf16 v[18:21], v[34:37], v[54:57], v[18:21]
	v_mfma_f32_16x16x32_bf16 v[14:17], v[34:37], v[58:61], v[14:17]
	v_mfma_f32_16x16x32_bf16 v[10:13], v[38:41], v[42:45], v[10:13]
	v_mfma_f32_16x16x32_bf16 v[6:9], v[38:41], v[46:49], v[6:9]
	v_mfma_f32_16x16x32_bf16 v[2:5], v[38:41], v[54:57], v[2:5]
	v_mfma_f32_16x16x32_bf16 v[78:81], v[38:41], v[58:61], v[78:81]
	s_waitcnt lgkmcnt(0)
	v_mfma_f32_16x16x32_bf16 v[94:97], v[98:101], v[114:117], v[94:97]
	v_mfma_f32_16x16x32_bf16 v[90:93], v[98:101], v[118:121], v[90:93]
	v_mfma_f32_16x16x32_bf16 v[86:89], v[98:101], v[122:125], v[86:89]
	v_mfma_f32_16x16x32_bf16 v[82:85], v[98:101], v[126:129], v[82:85]
	v_mfma_f32_16x16x32_bf16 v[74:77], v[102:105], v[114:117], v[74:77]
	v_mfma_f32_16x16x32_bf16 v[70:73], v[102:105], v[118:121], v[70:73]
	v_mfma_f32_16x16x32_bf16 v[66:69], v[102:105], v[122:125], v[66:69]
	v_mfma_f32_16x16x32_bf16 v[62:65], v[102:105], v[126:129], v[62:65]
	v_mfma_f32_16x16x32_bf16 v[50:53], v[106:109], v[114:117], v[50:53]
	v_mfma_f32_16x16x32_bf16 v[30:33], v[106:109], v[118:121], v[30:33]
	v_mfma_f32_16x16x32_bf16 v[18:21], v[106:109], v[122:125], v[18:21]
	v_mfma_f32_16x16x32_bf16 v[14:17], v[106:109], v[126:129], v[14:17]
	v_mfma_f32_16x16x32_bf16 v[10:13], v[110:113], v[114:117], v[10:13]
	v_mfma_f32_16x16x32_bf16 v[6:9], v[110:113], v[118:121], v[6:9]
	v_mfma_f32_16x16x32_bf16 v[2:5], v[110:113], v[122:125], v[2:5]
	v_mfma_f32_16x16x32_bf16 v[78:81], v[110:113], v[126:129], v[78:81]
	s_setprio 0
	s_waitcnt vmcnt(7)
	v_add_u32_e32 v22, 0x400, v170
	s_barrier
	ds_write2_b32 v170, v94, v90 offset1:16
	ds_write2_b32 v170, v95, v91 offset0:132 offset1:148
	ds_write2_b32 v22, v96, v92 offset0:8 offset1:24
	ds_write2_b32 v22, v97, v93 offset0:140 offset1:156
	ds_write2_b32 v170, v86, v82 offset0:32 offset1:48
	ds_write2_b32 v170, v87, v83 offset0:164 offset1:180
	ds_write2_b32 v22, v88, v84 offset0:40 offset1:56
	ds_write2_b32 v22, v89, v85 offset0:172 offset1:188
	v_add_u32_e32 v22, 0x2000, v170
	v_add_u32_e32 v23, 0x2400, v170
	s_cmp_gt_i32 s66, 63
	ds_write2_b32 v22, v74, v70 offset0:64 offset1:80
	ds_write2_b32 v22, v75, v71 offset0:196 offset1:212
	ds_write2_b32 v23, v76, v72 offset0:72 offset1:88
	ds_write2_b32 v23, v77, v73 offset0:204 offset1:220
	ds_write2_b32 v22, v66, v62 offset0:96 offset1:112
	ds_write2_b32 v22, v67, v63 offset0:228 offset1:244
	ds_write2_b32 v23, v68, v64 offset0:104 offset1:120
	ds_write2_b32 v23, v69, v65 offset0:236 offset1:252
	v_add_u32_e32 v22, 0x4000, v170
	v_add_u32_e32 v23, 0x4400, v170
	v_add_u32_e32 v24, 0x4800, v170
	s_cselect_b64 s[34:35], -1, 0
	s_cmp_lt_i32 s66, 64
	ds_write2_b32 v22, v50, v30 offset0:128 offset1:144
	ds_write2_b32 v23, v51, v31 offset0:4 offset1:20
	ds_write2_b32 v23, v52, v32 offset0:136 offset1:152
	ds_write2_b32 v24, v53, v33 offset0:12 offset1:28
	ds_write2_b32 v22, v18, v14 offset0:160 offset1:176
	ds_write2_b32 v23, v19, v15 offset0:36 offset1:52
	ds_write2_b32 v23, v20, v16 offset0:168 offset1:184
	ds_write2_b32 v24, v21, v17 offset0:44 offset1:60
	v_add_u32_e32 v14, 0x6000, v170
	s_cselect_b64 s[36:37], -1, 0
	s_add_i32 s6, s28, 0xffffe000
	ds_write2_b32 v14, v10, v6 offset0:192 offset1:208
	v_add_u32_e32 v6, 0x6400, v170
	s_lshr_b32 s68, s6, 10
	s_ashr_i32 s30, s66, 1
	s_and_b32 s67, s28, 0x380
	s_and_b32 s25, s28, 0x80
	ds_write2_b32 v6, v11, v7 offset0:68 offset1:84
	ds_write2_b32 v6, v12, v8 offset0:200 offset1:216
	v_add_u32_e32 v7, 0x6800, v170
	v_add_u32_e32 v164, s28, v167
	s_cmp_gt_i32 s24, 9
	s_mov_b64 s[6:7], -1
	ds_write2_b32 v7, v13, v9 offset0:76 offset1:92
	ds_write2_b32 v14, v2, v78 offset0:224 offset1:240
	ds_write2_b32 v6, v3, v79 offset0:100 offset1:116
	ds_write2_b32 v6, v4, v80 offset0:232 offset1:248
	ds_write2_b32 v7, v5, v81 offset0:108 offset1:124
	s_waitcnt lgkmcnt(0)
	s_barrier
	s_cbranch_scc0 .LBB0_979
	s_cmp_gt_u32 s24, 11
	s_cbranch_scc0 .LBB0_964
	s_cmp_lg_u32 s24, 36
	s_cbranch_scc0 .LBB0_959
	s_sub_i32 s6, s24, 20
	s_cmp_gt_u32 s6, 7
	s_mov_b64 s[6:7], -1
	s_cbranch_scc0 .LBB0_955
	s_cmp_lt_u32 s24, 16
	s_cselect_b64 s[46:47], -1, 0
	s_cmp_gt_u32 s24, 15
	s_mov_b64 s[52:53], -1
	s_cbranch_scc0 .LBB0_942
	s_cmp_gt_u32 s24, 19
	s_cbranch_scc0 .LBB0_939
	s_mov_b64 s[48:49], -1
	s_cmp_gt_u32 s24, 35
	s_mov_b64 s[8:9], -1
	s_cbranch_scc0 .LBB0_937
	s_lshl_b64 s[6:7], s[28:29], 12
	s_add_u32 s6, s42, s6
	s_addc_u32 s7, s43, s7
	s_mov_b64 s[8:9], 0

.LBB0_1292:
	s_and_b32 s70, s69, 0xff
	s_mul_i32 s4, s70, 0xab
	s_lshr_b32 s73, s4, 11
	s_mul_i32 s4, s73, 12
	s_sub_i32 s4, s69, s4
	s_and_b32 s4, s4, 0xff
	s_lshl_b32 s4, s4, 10
	s_or_b32 s8, s4, s52
	s_lshl_b32 s71, s8, 10
	s_lshl_b32 s4, s8, 11
	s_add_u32 s4, s53, s4
	s_addc_u32 s5, s54, 0
	s_lshl_b32 s6, s73, 17
	s_add_i32 s72, s6, 0x100000
	s_lshl_b32 s6, s72, 1
	s_add_u32 s6, s55, s6
	s_addc_u32 s7, s56, 0
	v_and_b32_e32 v164, 15, v0
	v_bfe_u32 v165, v0, 4, 2
	v_and_b32_e32 v111, 7, v164
	v_xor_b32_e32 v165, v165, v111
	v_lshlrev_b32_e32 v165, 4, v165
	v_lshl_or_b32 v165, v164, 7, v165
	v_bfe_u32 v164, v0, 7, 1
	v_lshl_or_b32 v100, v164, 13, v165
	v_bfe_u32 v164, v0, 6, 1
	v_lshl_or_b32 v158, v164, 13, v165
	v_or_b32_e32 v158, 0x4000, v158
	v_xor_b32_e32 v111, 64, v100
	v_xor_b32_e32 v159, 64, v158
	v_bfe_u32 v164, v0, 3, 3
	v_and_b32_e32 v165, 7, v0
	v_xor_b32_e32 v165, v165, v164
	v_lshlrev_b32_e32 v165, 4, v165
	v_lshl_or_b32 v165, v164, 11, v165
	v_lshrrev_b32_e32 v164, 6, v0
	v_and_b32_e32 v164, 3, v164
	v_lshl_or_b32 v160, v164, 16, v165
	v_add_u32_e32 v161, 0x3c00, v160
	v_add_u32_e32 v162, 0x7800, v160
	v_add_u32_e32 v163, 0xb400, v160
	v_lshlrev_b32_e32 v164, 12, v164
	s_nop 0
	v_readfirstlane_b32 s10, v164
	s_add_u32 s10, s10, 32
	v_mov_b32_e32 v94, 0
	v_mov_b32_e32 v95, 0
	v_mov_b32_e32 v96, 0
	v_mov_b32_e32 v97, 0
	v_mov_b32_e32 v90, 0
	v_mov_b32_e32 v91, 0
	v_mov_b32_e32 v92, 0
	v_mov_b32_e32 v93, 0
	v_mov_b32_e32 v82, 0
	v_mov_b32_e32 v83, 0
	v_mov_b32_e32 v84, 0
	v_mov_b32_e32 v85, 0
	v_mov_b32_e32 v78, 0
	v_mov_b32_e32 v79, 0
	v_mov_b32_e32 v80, 0
	v_mov_b32_e32 v81, 0
	v_mov_b32_e32 v74, 0
	v_mov_b32_e32 v75, 0
	v_mov_b32_e32 v76, 0
	v_mov_b32_e32 v77, 0
	v_mov_b32_e32 v70, 0
	v_mov_b32_e32 v71, 0
	v_mov_b32_e32 v72, 0
	v_mov_b32_e32 v73, 0
	v_mov_b32_e32 v66, 0
	v_mov_b32_e32 v67, 0
	v_mov_b32_e32 v68, 0
	v_mov_b32_e32 v69, 0
	v_mov_b32_e32 v58, 0
	v_mov_b32_e32 v59, 0
	v_mov_b32_e32 v60, 0
	v_mov_b32_e32 v61, 0
	v_mov_b32_e32 v26, 0
	v_mov_b32_e32 v27, 0
	v_mov_b32_e32 v28, 0
	v_mov_b32_e32 v29, 0
	v_mov_b32_e32 v22, 0
	v_mov_b32_e32 v23, 0
	v_mov_b32_e32 v24, 0
	v_mov_b32_e32 v25, 0
	v_mov_b32_e32 v18, 0
	v_mov_b32_e32 v19, 0
	v_mov_b32_e32 v20, 0
	v_mov_b32_e32 v21, 0
	v_mov_b32_e32 v14, 0
	v_mov_b32_e32 v15, 0
	v_mov_b32_e32 v16, 0
	v_mov_b32_e32 v17, 0
	v_mov_b32_e32 v10, 0
	v_mov_b32_e32 v11, 0
	v_mov_b32_e32 v12, 0
	v_mov_b32_e32 v13, 0
	v_mov_b32_e32 v6, 0
	v_mov_b32_e32 v7, 0
	v_mov_b32_e32 v8, 0
	v_mov_b32_e32 v9, 0
	v_mov_b32_e32 v2, 0
	v_mov_b32_e32 v3, 0
	v_mov_b32_e32 v4, 0
	v_mov_b32_e32 v5, 0
	v_mov_b32_e32 v86, 0
	v_mov_b32_e32 v87, 0
	v_mov_b32_e32 v88, 0
	v_mov_b32_e32 v89, 0
	v_mov_b32_e32 v114, 0
	v_mov_b32_e32 v115, 0
	v_mov_b32_e32 v116, 0
	v_mov_b32_e32 v117, 0
	v_mov_b32_e32 v118, 0
	v_mov_b32_e32 v119, 0
	v_mov_b32_e32 v120, 0
	v_mov_b32_e32 v121, 0
	v_mov_b32_e32 v122, 0
	v_mov_b32_e32 v123, 0
	v_mov_b32_e32 v124, 0
	v_mov_b32_e32 v125, 0
	v_mov_b32_e32 v138, 0
	v_mov_b32_e32 v139, 0
	v_mov_b32_e32 v140, 0
	v_mov_b32_e32 v141, 0
	v_mov_b32_e32 v142, 0
	v_mov_b32_e32 v143, 0
	v_mov_b32_e32 v144, 0
	v_mov_b32_e32 v145, 0
	v_mov_b32_e32 v146, 0
	v_mov_b32_e32 v147, 0
	v_mov_b32_e32 v148, 0
	v_mov_b32_e32 v149, 0
	v_mov_b32_e32 v150, 0
	v_mov_b32_e32 v151, 0
	v_mov_b32_e32 v152, 0
	v_mov_b32_e32 v153, 0
	v_mov_b32_e32 v154, 0
	v_mov_b32_e32 v155, 0
	v_mov_b32_e32 v156, 0
	v_mov_b32_e32 v157, 0
	s_waitcnt lgkmcnt(0)
	s_barrier
	v_readlane_b32 s98, v255, 16
	s_and_b32 s98, s98, 7
	s_lshl_b32 s98, s98, 1
	s_lshl_b32 s99, s98, 7
	s_add_u32 s4, s4, s99
	s_addc_u32 s5, s5, 0
	s_add_u32 s6, s6, s99
	s_addc_u32 s7, s7, 0
	s_add_u32 m0, s10, 0
	s_nop 0
	global_load_lds_dwordx4 v160, s[4:5] offset:0
	global_load_lds_dwordx4 v161, s[4:5] offset:1024
	global_load_lds_dwordx4 v162, s[4:5] offset:2048
	global_load_lds_dwordx4 v163, s[4:5] offset:3072
	s_add_u32 m0, s10, 16384
	s_nop 0
	global_load_lds_dwordx4 v160, s[6:7] offset:0
	global_load_lds_dwordx4 v161, s[6:7] offset:1024
	global_load_lds_dwordx4 v162, s[6:7] offset:2048
	global_load_lds_dwordx4 v163, s[6:7] offset:3072
	s_add_u32 s98, s98, 1
	s_and_b32 s98, s98, 15
	s_cmp_eq_u32 s98, 0
	s_cselect_b32 s99, 0x800, 0
	s_add_u32 s4, s4, 0x80
	s_addc_u32 s5, s5, 0
	s_sub_u32 s4, s4, s99
	s_subb_u32 s5, s5, 0
	s_add_u32 s6, s6, 0x80
	s_addc_u32 s7, s7, 0
	s_sub_u32 s6, s6, s99
	s_subb_u32 s7, s7, 0
	s_mov_b32 s9, 0
	s_waitcnt vmcnt(0)
	s_setprio 1
.Lk_aol1a_loop:
	s_barrier
	s_add_u32 m0, s10, 32768
	v_mfma_f32_16x16x32_bf16 v[94:97], v[114:117], v[142:145], v[94:97]
	ds_read_b128 v[30:33], v100 offset:32
	global_load_lds_dwordx4 v160, s[4:5] offset:0
	v_mfma_f32_16x16x32_bf16 v[90:93], v[114:117], v[146:149], v[90:93]
	ds_read_b128 v[46:49], v158 offset:32
	global_load_lds_dwordx4 v161, s[4:5] offset:1024
	v_mfma_f32_16x16x32_bf16 v[82:85], v[114:117], v[150:153], v[82:85]
	ds_read_b128 v[50:53], v158 offset:2080
	global_load_lds_dwordx4 v162, s[4:5] offset:2048
	v_mfma_f32_16x16x32_bf16 v[78:81], v[114:117], v[154:157], v[78:81]
	ds_read_b128 v[34:37], v100 offset:2080
	global_load_lds_dwordx4 v163, s[4:5] offset:3072
	s_add_u32 m0, s10, 49152
	v_mfma_f32_16x16x32_bf16 v[74:77], v[118:121], v[142:145], v[74:77]
	ds_read_b128 v[54:57], v158 offset:4128
	global_load_lds_dwordx4 v160, s[6:7] offset:0
	v_mfma_f32_16x16x32_bf16 v[70:73], v[118:121], v[146:149], v[70:73]
	ds_read_b128 v[62:65], v158 offset:6176
	global_load_lds_dwordx4 v161, s[6:7] offset:1024
	v_mfma_f32_16x16x32_bf16 v[66:69], v[118:121], v[150:153], v[66:69]
	ds_read_b128 v[38:41], v100 offset:4128
	global_load_lds_dwordx4 v162, s[6:7] offset:2048
	v_mfma_f32_16x16x32_bf16 v[58:61], v[118:121], v[154:157], v[58:61]
	ds_read_b128 v[42:45], v100 offset:6176
	global_load_lds_dwordx4 v163, s[6:7] offset:3072
	v_mfma_f32_16x16x32_bf16 v[26:29], v[122:125], v[142:145], v[26:29]
	v_mfma_f32_16x16x32_bf16 v[22:25], v[122:125], v[146:149], v[22:25]
	v_mfma_f32_16x16x32_bf16 v[18:21], v[122:125], v[150:153], v[18:21]
	v_mfma_f32_16x16x32_bf16 v[14:17], v[122:125], v[154:157], v[14:17]
	v_mfma_f32_16x16x32_bf16 v[10:13], v[138:141], v[142:145], v[10:13]
	v_mfma_f32_16x16x32_bf16 v[6:9], v[138:141], v[146:149], v[6:9]
	v_mfma_f32_16x16x32_bf16 v[2:5], v[138:141], v[150:153], v[2:5]
	v_mfma_f32_16x16x32_bf16 v[86:89], v[138:141], v[154:157], v[86:89]
	s_add_u32 s98, s98, 1
	s_and_b32 s98, s98, 15
	s_cmp_eq_u32 s98, 0
	s_cselect_b32 s99, 0x800, 0
	s_add_u32 s4, s4, 0x80
	s_addc_u32 s5, s5, 0
	s_sub_u32 s4, s4, s99
	s_subb_u32 s5, s5, 0
	s_add_u32 s6, s6, 0x80
	s_addc_u32 s7, s7, 0
	s_sub_u32 s6, s6, s99
	s_subb_u32 s7, s7, 0
	s_waitcnt lgkmcnt(0)
	v_mfma_f32_16x16x32_bf16 v[94:97], v[30:33], v[46:49], v[94:97]
	ds_read_b128 v[114:117], v111 offset:32
	v_mfma_f32_16x16x32_bf16 v[90:93], v[30:33], v[50:53], v[90:93]
	ds_read_b128 v[142:145], v159 offset:32
	v_mfma_f32_16x16x32_bf16 v[82:85], v[30:33], v[54:57], v[82:85]
	ds_read_b128 v[146:149], v159 offset:2080
	v_mfma_f32_16x16x32_bf16 v[78:81], v[30:33], v[62:65], v[78:81]
	ds_read_b128 v[118:121], v111 offset:2080
	v_mfma_f32_16x16x32_bf16 v[74:77], v[34:37], v[46:49], v[74:77]
	ds_read_b128 v[150:153], v159 offset:4128
	v_mfma_f32_16x16x32_bf16 v[70:73], v[34:37], v[50:53], v[70:73]
	ds_read_b128 v[154:157], v159 offset:6176
	v_mfma_f32_16x16x32_bf16 v[66:69], v[34:37], v[54:57], v[66:69]
	ds_read_b128 v[122:125], v111 offset:4128
	v_mfma_f32_16x16x32_bf16 v[58:61], v[34:37], v[62:65], v[58:61]
	ds_read_b128 v[138:141], v111 offset:6176
	v_mfma_f32_16x16x32_bf16 v[26:29], v[38:41], v[46:49], v[26:29]
	v_mfma_f32_16x16x32_bf16 v[22:25], v[38:41], v[50:53], v[22:25]
	v_mfma_f32_16x16x32_bf16 v[18:21], v[38:41], v[54:57], v[18:21]
	v_mfma_f32_16x16x32_bf16 v[14:17], v[38:41], v[62:65], v[14:17]
	v_mfma_f32_16x16x32_bf16 v[10:13], v[42:45], v[46:49], v[10:13]
	v_mfma_f32_16x16x32_bf16 v[6:9], v[42:45], v[50:53], v[6:9]
	v_mfma_f32_16x16x32_bf16 v[2:5], v[42:45], v[54:57], v[2:5]
	v_mfma_f32_16x16x32_bf16 v[86:89], v[42:45], v[62:65], v[86:89]
	s_waitcnt lgkmcnt(0)
	s_waitcnt vmcnt(0)
	s_barrier
	s_add_u32 m0, s10, 0
	v_mfma_f32_16x16x32_bf16 v[94:97], v[114:117], v[142:145], v[94:97]
	ds_read_b128 v[30:33], v100 offset:32800
	global_load_lds_dwordx4 v160, s[4:5] offset:0
	v_mfma_f32_16x16x32_bf16 v[90:93], v[114:117], v[146:149], v[90:93]
	ds_read_b128 v[46:49], v158 offset:32800
	global_load_lds_dwordx4 v161, s[4:5] offset:1024
	v_mfma_f32_16x16x32_bf16 v[82:85], v[114:117], v[150:153], v[82:85]
	ds_read_b128 v[50:53], v158 offset:34848
	global_load_lds_dwordx4 v162, s[4:5] offset:2048
	v_mfma_f32_16x16x32_bf16 v[78:81], v[114:117], v[154:157], v[78:81]
	ds_read_b128 v[34:37], v100 offset:34848
	global_load_lds_dwordx4 v163, s[4:5] offset:3072
	s_add_u32 m0, s10, 16384
	v_mfma_f32_16x16x32_bf16 v[74:77], v[118:121], v[142:145], v[74:77]
	ds_read_b128 v[54:57], v158 offset:36896
	global_load_lds_dwordx4 v160, s[6:7] offset:0
	v_mfma_f32_16x16x32_bf16 v[70:73], v[118:121], v[146:149], v[70:73]
	ds_read_b128 v[62:65], v158 offset:38944
	global_load_lds_dwordx4 v161, s[6:7] offset:1024
	v_mfma_f32_16x16x32_bf16 v[66:69], v[118:121], v[150:153], v[66:69]
	ds_read_b128 v[38:41], v100 offset:36896
	global_load_lds_dwordx4 v162, s[6:7] offset:2048
	v_mfma_f32_16x16x32_bf16 v[58:61], v[118:121], v[154:157], v[58:61]
	ds_read_b128 v[42:45], v100 offset:38944
	global_load_lds_dwordx4 v163, s[6:7] offset:3072
	v_mfma_f32_16x16x32_bf16 v[26:29], v[122:125], v[142:145], v[26:29]
	v_mfma_f32_16x16x32_bf16 v[22:25], v[122:125], v[146:149], v[22:25]
	v_mfma_f32_16x16x32_bf16 v[18:21], v[122:125], v[150:153], v[18:21]
	v_mfma_f32_16x16x32_bf16 v[14:17], v[122:125], v[154:157], v[14:17]
	v_mfma_f32_16x16x32_bf16 v[10:13], v[138:141], v[142:145], v[10:13]
	v_mfma_f32_16x16x32_bf16 v[6:9], v[138:141], v[146:149], v[6:9]
	v_mfma_f32_16x16x32_bf16 v[2:5], v[138:141], v[150:153], v[2:5]
	v_mfma_f32_16x16x32_bf16 v[86:89], v[138:141], v[154:157], v[86:89]
	s_add_u32 s98, s98, 1
	s_and_b32 s98, s98, 15
	s_cmp_eq_u32 s98, 0
	s_cselect_b32 s99, 0x800, 0
	s_add_u32 s4, s4, 0x80
	s_addc_u32 s5, s5, 0
	s_sub_u32 s4, s4, s99
	s_subb_u32 s5, s5, 0
	s_add_u32 s6, s6, 0x80
	s_addc_u32 s7, s7, 0
	s_sub_u32 s6, s6, s99
	s_subb_u32 s7, s7, 0
	s_waitcnt lgkmcnt(0)
	v_mfma_f32_16x16x32_bf16 v[94:97], v[30:33], v[46:49], v[94:97]
	ds_read_b128 v[114:117], v111 offset:32800
	v_mfma_f32_16x16x32_bf16 v[90:93], v[30:33], v[50:53], v[90:93]
	ds_read_b128 v[142:145], v159 offset:32800
	v_mfma_f32_16x16x32_bf16 v[82:85], v[30:33], v[54:57], v[82:85]
	ds_read_b128 v[146:149], v159 offset:34848
	v_mfma_f32_16x16x32_bf16 v[78:81], v[30:33], v[62:65], v[78:81]
	ds_read_b128 v[118:121], v111 offset:34848
	v_mfma_f32_16x16x32_bf16 v[74:77], v[34:37], v[46:49], v[74:77]
	ds_read_b128 v[150:153], v159 offset:36896
	v_mfma_f32_16x16x32_bf16 v[70:73], v[34:37], v[50:53], v[70:73]
	ds_read_b128 v[154:157], v159 offset:38944
	v_mfma_f32_16x16x32_bf16 v[66:69], v[34:37], v[54:57], v[66:69]
	ds_read_b128 v[122:125], v111 offset:36896
	v_mfma_f32_16x16x32_bf16 v[58:61], v[34:37], v[62:65], v[58:61]
	ds_read_b128 v[138:141], v111 offset:38944
	v_mfma_f32_16x16x32_bf16 v[26:29], v[38:41], v[46:49], v[26:29]
	v_mfma_f32_16x16x32_bf16 v[22:25], v[38:41], v[50:53], v[22:25]
	v_mfma_f32_16x16x32_bf16 v[18:21], v[38:41], v[54:57], v[18:21]
	v_mfma_f32_16x16x32_bf16 v[14:17], v[38:41], v[62:65], v[14:17]
	v_mfma_f32_16x16x32_bf16 v[10:13], v[42:45], v[46:49], v[10:13]
	v_mfma_f32_16x16x32_bf16 v[6:9], v[42:45], v[50:53], v[6:9]
	v_mfma_f32_16x16x32_bf16 v[2:5], v[42:45], v[54:57], v[2:5]
	v_mfma_f32_16x16x32_bf16 v[86:89], v[42:45], v[62:65], v[86:89]
	s_waitcnt lgkmcnt(0)
	s_waitcnt vmcnt(0)
	s_add_u32 s9, s9, 1
	s_cmp_lt_u32 s9, 7
	s_cbranch_scc1 .Lk_aol1a_loop
	s_barrier
	s_add_u32 m0, s10, 32768
	v_mfma_f32_16x16x32_bf16 v[94:97], v[114:117], v[142:145], v[94:97]
	ds_read_b128 v[30:33], v100 offset:32
	global_load_lds_dwordx4 v160, s[4:5] offset:0
	v_mfma_f32_16x16x32_bf16 v[90:93], v[114:117], v[146:149], v[90:93]
	ds_read_b128 v[46:49], v158 offset:32
	global_load_lds_dwordx4 v161, s[4:5] offset:1024
	v_mfma_f32_16x16x32_bf16 v[82:85], v[114:117], v[150:153], v[82:85]
	ds_read_b128 v[50:53], v158 offset:2080
	global_load_lds_dwordx4 v162, s[4:5] offset:2048
	v_mfma_f32_16x16x32_bf16 v[78:81], v[114:117], v[154:157], v[78:81]
	ds_read_b128 v[34:37], v100 offset:2080
	global_load_lds_dwordx4 v163, s[4:5] offset:3072
	s_add_u32 m0, s10, 49152
	v_mfma_f32_16x16x32_bf16 v[74:77], v[118:121], v[142:145], v[74:77]
	ds_read_b128 v[54:57], v158 offset:4128
	global_load_lds_dwordx4 v160, s[6:7] offset:0
	v_mfma_f32_16x16x32_bf16 v[70:73], v[118:121], v[146:149], v[70:73]
	ds_read_b128 v[62:65], v158 offset:6176
	global_load_lds_dwordx4 v161, s[6:7] offset:1024
	v_mfma_f32_16x16x32_bf16 v[66:69], v[118:121], v[150:153], v[66:69]
	ds_read_b128 v[38:41], v100 offset:4128
	global_load_lds_dwordx4 v162, s[6:7] offset:2048
	v_mfma_f32_16x16x32_bf16 v[58:61], v[118:121], v[154:157], v[58:61]
	ds_read_b128 v[42:45], v100 offset:6176
	global_load_lds_dwordx4 v163, s[6:7] offset:3072
	v_mfma_f32_16x16x32_bf16 v[26:29], v[122:125], v[142:145], v[26:29]
	v_mfma_f32_16x16x32_bf16 v[22:25], v[122:125], v[146:149], v[22:25]
	v_mfma_f32_16x16x32_bf16 v[18:21], v[122:125], v[150:153], v[18:21]
	v_mfma_f32_16x16x32_bf16 v[14:17], v[122:125], v[154:157], v[14:17]
	v_mfma_f32_16x16x32_bf16 v[10:13], v[138:141], v[142:145], v[10:13]
	v_mfma_f32_16x16x32_bf16 v[6:9], v[138:141], v[146:149], v[6:9]
	v_mfma_f32_16x16x32_bf16 v[2:5], v[138:141], v[150:153], v[2:5]
	v_mfma_f32_16x16x32_bf16 v[86:89], v[138:141], v[154:157], v[86:89]
	s_add_u32 s98, s98, 1
	s_and_b32 s98, s98, 15
	s_cmp_eq_u32 s98, 0
	s_cselect_b32 s99, 0x800, 0
	s_add_u32 s4, s4, 0x80
	s_addc_u32 s5, s5, 0
	s_sub_u32 s4, s4, s99
	s_subb_u32 s5, s5, 0
	s_add_u32 s6, s6, 0x80
	s_addc_u32 s7, s7, 0
	s_sub_u32 s6, s6, s99
	s_subb_u32 s7, s7, 0
	s_waitcnt lgkmcnt(0)
	v_mfma_f32_16x16x32_bf16 v[94:97], v[30:33], v[46:49], v[94:97]
	ds_read_b128 v[114:117], v111 offset:32
	v_mfma_f32_16x16x32_bf16 v[90:93], v[30:33], v[50:53], v[90:93]
	ds_read_b128 v[142:145], v159 offset:32
	v_mfma_f32_16x16x32_bf16 v[82:85], v[30:33], v[54:57], v[82:85]
	ds_read_b128 v[146:149], v159 offset:2080
	v_mfma_f32_16x16x32_bf16 v[78:81], v[30:33], v[62:65], v[78:81]
	ds_read_b128 v[118:121], v111 offset:2080
	v_mfma_f32_16x16x32_bf16 v[74:77], v[34:37], v[46:49], v[74:77]
	ds_read_b128 v[150:153], v159 offset:4128
	v_mfma_f32_16x16x32_bf16 v[70:73], v[34:37], v[50:53], v[70:73]
	ds_read_b128 v[154:157], v159 offset:6176
	v_mfma_f32_16x16x32_bf16 v[66:69], v[34:37], v[54:57], v[66:69]
	ds_read_b128 v[122:125], v111 offset:4128
	v_mfma_f32_16x16x32_bf16 v[58:61], v[34:37], v[62:65], v[58:61]
	ds_read_b128 v[138:141], v111 offset:6176
	v_mfma_f32_16x16x32_bf16 v[26:29], v[38:41], v[46:49], v[26:29]
	v_mfma_f32_16x16x32_bf16 v[22:25], v[38:41], v[50:53], v[22:25]
	v_mfma_f32_16x16x32_bf16 v[18:21], v[38:41], v[54:57], v[18:21]
	v_mfma_f32_16x16x32_bf16 v[14:17], v[38:41], v[62:65], v[14:17]
	v_mfma_f32_16x16x32_bf16 v[10:13], v[42:45], v[46:49], v[10:13]
	v_mfma_f32_16x16x32_bf16 v[6:9], v[42:45], v[50:53], v[6:9]
	v_mfma_f32_16x16x32_bf16 v[2:5], v[42:45], v[54:57], v[2:5]
	v_mfma_f32_16x16x32_bf16 v[86:89], v[42:45], v[62:65], v[86:89]
	s_waitcnt lgkmcnt(0)
	s_waitcnt vmcnt(0)
	s_barrier
	v_mfma_f32_16x16x32_bf16 v[94:97], v[114:117], v[142:145], v[94:97]
	ds_read_b128 v[30:33], v100 offset:32800
	v_mfma_f32_16x16x32_bf16 v[90:93], v[114:117], v[146:149], v[90:93]
	ds_read_b128 v[46:49], v158 offset:32800
	v_mfma_f32_16x16x32_bf16 v[82:85], v[114:117], v[150:153], v[82:85]
	ds_read_b128 v[50:53], v158 offset:34848
	v_mfma_f32_16x16x32_bf16 v[78:81], v[114:117], v[154:157], v[78:81]
	ds_read_b128 v[34:37], v100 offset:34848
	v_mfma_f32_16x16x32_bf16 v[74:77], v[118:121], v[142:145], v[74:77]
	ds_read_b128 v[54:57], v158 offset:36896
	v_mfma_f32_16x16x32_bf16 v[70:73], v[118:121], v[146:149], v[70:73]
	ds_read_b128 v[62:65], v158 offset:38944
	v_mfma_f32_16x16x32_bf16 v[66:69], v[118:121], v[150:153], v[66:69]
	ds_read_b128 v[38:41], v100 offset:36896
	v_mfma_f32_16x16x32_bf16 v[58:61], v[118:121], v[154:157], v[58:61]
	ds_read_b128 v[42:45], v100 offset:38944
	v_mfma_f32_16x16x32_bf16 v[26:29], v[122:125], v[142:145], v[26:29]
	v_mfma_f32_16x16x32_bf16 v[22:25], v[122:125], v[146:149], v[22:25]
	v_mfma_f32_16x16x32_bf16 v[18:21], v[122:125], v[150:153], v[18:21]
	v_mfma_f32_16x16x32_bf16 v[14:17], v[122:125], v[154:157], v[14:17]
	v_mfma_f32_16x16x32_bf16 v[10:13], v[138:141], v[142:145], v[10:13]
	v_mfma_f32_16x16x32_bf16 v[6:9], v[138:141], v[146:149], v[6:9]
	v_mfma_f32_16x16x32_bf16 v[2:5], v[138:141], v[150:153], v[2:5]
	v_mfma_f32_16x16x32_bf16 v[86:89], v[138:141], v[154:157], v[86:89]
	s_waitcnt lgkmcnt(0)
	v_mfma_f32_16x16x32_bf16 v[94:97], v[30:33], v[46:49], v[94:97]
	ds_read_b128 v[114:117], v111 offset:32800
	v_mfma_f32_16x16x32_bf16 v[90:93], v[30:33], v[50:53], v[90:93]
	ds_read_b128 v[142:145], v159 offset:32800
	v_mfma_f32_16x16x32_bf16 v[82:85], v[30:33], v[54:57], v[82:85]
	ds_read_b128 v[146:149], v159 offset:34848
	v_mfma_f32_16x16x32_bf16 v[78:81], v[30:33], v[62:65], v[78:81]
	ds_read_b128 v[118:121], v111 offset:34848
	v_mfma_f32_16x16x32_bf16 v[74:77], v[34:37], v[46:49], v[74:77]
	ds_read_b128 v[150:153], v159 offset:36896
	v_mfma_f32_16x16x32_bf16 v[70:73], v[34:37], v[50:53], v[70:73]
	ds_read_b128 v[154:157], v159 offset:38944
	v_mfma_f32_16x16x32_bf16 v[66:69], v[34:37], v[54:57], v[66:69]
	ds_read_b128 v[122:125], v111 offset:36896
	v_mfma_f32_16x16x32_bf16 v[58:61], v[34:37], v[62:65], v[58:61]
	ds_read_b128 v[138:141], v111 offset:38944
	v_mfma_f32_16x16x32_bf16 v[26:29], v[38:41], v[46:49], v[26:29]
	v_mfma_f32_16x16x32_bf16 v[22:25], v[38:41], v[50:53], v[22:25]
	v_mfma_f32_16x16x32_bf16 v[18:21], v[38:41], v[54:57], v[18:21]
	v_mfma_f32_16x16x32_bf16 v[14:17], v[38:41], v[62:65], v[14:17]
	v_mfma_f32_16x16x32_bf16 v[10:13], v[42:45], v[46:49], v[10:13]
	v_mfma_f32_16x16x32_bf16 v[6:9], v[42:45], v[50:53], v[6:9]
	v_mfma_f32_16x16x32_bf16 v[2:5], v[42:45], v[54:57], v[2:5]
	v_mfma_f32_16x16x32_bf16 v[86:89], v[42:45], v[62:65], v[86:89]
	s_waitcnt lgkmcnt(0)
	v_mfma_f32_16x16x32_bf16 v[94:97], v[114:117], v[142:145], v[94:97]
	v_mfma_f32_16x16x32_bf16 v[90:93], v[114:117], v[146:149], v[90:93]
	v_mfma_f32_16x16x32_bf16 v[82:85], v[114:117], v[150:153], v[82:85]
	v_mfma_f32_16x16x32_bf16 v[78:81], v[114:117], v[154:157], v[78:81]
	v_mfma_f32_16x16x32_bf16 v[74:77], v[118:121], v[142:145], v[74:77]
	v_mfma_f32_16x16x32_bf16 v[70:73], v[118:121], v[146:149], v[70:73]
	v_mfma_f32_16x16x32_bf16 v[66:69], v[118:121], v[150:153], v[66:69]
	v_mfma_f32_16x16x32_bf16 v[58:61], v[118:121], v[154:157], v[58:61]
	v_mfma_f32_16x16x32_bf16 v[26:29], v[122:125], v[142:145], v[26:29]
	v_mfma_f32_16x16x32_bf16 v[22:25], v[122:125], v[146:149], v[22:25]
	v_mfma_f32_16x16x32_bf16 v[18:21], v[122:125], v[150:153], v[18:21]
	v_mfma_f32_16x16x32_bf16 v[14:17], v[122:125], v[154:157], v[14:17]
	v_mfma_f32_16x16x32_bf16 v[10:13], v[138:141], v[142:145], v[10:13]
	v_mfma_f32_16x16x32_bf16 v[6:9], v[138:141], v[146:149], v[6:9]
	v_mfma_f32_16x16x32_bf16 v[2:5], v[138:141], v[150:153], v[2:5]
	v_mfma_f32_16x16x32_bf16 v[86:89], v[138:141], v[154:157], v[86:89]
	s_setprio 0
	v_lshrrev_b32_e32 v117, 4, v0
	v_and_b32_e32 v117, 15, v117
	v_and_b32_e32 v118, 15, v0
	v_lshlrev_b32_e32 v118, 4, v118
	v_lshl_or_b32 v117, v117, 12, v118
	s_lshl_b32 s100, s8, 12
	s_lshl_b32 s98, s73, 8
	s_add_u32 s100, s100, s98
	s_add_u32 s98, s42, s100
	s_addc_u32 s99, s43, 0
	s_add_u32 s98, s98, 0x12d24000
	s_addc_u32 s99, s99, 0
	global_load_dwordx4 v[148:151], v117, s[98:99]
	global_load_dwordx4 v[152:155], v117, s[98:99] offset:2048
	s_add_u32 s98, s98, 0x10000
	s_addc_u32 s99, s99, 0
	global_load_dwordx4 v[156:159], v117, s[98:99]
	global_load_dwordx4 v[160:163], v117, s[98:99] offset:2048
	s_add_u32 s98, s98, 0x10000
	s_addc_u32 s99, s99, 0
	global_load_dwordx4 v[164:167], v117, s[98:99]
	global_load_dwordx4 v[168:171], v117, s[98:99] offset:2048
	s_add_u32 s98, s98, 0x10000
	s_addc_u32 s99, s99, 0
	global_load_dwordx4 v[172:175], v117, s[98:99]
	global_load_dwordx4 v[176:179], v117, s[98:99] offset:2048
	s_add_u32 s98, s98, 0x10000
	s_addc_u32 s99, s99, 0
	global_load_dwordx4 v[180:183], v117, s[98:99]
	global_load_dwordx4 v[184:187], v117, s[98:99] offset:2048
	s_add_u32 s98, s98, 0x10000
	s_addc_u32 s99, s99, 0
	global_load_dwordx4 v[188:191], v117, s[98:99]
	global_load_dwordx4 v[192:195], v117, s[98:99] offset:2048
	s_add_u32 s98, s98, 0x10000
	s_addc_u32 s99, s99, 0
	global_load_dwordx4 v[196:199], v117, s[98:99]
	global_load_dwordx4 v[34:37], v117, s[98:99] offset:2048
	s_add_u32 s98, s98, 0x10000
	s_addc_u32 s99, s99, 0
	global_load_dwordx4 v[38:41], v117, s[98:99]
	global_load_dwordx4 v[52:55], v117, s[98:99] offset:2048
	s_mul_i32 s4, s68, s62
	s_add_i32 s4, s4, s67
	s_and_b32 s4, s4, 0xff
	v_lshl_or_b32 v30, s4, 10, v132
	s_mul_hi_u32 s4, s4, 0x15555556
	s_mulk_i32 s4, 0xd000
	v_add_u32_e32 v30, s4, v30
	s_lshl_b32 s36, s73, 8
	v_add_u32_e32 v138, 0x400, v129
	v_add_u32_e32 v139, 0x2000, v129
	v_add_u32_e32 v140, 0x2400, v129
	v_add_u32_e32 v141, 0x4000, v129
	v_add_u32_e32 v142, 0x4400, v129
	v_add_u32_e32 v143, 0x4800, v129
	v_add_u32_e32 v144, 0x6000, v129
	v_add_u32_e32 v145, 0x6400, v129
	v_add_u32_e32 v146, 0x6800, v129
	v_lshl_add_u64 v[114:115], v[102:103], 0, s[36:37]
	v_cmp_gt_u32_e32 vcc, s66, v30
	s_barrier
	ds_write2_b32 v129, v94, v90 offset1:16
	ds_write2_b32 v129, v95, v91 offset0:132 offset1:148
	ds_write2_b32 v138, v96, v92 offset0:8 offset1:24
	ds_write2_b32 v138, v97, v93 offset0:140 offset1:156
	ds_write2_b32 v129, v82, v78 offset0:32 offset1:48
	ds_write2_b32 v129, v83, v79 offset0:164 offset1:180
	ds_write2_b32 v138, v84, v80 offset0:40 offset1:56
	ds_write2_b32 v138, v85, v81 offset0:172 offset1:188
	ds_write2_b32 v139, v74, v70 offset0:64 offset1:80
	ds_write2_b32 v139, v75, v71 offset0:196 offset1:212
	ds_write2_b32 v140, v76, v72 offset0:72 offset1:88
	ds_write2_b32 v140, v77, v73 offset0:204 offset1:220
	ds_write2_b32 v139, v66, v58 offset0:96 offset1:112
	ds_write2_b32 v139, v67, v59 offset0:228 offset1:244
	ds_write2_b32 v140, v68, v60 offset0:104 offset1:120
	ds_write2_b32 v140, v69, v61 offset0:236 offset1:252
	ds_write2_b32 v141, v26, v22 offset0:128 offset1:144
	ds_write2_b32 v142, v27, v23 offset0:4 offset1:20
	ds_write2_b32 v142, v28, v24 offset0:136 offset1:152
	ds_write2_b32 v143, v29, v25 offset0:12 offset1:28
	ds_write2_b32 v141, v18, v14 offset0:160 offset1:176
	ds_write2_b32 v142, v19, v15 offset0:36 offset1:52
	ds_write2_b32 v142, v20, v16 offset0:168 offset1:184
	ds_write2_b32 v143, v21, v17 offset0:44 offset1:60
	ds_write2_b32 v144, v10, v6 offset0:192 offset1:208
	ds_write2_b32 v145, v11, v7 offset0:68 offset1:84
	ds_write2_b32 v145, v12, v8 offset0:200 offset1:216
	ds_write2_b32 v146, v13, v9 offset0:76 offset1:92
	ds_write2_b32 v144, v2, v86 offset0:224 offset1:240
	ds_write2_b32 v145, v3, v87 offset0:100 offset1:116
	ds_write2_b32 v145, v4, v88 offset0:232 offset1:248
	ds_write2_b32 v146, v5, v89 offset0:108 offset1:124
	s_waitcnt lgkmcnt(0)
	s_barrier
	v_lshrrev_b32_e32 v50, 4, v0
	v_and_b32_e32 v50, 15, v50
	v_mul_u32_u24_e32 v50, 0x210, v50
	v_and_b32_e32 v2, 15, v0
	v_lshl_add_u32 v50, v2, 5, v50
	ds_read_b128 v[42:45], v50 offset:32
	ds_read_b128 v[46:49], v50 offset:48
	s_waitcnt vmcnt(14)
	v_lshlrev_b32_e32 v2, 16, v148
	v_lshlrev_b32_e32 v3, 16, v152
	v_div_scale_f32 v4, s[4:5], v3, v3, v2
	v_rcp_f32_e32 v5, v4
	s_nop 0
	v_fma_f32 v6, -v4, v5, 1.0
	v_fmac_f32_e32 v5, v6, v5
	v_div_scale_f32 v7, vcc, v2, v3, v2
	v_mul_f32_e32 v8, v7, v5
	v_fma_f32 v6, -v4, v8, v7
	v_fmac_f32_e32 v8, v6, v5
	v_fma_f32 v4, -v4, v8, v7
	v_div_fmas_f32 v4, v4, v5, v8
	v_div_fixup_f32 v10, v4, v3, v2
	v_and_b32_e32 v2, 0xffff0000, v148
	v_and_b32_e32 v3, 0xffff0000, v152
	v_div_scale_f32 v4, s[4:5], v3, v3, v2
	v_rcp_f32_e32 v5, v4
	s_nop 0
	v_fma_f32 v6, -v4, v5, 1.0
	v_fmac_f32_e32 v5, v6, v5
	v_div_scale_f32 v7, vcc, v2, v3, v2
	v_mul_f32_e32 v8, v7, v5
	v_fma_f32 v6, -v4, v8, v7
	v_fmac_f32_e32 v8, v6, v5
	v_fma_f32 v4, -v4, v8, v7
	v_div_fmas_f32 v4, v4, v5, v8
	v_div_fixup_f32 v11, v4, v3, v2
	v_lshlrev_b32_e32 v2, 16, v149
	v_lshlrev_b32_e32 v3, 16, v153
	v_div_scale_f32 v4, s[4:5], v3, v3, v2
	v_rcp_f32_e32 v5, v4
	s_nop 0
	v_fma_f32 v6, -v4, v5, 1.0
	v_fmac_f32_e32 v5, v6, v5
	v_div_scale_f32 v7, vcc, v2, v3, v2
	v_mul_f32_e32 v8, v7, v5
	v_fma_f32 v6, -v4, v8, v7
	v_fmac_f32_e32 v8, v6, v5
	v_fma_f32 v4, -v4, v8, v7
	v_div_fmas_f32 v4, v4, v5, v8
	v_div_fixup_f32 v12, v4, v3, v2
	v_and_b32_e32 v2, 0xffff0000, v149
	v_and_b32_e32 v3, 0xffff0000, v153
	v_div_scale_f32 v4, s[4:5], v3, v3, v2
	v_rcp_f32_e32 v5, v4
	s_nop 0
	v_fma_f32 v6, -v4, v5, 1.0
	v_fmac_f32_e32 v5, v6, v5
	v_div_scale_f32 v7, vcc, v2, v3, v2
	v_mul_f32_e32 v8, v7, v5
	v_fma_f32 v6, -v4, v8, v7
	v_fmac_f32_e32 v8, v6, v5
	v_fma_f32 v4, -v4, v8, v7
	v_div_fmas_f32 v4, v4, v5, v8
	v_div_fixup_f32 v13, v4, v3, v2
	v_lshlrev_b32_e32 v2, 16, v150
	v_lshlrev_b32_e32 v3, 16, v154
	v_div_scale_f32 v4, s[4:5], v3, v3, v2
	v_rcp_f32_e32 v5, v4
	s_nop 0
	v_fma_f32 v6, -v4, v5, 1.0
	v_fmac_f32_e32 v5, v6, v5
	v_div_scale_f32 v7, vcc, v2, v3, v2
	v_mul_f32_e32 v8, v7, v5
	v_fma_f32 v6, -v4, v8, v7
	v_fmac_f32_e32 v8, v6, v5
	v_fma_f32 v4, -v4, v8, v7
	v_div_fmas_f32 v4, v4, v5, v8
	v_div_fixup_f32 v14, v4, v3, v2
	v_and_b32_e32 v2, 0xffff0000, v150
	v_and_b32_e32 v3, 0xffff0000, v154
	v_div_scale_f32 v4, s[4:5], v3, v3, v2
	v_rcp_f32_e32 v5, v4
	s_nop 0
	v_fma_f32 v6, -v4, v5, 1.0
	v_fmac_f32_e32 v5, v6, v5
	v_div_scale_f32 v7, vcc, v2, v3, v2
	v_mul_f32_e32 v8, v7, v5
	v_fma_f32 v6, -v4, v8, v7
	v_fmac_f32_e32 v8, v6, v5
	v_fma_f32 v4, -v4, v8, v7
	v_div_fmas_f32 v4, v4, v5, v8
	v_div_fixup_f32 v15, v4, v3, v2
	v_lshlrev_b32_e32 v2, 16, v151
	v_lshlrev_b32_e32 v3, 16, v155
	v_div_scale_f32 v4, s[4:5], v3, v3, v2
	v_rcp_f32_e32 v5, v4
	s_nop 0
	v_fma_f32 v6, -v4, v5, 1.0
	v_fmac_f32_e32 v5, v6, v5
	v_div_scale_f32 v7, vcc, v2, v3, v2
	v_mul_f32_e32 v8, v7, v5
	v_fma_f32 v6, -v4, v8, v7
	v_fmac_f32_e32 v8, v6, v5
	v_fma_f32 v4, -v4, v8, v7
	v_div_fmas_f32 v4, v4, v5, v8
	v_div_fixup_f32 v16, v4, v3, v2
	v_and_b32_e32 v2, 0xffff0000, v151
	v_and_b32_e32 v3, 0xffff0000, v155
	v_div_scale_f32 v4, s[4:5], v3, v3, v2
	v_rcp_f32_e32 v5, v4
	s_nop 0
	v_fma_f32 v6, -v4, v5, 1.0
	v_fmac_f32_e32 v5, v6, v5
	v_div_scale_f32 v7, vcc, v2, v3, v2
	v_mul_f32_e32 v8, v7, v5
	v_fma_f32 v6, -v4, v8, v7
	v_fmac_f32_e32 v8, v6, v5
	v_fma_f32 v4, -v4, v8, v7
	v_div_fmas_f32 v4, v4, v5, v8
	v_div_fixup_f32 v17, v4, v3, v2
	s_waitcnt lgkmcnt(0)
	v_pk_mul_f32 v[42:43], v[42:43], v[10:11]
	v_pk_mul_f32 v[44:45], v[44:45], v[12:13]
	v_pk_mul_f32 v[46:47], v[46:47], v[14:15]
	v_pk_mul_f32 v[48:49], v[48:49], v[16:17]
	ds_write_b128 v50, v[42:45] offset:32
	ds_write_b128 v50, v[46:49] offset:48
	ds_read_b128 v[42:45], v50 offset:8480
	ds_read_b128 v[46:49], v50 offset:8496
	s_waitcnt vmcnt(12)
	v_lshlrev_b32_e32 v2, 16, v156
	v_lshlrev_b32_e32 v3, 16, v160
	v_div_scale_f32 v4, s[4:5], v3, v3, v2
	v_rcp_f32_e32 v5, v4
	s_nop 0
	v_fma_f32 v6, -v4, v5, 1.0
	v_fmac_f32_e32 v5, v6, v5
	v_div_scale_f32 v7, vcc, v2, v3, v2
	v_mul_f32_e32 v8, v7, v5
	v_fma_f32 v6, -v4, v8, v7
	v_fmac_f32_e32 v8, v6, v5
	v_fma_f32 v4, -v4, v8, v7
	v_div_fmas_f32 v4, v4, v5, v8
	v_div_fixup_f32 v10, v4, v3, v2
	v_and_b32_e32 v2, 0xffff0000, v156
	v_and_b32_e32 v3, 0xffff0000, v160
	v_div_scale_f32 v4, s[4:5], v3, v3, v2
	v_rcp_f32_e32 v5, v4
	s_nop 0
	v_fma_f32 v6, -v4, v5, 1.0
	v_fmac_f32_e32 v5, v6, v5
	v_div_scale_f32 v7, vcc, v2, v3, v2
	v_mul_f32_e32 v8, v7, v5
	v_fma_f32 v6, -v4, v8, v7
	v_fmac_f32_e32 v8, v6, v5
	v_fma_f32 v4, -v4, v8, v7
	v_div_fmas_f32 v4, v4, v5, v8
	v_div_fixup_f32 v11, v4, v3, v2
	v_lshlrev_b32_e32 v2, 16, v157
	v_lshlrev_b32_e32 v3, 16, v161
	v_div_scale_f32 v4, s[4:5], v3, v3, v2
	v_rcp_f32_e32 v5, v4
	s_nop 0
	v_fma_f32 v6, -v4, v5, 1.0
	v_fmac_f32_e32 v5, v6, v5
	v_div_scale_f32 v7, vcc, v2, v3, v2
	v_mul_f32_e32 v8, v7, v5
	v_fma_f32 v6, -v4, v8, v7
	v_fmac_f32_e32 v8, v6, v5
	v_fma_f32 v4, -v4, v8, v7
	v_div_fmas_f32 v4, v4, v5, v8
	v_div_fixup_f32 v12, v4, v3, v2
	v_and_b32_e32 v2, 0xffff0000, v157
	v_and_b32_e32 v3, 0xffff0000, v161
	v_div_scale_f32 v4, s[4:5], v3, v3, v2
	v_rcp_f32_e32 v5, v4
	s_nop 0
	v_fma_f32 v6, -v4, v5, 1.0
	v_fmac_f32_e32 v5, v6, v5
	v_div_scale_f32 v7, vcc, v2, v3, v2
	v_mul_f32_e32 v8, v7, v5
	v_fma_f32 v6, -v4, v8, v7
	v_fmac_f32_e32 v8, v6, v5
	v_fma_f32 v4, -v4, v8, v7
	v_div_fmas_f32 v4, v4, v5, v8
	v_div_fixup_f32 v13, v4, v3, v2
	v_lshlrev_b32_e32 v2, 16, v158
	v_lshlrev_b32_e32 v3, 16, v162
	v_div_scale_f32 v4, s[4:5], v3, v3, v2
	v_rcp_f32_e32 v5, v4
	s_nop 0
	v_fma_f32 v6, -v4, v5, 1.0
	v_fmac_f32_e32 v5, v6, v5
	v_div_scale_f32 v7, vcc, v2, v3, v2
	v_mul_f32_e32 v8, v7, v5
	v_fma_f32 v6, -v4, v8, v7
	v_fmac_f32_e32 v8, v6, v5
	v_fma_f32 v4, -v4, v8, v7
	v_div_fmas_f32 v4, v4, v5, v8
	v_div_fixup_f32 v14, v4, v3, v2
	v_and_b32_e32 v2, 0xffff0000, v158
	v_and_b32_e32 v3, 0xffff0000, v162
	v_div_scale_f32 v4, s[4:5], v3, v3, v2
	v_rcp_f32_e32 v5, v4
	s_nop 0
	v_fma_f32 v6, -v4, v5, 1.0
	v_fmac_f32_e32 v5, v6, v5
	v_div_scale_f32 v7, vcc, v2, v3, v2
	v_mul_f32_e32 v8, v7, v5
	v_fma_f32 v6, -v4, v8, v7
	v_fmac_f32_e32 v8, v6, v5
	v_fma_f32 v4, -v4, v8, v7
	v_div_fmas_f32 v4, v4, v5, v8
	v_div_fixup_f32 v15, v4, v3, v2
	v_lshlrev_b32_e32 v2, 16, v159
	v_lshlrev_b32_e32 v3, 16, v163
	v_div_scale_f32 v4, s[4:5], v3, v3, v2
	v_rcp_f32_e32 v5, v4
	s_nop 0
	v_fma_f32 v6, -v4, v5, 1.0
	v_fmac_f32_e32 v5, v6, v5
	v_div_scale_f32 v7, vcc, v2, v3, v2
	v_mul_f32_e32 v8, v7, v5
	v_fma_f32 v6, -v4, v8, v7
	v_fmac_f32_e32 v8, v6, v5
	v_fma_f32 v4, -v4, v8, v7
	v_div_fmas_f32 v4, v4, v5, v8
	v_div_fixup_f32 v16, v4, v3, v2
	v_and_b32_e32 v2, 0xffff0000, v159
	v_and_b32_e32 v3, 0xffff0000, v163
	v_div_scale_f32 v4, s[4:5], v3, v3, v2
	v_rcp_f32_e32 v5, v4
	s_nop 0
	v_fma_f32 v6, -v4, v5, 1.0
	v_fmac_f32_e32 v5, v6, v5
	v_div_scale_f32 v7, vcc, v2, v3, v2
	v_mul_f32_e32 v8, v7, v5
	v_fma_f32 v6, -v4, v8, v7
	v_fmac_f32_e32 v8, v6, v5
	v_fma_f32 v4, -v4, v8, v7
	v_div_fmas_f32 v4, v4, v5, v8
	v_div_fixup_f32 v17, v4, v3, v2
	s_waitcnt lgkmcnt(0)
	v_pk_mul_f32 v[42:43], v[42:43], v[10:11]
	v_pk_mul_f32 v[44:45], v[44:45], v[12:13]
	v_pk_mul_f32 v[46:47], v[46:47], v[14:15]
	v_pk_mul_f32 v[48:49], v[48:49], v[16:17]
	ds_write_b128 v50, v[42:45] offset:8480
	ds_write_b128 v50, v[46:49] offset:8496
	ds_read_b128 v[42:45], v50 offset:16928
	ds_read_b128 v[46:49], v50 offset:16944
	s_waitcnt vmcnt(10)
	v_lshlrev_b32_e32 v2, 16, v164
	v_lshlrev_b32_e32 v3, 16, v168
	v_div_scale_f32 v4, s[4:5], v3, v3, v2
	v_rcp_f32_e32 v5, v4
	s_nop 0
	v_fma_f32 v6, -v4, v5, 1.0
	v_fmac_f32_e32 v5, v6, v5
	v_div_scale_f32 v7, vcc, v2, v3, v2
	v_mul_f32_e32 v8, v7, v5
	v_fma_f32 v6, -v4, v8, v7
	v_fmac_f32_e32 v8, v6, v5
	v_fma_f32 v4, -v4, v8, v7
	v_div_fmas_f32 v4, v4, v5, v8
	v_div_fixup_f32 v10, v4, v3, v2
	v_and_b32_e32 v2, 0xffff0000, v164
	v_and_b32_e32 v3, 0xffff0000, v168
	v_div_scale_f32 v4, s[4:5], v3, v3, v2
	v_rcp_f32_e32 v5, v4
	s_nop 0
	v_fma_f32 v6, -v4, v5, 1.0
	v_fmac_f32_e32 v5, v6, v5
	v_div_scale_f32 v7, vcc, v2, v3, v2
	v_mul_f32_e32 v8, v7, v5
	v_fma_f32 v6, -v4, v8, v7
	v_fmac_f32_e32 v8, v6, v5
	v_fma_f32 v4, -v4, v8, v7
	v_div_fmas_f32 v4, v4, v5, v8
	v_div_fixup_f32 v11, v4, v3, v2
	v_lshlrev_b32_e32 v2, 16, v165
	v_lshlrev_b32_e32 v3, 16, v169
	v_div_scale_f32 v4, s[4:5], v3, v3, v2
	v_rcp_f32_e32 v5, v4
	s_nop 0
	v_fma_f32 v6, -v4, v5, 1.0
	v_fmac_f32_e32 v5, v6, v5
	v_div_scale_f32 v7, vcc, v2, v3, v2
	v_mul_f32_e32 v8, v7, v5
	v_fma_f32 v6, -v4, v8, v7
	v_fmac_f32_e32 v8, v6, v5
	v_fma_f32 v4, -v4, v8, v7
	v_div_fmas_f32 v4, v4, v5, v8
	v_div_fixup_f32 v12, v4, v3, v2
	v_and_b32_e32 v2, 0xffff0000, v165
	v_and_b32_e32 v3, 0xffff0000, v169
	v_div_scale_f32 v4, s[4:5], v3, v3, v2
	v_rcp_f32_e32 v5, v4
	s_nop 0
	v_fma_f32 v6, -v4, v5, 1.0
	v_fmac_f32_e32 v5, v6, v5
	v_div_scale_f32 v7, vcc, v2, v3, v2
	v_mul_f32_e32 v8, v7, v5
	v_fma_f32 v6, -v4, v8, v7
	v_fmac_f32_e32 v8, v6, v5
	v_fma_f32 v4, -v4, v8, v7
	v_div_fmas_f32 v4, v4, v5, v8
	v_div_fixup_f32 v13, v4, v3, v2
	v_lshlrev_b32_e32 v2, 16, v166
	v_lshlrev_b32_e32 v3, 16, v170
	v_div_scale_f32 v4, s[4:5], v3, v3, v2
	v_rcp_f32_e32 v5, v4
	s_nop 0
	v_fma_f32 v6, -v4, v5, 1.0
	v_fmac_f32_e32 v5, v6, v5
	v_div_scale_f32 v7, vcc, v2, v3, v2
	v_mul_f32_e32 v8, v7, v5
	v_fma_f32 v6, -v4, v8, v7
	v_fmac_f32_e32 v8, v6, v5
	v_fma_f32 v4, -v4, v8, v7
	v_div_fmas_f32 v4, v4, v5, v8
	v_div_fixup_f32 v14, v4, v3, v2
	v_and_b32_e32 v2, 0xffff0000, v166
	v_and_b32_e32 v3, 0xffff0000, v170
	v_div_scale_f32 v4, s[4:5], v3, v3, v2
	v_rcp_f32_e32 v5, v4
	s_nop 0
	v_fma_f32 v6, -v4, v5, 1.0
	v_fmac_f32_e32 v5, v6, v5
	v_div_scale_f32 v7, vcc, v2, v3, v2
	v_mul_f32_e32 v8, v7, v5
	v_fma_f32 v6, -v4, v8, v7
	v_fmac_f32_e32 v8, v6, v5
	v_fma_f32 v4, -v4, v8, v7
	v_div_fmas_f32 v4, v4, v5, v8
	v_div_fixup_f32 v15, v4, v3, v2
	v_lshlrev_b32_e32 v2, 16, v167
	v_lshlrev_b32_e32 v3, 16, v171
	v_div_scale_f32 v4, s[4:5], v3, v3, v2
	v_rcp_f32_e32 v5, v4
	s_nop 0
	v_fma_f32 v6, -v4, v5, 1.0
	v_fmac_f32_e32 v5, v6, v5
	v_div_scale_f32 v7, vcc, v2, v3, v2
	v_mul_f32_e32 v8, v7, v5
	v_fma_f32 v6, -v4, v8, v7
	v_fmac_f32_e32 v8, v6, v5
	v_fma_f32 v4, -v4, v8, v7
	v_div_fmas_f32 v4, v4, v5, v8
	v_div_fixup_f32 v16, v4, v3, v2
	v_and_b32_e32 v2, 0xffff0000, v167
	v_and_b32_e32 v3, 0xffff0000, v171
	v_div_scale_f32 v4, s[4:5], v3, v3, v2
	v_rcp_f32_e32 v5, v4
	s_nop 0
	v_fma_f32 v6, -v4, v5, 1.0
	v_fmac_f32_e32 v5, v6, v5
	v_div_scale_f32 v7, vcc, v2, v3, v2
	v_mul_f32_e32 v8, v7, v5
	v_fma_f32 v6, -v4, v8, v7
	v_fmac_f32_e32 v8, v6, v5
	v_fma_f32 v4, -v4, v8, v7
	v_div_fmas_f32 v4, v4, v5, v8
	v_div_fixup_f32 v17, v4, v3, v2
	s_waitcnt lgkmcnt(0)
	v_pk_mul_f32 v[42:43], v[42:43], v[10:11]
	v_pk_mul_f32 v[44:45], v[44:45], v[12:13]
	v_pk_mul_f32 v[46:47], v[46:47], v[14:15]
	v_pk_mul_f32 v[48:49], v[48:49], v[16:17]
	ds_write_b128 v50, v[42:45] offset:16928
	ds_write_b128 v50, v[46:49] offset:16944
	ds_read_b128 v[42:45], v50 offset:25376
	ds_read_b128 v[46:49], v50 offset:25392
	s_waitcnt vmcnt(8)
	v_lshlrev_b32_e32 v2, 16, v172
	v_lshlrev_b32_e32 v3, 16, v176
	v_div_scale_f32 v4, s[4:5], v3, v3, v2
	v_rcp_f32_e32 v5, v4
	s_nop 0
	v_fma_f32 v6, -v4, v5, 1.0
	v_fmac_f32_e32 v5, v6, v5
	v_div_scale_f32 v7, vcc, v2, v3, v2
	v_mul_f32_e32 v8, v7, v5
	v_fma_f32 v6, -v4, v8, v7
	v_fmac_f32_e32 v8, v6, v5
	v_fma_f32 v4, -v4, v8, v7
	v_div_fmas_f32 v4, v4, v5, v8
	v_div_fixup_f32 v10, v4, v3, v2
	v_and_b32_e32 v2, 0xffff0000, v172
	v_and_b32_e32 v3, 0xffff0000, v176
	v_div_scale_f32 v4, s[4:5], v3, v3, v2
	v_rcp_f32_e32 v5, v4
	s_nop 0
	v_fma_f32 v6, -v4, v5, 1.0
	v_fmac_f32_e32 v5, v6, v5
	v_div_scale_f32 v7, vcc, v2, v3, v2
	v_mul_f32_e32 v8, v7, v5
	v_fma_f32 v6, -v4, v8, v7
	v_fmac_f32_e32 v8, v6, v5
	v_fma_f32 v4, -v4, v8, v7
	v_div_fmas_f32 v4, v4, v5, v8
	v_div_fixup_f32 v11, v4, v3, v2
	v_lshlrev_b32_e32 v2, 16, v173
	v_lshlrev_b32_e32 v3, 16, v177
	v_div_scale_f32 v4, s[4:5], v3, v3, v2
	v_rcp_f32_e32 v5, v4
	s_nop 0
	v_fma_f32 v6, -v4, v5, 1.0
	v_fmac_f32_e32 v5, v6, v5
	v_div_scale_f32 v7, vcc, v2, v3, v2
	v_mul_f32_e32 v8, v7, v5
	v_fma_f32 v6, -v4, v8, v7
	v_fmac_f32_e32 v8, v6, v5
	v_fma_f32 v4, -v4, v8, v7
	v_div_fmas_f32 v4, v4, v5, v8
	v_div_fixup_f32 v12, v4, v3, v2
	v_and_b32_e32 v2, 0xffff0000, v173
	v_and_b32_e32 v3, 0xffff0000, v177
	v_div_scale_f32 v4, s[4:5], v3, v3, v2
	v_rcp_f32_e32 v5, v4
	s_nop 0
	v_fma_f32 v6, -v4, v5, 1.0
	v_fmac_f32_e32 v5, v6, v5
	v_div_scale_f32 v7, vcc, v2, v3, v2
	v_mul_f32_e32 v8, v7, v5
	v_fma_f32 v6, -v4, v8, v7
	v_fmac_f32_e32 v8, v6, v5
	v_fma_f32 v4, -v4, v8, v7
	v_div_fmas_f32 v4, v4, v5, v8
	v_div_fixup_f32 v13, v4, v3, v2
	v_lshlrev_b32_e32 v2, 16, v174
	v_lshlrev_b32_e32 v3, 16, v178
	v_div_scale_f32 v4, s[4:5], v3, v3, v2
	v_rcp_f32_e32 v5, v4
	s_nop 0
	v_fma_f32 v6, -v4, v5, 1.0
	v_fmac_f32_e32 v5, v6, v5
	v_div_scale_f32 v7, vcc, v2, v3, v2
	v_mul_f32_e32 v8, v7, v5
	v_fma_f32 v6, -v4, v8, v7
	v_fmac_f32_e32 v8, v6, v5
	v_fma_f32 v4, -v4, v8, v7
	v_div_fmas_f32 v4, v4, v5, v8
	v_div_fixup_f32 v14, v4, v3, v2
	v_and_b32_e32 v2, 0xffff0000, v174
	v_and_b32_e32 v3, 0xffff0000, v178
	v_div_scale_f32 v4, s[4:5], v3, v3, v2
	v_rcp_f32_e32 v5, v4
	s_nop 0
	v_fma_f32 v6, -v4, v5, 1.0
	v_fmac_f32_e32 v5, v6, v5
	v_div_scale_f32 v7, vcc, v2, v3, v2
	v_mul_f32_e32 v8, v7, v5
	v_fma_f32 v6, -v4, v8, v7
	v_fmac_f32_e32 v8, v6, v5
	v_fma_f32 v4, -v4, v8, v7
	v_div_fmas_f32 v4, v4, v5, v8
	v_div_fixup_f32 v15, v4, v3, v2
	v_lshlrev_b32_e32 v2, 16, v175
	v_lshlrev_b32_e32 v3, 16, v179
	v_div_scale_f32 v4, s[4:5], v3, v3, v2
	v_rcp_f32_e32 v5, v4
	s_nop 0
	v_fma_f32 v6, -v4, v5, 1.0
	v_fmac_f32_e32 v5, v6, v5
	v_div_scale_f32 v7, vcc, v2, v3, v2
	v_mul_f32_e32 v8, v7, v5
	v_fma_f32 v6, -v4, v8, v7
	v_fmac_f32_e32 v8, v6, v5
	v_fma_f32 v4, -v4, v8, v7
	v_div_fmas_f32 v4, v4, v5, v8
	v_div_fixup_f32 v16, v4, v3, v2
	v_and_b32_e32 v2, 0xffff0000, v175
	v_and_b32_e32 v3, 0xffff0000, v179
	v_div_scale_f32 v4, s[4:5], v3, v3, v2
	v_rcp_f32_e32 v5, v4
	s_nop 0
	v_fma_f32 v6, -v4, v5, 1.0
	v_fmac_f32_e32 v5, v6, v5
	v_div_scale_f32 v7, vcc, v2, v3, v2
	v_mul_f32_e32 v8, v7, v5
	v_fma_f32 v6, -v4, v8, v7
	v_fmac_f32_e32 v8, v6, v5
	v_fma_f32 v4, -v4, v8, v7
	v_div_fmas_f32 v4, v4, v5, v8
	v_div_fixup_f32 v17, v4, v3, v2
	s_waitcnt lgkmcnt(0)
	v_pk_mul_f32 v[42:43], v[42:43], v[10:11]
	v_pk_mul_f32 v[44:45], v[44:45], v[12:13]
	v_pk_mul_f32 v[46:47], v[46:47], v[14:15]
	v_pk_mul_f32 v[48:49], v[48:49], v[16:17]
	ds_write_b128 v50, v[42:45] offset:25376
	ds_write_b128 v50, v[46:49] offset:25392
	ds_read_b128 v[42:45], v50 offset:33824
	ds_read_b128 v[46:49], v50 offset:33840
	s_waitcnt vmcnt(6)
	v_lshlrev_b32_e32 v2, 16, v180
	v_lshlrev_b32_e32 v3, 16, v184
	v_div_scale_f32 v4, s[4:5], v3, v3, v2
	v_rcp_f32_e32 v5, v4
	s_nop 0
	v_fma_f32 v6, -v4, v5, 1.0
	v_fmac_f32_e32 v5, v6, v5
	v_div_scale_f32 v7, vcc, v2, v3, v2
	v_mul_f32_e32 v8, v7, v5
	v_fma_f32 v6, -v4, v8, v7
	v_fmac_f32_e32 v8, v6, v5
	v_fma_f32 v4, -v4, v8, v7
	v_div_fmas_f32 v4, v4, v5, v8
	v_div_fixup_f32 v10, v4, v3, v2
	v_and_b32_e32 v2, 0xffff0000, v180
	v_and_b32_e32 v3, 0xffff0000, v184
	v_div_scale_f32 v4, s[4:5], v3, v3, v2
	v_rcp_f32_e32 v5, v4
	s_nop 0
	v_fma_f32 v6, -v4, v5, 1.0
	v_fmac_f32_e32 v5, v6, v5
	v_div_scale_f32 v7, vcc, v2, v3, v2
	v_mul_f32_e32 v8, v7, v5
	v_fma_f32 v6, -v4, v8, v7
	v_fmac_f32_e32 v8, v6, v5
	v_fma_f32 v4, -v4, v8, v7
	v_div_fmas_f32 v4, v4, v5, v8
	v_div_fixup_f32 v11, v4, v3, v2
	v_lshlrev_b32_e32 v2, 16, v181
	v_lshlrev_b32_e32 v3, 16, v185
	v_div_scale_f32 v4, s[4:5], v3, v3, v2
	v_rcp_f32_e32 v5, v4
	s_nop 0
	v_fma_f32 v6, -v4, v5, 1.0
	v_fmac_f32_e32 v5, v6, v5
	v_div_scale_f32 v7, vcc, v2, v3, v2
	v_mul_f32_e32 v8, v7, v5
	v_fma_f32 v6, -v4, v8, v7
	v_fmac_f32_e32 v8, v6, v5
	v_fma_f32 v4, -v4, v8, v7
	v_div_fmas_f32 v4, v4, v5, v8
	v_div_fixup_f32 v12, v4, v3, v2
	v_and_b32_e32 v2, 0xffff0000, v181
	v_and_b32_e32 v3, 0xffff0000, v185
	v_div_scale_f32 v4, s[4:5], v3, v3, v2
	v_rcp_f32_e32 v5, v4
	s_nop 0
	v_fma_f32 v6, -v4, v5, 1.0
	v_fmac_f32_e32 v5, v6, v5
	v_div_scale_f32 v7, vcc, v2, v3, v2
	v_mul_f32_e32 v8, v7, v5
	v_fma_f32 v6, -v4, v8, v7
	v_fmac_f32_e32 v8, v6, v5
	v_fma_f32 v4, -v4, v8, v7
	v_div_fmas_f32 v4, v4, v5, v8
	v_div_fixup_f32 v13, v4, v3, v2
	v_lshlrev_b32_e32 v2, 16, v182
	v_lshlrev_b32_e32 v3, 16, v186
	v_div_scale_f32 v4, s[4:5], v3, v3, v2
	v_rcp_f32_e32 v5, v4
	s_nop 0
	v_fma_f32 v6, -v4, v5, 1.0
	v_fmac_f32_e32 v5, v6, v5
	v_div_scale_f32 v7, vcc, v2, v3, v2
	v_mul_f32_e32 v8, v7, v5
	v_fma_f32 v6, -v4, v8, v7
	v_fmac_f32_e32 v8, v6, v5
	v_fma_f32 v4, -v4, v8, v7
	v_div_fmas_f32 v4, v4, v5, v8
	v_div_fixup_f32 v14, v4, v3, v2
	v_and_b32_e32 v2, 0xffff0000, v182
	v_and_b32_e32 v3, 0xffff0000, v186
	v_div_scale_f32 v4, s[4:5], v3, v3, v2
	v_rcp_f32_e32 v5, v4
	s_nop 0
	v_fma_f32 v6, -v4, v5, 1.0
	v_fmac_f32_e32 v5, v6, v5
	v_div_scale_f32 v7, vcc, v2, v3, v2
	v_mul_f32_e32 v8, v7, v5
	v_fma_f32 v6, -v4, v8, v7
	v_fmac_f32_e32 v8, v6, v5
	v_fma_f32 v4, -v4, v8, v7
	v_div_fmas_f32 v4, v4, v5, v8
	v_div_fixup_f32 v15, v4, v3, v2
	v_lshlrev_b32_e32 v2, 16, v183
	v_lshlrev_b32_e32 v3, 16, v187
	v_div_scale_f32 v4, s[4:5], v3, v3, v2
	v_rcp_f32_e32 v5, v4
	s_nop 0
	v_fma_f32 v6, -v4, v5, 1.0
	v_fmac_f32_e32 v5, v6, v5
	v_div_scale_f32 v7, vcc, v2, v3, v2
	v_mul_f32_e32 v8, v7, v5
	v_fma_f32 v6, -v4, v8, v7
	v_fmac_f32_e32 v8, v6, v5
	v_fma_f32 v4, -v4, v8, v7
	v_div_fmas_f32 v4, v4, v5, v8
	v_div_fixup_f32 v16, v4, v3, v2
	v_and_b32_e32 v2, 0xffff0000, v183
	v_and_b32_e32 v3, 0xffff0000, v187
	v_div_scale_f32 v4, s[4:5], v3, v3, v2
	v_rcp_f32_e32 v5, v4
	s_nop 0
	v_fma_f32 v6, -v4, v5, 1.0
	v_fmac_f32_e32 v5, v6, v5
	v_div_scale_f32 v7, vcc, v2, v3, v2
	v_mul_f32_e32 v8, v7, v5
	v_fma_f32 v6, -v4, v8, v7
	v_fmac_f32_e32 v8, v6, v5
	v_fma_f32 v4, -v4, v8, v7
	v_div_fmas_f32 v4, v4, v5, v8
	v_div_fixup_f32 v17, v4, v3, v2
	s_waitcnt lgkmcnt(0)
	v_pk_mul_f32 v[42:43], v[42:43], v[10:11]
	v_pk_mul_f32 v[44:45], v[44:45], v[12:13]
	v_pk_mul_f32 v[46:47], v[46:47], v[14:15]
	v_pk_mul_f32 v[48:49], v[48:49], v[16:17]
	ds_write_b128 v50, v[42:45] offset:33824
	ds_write_b128 v50, v[46:49] offset:33840
	ds_read_b128 v[42:45], v50 offset:42272
	ds_read_b128 v[46:49], v50 offset:42288
	s_waitcnt vmcnt(4)
	v_lshlrev_b32_e32 v2, 16, v188
	v_lshlrev_b32_e32 v3, 16, v192
	v_div_scale_f32 v4, s[4:5], v3, v3, v2
	v_rcp_f32_e32 v5, v4
	s_nop 0
	v_fma_f32 v6, -v4, v5, 1.0
	v_fmac_f32_e32 v5, v6, v5
	v_div_scale_f32 v7, vcc, v2, v3, v2
	v_mul_f32_e32 v8, v7, v5
	v_fma_f32 v6, -v4, v8, v7
	v_fmac_f32_e32 v8, v6, v5
	v_fma_f32 v4, -v4, v8, v7
	v_div_fmas_f32 v4, v4, v5, v8
	v_div_fixup_f32 v10, v4, v3, v2
	v_and_b32_e32 v2, 0xffff0000, v188
	v_and_b32_e32 v3, 0xffff0000, v192
	v_div_scale_f32 v4, s[4:5], v3, v3, v2
	v_rcp_f32_e32 v5, v4
	s_nop 0
	v_fma_f32 v6, -v4, v5, 1.0
	v_fmac_f32_e32 v5, v6, v5
	v_div_scale_f32 v7, vcc, v2, v3, v2
	v_mul_f32_e32 v8, v7, v5
	v_fma_f32 v6, -v4, v8, v7
	v_fmac_f32_e32 v8, v6, v5
	v_fma_f32 v4, -v4, v8, v7
	v_div_fmas_f32 v4, v4, v5, v8
	v_div_fixup_f32 v11, v4, v3, v2
	v_lshlrev_b32_e32 v2, 16, v189
	v_lshlrev_b32_e32 v3, 16, v193
	v_div_scale_f32 v4, s[4:5], v3, v3, v2
	v_rcp_f32_e32 v5, v4
	s_nop 0
	v_fma_f32 v6, -v4, v5, 1.0
	v_fmac_f32_e32 v5, v6, v5
	v_div_scale_f32 v7, vcc, v2, v3, v2
	v_mul_f32_e32 v8, v7, v5
	v_fma_f32 v6, -v4, v8, v7
	v_fmac_f32_e32 v8, v6, v5
	v_fma_f32 v4, -v4, v8, v7
	v_div_fmas_f32 v4, v4, v5, v8
	v_div_fixup_f32 v12, v4, v3, v2
	v_and_b32_e32 v2, 0xffff0000, v189
	v_and_b32_e32 v3, 0xffff0000, v193
	v_div_scale_f32 v4, s[4:5], v3, v3, v2
	v_rcp_f32_e32 v5, v4
	s_nop 0
	v_fma_f32 v6, -v4, v5, 1.0
	v_fmac_f32_e32 v5, v6, v5
	v_div_scale_f32 v7, vcc, v2, v3, v2
	v_mul_f32_e32 v8, v7, v5
	v_fma_f32 v6, -v4, v8, v7
	v_fmac_f32_e32 v8, v6, v5
	v_fma_f32 v4, -v4, v8, v7
	v_div_fmas_f32 v4, v4, v5, v8
	v_div_fixup_f32 v13, v4, v3, v2
	v_lshlrev_b32_e32 v2, 16, v190
	v_lshlrev_b32_e32 v3, 16, v194
	v_div_scale_f32 v4, s[4:5], v3, v3, v2
	v_rcp_f32_e32 v5, v4
	s_nop 0
	v_fma_f32 v6, -v4, v5, 1.0
	v_fmac_f32_e32 v5, v6, v5
	v_div_scale_f32 v7, vcc, v2, v3, v2
	v_mul_f32_e32 v8, v7, v5
	v_fma_f32 v6, -v4, v8, v7
	v_fmac_f32_e32 v8, v6, v5
	v_fma_f32 v4, -v4, v8, v7
	v_div_fmas_f32 v4, v4, v5, v8
	v_div_fixup_f32 v14, v4, v3, v2
	v_and_b32_e32 v2, 0xffff0000, v190
	v_and_b32_e32 v3, 0xffff0000, v194
	v_div_scale_f32 v4, s[4:5], v3, v3, v2
	v_rcp_f32_e32 v5, v4
	s_nop 0
	v_fma_f32 v6, -v4, v5, 1.0
	v_fmac_f32_e32 v5, v6, v5
	v_div_scale_f32 v7, vcc, v2, v3, v2
	v_mul_f32_e32 v8, v7, v5
	v_fma_f32 v6, -v4, v8, v7
	v_fmac_f32_e32 v8, v6, v5
	v_fma_f32 v4, -v4, v8, v7
	v_div_fmas_f32 v4, v4, v5, v8
	v_div_fixup_f32 v15, v4, v3, v2
	v_lshlrev_b32_e32 v2, 16, v191
	v_lshlrev_b32_e32 v3, 16, v195
	v_div_scale_f32 v4, s[4:5], v3, v3, v2
	v_rcp_f32_e32 v5, v4
	s_nop 0
	v_fma_f32 v6, -v4, v5, 1.0
	v_fmac_f32_e32 v5, v6, v5
	v_div_scale_f32 v7, vcc, v2, v3, v2
	v_mul_f32_e32 v8, v7, v5
	v_fma_f32 v6, -v4, v8, v7
	v_fmac_f32_e32 v8, v6, v5
	v_fma_f32 v4, -v4, v8, v7
	v_div_fmas_f32 v4, v4, v5, v8
	v_div_fixup_f32 v16, v4, v3, v2
	v_and_b32_e32 v2, 0xffff0000, v191
	v_and_b32_e32 v3, 0xffff0000, v195
	v_div_scale_f32 v4, s[4:5], v3, v3, v2
	v_rcp_f32_e32 v5, v4
	s_nop 0
	v_fma_f32 v6, -v4, v5, 1.0
	v_fmac_f32_e32 v5, v6, v5
	v_div_scale_f32 v7, vcc, v2, v3, v2
	v_mul_f32_e32 v8, v7, v5
	v_fma_f32 v6, -v4, v8, v7
	v_fmac_f32_e32 v8, v6, v5
	v_fma_f32 v4, -v4, v8, v7
	v_div_fmas_f32 v4, v4, v5, v8
	v_div_fixup_f32 v17, v4, v3, v2
	s_waitcnt lgkmcnt(0)
	v_pk_mul_f32 v[42:43], v[42:43], v[10:11]
	v_pk_mul_f32 v[44:45], v[44:45], v[12:13]
	v_pk_mul_f32 v[46:47], v[46:47], v[14:15]
	v_pk_mul_f32 v[48:49], v[48:49], v[16:17]
	ds_write_b128 v50, v[42:45] offset:42272
	ds_write_b128 v50, v[46:49] offset:42288
	ds_read_b128 v[42:45], v50 offset:50720
	ds_read_b128 v[46:49], v50 offset:50736
	s_waitcnt vmcnt(2)
	v_lshlrev_b32_e32 v2, 16, v196
	v_lshlrev_b32_e32 v3, 16, v34
	v_div_scale_f32 v4, s[4:5], v3, v3, v2
	v_rcp_f32_e32 v5, v4
	s_nop 0
	v_fma_f32 v6, -v4, v5, 1.0
	v_fmac_f32_e32 v5, v6, v5
	v_div_scale_f32 v7, vcc, v2, v3, v2
	v_mul_f32_e32 v8, v7, v5
	v_fma_f32 v6, -v4, v8, v7
	v_fmac_f32_e32 v8, v6, v5
	v_fma_f32 v4, -v4, v8, v7
	v_div_fmas_f32 v4, v4, v5, v8
	v_div_fixup_f32 v10, v4, v3, v2
	v_and_b32_e32 v2, 0xffff0000, v196
	v_and_b32_e32 v3, 0xffff0000, v34
	v_div_scale_f32 v4, s[4:5], v3, v3, v2
	v_rcp_f32_e32 v5, v4
	s_nop 0
	v_fma_f32 v6, -v4, v5, 1.0
	v_fmac_f32_e32 v5, v6, v5
	v_div_scale_f32 v7, vcc, v2, v3, v2
	v_mul_f32_e32 v8, v7, v5
	v_fma_f32 v6, -v4, v8, v7
	v_fmac_f32_e32 v8, v6, v5
	v_fma_f32 v4, -v4, v8, v7
	v_div_fmas_f32 v4, v4, v5, v8
	v_div_fixup_f32 v11, v4, v3, v2
	v_lshlrev_b32_e32 v2, 16, v197
	v_lshlrev_b32_e32 v3, 16, v35
	v_div_scale_f32 v4, s[4:5], v3, v3, v2
	v_rcp_f32_e32 v5, v4
	s_nop 0
	v_fma_f32 v6, -v4, v5, 1.0
	v_fmac_f32_e32 v5, v6, v5
	v_div_scale_f32 v7, vcc, v2, v3, v2
	v_mul_f32_e32 v8, v7, v5
	v_fma_f32 v6, -v4, v8, v7
	v_fmac_f32_e32 v8, v6, v5
	v_fma_f32 v4, -v4, v8, v7
	v_div_fmas_f32 v4, v4, v5, v8
	v_div_fixup_f32 v12, v4, v3, v2
	v_and_b32_e32 v2, 0xffff0000, v197
	v_and_b32_e32 v3, 0xffff0000, v35
	v_div_scale_f32 v4, s[4:5], v3, v3, v2
	v_rcp_f32_e32 v5, v4
	s_nop 0
	v_fma_f32 v6, -v4, v5, 1.0
	v_fmac_f32_e32 v5, v6, v5
	v_div_scale_f32 v7, vcc, v2, v3, v2
	v_mul_f32_e32 v8, v7, v5
	v_fma_f32 v6, -v4, v8, v7
	v_fmac_f32_e32 v8, v6, v5
	v_fma_f32 v4, -v4, v8, v7
	v_div_fmas_f32 v4, v4, v5, v8
	v_div_fixup_f32 v13, v4, v3, v2
	v_lshlrev_b32_e32 v2, 16, v198
	v_lshlrev_b32_e32 v3, 16, v36
	v_div_scale_f32 v4, s[4:5], v3, v3, v2
	v_rcp_f32_e32 v5, v4
	s_nop 0
	v_fma_f32 v6, -v4, v5, 1.0
	v_fmac_f32_e32 v5, v6, v5
	v_div_scale_f32 v7, vcc, v2, v3, v2
	v_mul_f32_e32 v8, v7, v5
	v_fma_f32 v6, -v4, v8, v7
	v_fmac_f32_e32 v8, v6, v5
	v_fma_f32 v4, -v4, v8, v7
	v_div_fmas_f32 v4, v4, v5, v8
	v_div_fixup_f32 v14, v4, v3, v2
	v_and_b32_e32 v2, 0xffff0000, v198
	v_and_b32_e32 v3, 0xffff0000, v36
	v_div_scale_f32 v4, s[4:5], v3, v3, v2
	v_rcp_f32_e32 v5, v4
	s_nop 0
	v_fma_f32 v6, -v4, v5, 1.0
	v_fmac_f32_e32 v5, v6, v5
	v_div_scale_f32 v7, vcc, v2, v3, v2
	v_mul_f32_e32 v8, v7, v5
	v_fma_f32 v6, -v4, v8, v7
	v_fmac_f32_e32 v8, v6, v5
	v_fma_f32 v4, -v4, v8, v7
	v_div_fmas_f32 v4, v4, v5, v8
	v_div_fixup_f32 v15, v4, v3, v2
	v_lshlrev_b32_e32 v2, 16, v199
	v_lshlrev_b32_e32 v3, 16, v37
	v_div_scale_f32 v4, s[4:5], v3, v3, v2
	v_rcp_f32_e32 v5, v4
	s_nop 0
	v_fma_f32 v6, -v4, v5, 1.0
	v_fmac_f32_e32 v5, v6, v5
	v_div_scale_f32 v7, vcc, v2, v3, v2
	v_mul_f32_e32 v8, v7, v5
	v_fma_f32 v6, -v4, v8, v7
	v_fmac_f32_e32 v8, v6, v5
	v_fma_f32 v4, -v4, v8, v7
	v_div_fmas_f32 v4, v4, v5, v8
	v_div_fixup_f32 v16, v4, v3, v2
	v_and_b32_e32 v2, 0xffff0000, v199
	v_and_b32_e32 v3, 0xffff0000, v37
	v_div_scale_f32 v4, s[4:5], v3, v3, v2
	v_rcp_f32_e32 v5, v4
	s_nop 0
	v_fma_f32 v6, -v4, v5, 1.0
	v_fmac_f32_e32 v5, v6, v5
	v_div_scale_f32 v7, vcc, v2, v3, v2
	v_mul_f32_e32 v8, v7, v5
	v_fma_f32 v6, -v4, v8, v7
	v_fmac_f32_e32 v8, v6, v5
	v_fma_f32 v4, -v4, v8, v7
	v_div_fmas_f32 v4, v4, v5, v8
	v_div_fixup_f32 v17, v4, v3, v2
	s_waitcnt lgkmcnt(0)
	v_pk_mul_f32 v[42:43], v[42:43], v[10:11]
	v_pk_mul_f32 v[44:45], v[44:45], v[12:13]
	v_pk_mul_f32 v[46:47], v[46:47], v[14:15]
	v_pk_mul_f32 v[48:49], v[48:49], v[16:17]
	ds_write_b128 v50, v[42:45] offset:50720
	ds_write_b128 v50, v[46:49] offset:50736
	ds_read_b128 v[42:45], v50 offset:59168
	ds_read_b128 v[46:49], v50 offset:59184
	s_waitcnt vmcnt(0)
	v_lshlrev_b32_e32 v2, 16, v38
	v_lshlrev_b32_e32 v3, 16, v52
	v_div_scale_f32 v4, s[4:5], v3, v3, v2
	v_rcp_f32_e32 v5, v4
	s_nop 0
	v_fma_f32 v6, -v4, v5, 1.0
	v_fmac_f32_e32 v5, v6, v5
	v_div_scale_f32 v7, vcc, v2, v3, v2
	v_mul_f32_e32 v8, v7, v5
	v_fma_f32 v6, -v4, v8, v7
	v_fmac_f32_e32 v8, v6, v5
	v_fma_f32 v4, -v4, v8, v7
	v_div_fmas_f32 v4, v4, v5, v8
	v_div_fixup_f32 v10, v4, v3, v2
	v_and_b32_e32 v2, 0xffff0000, v38
	v_and_b32_e32 v3, 0xffff0000, v52
	v_div_scale_f32 v4, s[4:5], v3, v3, v2
	v_rcp_f32_e32 v5, v4
	s_nop 0
	v_fma_f32 v6, -v4, v5, 1.0
	v_fmac_f32_e32 v5, v6, v5
	v_div_scale_f32 v7, vcc, v2, v3, v2
	v_mul_f32_e32 v8, v7, v5
	v_fma_f32 v6, -v4, v8, v7
	v_fmac_f32_e32 v8, v6, v5
	v_fma_f32 v4, -v4, v8, v7
	v_div_fmas_f32 v4, v4, v5, v8
	v_div_fixup_f32 v11, v4, v3, v2
	v_lshlrev_b32_e32 v2, 16, v39
	v_lshlrev_b32_e32 v3, 16, v53
	v_div_scale_f32 v4, s[4:5], v3, v3, v2
	v_rcp_f32_e32 v5, v4
	s_nop 0
	v_fma_f32 v6, -v4, v5, 1.0
	v_fmac_f32_e32 v5, v6, v5
	v_div_scale_f32 v7, vcc, v2, v3, v2
	v_mul_f32_e32 v8, v7, v5
	v_fma_f32 v6, -v4, v8, v7
	v_fmac_f32_e32 v8, v6, v5
	v_fma_f32 v4, -v4, v8, v7
	v_div_fmas_f32 v4, v4, v5, v8
	v_div_fixup_f32 v12, v4, v3, v2
	v_and_b32_e32 v2, 0xffff0000, v39
	v_and_b32_e32 v3, 0xffff0000, v53
	v_div_scale_f32 v4, s[4:5], v3, v3, v2
	v_rcp_f32_e32 v5, v4
	s_nop 0
	v_fma_f32 v6, -v4, v5, 1.0
	v_fmac_f32_e32 v5, v6, v5
	v_div_scale_f32 v7, vcc, v2, v3, v2
	v_mul_f32_e32 v8, v7, v5
	v_fma_f32 v6, -v4, v8, v7
	v_fmac_f32_e32 v8, v6, v5
	v_fma_f32 v4, -v4, v8, v7
	v_div_fmas_f32 v4, v4, v5, v8
	v_div_fixup_f32 v13, v4, v3, v2
	v_lshlrev_b32_e32 v2, 16, v40
	v_lshlrev_b32_e32 v3, 16, v54
	v_div_scale_f32 v4, s[4:5], v3, v3, v2
	v_rcp_f32_e32 v5, v4
	s_nop 0
	v_fma_f32 v6, -v4, v5, 1.0
	v_fmac_f32_e32 v5, v6, v5
	v_div_scale_f32 v7, vcc, v2, v3, v2
	v_mul_f32_e32 v8, v7, v5
	v_fma_f32 v6, -v4, v8, v7
	v_fmac_f32_e32 v8, v6, v5
	v_fma_f32 v4, -v4, v8, v7
	v_div_fmas_f32 v4, v4, v5, v8
	v_div_fixup_f32 v14, v4, v3, v2
	v_and_b32_e32 v2, 0xffff0000, v40
	v_and_b32_e32 v3, 0xffff0000, v54
	v_div_scale_f32 v4, s[4:5], v3, v3, v2
	v_rcp_f32_e32 v5, v4
	s_nop 0
	v_fma_f32 v6, -v4, v5, 1.0
	v_fmac_f32_e32 v5, v6, v5
	v_div_scale_f32 v7, vcc, v2, v3, v2
	v_mul_f32_e32 v8, v7, v5
	v_fma_f32 v6, -v4, v8, v7
	v_fmac_f32_e32 v8, v6, v5
	v_fma_f32 v4, -v4, v8, v7
	v_div_fmas_f32 v4, v4, v5, v8
	v_div_fixup_f32 v15, v4, v3, v2
	v_lshlrev_b32_e32 v2, 16, v41
	v_lshlrev_b32_e32 v3, 16, v55
	v_div_scale_f32 v4, s[4:5], v3, v3, v2
	v_rcp_f32_e32 v5, v4
	s_nop 0
	v_fma_f32 v6, -v4, v5, 1.0
	v_fmac_f32_e32 v5, v6, v5
	v_div_scale_f32 v7, vcc, v2, v3, v2
	v_mul_f32_e32 v8, v7, v5
	v_fma_f32 v6, -v4, v8, v7
	v_fmac_f32_e32 v8, v6, v5
	v_fma_f32 v4, -v4, v8, v7
	v_div_fmas_f32 v4, v4, v5, v8
	v_div_fixup_f32 v16, v4, v3, v2
	v_and_b32_e32 v2, 0xffff0000, v41
	v_and_b32_e32 v3, 0xffff0000, v55
	v_div_scale_f32 v4, s[4:5], v3, v3, v2
	v_rcp_f32_e32 v5, v4
	s_nop 0
	v_fma_f32 v6, -v4, v5, 1.0
	v_fmac_f32_e32 v5, v6, v5
	v_div_scale_f32 v7, vcc, v2, v3, v2
	v_mul_f32_e32 v8, v7, v5
	v_fma_f32 v6, -v4, v8, v7
	v_fmac_f32_e32 v8, v6, v5
	v_fma_f32 v4, -v4, v8, v7
	v_div_fmas_f32 v4, v4, v5, v8
	v_div_fixup_f32 v17, v4, v3, v2
	s_waitcnt lgkmcnt(0)
	v_pk_mul_f32 v[42:43], v[42:43], v[10:11]
	v_pk_mul_f32 v[44:45], v[44:45], v[12:13]
	v_pk_mul_f32 v[46:47], v[46:47], v[14:15]
	v_pk_mul_f32 v[48:49], v[48:49], v[16:17]
	ds_write_b128 v50, v[42:45] offset:59168
	ds_write_b128 v50, v[46:49] offset:59184
.LBB0_1300:
	s_or_b64 exec, exec, s[50:51]
	s_lshl_b32 s4, s73, 7
	s_lshl_b32 s5, s71, 1
	s_add_u32 s6, s58, s5
	s_addc_u32 s7, s59, 0
	s_lshl_b32 s5, s72, 1
	v_mov_b32_e32 v111, v101
	s_add_u32 s8, s60, s5
	s_addc_u32 s9, s61, 0
	s_waitcnt lgkmcnt(0)
	s_barrier
	ds_read2_b32 v[26:27], v129 offset1:16
	ds_read2_b32 v[148:149], v129 offset0:132 offset1:148
	ds_read2_b32 v[28:29], v138 offset0:8 offset1:24
	ds_read2_b32 v[150:151], v138 offset0:140 offset1:156
	ds_read2_b32 v[22:23], v129 offset0:32 offset1:48
	ds_read2_b32 v[152:153], v129 offset0:164 offset1:180
	ds_read2_b32 v[24:25], v138 offset0:40 offset1:56
	ds_read2_b32 v[154:155], v138 offset0:172 offset1:188
	ds_read2_b32 v[18:19], v139 offset0:64 offset1:80
	ds_read2_b32 v[156:157], v139 offset0:196 offset1:212
	ds_read2_b32 v[20:21], v140 offset0:72 offset1:88
	ds_read2_b32 v[158:159], v140 offset0:204 offset1:220
	ds_read2_b32 v[14:15], v139 offset0:96 offset1:112
	ds_read2_b32 v[160:161], v139 offset0:228 offset1:244
	ds_read2_b32 v[16:17], v140 offset0:104 offset1:120
	ds_read2_b32 v[162:163], v140 offset0:236 offset1:252
	ds_read2_b32 v[10:11], v141 offset0:128 offset1:144
	ds_read2_b32 v[164:165], v142 offset0:4 offset1:20
	ds_read2_b32 v[12:13], v142 offset0:136 offset1:152
	ds_read2_b32 v[166:167], v143 offset0:12 offset1:28
	ds_read2_b32 v[6:7], v141 offset0:160 offset1:176
	ds_read2_b32 v[168:169], v142 offset0:36 offset1:52
	ds_read2_b32 v[8:9], v142 offset0:168 offset1:184
	ds_read2_b32 v[170:171], v143 offset0:44 offset1:60
	ds_read2_b32 v[2:3], v144 offset0:192 offset1:208
	ds_read2_b32 v[172:173], v145 offset0:68 offset1:84
	ds_read2_b32 v[4:5], v145 offset0:200 offset1:216
	ds_read2_b32 v[174:175], v146 offset0:76 offset1:92
	ds_read2_b32 v[30:31], v144 offset0:224 offset1:240
	ds_read2_b32 v[176:177], v145 offset0:100 offset1:116
	ds_read2_b32 v[32:33], v145 offset0:232 offset1:248
	ds_read2_b32 v[178:179], v146 offset0:108 offset1:124
	s_waitcnt lgkmcnt(0)
	s_barrier
	v_mov_b32_e32 v94, v31
	v_mov_b32_e32 v95, v177
	v_mov_b32_e32 v96, v33
	v_mov_b32_e32 v97, v179
	v_mov_b32_e32 v31, v176
	v_mov_b32_e32 v33, v178
	v_mov_b32_e32 v66, v3
	v_mov_b32_e32 v67, v173
	v_mov_b32_e32 v68, v5
	v_mov_b32_e32 v69, v175
	v_mov_b32_e32 v3, v172
	v_mov_b32_e32 v5, v174
	v_mov_b32_e32 v70, v7
	v_mov_b32_e32 v71, v169
	v_mov_b32_e32 v72, v9
	v_mov_b32_e32 v73, v171
	v_mov_b32_e32 v7, v168
	v_mov_b32_e32 v9, v170
	v_mov_b32_e32 v74, v11
	v_mov_b32_e32 v75, v165
	v_mov_b32_e32 v76, v13
	v_mov_b32_e32 v77, v167
	v_mov_b32_e32 v11, v164
	v_mov_b32_e32 v13, v166
	v_mov_b32_e32 v78, v15
	v_mov_b32_e32 v79, v161
	v_mov_b32_e32 v80, v17
	v_mov_b32_e32 v81, v163
	v_mov_b32_e32 v15, v160
	v_mov_b32_e32 v17, v162
	v_mov_b32_e32 v82, v19
	v_mov_b32_e32 v83, v157
	v_mov_b32_e32 v84, v21
	v_mov_b32_e32 v85, v159
	v_mov_b32_e32 v19, v156
	v_mov_b32_e32 v21, v158
	v_mov_b32_e32 v86, v23
	v_mov_b32_e32 v87, v153
	v_mov_b32_e32 v88, v25
	v_mov_b32_e32 v89, v155
	v_mov_b32_e32 v23, v152
	v_mov_b32_e32 v25, v154
	v_mov_b32_e32 v90, v27
	v_mov_b32_e32 v91, v149
	v_mov_b32_e32 v92, v29
	v_mov_b32_e32 v93, v151
	v_mov_b32_e32 v27, v148
	v_mov_b32_e32 v29, v150
	s_waitcnt lgkmcnt(0)
	s_barrier
	v_and_b32_e32 v174, 15, v0
	v_bfe_u32 v175, v0, 4, 2
	v_and_b32_e32 v111, 7, v174
	v_xor_b32_e32 v175, v175, v111
	v_lshlrev_b32_e32 v175, 4, v175
	v_lshl_or_b32 v175, v174, 7, v175
	v_bfe_u32 v174, v0, 7, 1
	v_lshl_or_b32 v100, v174, 13, v175
	v_bfe_u32 v174, v0, 6, 1
	v_lshl_or_b32 v168, v174, 13, v175
	v_or_b32_e32 v168, 0x4000, v168
	v_xor_b32_e32 v111, 64, v100
	v_xor_b32_e32 v169, 64, v168
	v_bfe_u32 v174, v0, 3, 3
	v_and_b32_e32 v175, 7, v0
	v_xor_b32_e32 v175, v175, v174
	v_lshlrev_b32_e32 v175, 4, v175
	v_lshl_or_b32 v175, v174, 11, v175
	v_lshrrev_b32_e32 v174, 6, v0
	v_and_b32_e32 v174, 3, v174
	v_lshl_or_b32 v170, v174, 16, v175
	v_add_u32_e32 v171, 0x3c00, v170
	v_add_u32_e32 v172, 0x7800, v170
	v_add_u32_e32 v173, 0xb400, v170
	v_lshlrev_b32_e32 v174, 12, v174
	s_nop 0
	v_readfirstlane_b32 s36, v174
	s_add_u32 s36, s36, 32
	v_mov_b32_e32 v116, 0
	v_mov_b32_e32 v117, 0
	v_mov_b32_e32 v118, 0
	v_mov_b32_e32 v119, 0
	v_mov_b32_e32 v120, 0
	v_mov_b32_e32 v121, 0
	v_mov_b32_e32 v122, 0
	v_mov_b32_e32 v123, 0
	v_mov_b32_e32 v124, 0
	v_mov_b32_e32 v125, 0
	v_mov_b32_e32 v126, 0
	v_mov_b32_e32 v127, 0
	v_mov_b32_e32 v148, 0
	v_mov_b32_e32 v149, 0
	v_mov_b32_e32 v150, 0
	v_mov_b32_e32 v151, 0
	v_mov_b32_e32 v152, 0
	v_mov_b32_e32 v153, 0
	v_mov_b32_e32 v154, 0
	v_mov_b32_e32 v155, 0
	v_mov_b32_e32 v156, 0
	v_mov_b32_e32 v157, 0
	v_mov_b32_e32 v158, 0
	v_mov_b32_e32 v159, 0
	v_mov_b32_e32 v160, 0
	v_mov_b32_e32 v161, 0
	v_mov_b32_e32 v162, 0
	v_mov_b32_e32 v163, 0
	v_mov_b32_e32 v164, 0
	v_mov_b32_e32 v165, 0
	v_mov_b32_e32 v166, 0
	v_mov_b32_e32 v167, 0
	s_waitcnt lgkmcnt(0)
	s_barrier
	v_readlane_b32 s98, v255, 16
	s_and_b32 s98, s98, 7
	s_lshl_b32 s98, s98, 1
	s_lshl_b32 s99, s98, 7
	s_add_u32 s6, s6, s99
	s_addc_u32 s7, s7, 0
	s_add_u32 s8, s8, s99
	s_addc_u32 s9, s9, 0
	s_add_u32 m0, s36, 0
	s_nop 0
	global_load_lds_dwordx4 v170, s[6:7] offset:0
	global_load_lds_dwordx4 v171, s[6:7] offset:1024
	global_load_lds_dwordx4 v172, s[6:7] offset:2048
	global_load_lds_dwordx4 v173, s[6:7] offset:3072
	s_add_u32 m0, s36, 16384
	s_nop 0
	global_load_lds_dwordx4 v170, s[8:9] offset:0
	global_load_lds_dwordx4 v171, s[8:9] offset:1024
	global_load_lds_dwordx4 v172, s[8:9] offset:2048
	global_load_lds_dwordx4 v173, s[8:9] offset:3072
	s_add_u32 s98, s98, 1
	s_and_b32 s98, s98, 15
	s_cmp_eq_u32 s98, 0
	s_cselect_b32 s99, 0x800, 0
	s_add_u32 s6, s6, 0x80
	s_addc_u32 s7, s7, 0
	s_sub_u32 s6, s6, s99
	s_subb_u32 s7, s7, 0
	s_add_u32 s8, s8, 0x80
	s_addc_u32 s9, s9, 0
	s_sub_u32 s8, s8, s99
	s_subb_u32 s9, s9, 0
	s_mov_b32 s5, 0
	s_waitcnt vmcnt(0)
	s_setprio 1
.Lk_aol1b_loop:
	s_barrier
	s_add_u32 m0, s36, 32768
	v_mfma_f32_16x16x32_bf16 v[26:29], v[116:119], v[152:155], v[26:29]
	ds_read_b128 v[34:37], v100 offset:32
	global_load_lds_dwordx4 v170, s[6:7] offset:0
	v_mfma_f32_16x16x32_bf16 v[90:93], v[116:119], v[156:159], v[90:93]
	ds_read_b128 v[50:53], v168 offset:32
	global_load_lds_dwordx4 v171, s[6:7] offset:1024
	v_mfma_f32_16x16x32_bf16 v[22:25], v[116:119], v[160:163], v[22:25]
	ds_read_b128 v[54:57], v168 offset:2080
	global_load_lds_dwordx4 v172, s[6:7] offset:2048
	v_mfma_f32_16x16x32_bf16 v[86:89], v[116:119], v[164:167], v[86:89]
	ds_read_b128 v[38:41], v100 offset:2080
	global_load_lds_dwordx4 v173, s[6:7] offset:3072
	s_add_u32 m0, s36, 49152
	v_mfma_f32_16x16x32_bf16 v[18:21], v[120:123], v[152:155], v[18:21]
	ds_read_b128 v[58:61], v168 offset:4128
	global_load_lds_dwordx4 v170, s[8:9] offset:0
	v_mfma_f32_16x16x32_bf16 v[82:85], v[120:123], v[156:159], v[82:85]
	ds_read_b128 v[62:65], v168 offset:6176
	global_load_lds_dwordx4 v171, s[8:9] offset:1024
	v_mfma_f32_16x16x32_bf16 v[14:17], v[120:123], v[160:163], v[14:17]
	ds_read_b128 v[42:45], v100 offset:4128
	global_load_lds_dwordx4 v172, s[8:9] offset:2048
	v_mfma_f32_16x16x32_bf16 v[78:81], v[120:123], v[164:167], v[78:81]
	ds_read_b128 v[46:49], v100 offset:6176
	global_load_lds_dwordx4 v173, s[8:9] offset:3072
	v_mfma_f32_16x16x32_bf16 v[10:13], v[124:127], v[152:155], v[10:13]
	v_mfma_f32_16x16x32_bf16 v[74:77], v[124:127], v[156:159], v[74:77]
	v_mfma_f32_16x16x32_bf16 v[6:9], v[124:127], v[160:163], v[6:9]
	v_mfma_f32_16x16x32_bf16 v[70:73], v[124:127], v[164:167], v[70:73]
	v_mfma_f32_16x16x32_bf16 v[2:5], v[148:151], v[152:155], v[2:5]
	v_mfma_f32_16x16x32_bf16 v[66:69], v[148:151], v[156:159], v[66:69]
	v_mfma_f32_16x16x32_bf16 v[30:33], v[148:151], v[160:163], v[30:33]
	v_mfma_f32_16x16x32_bf16 v[94:97], v[148:151], v[164:167], v[94:97]
	s_add_u32 s98, s98, 1
	s_and_b32 s98, s98, 15
	s_cmp_eq_u32 s98, 0
	s_cselect_b32 s99, 0x800, 0
	s_add_u32 s6, s6, 0x80
	s_addc_u32 s7, s7, 0
	s_sub_u32 s6, s6, s99
	s_subb_u32 s7, s7, 0
	s_add_u32 s8, s8, 0x80
	s_addc_u32 s9, s9, 0
	s_sub_u32 s8, s8, s99
	s_subb_u32 s9, s9, 0
	s_waitcnt lgkmcnt(0)
	v_mfma_f32_16x16x32_bf16 v[26:29], v[34:37], v[50:53], v[26:29]
	ds_read_b128 v[116:119], v111 offset:32
	v_mfma_f32_16x16x32_bf16 v[90:93], v[34:37], v[54:57], v[90:93]
	ds_read_b128 v[152:155], v169 offset:32
	v_mfma_f32_16x16x32_bf16 v[22:25], v[34:37], v[58:61], v[22:25]
	ds_read_b128 v[156:159], v169 offset:2080
	v_mfma_f32_16x16x32_bf16 v[86:89], v[34:37], v[62:65], v[86:89]
	ds_read_b128 v[120:123], v111 offset:2080
	v_mfma_f32_16x16x32_bf16 v[18:21], v[38:41], v[50:53], v[18:21]
	ds_read_b128 v[160:163], v169 offset:4128
	v_mfma_f32_16x16x32_bf16 v[82:85], v[38:41], v[54:57], v[82:85]
	ds_read_b128 v[164:167], v169 offset:6176
	v_mfma_f32_16x16x32_bf16 v[14:17], v[38:41], v[58:61], v[14:17]
	ds_read_b128 v[124:127], v111 offset:4128
	v_mfma_f32_16x16x32_bf16 v[78:81], v[38:41], v[62:65], v[78:81]
	ds_read_b128 v[148:151], v111 offset:6176
	v_mfma_f32_16x16x32_bf16 v[10:13], v[42:45], v[50:53], v[10:13]
	v_mfma_f32_16x16x32_bf16 v[74:77], v[42:45], v[54:57], v[74:77]
	v_mfma_f32_16x16x32_bf16 v[6:9], v[42:45], v[58:61], v[6:9]
	v_mfma_f32_16x16x32_bf16 v[70:73], v[42:45], v[62:65], v[70:73]
	v_mfma_f32_16x16x32_bf16 v[2:5], v[46:49], v[50:53], v[2:5]
	v_mfma_f32_16x16x32_bf16 v[66:69], v[46:49], v[54:57], v[66:69]
	v_mfma_f32_16x16x32_bf16 v[30:33], v[46:49], v[58:61], v[30:33]
	v_mfma_f32_16x16x32_bf16 v[94:97], v[46:49], v[62:65], v[94:97]
	s_waitcnt lgkmcnt(0)
	s_waitcnt vmcnt(0)
	s_barrier
	s_add_u32 m0, s36, 0
	v_mfma_f32_16x16x32_bf16 v[26:29], v[116:119], v[152:155], v[26:29]
	ds_read_b128 v[34:37], v100 offset:32800
	global_load_lds_dwordx4 v170, s[6:7] offset:0
	v_mfma_f32_16x16x32_bf16 v[90:93], v[116:119], v[156:159], v[90:93]
	ds_read_b128 v[50:53], v168 offset:32800
	global_load_lds_dwordx4 v171, s[6:7] offset:1024
	v_mfma_f32_16x16x32_bf16 v[22:25], v[116:119], v[160:163], v[22:25]
	ds_read_b128 v[54:57], v168 offset:34848
	global_load_lds_dwordx4 v172, s[6:7] offset:2048
	v_mfma_f32_16x16x32_bf16 v[86:89], v[116:119], v[164:167], v[86:89]
	ds_read_b128 v[38:41], v100 offset:34848
	global_load_lds_dwordx4 v173, s[6:7] offset:3072
	s_add_u32 m0, s36, 16384
	v_mfma_f32_16x16x32_bf16 v[18:21], v[120:123], v[152:155], v[18:21]
	ds_read_b128 v[58:61], v168 offset:36896
	global_load_lds_dwordx4 v170, s[8:9] offset:0
	v_mfma_f32_16x16x32_bf16 v[82:85], v[120:123], v[156:159], v[82:85]
	ds_read_b128 v[62:65], v168 offset:38944
	global_load_lds_dwordx4 v171, s[8:9] offset:1024
	v_mfma_f32_16x16x32_bf16 v[14:17], v[120:123], v[160:163], v[14:17]
	ds_read_b128 v[42:45], v100 offset:36896
	global_load_lds_dwordx4 v172, s[8:9] offset:2048
	v_mfma_f32_16x16x32_bf16 v[78:81], v[120:123], v[164:167], v[78:81]
	ds_read_b128 v[46:49], v100 offset:38944
	global_load_lds_dwordx4 v173, s[8:9] offset:3072
	v_mfma_f32_16x16x32_bf16 v[10:13], v[124:127], v[152:155], v[10:13]
	v_mfma_f32_16x16x32_bf16 v[74:77], v[124:127], v[156:159], v[74:77]
	v_mfma_f32_16x16x32_bf16 v[6:9], v[124:127], v[160:163], v[6:9]
	v_mfma_f32_16x16x32_bf16 v[70:73], v[124:127], v[164:167], v[70:73]
	v_mfma_f32_16x16x32_bf16 v[2:5], v[148:151], v[152:155], v[2:5]
	v_mfma_f32_16x16x32_bf16 v[66:69], v[148:151], v[156:159], v[66:69]
	v_mfma_f32_16x16x32_bf16 v[30:33], v[148:151], v[160:163], v[30:33]
	v_mfma_f32_16x16x32_bf16 v[94:97], v[148:151], v[164:167], v[94:97]
	s_add_u32 s98, s98, 1
	s_and_b32 s98, s98, 15
	s_cmp_eq_u32 s98, 0
	s_cselect_b32 s99, 0x800, 0
	s_add_u32 s6, s6, 0x80
	s_addc_u32 s7, s7, 0
	s_sub_u32 s6, s6, s99
	s_subb_u32 s7, s7, 0
	s_add_u32 s8, s8, 0x80
	s_addc_u32 s9, s9, 0
	s_sub_u32 s8, s8, s99
	s_subb_u32 s9, s9, 0
	s_waitcnt lgkmcnt(0)
	v_mfma_f32_16x16x32_bf16 v[26:29], v[34:37], v[50:53], v[26:29]
	ds_read_b128 v[116:119], v111 offset:32800
	v_mfma_f32_16x16x32_bf16 v[90:93], v[34:37], v[54:57], v[90:93]
	ds_read_b128 v[152:155], v169 offset:32800
	v_mfma_f32_16x16x32_bf16 v[22:25], v[34:37], v[58:61], v[22:25]
	ds_read_b128 v[156:159], v169 offset:34848
	v_mfma_f32_16x16x32_bf16 v[86:89], v[34:37], v[62:65], v[86:89]
	ds_read_b128 v[120:123], v111 offset:34848
	v_mfma_f32_16x16x32_bf16 v[18:21], v[38:41], v[50:53], v[18:21]
	ds_read_b128 v[160:163], v169 offset:36896
	v_mfma_f32_16x16x32_bf16 v[82:85], v[38:41], v[54:57], v[82:85]
	ds_read_b128 v[164:167], v169 offset:38944
	v_mfma_f32_16x16x32_bf16 v[14:17], v[38:41], v[58:61], v[14:17]
	ds_read_b128 v[124:127], v111 offset:36896
	v_mfma_f32_16x16x32_bf16 v[78:81], v[38:41], v[62:65], v[78:81]
	ds_read_b128 v[148:151], v111 offset:38944
	v_mfma_f32_16x16x32_bf16 v[10:13], v[42:45], v[50:53], v[10:13]
	v_mfma_f32_16x16x32_bf16 v[74:77], v[42:45], v[54:57], v[74:77]
	v_mfma_f32_16x16x32_bf16 v[6:9], v[42:45], v[58:61], v[6:9]
	v_mfma_f32_16x16x32_bf16 v[70:73], v[42:45], v[62:65], v[70:73]
	v_mfma_f32_16x16x32_bf16 v[2:5], v[46:49], v[50:53], v[2:5]
	v_mfma_f32_16x16x32_bf16 v[66:69], v[46:49], v[54:57], v[66:69]
	v_mfma_f32_16x16x32_bf16 v[30:33], v[46:49], v[58:61], v[30:33]
	v_mfma_f32_16x16x32_bf16 v[94:97], v[46:49], v[62:65], v[94:97]
	s_waitcnt lgkmcnt(0)
	s_waitcnt vmcnt(0)
	s_add_u32 s5, s5, 1
	s_cmp_lt_u32 s5, 7
	s_cbranch_scc1 .Lk_aol1b_loop
	s_barrier
	s_add_u32 m0, s36, 32768
	v_mfma_f32_16x16x32_bf16 v[26:29], v[116:119], v[152:155], v[26:29]
	ds_read_b128 v[34:37], v100 offset:32
	global_load_lds_dwordx4 v170, s[6:7] offset:0
	v_mfma_f32_16x16x32_bf16 v[90:93], v[116:119], v[156:159], v[90:93]
	ds_read_b128 v[50:53], v168 offset:32
	global_load_lds_dwordx4 v171, s[6:7] offset:1024
	v_mfma_f32_16x16x32_bf16 v[22:25], v[116:119], v[160:163], v[22:25]
	ds_read_b128 v[54:57], v168 offset:2080
	global_load_lds_dwordx4 v172, s[6:7] offset:2048
	v_mfma_f32_16x16x32_bf16 v[86:89], v[116:119], v[164:167], v[86:89]
	ds_read_b128 v[38:41], v100 offset:2080
	global_load_lds_dwordx4 v173, s[6:7] offset:3072
	s_add_u32 m0, s36, 49152
	v_mfma_f32_16x16x32_bf16 v[18:21], v[120:123], v[152:155], v[18:21]
	ds_read_b128 v[58:61], v168 offset:4128
	global_load_lds_dwordx4 v170, s[8:9] offset:0
	v_mfma_f32_16x16x32_bf16 v[82:85], v[120:123], v[156:159], v[82:85]
	ds_read_b128 v[62:65], v168 offset:6176
	global_load_lds_dwordx4 v171, s[8:9] offset:1024
	v_mfma_f32_16x16x32_bf16 v[14:17], v[120:123], v[160:163], v[14:17]
	ds_read_b128 v[42:45], v100 offset:4128
	global_load_lds_dwordx4 v172, s[8:9] offset:2048
	v_mfma_f32_16x16x32_bf16 v[78:81], v[120:123], v[164:167], v[78:81]
	ds_read_b128 v[46:49], v100 offset:6176
	global_load_lds_dwordx4 v173, s[8:9] offset:3072
	v_mfma_f32_16x16x32_bf16 v[10:13], v[124:127], v[152:155], v[10:13]
	v_mfma_f32_16x16x32_bf16 v[74:77], v[124:127], v[156:159], v[74:77]
	v_mfma_f32_16x16x32_bf16 v[6:9], v[124:127], v[160:163], v[6:9]
	v_mfma_f32_16x16x32_bf16 v[70:73], v[124:127], v[164:167], v[70:73]
	v_mfma_f32_16x16x32_bf16 v[2:5], v[148:151], v[152:155], v[2:5]
	v_mfma_f32_16x16x32_bf16 v[66:69], v[148:151], v[156:159], v[66:69]
	v_mfma_f32_16x16x32_bf16 v[30:33], v[148:151], v[160:163], v[30:33]
	v_mfma_f32_16x16x32_bf16 v[94:97], v[148:151], v[164:167], v[94:97]
	s_add_u32 s98, s98, 1
	s_and_b32 s98, s98, 15
	s_cmp_eq_u32 s98, 0
	s_cselect_b32 s99, 0x800, 0
	s_add_u32 s6, s6, 0x80
	s_addc_u32 s7, s7, 0
	s_sub_u32 s6, s6, s99
	s_subb_u32 s7, s7, 0
	s_add_u32 s8, s8, 0x80
	s_addc_u32 s9, s9, 0
	s_sub_u32 s8, s8, s99
	s_subb_u32 s9, s9, 0
	s_waitcnt lgkmcnt(0)
	v_mfma_f32_16x16x32_bf16 v[26:29], v[34:37], v[50:53], v[26:29]
	ds_read_b128 v[116:119], v111 offset:32
	v_mfma_f32_16x16x32_bf16 v[90:93], v[34:37], v[54:57], v[90:93]
	ds_read_b128 v[152:155], v169 offset:32
	v_mfma_f32_16x16x32_bf16 v[22:25], v[34:37], v[58:61], v[22:25]
	ds_read_b128 v[156:159], v169 offset:2080
	v_mfma_f32_16x16x32_bf16 v[86:89], v[34:37], v[62:65], v[86:89]
	ds_read_b128 v[120:123], v111 offset:2080
	v_mfma_f32_16x16x32_bf16 v[18:21], v[38:41], v[50:53], v[18:21]
	ds_read_b128 v[160:163], v169 offset:4128
	v_mfma_f32_16x16x32_bf16 v[82:85], v[38:41], v[54:57], v[82:85]
	ds_read_b128 v[164:167], v169 offset:6176
	v_mfma_f32_16x16x32_bf16 v[14:17], v[38:41], v[58:61], v[14:17]
	ds_read_b128 v[124:127], v111 offset:4128
	v_mfma_f32_16x16x32_bf16 v[78:81], v[38:41], v[62:65], v[78:81]
	ds_read_b128 v[148:151], v111 offset:6176
	v_mfma_f32_16x16x32_bf16 v[10:13], v[42:45], v[50:53], v[10:13]
	v_mfma_f32_16x16x32_bf16 v[74:77], v[42:45], v[54:57], v[74:77]
	v_mfma_f32_16x16x32_bf16 v[6:9], v[42:45], v[58:61], v[6:9]
	v_mfma_f32_16x16x32_bf16 v[70:73], v[42:45], v[62:65], v[70:73]
	v_mfma_f32_16x16x32_bf16 v[2:5], v[46:49], v[50:53], v[2:5]
	v_mfma_f32_16x16x32_bf16 v[66:69], v[46:49], v[54:57], v[66:69]
	v_mfma_f32_16x16x32_bf16 v[30:33], v[46:49], v[58:61], v[30:33]
	v_mfma_f32_16x16x32_bf16 v[94:97], v[46:49], v[62:65], v[94:97]
	s_waitcnt lgkmcnt(0)
	s_waitcnt vmcnt(0)
	s_barrier
	v_mfma_f32_16x16x32_bf16 v[26:29], v[116:119], v[152:155], v[26:29]
	ds_read_b128 v[34:37], v100 offset:32800
	v_mfma_f32_16x16x32_bf16 v[90:93], v[116:119], v[156:159], v[90:93]
	ds_read_b128 v[50:53], v168 offset:32800
	v_mfma_f32_16x16x32_bf16 v[22:25], v[116:119], v[160:163], v[22:25]
	ds_read_b128 v[54:57], v168 offset:34848
	v_mfma_f32_16x16x32_bf16 v[86:89], v[116:119], v[164:167], v[86:89]
	ds_read_b128 v[38:41], v100 offset:34848
	v_mfma_f32_16x16x32_bf16 v[18:21], v[120:123], v[152:155], v[18:21]
	ds_read_b128 v[58:61], v168 offset:36896
	v_mfma_f32_16x16x32_bf16 v[82:85], v[120:123], v[156:159], v[82:85]
	ds_read_b128 v[62:65], v168 offset:38944
	v_mfma_f32_16x16x32_bf16 v[14:17], v[120:123], v[160:163], v[14:17]
	ds_read_b128 v[42:45], v100 offset:36896
	v_mfma_f32_16x16x32_bf16 v[78:81], v[120:123], v[164:167], v[78:81]
	ds_read_b128 v[46:49], v100 offset:38944
	v_mfma_f32_16x16x32_bf16 v[10:13], v[124:127], v[152:155], v[10:13]
	v_mfma_f32_16x16x32_bf16 v[74:77], v[124:127], v[156:159], v[74:77]
	v_mfma_f32_16x16x32_bf16 v[6:9], v[124:127], v[160:163], v[6:9]
	v_mfma_f32_16x16x32_bf16 v[70:73], v[124:127], v[164:167], v[70:73]
	v_mfma_f32_16x16x32_bf16 v[2:5], v[148:151], v[152:155], v[2:5]
	v_mfma_f32_16x16x32_bf16 v[66:69], v[148:151], v[156:159], v[66:69]
	v_mfma_f32_16x16x32_bf16 v[30:33], v[148:151], v[160:163], v[30:33]
	v_mfma_f32_16x16x32_bf16 v[94:97], v[148:151], v[164:167], v[94:97]
	s_waitcnt lgkmcnt(0)
	v_mfma_f32_16x16x32_bf16 v[26:29], v[34:37], v[50:53], v[26:29]
	ds_read_b128 v[116:119], v111 offset:32800
	v_mfma_f32_16x16x32_bf16 v[90:93], v[34:37], v[54:57], v[90:93]
	ds_read_b128 v[152:155], v169 offset:32800
	v_mfma_f32_16x16x32_bf16 v[22:25], v[34:37], v[58:61], v[22:25]
	ds_read_b128 v[156:159], v169 offset:34848
	v_mfma_f32_16x16x32_bf16 v[86:89], v[34:37], v[62:65], v[86:89]
	ds_read_b128 v[120:123], v111 offset:34848
	v_mfma_f32_16x16x32_bf16 v[18:21], v[38:41], v[50:53], v[18:21]
	ds_read_b128 v[160:163], v169 offset:36896
	v_mfma_f32_16x16x32_bf16 v[82:85], v[38:41], v[54:57], v[82:85]
	ds_read_b128 v[164:167], v169 offset:38944
	v_mfma_f32_16x16x32_bf16 v[14:17], v[38:41], v[58:61], v[14:17]
	ds_read_b128 v[124:127], v111 offset:36896
	v_mfma_f32_16x16x32_bf16 v[78:81], v[38:41], v[62:65], v[78:81]
	ds_read_b128 v[148:151], v111 offset:38944
	v_mfma_f32_16x16x32_bf16 v[10:13], v[42:45], v[50:53], v[10:13]
	v_mfma_f32_16x16x32_bf16 v[74:77], v[42:45], v[54:57], v[74:77]
	v_mfma_f32_16x16x32_bf16 v[6:9], v[42:45], v[58:61], v[6:9]
	v_mfma_f32_16x16x32_bf16 v[70:73], v[42:45], v[62:65], v[70:73]
	v_mfma_f32_16x16x32_bf16 v[2:5], v[46:49], v[50:53], v[2:5]
	v_mfma_f32_16x16x32_bf16 v[66:69], v[46:49], v[54:57], v[66:69]
	v_mfma_f32_16x16x32_bf16 v[30:33], v[46:49], v[58:61], v[30:33]
	v_mfma_f32_16x16x32_bf16 v[94:97], v[46:49], v[62:65], v[94:97]
	s_waitcnt lgkmcnt(0)
	v_mfma_f32_16x16x32_bf16 v[26:29], v[116:119], v[152:155], v[26:29]
	v_mfma_f32_16x16x32_bf16 v[90:93], v[116:119], v[156:159], v[90:93]
	v_mfma_f32_16x16x32_bf16 v[22:25], v[116:119], v[160:163], v[22:25]
	v_mfma_f32_16x16x32_bf16 v[86:89], v[116:119], v[164:167], v[86:89]
	v_mfma_f32_16x16x32_bf16 v[18:21], v[120:123], v[152:155], v[18:21]
	v_mfma_f32_16x16x32_bf16 v[82:85], v[120:123], v[156:159], v[82:85]
	v_mfma_f32_16x16x32_bf16 v[14:17], v[120:123], v[160:163], v[14:17]
	v_mfma_f32_16x16x32_bf16 v[78:81], v[120:123], v[164:167], v[78:81]
	v_mfma_f32_16x16x32_bf16 v[10:13], v[124:127], v[152:155], v[10:13]
	v_mfma_f32_16x16x32_bf16 v[74:77], v[124:127], v[156:159], v[74:77]
	v_mfma_f32_16x16x32_bf16 v[6:9], v[124:127], v[160:163], v[6:9]
	v_mfma_f32_16x16x32_bf16 v[70:73], v[124:127], v[164:167], v[70:73]
	v_mfma_f32_16x16x32_bf16 v[2:5], v[148:151], v[152:155], v[2:5]
	v_mfma_f32_16x16x32_bf16 v[66:69], v[148:151], v[156:159], v[66:69]
	v_mfma_f32_16x16x32_bf16 v[30:33], v[148:151], v[160:163], v[30:33]
	v_mfma_f32_16x16x32_bf16 v[94:97], v[148:151], v[164:167], v[94:97]
	s_setprio 0
	s_lshr_b32 s101, s71, 10
	v_lshrrev_b32_e32 v117, 4, v0
	v_and_b32_e32 v117, 15, v117
	v_and_b32_e32 v118, 15, v0
	v_lshlrev_b32_e32 v118, 4, v118
	v_lshl_or_b32 v117, v117, 12, v118
	s_lshl_b32 s100, s101, 12
	s_lshl_b32 s98, s73, 8
	s_add_u32 s100, s100, s98
	s_add_u32 s98, s42, s100
	s_addc_u32 s99, s43, 0
	s_add_u32 s98, s98, 0x12d24800
	s_addc_u32 s99, s99, 0
	global_load_dwordx4 v[148:151], v117, s[98:99]
	s_add_u32 s98, s98, 0x10000
	s_addc_u32 s99, s99, 0
	global_load_dwordx4 v[152:155], v117, s[98:99]
	s_add_u32 s98, s98, 0x10000
	s_addc_u32 s99, s99, 0
	global_load_dwordx4 v[156:159], v117, s[98:99]
	s_add_u32 s98, s98, 0x10000
	s_addc_u32 s99, s99, 0
	global_load_dwordx4 v[160:163], v117, s[98:99]
	s_add_u32 s98, s98, 0x10000
	s_addc_u32 s99, s99, 0
	global_load_dwordx4 v[164:167], v117, s[98:99]
	s_add_u32 s98, s98, 0x10000
	s_addc_u32 s99, s99, 0
	global_load_dwordx4 v[168:171], v117, s[98:99]
	s_add_u32 s98, s98, 0x10000
	s_addc_u32 s99, s99, 0
	global_load_dwordx4 v[172:175], v117, s[98:99]
	s_add_u32 s98, s98, 0x10000
	s_addc_u32 s99, s99, 0
	global_load_dwordx4 v[176:179], v117, s[98:99]
	s_lshl_b32 s36, s4, 1
	s_lshl_b32 s4, s70, 10
	s_mul_hi_u32 s5, s70, 0x15555556
	s_barrier
	ds_write2_b32 v129, v26, v90 offset1:16
	ds_write2_b32 v129, v27, v91 offset0:132 offset1:148
	ds_write2_b32 v138, v28, v92 offset0:8 offset1:24
	ds_write2_b32 v138, v29, v93 offset0:140 offset1:156
	ds_write2_b32 v129, v22, v86 offset0:32 offset1:48
	ds_write2_b32 v129, v23, v87 offset0:164 offset1:180
	ds_write2_b32 v138, v24, v88 offset0:40 offset1:56
	ds_write2_b32 v138, v25, v89 offset0:172 offset1:188
	ds_write2_b32 v139, v18, v82 offset0:64 offset1:80
	ds_write2_b32 v139, v19, v83 offset0:196 offset1:212
	ds_write2_b32 v140, v20, v84 offset0:72 offset1:88
	ds_write2_b32 v140, v21, v85 offset0:204 offset1:220
	ds_write2_b32 v139, v14, v78 offset0:96 offset1:112
	ds_write2_b32 v139, v15, v79 offset0:228 offset1:244
	ds_write2_b32 v140, v16, v80 offset0:104 offset1:120
	ds_write2_b32 v140, v17, v81 offset0:236 offset1:252
	ds_write2_b32 v141, v10, v74 offset0:128 offset1:144
	ds_write2_b32 v142, v11, v75 offset0:4 offset1:20
	ds_write2_b32 v142, v12, v76 offset0:136 offset1:152
	ds_write2_b32 v143, v13, v77 offset0:12 offset1:28
	ds_write2_b32 v141, v6, v70 offset0:160 offset1:176
	ds_write2_b32 v142, v7, v71 offset0:36 offset1:52
	ds_write2_b32 v142, v8, v72 offset0:168 offset1:184
	ds_write2_b32 v143, v9, v73 offset0:44 offset1:60
	ds_write2_b32 v144, v2, v66 offset0:192 offset1:208
	ds_write2_b32 v145, v3, v67 offset0:68 offset1:84
	ds_write2_b32 v145, v4, v68 offset0:200 offset1:216
	ds_write2_b32 v146, v5, v69 offset0:76 offset1:92
	ds_write2_b32 v144, v30, v94 offset0:224 offset1:240
	ds_write2_b32 v145, v31, v95 offset0:100 offset1:116
	ds_write2_b32 v145, v32, v96 offset0:232 offset1:248
	ds_write2_b32 v146, v33, v97 offset0:108 offset1:124
	v_or_b32_e32 v4, s4, v134
	s_mulk_i32 s5, 0x3000
	v_or_b32_e32 v5, s4, v132
	v_lshl_add_u64 v[2:3], v[106:107], 0, s[36:37]
	v_subrev_u32_e32 v4, s5, v4
	v_subrev_u32_e32 v100, s5, v5
	s_mov_b32 s4, 0
	s_waitcnt lgkmcnt(0)
	s_barrier
	v_lshrrev_b32_e32 v52, 4, v0
	v_and_b32_e32 v52, 15, v52
	v_and_b32_e32 v50, 15, v0
	v_lshlrev_b32_e32 v53, 4, v50
	v_lshl_or_b32 v53, v52, 11, v53
	v_mul_u32_u24_e32 v52, 0x210, v52
	v_lshl_add_u32 v52, v50, 5, v52
	s_lshl_b32 s100, s101, 11
	s_lshl_b32 s98, s73, 8
	s_add_u32 s100, s100, s98
	s_add_u32 s98, s42, s100
	s_addc_u32 s99, s43, 0
	s_add_u32 s98, s98, 0xb724000
	s_addc_u32 s99, s99, 0
	ds_read_b128 v[34:37], v52 offset:32
	ds_read_b128 v[38:41], v52 offset:48
	ds_read_b128 v[42:45], v52 offset:8480
	ds_read_b128 v[46:49], v52 offset:8496
	s_waitcnt vmcnt(7) lgkmcnt(2)
	v_lshlrev_b32_e32 v51, 16, v148
	v_mul_f32_e32 v34, v34, v51
	v_and_b32_e32 v51, 0xffff0000, v148
	v_mul_f32_e32 v35, v35, v51
	v_lshlrev_b32_e32 v51, 16, v149
	v_mul_f32_e32 v36, v36, v51
	v_and_b32_e32 v51, 0xffff0000, v149
	v_mul_f32_e32 v37, v37, v51
	v_lshlrev_b32_e32 v51, 16, v150
	v_mul_f32_e32 v38, v38, v51
	v_and_b32_e32 v51, 0xffff0000, v150
	v_mul_f32_e32 v39, v39, v51
	v_lshlrev_b32_e32 v51, 16, v151
	v_mul_f32_e32 v40, v40, v51
	v_and_b32_e32 v51, 0xffff0000, v151
	v_mul_f32_e32 v41, v41, v51
	v_cvt_pk_bf16_f32 v34, v34, v35
	v_cvt_pk_bf16_f32 v35, v36, v37
	v_cvt_pk_bf16_f32 v36, v38, v39
	v_cvt_pk_bf16_f32 v37, v40, v41
	global_store_dwordx4 v53, v[34:37], s[98:99]
	s_add_u32 s98, s98, 0x8000
	s_addc_u32 s99, s99, 0
	s_nop 1
	ds_read_b128 v[34:37], v52 offset:16928
	ds_read_b128 v[38:41], v52 offset:16944
	s_waitcnt vmcnt(7) lgkmcnt(2)
	v_lshlrev_b32_e32 v51, 16, v152
	v_mul_f32_e32 v42, v42, v51
	v_and_b32_e32 v51, 0xffff0000, v152
	v_mul_f32_e32 v43, v43, v51
	v_lshlrev_b32_e32 v51, 16, v153
	v_mul_f32_e32 v44, v44, v51
	v_and_b32_e32 v51, 0xffff0000, v153
	v_mul_f32_e32 v45, v45, v51
	v_lshlrev_b32_e32 v51, 16, v154
	v_mul_f32_e32 v46, v46, v51
	v_and_b32_e32 v51, 0xffff0000, v154
	v_mul_f32_e32 v47, v47, v51
	v_lshlrev_b32_e32 v51, 16, v155
	v_mul_f32_e32 v48, v48, v51
	v_and_b32_e32 v51, 0xffff0000, v155
	v_mul_f32_e32 v49, v49, v51
	v_cvt_pk_bf16_f32 v42, v42, v43
	v_cvt_pk_bf16_f32 v43, v44, v45
	v_cvt_pk_bf16_f32 v44, v46, v47
	v_cvt_pk_bf16_f32 v45, v48, v49
	global_store_dwordx4 v53, v[42:45], s[98:99]
	s_add_u32 s98, s98, 0x8000
	s_addc_u32 s99, s99, 0
	s_nop 1
	ds_read_b128 v[42:45], v52 offset:25376
	ds_read_b128 v[46:49], v52 offset:25392
	s_waitcnt vmcnt(7) lgkmcnt(2)
	v_lshlrev_b32_e32 v51, 16, v156
	v_mul_f32_e32 v34, v34, v51
	v_and_b32_e32 v51, 0xffff0000, v156
	v_mul_f32_e32 v35, v35, v51
	v_lshlrev_b32_e32 v51, 16, v157
	v_mul_f32_e32 v36, v36, v51
	v_and_b32_e32 v51, 0xffff0000, v157
	v_mul_f32_e32 v37, v37, v51
	v_lshlrev_b32_e32 v51, 16, v158
	v_mul_f32_e32 v38, v38, v51
	v_and_b32_e32 v51, 0xffff0000, v158
	v_mul_f32_e32 v39, v39, v51
	v_lshlrev_b32_e32 v51, 16, v159
	v_mul_f32_e32 v40, v40, v51
	v_and_b32_e32 v51, 0xffff0000, v159
	v_mul_f32_e32 v41, v41, v51
	v_cvt_pk_bf16_f32 v34, v34, v35
	v_cvt_pk_bf16_f32 v35, v36, v37
	v_cvt_pk_bf16_f32 v36, v38, v39
	v_cvt_pk_bf16_f32 v37, v40, v41
	global_store_dwordx4 v53, v[34:37], s[98:99]
	s_add_u32 s98, s98, 0x8000
	s_addc_u32 s99, s99, 0
	s_nop 1
	ds_read_b128 v[34:37], v52 offset:33824
	ds_read_b128 v[38:41], v52 offset:33840
	s_waitcnt vmcnt(7) lgkmcnt(2)
	v_lshlrev_b32_e32 v51, 16, v160
	v_mul_f32_e32 v42, v42, v51
	v_and_b32_e32 v51, 0xffff0000, v160
	v_mul_f32_e32 v43, v43, v51
	v_lshlrev_b32_e32 v51, 16, v161
	v_mul_f32_e32 v44, v44, v51
	v_and_b32_e32 v51, 0xffff0000, v161
	v_mul_f32_e32 v45, v45, v51
	v_lshlrev_b32_e32 v51, 16, v162
	v_mul_f32_e32 v46, v46, v51
	v_and_b32_e32 v51, 0xffff0000, v162
	v_mul_f32_e32 v47, v47, v51
	v_lshlrev_b32_e32 v51, 16, v163
	v_mul_f32_e32 v48, v48, v51
	v_and_b32_e32 v51, 0xffff0000, v163
	v_mul_f32_e32 v49, v49, v51
	v_cvt_pk_bf16_f32 v42, v42, v43
	v_cvt_pk_bf16_f32 v43, v44, v45
	v_cvt_pk_bf16_f32 v44, v46, v47
	v_cvt_pk_bf16_f32 v45, v48, v49
	global_store_dwordx4 v53, v[42:45], s[98:99]
	s_add_u32 s98, s98, 0x8000
	s_addc_u32 s99, s99, 0
	s_nop 1
	ds_read_b128 v[42:45], v52 offset:42272
	ds_read_b128 v[46:49], v52 offset:42288
	s_waitcnt vmcnt(7) lgkmcnt(2)
	v_lshlrev_b32_e32 v51, 16, v164
	v_mul_f32_e32 v34, v34, v51
	v_and_b32_e32 v51, 0xffff0000, v164
	v_mul_f32_e32 v35, v35, v51
	v_lshlrev_b32_e32 v51, 16, v165
	v_mul_f32_e32 v36, v36, v51
	v_and_b32_e32 v51, 0xffff0000, v165
	v_mul_f32_e32 v37, v37, v51
	v_lshlrev_b32_e32 v51, 16, v166
	v_mul_f32_e32 v38, v38, v51
	v_and_b32_e32 v51, 0xffff0000, v166
	v_mul_f32_e32 v39, v39, v51
	v_lshlrev_b32_e32 v51, 16, v167
	v_mul_f32_e32 v40, v40, v51
	v_and_b32_e32 v51, 0xffff0000, v167
	v_mul_f32_e32 v41, v41, v51
	v_cvt_pk_bf16_f32 v34, v34, v35
	v_cvt_pk_bf16_f32 v35, v36, v37
	v_cvt_pk_bf16_f32 v36, v38, v39
	v_cvt_pk_bf16_f32 v37, v40, v41
	global_store_dwordx4 v53, v[34:37], s[98:99]
	s_add_u32 s98, s98, 0x8000
	s_addc_u32 s99, s99, 0
	s_nop 1
	ds_read_b128 v[34:37], v52 offset:50720
	ds_read_b128 v[38:41], v52 offset:50736
	s_waitcnt vmcnt(7) lgkmcnt(2)
	v_lshlrev_b32_e32 v51, 16, v168
	v_mul_f32_e32 v42, v42, v51
	v_and_b32_e32 v51, 0xffff0000, v168
	v_mul_f32_e32 v43, v43, v51
	v_lshlrev_b32_e32 v51, 16, v169
	v_mul_f32_e32 v44, v44, v51
	v_and_b32_e32 v51, 0xffff0000, v169
	v_mul_f32_e32 v45, v45, v51
	v_lshlrev_b32_e32 v51, 16, v170
	v_mul_f32_e32 v46, v46, v51
	v_and_b32_e32 v51, 0xffff0000, v170
	v_mul_f32_e32 v47, v47, v51
	v_lshlrev_b32_e32 v51, 16, v171
	v_mul_f32_e32 v48, v48, v51
	v_and_b32_e32 v51, 0xffff0000, v171
	v_mul_f32_e32 v49, v49, v51
	v_cvt_pk_bf16_f32 v42, v42, v43
	v_cvt_pk_bf16_f32 v43, v44, v45
	v_cvt_pk_bf16_f32 v44, v46, v47
	v_cvt_pk_bf16_f32 v45, v48, v49
	global_store_dwordx4 v53, v[42:45], s[98:99]
	s_add_u32 s98, s98, 0x8000
	s_addc_u32 s99, s99, 0
	s_nop 1
	ds_read_b128 v[42:45], v52 offset:59168
	ds_read_b128 v[46:49], v52 offset:59184
	s_waitcnt vmcnt(7) lgkmcnt(2)
	v_lshlrev_b32_e32 v51, 16, v172
	v_mul_f32_e32 v34, v34, v51
	v_and_b32_e32 v51, 0xffff0000, v172
	v_mul_f32_e32 v35, v35, v51
	v_lshlrev_b32_e32 v51, 16, v173
	v_mul_f32_e32 v36, v36, v51
	v_and_b32_e32 v51, 0xffff0000, v173
	v_mul_f32_e32 v37, v37, v51
	v_lshlrev_b32_e32 v51, 16, v174
	v_mul_f32_e32 v38, v38, v51
	v_and_b32_e32 v51, 0xffff0000, v174
	v_mul_f32_e32 v39, v39, v51
	v_lshlrev_b32_e32 v51, 16, v175
	v_mul_f32_e32 v40, v40, v51
	v_and_b32_e32 v51, 0xffff0000, v175
	v_mul_f32_e32 v41, v41, v51
	v_cvt_pk_bf16_f32 v34, v34, v35
	v_cvt_pk_bf16_f32 v35, v36, v37
	v_cvt_pk_bf16_f32 v36, v38, v39
	v_cvt_pk_bf16_f32 v37, v40, v41
	global_store_dwordx4 v53, v[34:37], s[98:99]
	s_add_u32 s98, s98, 0x8000
	s_addc_u32 s99, s99, 0
	s_waitcnt vmcnt(7) lgkmcnt(0)
	v_lshlrev_b32_e32 v51, 16, v176
	v_mul_f32_e32 v42, v42, v51
	v_and_b32_e32 v51, 0xffff0000, v176
	v_mul_f32_e32 v43, v43, v51
	v_lshlrev_b32_e32 v51, 16, v177
	v_mul_f32_e32 v44, v44, v51
	v_and_b32_e32 v51, 0xffff0000, v177
	v_mul_f32_e32 v45, v45, v51
	v_lshlrev_b32_e32 v51, 16, v178
	v_mul_f32_e32 v46, v46, v51
	v_and_b32_e32 v51, 0xffff0000, v178
	v_mul_f32_e32 v47, v47, v51
	v_lshlrev_b32_e32 v51, 16, v179
	v_mul_f32_e32 v48, v48, v51
	v_and_b32_e32 v51, 0xffff0000, v179
	v_mul_f32_e32 v49, v49, v51
	v_cvt_pk_bf16_f32 v42, v42, v43
	v_cvt_pk_bf16_f32 v43, v44, v45
	v_cvt_pk_bf16_f32 v44, v46, v47
	v_cvt_pk_bf16_f32 v45, v48, v49
	global_store_dwordx4 v53, v[42:45], s[98:99]
	s_add_i32 s69, s69, s62
	s_add_i32 s68, s68, 1
	s_cmpk_gt_u32 s69, 0x5f
	s_cbranch_scc0 .LBB0_1292
	v_readlane_b32 s70, v255, 18
	v_readlane_b32 s71, v255, 19
	v_readlane_b32 s66, v255, 16
	v_readlane_b32 s67, v255, 17

.LBB0_1372:
	s_and_b32 s28, s11, 0xff
	s_mul_i32 s2, s28, 0xab
	s_lshr_b32 s29, s2, 11
	s_mul_i32 s2, s29, 12
	s_sub_i32 s2, s11, s2
	s_and_b32 s2, s2, 0xff
	s_lshl_b32 s2, s2, 21
	s_or_b32 s2, s2, s21
	s_add_u32 s14, s16, s2
	s_addc_u32 s15, s17, 0
	s_lshl_b32 s2, s29, 18
	s_add_u32 s12, s18, s2
	s_addc_u32 s13, s19, 0
	v_and_b32_e32 v162, 15, v0
	v_bfe_u32 v163, v0, 4, 2
	v_and_b32_e32 v107, 7, v162
	v_xor_b32_e32 v163, v163, v107
	v_lshlrev_b32_e32 v163, 4, v163
	v_lshl_or_b32 v163, v162, 7, v163
	v_bfe_u32 v162, v0, 7, 1
	v_lshl_or_b32 v98, v162, 13, v163
	v_bfe_u32 v162, v0, 6, 1
	v_lshl_or_b32 v156, v162, 13, v163
	v_or_b32_e32 v156, 0x4000, v156
	v_xor_b32_e32 v107, 64, v98
	v_xor_b32_e32 v157, 64, v156
	v_bfe_u32 v162, v0, 3, 3
	v_and_b32_e32 v163, 7, v0
	v_xor_b32_e32 v163, v163, v162
	v_lshlrev_b32_e32 v163, 4, v163
	v_lshl_or_b32 v163, v162, 11, v163
	v_lshrrev_b32_e32 v162, 6, v0
	v_and_b32_e32 v162, 3, v162
	v_lshl_or_b32 v158, v162, 16, v163
	v_add_u32_e32 v159, 0x3c00, v158
	v_add_u32_e32 v160, 0x7800, v158
	v_add_u32_e32 v161, 0xb400, v158
	v_lshlrev_b32_e32 v162, 12, v162
	s_nop 0
	v_readfirstlane_b32 s31, v162
	s_add_u32 s31, s31, 32
	v_mov_b32_e32 v94, 0
	v_mov_b32_e32 v95, 0
	v_mov_b32_e32 v96, 0
	v_mov_b32_e32 v97, 0
	v_mov_b32_e32 v90, 0
	v_mov_b32_e32 v91, 0
	v_mov_b32_e32 v92, 0
	v_mov_b32_e32 v93, 0
	v_mov_b32_e32 v82, 0
	v_mov_b32_e32 v83, 0
	v_mov_b32_e32 v84, 0
	v_mov_b32_e32 v85, 0
	v_mov_b32_e32 v78, 0
	v_mov_b32_e32 v79, 0
	v_mov_b32_e32 v80, 0
	v_mov_b32_e32 v81, 0
	v_mov_b32_e32 v74, 0
	v_mov_b32_e32 v75, 0
	v_mov_b32_e32 v76, 0
	v_mov_b32_e32 v77, 0
	v_mov_b32_e32 v70, 0
	v_mov_b32_e32 v71, 0
	v_mov_b32_e32 v72, 0
	v_mov_b32_e32 v73, 0
	v_mov_b32_e32 v66, 0
	v_mov_b32_e32 v67, 0
	v_mov_b32_e32 v68, 0
	v_mov_b32_e32 v69, 0
	v_mov_b32_e32 v62, 0
	v_mov_b32_e32 v63, 0
	v_mov_b32_e32 v64, 0
	v_mov_b32_e32 v65, 0
	v_mov_b32_e32 v58, 0
	v_mov_b32_e32 v59, 0
	v_mov_b32_e32 v60, 0
	v_mov_b32_e32 v61, 0
	v_mov_b32_e32 v42, 0
	v_mov_b32_e32 v43, 0
	v_mov_b32_e32 v44, 0
	v_mov_b32_e32 v45, 0
	v_mov_b32_e32 v22, 0
	v_mov_b32_e32 v23, 0
	v_mov_b32_e32 v24, 0
	v_mov_b32_e32 v25, 0
	v_mov_b32_e32 v14, 0
	v_mov_b32_e32 v15, 0
	v_mov_b32_e32 v16, 0
	v_mov_b32_e32 v17, 0
	v_mov_b32_e32 v10, 0
	v_mov_b32_e32 v11, 0
	v_mov_b32_e32 v12, 0
	v_mov_b32_e32 v13, 0
	v_mov_b32_e32 v6, 0
	v_mov_b32_e32 v7, 0
	v_mov_b32_e32 v8, 0
	v_mov_b32_e32 v9, 0
	v_mov_b32_e32 v2, 0
	v_mov_b32_e32 v3, 0
	v_mov_b32_e32 v4, 0
	v_mov_b32_e32 v5, 0
	v_mov_b32_e32 v86, 0
	v_mov_b32_e32 v87, 0
	v_mov_b32_e32 v88, 0
	v_mov_b32_e32 v89, 0
	v_mov_b32_e32 v108, 0
	v_mov_b32_e32 v109, 0
	v_mov_b32_e32 v110, 0
	v_mov_b32_e32 v111, 0
	v_mov_b32_e32 v112, 0
	v_mov_b32_e32 v113, 0
	v_mov_b32_e32 v114, 0
	v_mov_b32_e32 v115, 0
	v_mov_b32_e32 v116, 0
	v_mov_b32_e32 v117, 0
	v_mov_b32_e32 v118, 0
	v_mov_b32_e32 v119, 0
	v_mov_b32_e32 v136, 0
	v_mov_b32_e32 v137, 0
	v_mov_b32_e32 v138, 0
	v_mov_b32_e32 v139, 0
	v_mov_b32_e32 v140, 0
	v_mov_b32_e32 v141, 0
	v_mov_b32_e32 v142, 0
	v_mov_b32_e32 v143, 0
	v_mov_b32_e32 v144, 0
	v_mov_b32_e32 v145, 0
	v_mov_b32_e32 v146, 0
	v_mov_b32_e32 v147, 0
	v_mov_b32_e32 v148, 0
	v_mov_b32_e32 v149, 0
	v_mov_b32_e32 v150, 0
	v_mov_b32_e32 v151, 0
	v_mov_b32_e32 v152, 0
	v_mov_b32_e32 v153, 0
	v_mov_b32_e32 v154, 0
	v_mov_b32_e32 v155, 0
	s_waitcnt lgkmcnt(0)
	s_barrier
	v_readlane_b32 s98, v255, 16
	s_and_b32 s98, s98, 7
	s_lshl_b32 s98, s98, 1
	s_lshl_b32 s99, s98, 7
	s_add_u32 s14, s14, s99
	s_addc_u32 s15, s15, 0
	s_add_u32 s12, s12, s99
	s_addc_u32 s13, s13, 0
	s_add_u32 m0, s31, 0
	s_nop 0
	global_load_lds_dwordx4 v158, s[14:15] offset:0
	global_load_lds_dwordx4 v159, s[14:15] offset:1024
	global_load_lds_dwordx4 v160, s[14:15] offset:2048
	global_load_lds_dwordx4 v161, s[14:15] offset:3072
	s_add_u32 m0, s31, 16384
	s_nop 0
	global_load_lds_dwordx4 v158, s[12:13] offset:0
	global_load_lds_dwordx4 v159, s[12:13] offset:1024
	global_load_lds_dwordx4 v160, s[12:13] offset:2048
	global_load_lds_dwordx4 v161, s[12:13] offset:3072
	s_add_u32 s98, s98, 1
	s_and_b32 s98, s98, 15
	s_cmp_eq_u32 s98, 0
	s_cselect_b32 s99, 0x800, 0
	s_add_u32 s14, s14, 0x80
	s_addc_u32 s15, s15, 0
	s_sub_u32 s14, s14, s99
	s_subb_u32 s15, s15, 0
	s_add_u32 s12, s12, 0x80
	s_addc_u32 s13, s13, 0
	s_sub_u32 s12, s12, s99
	s_subb_u32 s13, s13, 0
	s_mov_b32 s30, 0
	s_waitcnt vmcnt(0)
	s_setprio 1
.Lk_outl1_loop:
	s_barrier
	s_add_u32 m0, s31, 32768
	v_mfma_f32_16x16x32_bf16 v[94:97], v[108:111], v[140:143], v[94:97]
	ds_read_b128 v[18:21], v98 offset:32
	global_load_lds_dwordx4 v158, s[14:15] offset:0
	v_mfma_f32_16x16x32_bf16 v[90:93], v[108:111], v[144:147], v[90:93]
	ds_read_b128 v[38:41], v156 offset:32
	global_load_lds_dwordx4 v159, s[14:15] offset:1024
	v_mfma_f32_16x16x32_bf16 v[82:85], v[108:111], v[148:151], v[82:85]
	ds_read_b128 v[46:49], v156 offset:2080
	global_load_lds_dwordx4 v160, s[14:15] offset:2048
	v_mfma_f32_16x16x32_bf16 v[78:81], v[108:111], v[152:155], v[78:81]
	ds_read_b128 v[26:29], v98 offset:2080
	global_load_lds_dwordx4 v161, s[14:15] offset:3072
	s_add_u32 m0, s31, 49152
	v_mfma_f32_16x16x32_bf16 v[74:77], v[112:115], v[140:143], v[74:77]
	ds_read_b128 v[50:53], v156 offset:4128
	global_load_lds_dwordx4 v158, s[12:13] offset:0
	v_mfma_f32_16x16x32_bf16 v[70:73], v[112:115], v[144:147], v[70:73]
	ds_read_b128 v[54:57], v156 offset:6176
	global_load_lds_dwordx4 v159, s[12:13] offset:1024
	v_mfma_f32_16x16x32_bf16 v[66:69], v[112:115], v[148:151], v[66:69]
	ds_read_b128 v[30:33], v98 offset:4128
	global_load_lds_dwordx4 v160, s[12:13] offset:2048
	v_mfma_f32_16x16x32_bf16 v[62:65], v[112:115], v[152:155], v[62:65]
	ds_read_b128 v[34:37], v98 offset:6176
	global_load_lds_dwordx4 v161, s[12:13] offset:3072
	v_mfma_f32_16x16x32_bf16 v[58:61], v[116:119], v[140:143], v[58:61]
	v_mfma_f32_16x16x32_bf16 v[42:45], v[116:119], v[144:147], v[42:45]
	v_mfma_f32_16x16x32_bf16 v[22:25], v[116:119], v[148:151], v[22:25]
	v_mfma_f32_16x16x32_bf16 v[14:17], v[116:119], v[152:155], v[14:17]
	v_mfma_f32_16x16x32_bf16 v[10:13], v[136:139], v[140:143], v[10:13]
	v_mfma_f32_16x16x32_bf16 v[6:9], v[136:139], v[144:147], v[6:9]
	v_mfma_f32_16x16x32_bf16 v[2:5], v[136:139], v[148:151], v[2:5]
	v_mfma_f32_16x16x32_bf16 v[86:89], v[136:139], v[152:155], v[86:89]
	s_add_u32 s98, s98, 1
	s_and_b32 s98, s98, 15
	s_cmp_eq_u32 s98, 0
	s_cselect_b32 s99, 0x800, 0
	s_add_u32 s14, s14, 0x80
	s_addc_u32 s15, s15, 0
	s_sub_u32 s14, s14, s99
	s_subb_u32 s15, s15, 0
	s_add_u32 s12, s12, 0x80
	s_addc_u32 s13, s13, 0
	s_sub_u32 s12, s12, s99
	s_subb_u32 s13, s13, 0
	s_waitcnt lgkmcnt(0)
	v_mfma_f32_16x16x32_bf16 v[94:97], v[18:21], v[38:41], v[94:97]
	ds_read_b128 v[108:111], v107 offset:32
	v_mfma_f32_16x16x32_bf16 v[90:93], v[18:21], v[46:49], v[90:93]
	ds_read_b128 v[140:143], v157 offset:32
	v_mfma_f32_16x16x32_bf16 v[82:85], v[18:21], v[50:53], v[82:85]
	ds_read_b128 v[144:147], v157 offset:2080
	v_mfma_f32_16x16x32_bf16 v[78:81], v[18:21], v[54:57], v[78:81]
	ds_read_b128 v[112:115], v107 offset:2080
	v_mfma_f32_16x16x32_bf16 v[74:77], v[26:29], v[38:41], v[74:77]
	ds_read_b128 v[148:151], v157 offset:4128
	v_mfma_f32_16x16x32_bf16 v[70:73], v[26:29], v[46:49], v[70:73]
	ds_read_b128 v[152:155], v157 offset:6176
	v_mfma_f32_16x16x32_bf16 v[66:69], v[26:29], v[50:53], v[66:69]
	ds_read_b128 v[116:119], v107 offset:4128
	v_mfma_f32_16x16x32_bf16 v[62:65], v[26:29], v[54:57], v[62:65]
	ds_read_b128 v[136:139], v107 offset:6176
	v_mfma_f32_16x16x32_bf16 v[58:61], v[30:33], v[38:41], v[58:61]
	v_mfma_f32_16x16x32_bf16 v[42:45], v[30:33], v[46:49], v[42:45]
	v_mfma_f32_16x16x32_bf16 v[22:25], v[30:33], v[50:53], v[22:25]
	v_mfma_f32_16x16x32_bf16 v[14:17], v[30:33], v[54:57], v[14:17]
	v_mfma_f32_16x16x32_bf16 v[10:13], v[34:37], v[38:41], v[10:13]
	v_mfma_f32_16x16x32_bf16 v[6:9], v[34:37], v[46:49], v[6:9]
	v_mfma_f32_16x16x32_bf16 v[2:5], v[34:37], v[50:53], v[2:5]
	v_mfma_f32_16x16x32_bf16 v[86:89], v[34:37], v[54:57], v[86:89]
	s_waitcnt lgkmcnt(0)
	s_waitcnt vmcnt(0)
	s_barrier
	s_add_u32 m0, s31, 0
	v_mfma_f32_16x16x32_bf16 v[94:97], v[108:111], v[140:143], v[94:97]
	ds_read_b128 v[18:21], v98 offset:32800
	global_load_lds_dwordx4 v158, s[14:15] offset:0
	v_mfma_f32_16x16x32_bf16 v[90:93], v[108:111], v[144:147], v[90:93]
	ds_read_b128 v[38:41], v156 offset:32800
	global_load_lds_dwordx4 v159, s[14:15] offset:1024
	v_mfma_f32_16x16x32_bf16 v[82:85], v[108:111], v[148:151], v[82:85]
	ds_read_b128 v[46:49], v156 offset:34848
	global_load_lds_dwordx4 v160, s[14:15] offset:2048
	v_mfma_f32_16x16x32_bf16 v[78:81], v[108:111], v[152:155], v[78:81]
	ds_read_b128 v[26:29], v98 offset:34848
	global_load_lds_dwordx4 v161, s[14:15] offset:3072
	s_add_u32 m0, s31, 16384
	v_mfma_f32_16x16x32_bf16 v[74:77], v[112:115], v[140:143], v[74:77]
	ds_read_b128 v[50:53], v156 offset:36896
	global_load_lds_dwordx4 v158, s[12:13] offset:0
	v_mfma_f32_16x16x32_bf16 v[70:73], v[112:115], v[144:147], v[70:73]
	ds_read_b128 v[54:57], v156 offset:38944
	global_load_lds_dwordx4 v159, s[12:13] offset:1024
	v_mfma_f32_16x16x32_bf16 v[66:69], v[112:115], v[148:151], v[66:69]
	ds_read_b128 v[30:33], v98 offset:36896
	global_load_lds_dwordx4 v160, s[12:13] offset:2048
	v_mfma_f32_16x16x32_bf16 v[62:65], v[112:115], v[152:155], v[62:65]
	ds_read_b128 v[34:37], v98 offset:38944
	global_load_lds_dwordx4 v161, s[12:13] offset:3072
	v_mfma_f32_16x16x32_bf16 v[58:61], v[116:119], v[140:143], v[58:61]
	v_mfma_f32_16x16x32_bf16 v[42:45], v[116:119], v[144:147], v[42:45]
	v_mfma_f32_16x16x32_bf16 v[22:25], v[116:119], v[148:151], v[22:25]
	v_mfma_f32_16x16x32_bf16 v[14:17], v[116:119], v[152:155], v[14:17]
	v_mfma_f32_16x16x32_bf16 v[10:13], v[136:139], v[140:143], v[10:13]
	v_mfma_f32_16x16x32_bf16 v[6:9], v[136:139], v[144:147], v[6:9]
	v_mfma_f32_16x16x32_bf16 v[2:5], v[136:139], v[148:151], v[2:5]
	v_mfma_f32_16x16x32_bf16 v[86:89], v[136:139], v[152:155], v[86:89]
	s_add_u32 s98, s98, 1
	s_and_b32 s98, s98, 15
	s_cmp_eq_u32 s98, 0
	s_cselect_b32 s99, 0x800, 0
	s_add_u32 s14, s14, 0x80
	s_addc_u32 s15, s15, 0
	s_sub_u32 s14, s14, s99
	s_subb_u32 s15, s15, 0
	s_add_u32 s12, s12, 0x80
	s_addc_u32 s13, s13, 0
	s_sub_u32 s12, s12, s99
	s_subb_u32 s13, s13, 0
	s_waitcnt lgkmcnt(0)
	v_mfma_f32_16x16x32_bf16 v[94:97], v[18:21], v[38:41], v[94:97]
	ds_read_b128 v[108:111], v107 offset:32800
	v_mfma_f32_16x16x32_bf16 v[90:93], v[18:21], v[46:49], v[90:93]
	ds_read_b128 v[140:143], v157 offset:32800
	v_mfma_f32_16x16x32_bf16 v[82:85], v[18:21], v[50:53], v[82:85]
	ds_read_b128 v[144:147], v157 offset:34848
	v_mfma_f32_16x16x32_bf16 v[78:81], v[18:21], v[54:57], v[78:81]
	ds_read_b128 v[112:115], v107 offset:34848
	v_mfma_f32_16x16x32_bf16 v[74:77], v[26:29], v[38:41], v[74:77]
	ds_read_b128 v[148:151], v157 offset:36896
	v_mfma_f32_16x16x32_bf16 v[70:73], v[26:29], v[46:49], v[70:73]
	ds_read_b128 v[152:155], v157 offset:38944
	v_mfma_f32_16x16x32_bf16 v[66:69], v[26:29], v[50:53], v[66:69]
	ds_read_b128 v[116:119], v107 offset:36896
	v_mfma_f32_16x16x32_bf16 v[62:65], v[26:29], v[54:57], v[62:65]
	ds_read_b128 v[136:139], v107 offset:38944
	v_mfma_f32_16x16x32_bf16 v[58:61], v[30:33], v[38:41], v[58:61]
	v_mfma_f32_16x16x32_bf16 v[42:45], v[30:33], v[46:49], v[42:45]
	v_mfma_f32_16x16x32_bf16 v[22:25], v[30:33], v[50:53], v[22:25]
	v_mfma_f32_16x16x32_bf16 v[14:17], v[30:33], v[54:57], v[14:17]
	v_mfma_f32_16x16x32_bf16 v[10:13], v[34:37], v[38:41], v[10:13]
	v_mfma_f32_16x16x32_bf16 v[6:9], v[34:37], v[46:49], v[6:9]
	v_mfma_f32_16x16x32_bf16 v[2:5], v[34:37], v[50:53], v[2:5]
	v_mfma_f32_16x16x32_bf16 v[86:89], v[34:37], v[54:57], v[86:89]
	s_waitcnt lgkmcnt(0)
	s_waitcnt vmcnt(0)
	s_add_u32 s30, s30, 1
	s_cmp_lt_u32 s30, 7
	s_cbranch_scc1 .Lk_outl1_loop
	s_barrier
	s_add_u32 m0, s31, 32768
	v_mfma_f32_16x16x32_bf16 v[94:97], v[108:111], v[140:143], v[94:97]
	ds_read_b128 v[18:21], v98 offset:32
	global_load_lds_dwordx4 v158, s[14:15] offset:0
	v_mfma_f32_16x16x32_bf16 v[90:93], v[108:111], v[144:147], v[90:93]
	ds_read_b128 v[38:41], v156 offset:32
	global_load_lds_dwordx4 v159, s[14:15] offset:1024
	v_mfma_f32_16x16x32_bf16 v[82:85], v[108:111], v[148:151], v[82:85]
	ds_read_b128 v[46:49], v156 offset:2080
	global_load_lds_dwordx4 v160, s[14:15] offset:2048
	v_mfma_f32_16x16x32_bf16 v[78:81], v[108:111], v[152:155], v[78:81]
	ds_read_b128 v[26:29], v98 offset:2080
	global_load_lds_dwordx4 v161, s[14:15] offset:3072
	s_add_u32 m0, s31, 49152
	v_mfma_f32_16x16x32_bf16 v[74:77], v[112:115], v[140:143], v[74:77]
	ds_read_b128 v[50:53], v156 offset:4128
	global_load_lds_dwordx4 v158, s[12:13] offset:0
	v_mfma_f32_16x16x32_bf16 v[70:73], v[112:115], v[144:147], v[70:73]
	ds_read_b128 v[54:57], v156 offset:6176
	global_load_lds_dwordx4 v159, s[12:13] offset:1024
	v_mfma_f32_16x16x32_bf16 v[66:69], v[112:115], v[148:151], v[66:69]
	ds_read_b128 v[30:33], v98 offset:4128
	global_load_lds_dwordx4 v160, s[12:13] offset:2048
	v_mfma_f32_16x16x32_bf16 v[62:65], v[112:115], v[152:155], v[62:65]
	ds_read_b128 v[34:37], v98 offset:6176
	global_load_lds_dwordx4 v161, s[12:13] offset:3072
	v_mfma_f32_16x16x32_bf16 v[58:61], v[116:119], v[140:143], v[58:61]
	v_mfma_f32_16x16x32_bf16 v[42:45], v[116:119], v[144:147], v[42:45]
	v_mfma_f32_16x16x32_bf16 v[22:25], v[116:119], v[148:151], v[22:25]
	v_mfma_f32_16x16x32_bf16 v[14:17], v[116:119], v[152:155], v[14:17]
	v_mfma_f32_16x16x32_bf16 v[10:13], v[136:139], v[140:143], v[10:13]
	v_mfma_f32_16x16x32_bf16 v[6:9], v[136:139], v[144:147], v[6:9]
	v_mfma_f32_16x16x32_bf16 v[2:5], v[136:139], v[148:151], v[2:5]
	v_mfma_f32_16x16x32_bf16 v[86:89], v[136:139], v[152:155], v[86:89]
	s_add_u32 s98, s98, 1
	s_and_b32 s98, s98, 15
	s_cmp_eq_u32 s98, 0
	s_cselect_b32 s99, 0x800, 0
	s_add_u32 s14, s14, 0x80
	s_addc_u32 s15, s15, 0
	s_sub_u32 s14, s14, s99
	s_subb_u32 s15, s15, 0
	s_add_u32 s12, s12, 0x80
	s_addc_u32 s13, s13, 0
	s_sub_u32 s12, s12, s99
	s_subb_u32 s13, s13, 0
	s_waitcnt lgkmcnt(0)
	v_mfma_f32_16x16x32_bf16 v[94:97], v[18:21], v[38:41], v[94:97]
	ds_read_b128 v[108:111], v107 offset:32
	v_mfma_f32_16x16x32_bf16 v[90:93], v[18:21], v[46:49], v[90:93]
	ds_read_b128 v[140:143], v157 offset:32
	v_mfma_f32_16x16x32_bf16 v[82:85], v[18:21], v[50:53], v[82:85]
	ds_read_b128 v[144:147], v157 offset:2080
	v_mfma_f32_16x16x32_bf16 v[78:81], v[18:21], v[54:57], v[78:81]
	ds_read_b128 v[112:115], v107 offset:2080
	v_mfma_f32_16x16x32_bf16 v[74:77], v[26:29], v[38:41], v[74:77]
	ds_read_b128 v[148:151], v157 offset:4128
	v_mfma_f32_16x16x32_bf16 v[70:73], v[26:29], v[46:49], v[70:73]
	ds_read_b128 v[152:155], v157 offset:6176
	v_mfma_f32_16x16x32_bf16 v[66:69], v[26:29], v[50:53], v[66:69]
	ds_read_b128 v[116:119], v107 offset:4128
	v_mfma_f32_16x16x32_bf16 v[62:65], v[26:29], v[54:57], v[62:65]
	ds_read_b128 v[136:139], v107 offset:6176
	v_mfma_f32_16x16x32_bf16 v[58:61], v[30:33], v[38:41], v[58:61]
	v_mfma_f32_16x16x32_bf16 v[42:45], v[30:33], v[46:49], v[42:45]
	v_mfma_f32_16x16x32_bf16 v[22:25], v[30:33], v[50:53], v[22:25]
	v_mfma_f32_16x16x32_bf16 v[14:17], v[30:33], v[54:57], v[14:17]
	v_mfma_f32_16x16x32_bf16 v[10:13], v[34:37], v[38:41], v[10:13]
	v_mfma_f32_16x16x32_bf16 v[6:9], v[34:37], v[46:49], v[6:9]
	v_mfma_f32_16x16x32_bf16 v[2:5], v[34:37], v[50:53], v[2:5]
	v_mfma_f32_16x16x32_bf16 v[86:89], v[34:37], v[54:57], v[86:89]
	s_waitcnt lgkmcnt(0)
	s_waitcnt vmcnt(0)
	s_barrier
	v_mfma_f32_16x16x32_bf16 v[94:97], v[108:111], v[140:143], v[94:97]
	ds_read_b128 v[18:21], v98 offset:32800
	v_mfma_f32_16x16x32_bf16 v[90:93], v[108:111], v[144:147], v[90:93]
	ds_read_b128 v[38:41], v156 offset:32800
	v_mfma_f32_16x16x32_bf16 v[82:85], v[108:111], v[148:151], v[82:85]
	ds_read_b128 v[46:49], v156 offset:34848
	v_mfma_f32_16x16x32_bf16 v[78:81], v[108:111], v[152:155], v[78:81]
	ds_read_b128 v[26:29], v98 offset:34848
	v_mfma_f32_16x16x32_bf16 v[74:77], v[112:115], v[140:143], v[74:77]
	ds_read_b128 v[50:53], v156 offset:36896
	v_mfma_f32_16x16x32_bf16 v[70:73], v[112:115], v[144:147], v[70:73]
	ds_read_b128 v[54:57], v156 offset:38944
	v_mfma_f32_16x16x32_bf16 v[66:69], v[112:115], v[148:151], v[66:69]
	ds_read_b128 v[30:33], v98 offset:36896
	v_mfma_f32_16x16x32_bf16 v[62:65], v[112:115], v[152:155], v[62:65]
	ds_read_b128 v[34:37], v98 offset:38944
	v_mfma_f32_16x16x32_bf16 v[58:61], v[116:119], v[140:143], v[58:61]
	v_mfma_f32_16x16x32_bf16 v[42:45], v[116:119], v[144:147], v[42:45]
	v_mfma_f32_16x16x32_bf16 v[22:25], v[116:119], v[148:151], v[22:25]
	v_mfma_f32_16x16x32_bf16 v[14:17], v[116:119], v[152:155], v[14:17]
	v_mfma_f32_16x16x32_bf16 v[10:13], v[136:139], v[140:143], v[10:13]
	v_mfma_f32_16x16x32_bf16 v[6:9], v[136:139], v[144:147], v[6:9]
	v_mfma_f32_16x16x32_bf16 v[2:5], v[136:139], v[148:151], v[2:5]
	v_mfma_f32_16x16x32_bf16 v[86:89], v[136:139], v[152:155], v[86:89]
	s_waitcnt lgkmcnt(0)
	v_mfma_f32_16x16x32_bf16 v[94:97], v[18:21], v[38:41], v[94:97]
	ds_read_b128 v[108:111], v107 offset:32800
	v_mfma_f32_16x16x32_bf16 v[90:93], v[18:21], v[46:49], v[90:93]
	ds_read_b128 v[140:143], v157 offset:32800
	v_mfma_f32_16x16x32_bf16 v[82:85], v[18:21], v[50:53], v[82:85]
	ds_read_b128 v[144:147], v157 offset:34848
	v_mfma_f32_16x16x32_bf16 v[78:81], v[18:21], v[54:57], v[78:81]
	ds_read_b128 v[112:115], v107 offset:34848
	v_mfma_f32_16x16x32_bf16 v[74:77], v[26:29], v[38:41], v[74:77]
	ds_read_b128 v[148:151], v157 offset:36896
	v_mfma_f32_16x16x32_bf16 v[70:73], v[26:29], v[46:49], v[70:73]
	ds_read_b128 v[152:155], v157 offset:38944
	v_mfma_f32_16x16x32_bf16 v[66:69], v[26:29], v[50:53], v[66:69]
	ds_read_b128 v[116:119], v107 offset:36896
	v_mfma_f32_16x16x32_bf16 v[62:65], v[26:29], v[54:57], v[62:65]
	ds_read_b128 v[136:139], v107 offset:38944
	v_mfma_f32_16x16x32_bf16 v[58:61], v[30:33], v[38:41], v[58:61]
	v_mfma_f32_16x16x32_bf16 v[42:45], v[30:33], v[46:49], v[42:45]
	v_mfma_f32_16x16x32_bf16 v[22:25], v[30:33], v[50:53], v[22:25]
	v_mfma_f32_16x16x32_bf16 v[14:17], v[30:33], v[54:57], v[14:17]
	v_mfma_f32_16x16x32_bf16 v[10:13], v[34:37], v[38:41], v[10:13]
	v_mfma_f32_16x16x32_bf16 v[6:9], v[34:37], v[46:49], v[6:9]
	v_mfma_f32_16x16x32_bf16 v[2:5], v[34:37], v[50:53], v[2:5]
	v_mfma_f32_16x16x32_bf16 v[86:89], v[34:37], v[54:57], v[86:89]
	s_waitcnt lgkmcnt(0)
	v_mfma_f32_16x16x32_bf16 v[94:97], v[108:111], v[140:143], v[94:97]
	v_mfma_f32_16x16x32_bf16 v[90:93], v[108:111], v[144:147], v[90:93]
	v_mfma_f32_16x16x32_bf16 v[82:85], v[108:111], v[148:151], v[82:85]
	v_mfma_f32_16x16x32_bf16 v[78:81], v[108:111], v[152:155], v[78:81]
	v_mfma_f32_16x16x32_bf16 v[74:77], v[112:115], v[140:143], v[74:77]
	v_mfma_f32_16x16x32_bf16 v[70:73], v[112:115], v[144:147], v[70:73]
	v_mfma_f32_16x16x32_bf16 v[66:69], v[112:115], v[148:151], v[66:69]
	v_mfma_f32_16x16x32_bf16 v[62:65], v[112:115], v[152:155], v[62:65]
	v_mfma_f32_16x16x32_bf16 v[58:61], v[116:119], v[140:143], v[58:61]
	v_mfma_f32_16x16x32_bf16 v[42:45], v[116:119], v[144:147], v[42:45]
	v_mfma_f32_16x16x32_bf16 v[22:25], v[116:119], v[148:151], v[22:25]
	v_mfma_f32_16x16x32_bf16 v[14:17], v[116:119], v[152:155], v[14:17]
	v_mfma_f32_16x16x32_bf16 v[10:13], v[136:139], v[140:143], v[10:13]
	v_mfma_f32_16x16x32_bf16 v[6:9], v[136:139], v[144:147], v[6:9]
	v_mfma_f32_16x16x32_bf16 v[2:5], v[136:139], v[148:151], v[2:5]
	v_mfma_f32_16x16x32_bf16 v[86:89], v[136:139], v[152:155], v[86:89]
	s_setprio 0
	s_mul_i32 s12, s29, 12
	s_sub_u32 s12, s28, s12
	v_readlane_b32 s13, v255, 16
	s_and_b32 s13, s13, 7
	s_lshl_b32 s12, s12, 3
	s_or_b32 s12, s12, s13
	s_lshl_b32 s100, s12, 7
	s_lshl_b32 s101, s29, 9
	v_lshrrev_b32_e32 v112, 5, v0
	v_and_b32_e32 v112, 7, v112
	v_and_b32_e32 v113, 31, v0
	v_lshlrev_b32_e32 v113, 4, v113
	v_lshl_or_b32 v112, v112, 12, v113
	s_sub_u32 s12, s100, 0x2000
	s_lshr_b32 s12, s12, 10
	s_add_u32 s12, s12, 1
	s_cmp_lt_u32 s100, 0x2000
	s_cselect_b32 s12, 0, s12
	s_mul_i32 s12, s12, 0x6000
	s_add_u32 s12, s12, s101
	s_add_u32 s14, s42, s12
	s_addc_u32 s15, s43, 0
	s_add_u32 s14, s14, 0x6ec4000
	s_addc_u32 s15, s15, 0
	global_load_dwordx4 v[108:111], v113, s[14:15]
	s_lshl_b32 s12, s100, 12
	s_add_u32 s12, s12, s101
	s_add_u32 s14, s42, s12
	s_addc_u32 s15, s43, 0
	s_add_u32 s14, s14, 0x6f24000
	s_addc_u32 s15, s15, 0
	global_load_dwordx4 v[136:139], v112, s[14:15] nt
	s_add_u32 s14, s14, 0x8000
	s_addc_u32 s15, s15, 0
	global_load_dwordx4 v[140:143], v112, s[14:15] nt
	s_add_u32 s14, s14, 0x8000
	s_addc_u32 s15, s15, 0
	global_load_dwordx4 v[144:147], v112, s[14:15] nt
	s_add_u32 s14, s14, 0x8000
	s_addc_u32 s15, s15, 0
	global_load_dwordx4 v[148:151], v112, s[14:15] nt
	s_add_u32 s14, s14, 0x8000
	s_addc_u32 s15, s15, 0
	global_load_dwordx4 v[152:155], v112, s[14:15] nt
	s_add_u32 s14, s14, 0x8000
	s_addc_u32 s15, s15, 0
	global_load_dwordx4 v[156:159], v112, s[14:15] nt
	s_add_u32 s14, s14, 0x8000
	s_addc_u32 s15, s15, 0
	global_load_dwordx4 v[160:163], v112, s[14:15] nt
	s_add_u32 s14, s14, 0x8000
	s_addc_u32 s15, s15, 0
	global_load_dwordx4 v[164:167], v112, s[14:15] nt
	s_add_u32 s14, s14, 0x8000
	s_addc_u32 s15, s15, 0
	global_load_dwordx4 v[168:171], v112, s[14:15] nt
	s_add_u32 s14, s14, 0x8000
	s_addc_u32 s15, s15, 0
	global_load_dwordx4 v[172:175], v112, s[14:15] nt
	s_add_u32 s14, s14, 0x8000
	s_addc_u32 s15, s15, 0
	global_load_dwordx4 v[176:179], v112, s[14:15] nt
	s_add_u32 s14, s14, 0x8000
	s_addc_u32 s15, s15, 0
	global_load_dwordx4 v[180:183], v112, s[14:15] nt
	s_add_u32 s14, s14, 0x8000
	s_addc_u32 s15, s15, 0
	global_load_dwordx4 v[184:187], v112, s[14:15] nt
	s_add_u32 s14, s14, 0x8000
	s_addc_u32 s15, s15, 0
	global_load_dwordx4 v[188:191], v112, s[14:15] nt
	s_add_u32 s14, s14, 0x8000
	s_addc_u32 s15, s15, 0
	global_load_dwordx4 v[192:195], v112, s[14:15] nt
	s_add_u32 s14, s14, 0x8000
	s_addc_u32 s15, s15, 0
	global_load_dwordx4 v[196:199], v112, s[14:15] nt
	v_add_u32_e32 v18, 0x400, v123
	s_barrier
	ds_write2_b32 v123, v94, v90 offset1:16
	ds_write2_b32 v123, v95, v91 offset0:132 offset1:148
	ds_write2_b32 v18, v96, v92 offset0:8 offset1:24
	ds_write2_b32 v18, v97, v93 offset0:140 offset1:156
	ds_write2_b32 v123, v82, v78 offset0:32 offset1:48
	ds_write2_b32 v123, v83, v79 offset0:164 offset1:180
	ds_write2_b32 v18, v84, v80 offset0:40 offset1:56
	ds_write2_b32 v18, v85, v81 offset0:172 offset1:188
	v_add_u32_e32 v18, 0x2000, v123
	v_add_u32_e32 v19, 0x2400, v123
	ds_write2_b32 v18, v74, v70 offset0:64 offset1:80
	ds_write2_b32 v18, v75, v71 offset0:196 offset1:212
	ds_write2_b32 v19, v76, v72 offset0:72 offset1:88
	ds_write2_b32 v19, v77, v73 offset0:204 offset1:220
	ds_write2_b32 v18, v66, v62 offset0:96 offset1:112
	ds_write2_b32 v18, v67, v63 offset0:228 offset1:244
	ds_write2_b32 v19, v68, v64 offset0:104 offset1:120
	ds_write2_b32 v19, v69, v65 offset0:236 offset1:252
	v_add_u32_e32 v18, 0x4000, v123
	v_add_u32_e32 v19, 0x4400, v123
	v_add_u32_e32 v20, 0x4800, v123
	ds_write2_b32 v18, v58, v42 offset0:128 offset1:144
	ds_write2_b32 v19, v59, v43 offset0:4 offset1:20
	ds_write2_b32 v19, v60, v44 offset0:136 offset1:152
	ds_write2_b32 v20, v61, v45 offset0:12 offset1:28
	ds_write2_b32 v18, v22, v14 offset0:160 offset1:176
	ds_write2_b32 v19, v23, v15 offset0:36 offset1:52
	ds_write2_b32 v19, v24, v16 offset0:168 offset1:184
	ds_write2_b32 v20, v25, v17 offset0:44 offset1:60
	v_add_u32_e32 v14, 0x6000, v123
	ds_write2_b32 v14, v10, v6 offset0:192 offset1:208
	v_add_u32_e32 v6, 0x6400, v123
	ds_write2_b32 v6, v11, v7 offset0:68 offset1:84
	ds_write2_b32 v6, v12, v8 offset0:200 offset1:216
	v_add_u32_e32 v7, 0x6800, v123
	s_lshl_b32 s2, s29, 9
	ds_write2_b32 v7, v13, v9 offset0:76 offset1:92
	ds_write2_b32 v14, v2, v86 offset0:224 offset1:240
	ds_write2_b32 v6, v3, v87 offset0:100 offset1:116
	ds_write2_b32 v6, v4, v88 offset0:232 offset1:248
	ds_write2_b32 v7, v5, v89 offset0:108 offset1:124
	v_lshl_add_u64 v[2:3], v[100:101], 0, s[2:3]
	v_lshl_add_u64 v[4:5], v[102:103], 0, s[2:3]
	s_lshl_b32 s2, s28, 10
	s_mul_hi_u32 s12, s28, 0x15555556
	s_lshl_b32 s13, s29, 7
	v_or_b32_e32 v6, s2, v125
	s_mulk_i32 s12, 0x3000
	v_or_b32_e32 v7, s2, v127
	v_or_b32_e32 v8, s2, v129
	v_or_b32_e32 v9, s2, v133
	v_subrev_u32_e32 v6, s12, v6
	v_subrev_u32_e32 v7, s12, v7
	v_subrev_u32_e32 v8, s12, v8
	v_subrev_u32_e32 v9, s12, v9
	s_mov_b32 s12, 0
	s_lshl_b32 s2, s13, 2
	v_mov_b32_e32 v10, v132
	v_mov_b32_e32 v11, v128
	v_mov_b32_e32 v12, v126
	v_mov_b32_e32 v13, v124
	s_waitcnt lgkmcnt(0)
	s_barrier
	s_mov_b32 s98, 0x3fb504f3
	v_lshrrev_b32_e32 v114, 5, v0
	v_and_b32_e32 v114, 7, v114
	v_mul_u32_u24_e32 v114, 0x210, v114
	v_and_b32_e32 v26, 31, v0
	v_lshl_add_u32 v114, v26, 4, v114
	s_lshl_b32 s12, s100, 12
	s_add_u32 s12, s12, s101
	s_add_u32 s14, s42, s12
	s_addc_u32 s15, s43, 0
	s_add_u32 s14, s14, 0xfb24000
	s_addc_u32 s15, s15, 0
	ds_read_b128 v[26:29], v114 offset:32
	ds_read_b128 v[30:33], v114 offset:4256
	ds_read_b128 v[34:37], v114 offset:8480
	ds_read_b128 v[38:41], v114 offset:12704
	s_waitcnt vmcnt(15) lgkmcnt(3)
	v_pk_mul_f32 v[26:27], v[26:27], v[108:109]
	v_pk_mul_f32 v[28:29], v[28:29], v[110:111]
	v_pk_fma_f32 v[136:137], v[136:137], s[98:99], v[26:27] op_sel_hi:[1,0,1]
	v_pk_fma_f32 v[138:139], v[138:139], s[98:99], v[28:29] op_sel_hi:[1,0,1]
	ds_read_b128 v[26:29], v114 offset:16928
	global_store_dwordx4 v112, v[136:139], s[14:15]
	s_add_u32 s14, s14, 0x8000
	s_addc_u32 s15, s15, 0
	s_waitcnt vmcnt(15) lgkmcnt(3)
	v_pk_mul_f32 v[30:31], v[30:31], v[108:109]
	v_pk_mul_f32 v[32:33], v[32:33], v[110:111]
	v_pk_fma_f32 v[140:141], v[140:141], s[98:99], v[30:31] op_sel_hi:[1,0,1]
	v_pk_fma_f32 v[142:143], v[142:143], s[98:99], v[32:33] op_sel_hi:[1,0,1]
	ds_read_b128 v[30:33], v114 offset:21152
	global_store_dwordx4 v112, v[140:143], s[14:15]
	s_add_u32 s14, s14, 0x8000
	s_addc_u32 s15, s15, 0
	s_waitcnt vmcnt(15) lgkmcnt(3)
	v_pk_mul_f32 v[34:35], v[34:35], v[108:109]
	v_pk_mul_f32 v[36:37], v[36:37], v[110:111]
	v_pk_fma_f32 v[144:145], v[144:145], s[98:99], v[34:35] op_sel_hi:[1,0,1]
	v_pk_fma_f32 v[146:147], v[146:147], s[98:99], v[36:37] op_sel_hi:[1,0,1]
	ds_read_b128 v[34:37], v114 offset:25376
	global_store_dwordx4 v112, v[144:147], s[14:15]
	s_add_u32 s14, s14, 0x8000
	s_addc_u32 s15, s15, 0
	s_waitcnt vmcnt(15) lgkmcnt(3)
	v_pk_mul_f32 v[38:39], v[38:39], v[108:109]
	v_pk_mul_f32 v[40:41], v[40:41], v[110:111]
	v_pk_fma_f32 v[148:149], v[148:149], s[98:99], v[38:39] op_sel_hi:[1,0,1]
	v_pk_fma_f32 v[150:151], v[150:151], s[98:99], v[40:41] op_sel_hi:[1,0,1]
	ds_read_b128 v[38:41], v114 offset:29600
	global_store_dwordx4 v112, v[148:151], s[14:15]
	s_add_u32 s14, s14, 0x8000
	s_addc_u32 s15, s15, 0
	s_waitcnt vmcnt(15) lgkmcnt(3)
	v_pk_mul_f32 v[26:27], v[26:27], v[108:109]
	v_pk_mul_f32 v[28:29], v[28:29], v[110:111]
	v_pk_fma_f32 v[152:153], v[152:153], s[98:99], v[26:27] op_sel_hi:[1,0,1]
	v_pk_fma_f32 v[154:155], v[154:155], s[98:99], v[28:29] op_sel_hi:[1,0,1]
	ds_read_b128 v[26:29], v114 offset:33824
	global_store_dwordx4 v112, v[152:155], s[14:15]
	s_add_u32 s14, s14, 0x8000
	s_addc_u32 s15, s15, 0
	s_waitcnt vmcnt(15) lgkmcnt(3)
	v_pk_mul_f32 v[30:31], v[30:31], v[108:109]
	v_pk_mul_f32 v[32:33], v[32:33], v[110:111]
	v_pk_fma_f32 v[156:157], v[156:157], s[98:99], v[30:31] op_sel_hi:[1,0,1]
	v_pk_fma_f32 v[158:159], v[158:159], s[98:99], v[32:33] op_sel_hi:[1,0,1]
	ds_read_b128 v[30:33], v114 offset:38048
	global_store_dwordx4 v112, v[156:159], s[14:15]
	s_add_u32 s14, s14, 0x8000
	s_addc_u32 s15, s15, 0
	s_waitcnt vmcnt(15) lgkmcnt(3)
	v_pk_mul_f32 v[34:35], v[34:35], v[108:109]
	v_pk_mul_f32 v[36:37], v[36:37], v[110:111]
	v_pk_fma_f32 v[160:161], v[160:161], s[98:99], v[34:35] op_sel_hi:[1,0,1]
	v_pk_fma_f32 v[162:163], v[162:163], s[98:99], v[36:37] op_sel_hi:[1,0,1]
	ds_read_b128 v[34:37], v114 offset:42272
	global_store_dwordx4 v112, v[160:163], s[14:15]
	s_add_u32 s14, s14, 0x8000
	s_addc_u32 s15, s15, 0
	s_waitcnt vmcnt(15) lgkmcnt(3)
	v_pk_mul_f32 v[38:39], v[38:39], v[108:109]
	v_pk_mul_f32 v[40:41], v[40:41], v[110:111]
	v_pk_fma_f32 v[164:165], v[164:165], s[98:99], v[38:39] op_sel_hi:[1,0,1]
	v_pk_fma_f32 v[166:167], v[166:167], s[98:99], v[40:41] op_sel_hi:[1,0,1]
	ds_read_b128 v[38:41], v114 offset:46496
	global_store_dwordx4 v112, v[164:167], s[14:15]
	s_add_u32 s14, s14, 0x8000
	s_addc_u32 s15, s15, 0
	s_waitcnt vmcnt(15) lgkmcnt(3)
	v_pk_mul_f32 v[26:27], v[26:27], v[108:109]
	v_pk_mul_f32 v[28:29], v[28:29], v[110:111]
	v_pk_fma_f32 v[168:169], v[168:169], s[98:99], v[26:27] op_sel_hi:[1,0,1]
	v_pk_fma_f32 v[170:171], v[170:171], s[98:99], v[28:29] op_sel_hi:[1,0,1]
	ds_read_b128 v[26:29], v114 offset:50720
	global_store_dwordx4 v112, v[168:171], s[14:15]
	s_add_u32 s14, s14, 0x8000
	s_addc_u32 s15, s15, 0
	s_waitcnt vmcnt(15) lgkmcnt(3)
	v_pk_mul_f32 v[30:31], v[30:31], v[108:109]
	v_pk_mul_f32 v[32:33], v[32:33], v[110:111]
	v_pk_fma_f32 v[172:173], v[172:173], s[98:99], v[30:31] op_sel_hi:[1,0,1]
	v_pk_fma_f32 v[174:175], v[174:175], s[98:99], v[32:33] op_sel_hi:[1,0,1]
	ds_read_b128 v[30:33], v114 offset:54944
	global_store_dwordx4 v112, v[172:175], s[14:15]
	s_add_u32 s14, s14, 0x8000
	s_addc_u32 s15, s15, 0
	s_waitcnt vmcnt(15) lgkmcnt(3)
	v_pk_mul_f32 v[34:35], v[34:35], v[108:109]
	v_pk_mul_f32 v[36:37], v[36:37], v[110:111]
	v_pk_fma_f32 v[176:177], v[176:177], s[98:99], v[34:35] op_sel_hi:[1,0,1]
	v_pk_fma_f32 v[178:179], v[178:179], s[98:99], v[36:37] op_sel_hi:[1,0,1]
	ds_read_b128 v[34:37], v114 offset:59168
	global_store_dwordx4 v112, v[176:179], s[14:15]
	s_add_u32 s14, s14, 0x8000
	s_addc_u32 s15, s15, 0
	s_waitcnt vmcnt(15) lgkmcnt(3)
	v_pk_mul_f32 v[38:39], v[38:39], v[108:109]
	v_pk_mul_f32 v[40:41], v[40:41], v[110:111]
	v_pk_fma_f32 v[180:181], v[180:181], s[98:99], v[38:39] op_sel_hi:[1,0,1]
	v_pk_fma_f32 v[182:183], v[182:183], s[98:99], v[40:41] op_sel_hi:[1,0,1]
	ds_read_b128 v[38:41], v114 offset:63392
	global_store_dwordx4 v112, v[180:183], s[14:15]
	s_add_u32 s14, s14, 0x8000
	s_addc_u32 s15, s15, 0
	s_waitcnt vmcnt(15) lgkmcnt(3)
	v_pk_mul_f32 v[26:27], v[26:27], v[108:109]
	v_pk_mul_f32 v[28:29], v[28:29], v[110:111]
	v_pk_fma_f32 v[184:185], v[184:185], s[98:99], v[26:27] op_sel_hi:[1,0,1]
	v_pk_fma_f32 v[186:187], v[186:187], s[98:99], v[28:29] op_sel_hi:[1,0,1]
	global_store_dwordx4 v112, v[184:187], s[14:15]
	s_add_u32 s14, s14, 0x8000
	s_addc_u32 s15, s15, 0
	s_waitcnt vmcnt(15) lgkmcnt(2)
	v_pk_mul_f32 v[30:31], v[30:31], v[108:109]
	v_pk_mul_f32 v[32:33], v[32:33], v[110:111]
	v_pk_fma_f32 v[188:189], v[188:189], s[98:99], v[30:31] op_sel_hi:[1,0,1]
	v_pk_fma_f32 v[190:191], v[190:191], s[98:99], v[32:33] op_sel_hi:[1,0,1]
	global_store_dwordx4 v112, v[188:191], s[14:15]
	s_add_u32 s14, s14, 0x8000
	s_addc_u32 s15, s15, 0
	s_waitcnt vmcnt(15) lgkmcnt(1)
	v_pk_mul_f32 v[34:35], v[34:35], v[108:109]
	v_pk_mul_f32 v[36:37], v[36:37], v[110:111]
	v_pk_fma_f32 v[192:193], v[192:193], s[98:99], v[34:35] op_sel_hi:[1,0,1]
	v_pk_fma_f32 v[194:195], v[194:195], s[98:99], v[36:37] op_sel_hi:[1,0,1]
	global_store_dwordx4 v112, v[192:195], s[14:15]
	s_add_u32 s14, s14, 0x8000
	s_addc_u32 s15, s15, 0
	s_waitcnt vmcnt(15) lgkmcnt(0)
	v_pk_mul_f32 v[38:39], v[38:39], v[108:109]
	v_pk_mul_f32 v[40:41], v[40:41], v[110:111]
	v_pk_fma_f32 v[196:197], v[196:197], s[98:99], v[38:39] op_sel_hi:[1,0,1]
	v_pk_fma_f32 v[198:199], v[198:199], s[98:99], v[40:41] op_sel_hi:[1,0,1]
	global_store_dwordx4 v112, v[196:199], s[14:15]
	s_add_i32 s11, s11, s20
	s_cmpk_lt_u32 s11, 0x60
	s_cbranch_scc1 .LBB0_1372

.LBB0_1496:
	s_lshl_b32 s10, s50, 7
	s_or_b32 s46, s37, s10
	s_xor_b64 s[48:49], s[52:53], -1
	s_lshl_b64 s[52:53], s[46:47], 11
	s_add_u32 s52, s55, s52
	s_addc_u32 s53, s56, s53
	s_waitcnt lgkmcnt(0)
	s_lshl_b32 s98, s36, 11
	s_add_u32 s98, s33, s98
	s_addc_u32 s99, s54, 0
	v_and_b32_e32 v212, 15, v0
	v_bfe_u32 v213, v0, 4, 2
	v_and_b32_e32 v139, 7, v212
	v_xor_b32_e32 v213, v213, v139
	v_lshlrev_b32_e32 v213, 4, v213
	v_lshl_or_b32 v213, v212, 7, v213
	v_bfe_u32 v212, v0, 7, 1
	v_lshl_or_b32 v138, v212, 13, v213
	v_bfe_u32 v212, v0, 6, 1
	v_lshl_or_b32 v206, v212, 13, v213
	v_or_b32_e32 v206, 0x4000, v206
	v_xor_b32_e32 v139, 64, v138
	v_xor_b32_e32 v207, 64, v206
	v_bfe_u32 v212, v0, 3, 3
	v_and_b32_e32 v213, 7, v0
	v_xor_b32_e32 v213, v213, v212
	v_lshlrev_b32_e32 v213, 4, v213
	v_lshl_or_b32 v213, v212, 11, v213
	v_lshrrev_b32_e32 v212, 6, v0
	v_and_b32_e32 v212, 3, v212
	v_lshl_or_b32 v208, v212, 16, v213
	v_add_u32_e32 v209, 0x3c00, v208
	v_add_u32_e32 v210, 0x7800, v208
	v_add_u32_e32 v211, 0xb400, v208
	v_lshlrev_b32_e32 v212, 12, v212
	s_nop 0
	v_readfirstlane_b32 s101, v212
	s_add_u32 s101, s101, 32
	v_mov_b32_e32 v66, 0
	v_mov_b32_e32 v67, 0
	v_mov_b32_e32 v68, 0
	v_mov_b32_e32 v69, 0
	v_mov_b32_e32 v58, 0
	v_mov_b32_e32 v59, 0
	v_mov_b32_e32 v60, 0
	v_mov_b32_e32 v61, 0
	v_mov_b32_e32 v54, 0
	v_mov_b32_e32 v55, 0
	v_mov_b32_e32 v56, 0
	v_mov_b32_e32 v57, 0
	v_mov_b32_e32 v50, 0
	v_mov_b32_e32 v51, 0
	v_mov_b32_e32 v52, 0
	v_mov_b32_e32 v53, 0
	v_mov_b32_e32 v46, 0
	v_mov_b32_e32 v47, 0
	v_mov_b32_e32 v48, 0
	v_mov_b32_e32 v49, 0
	v_mov_b32_e32 v42, 0
	v_mov_b32_e32 v43, 0
	v_mov_b32_e32 v44, 0
	v_mov_b32_e32 v45, 0
	v_mov_b32_e32 v38, 0
	v_mov_b32_e32 v39, 0
	v_mov_b32_e32 v40, 0
	v_mov_b32_e32 v41, 0
	v_mov_b32_e32 v6, 0
	v_mov_b32_e32 v7, 0
	v_mov_b32_e32 v8, 0
	v_mov_b32_e32 v9, 0
	v_mov_b32_e32 v2, 0
	v_mov_b32_e32 v3, 0
	v_mov_b32_e32 v4, 0
	v_mov_b32_e32 v5, 0
	v_mov_b32_e32 v22, 0
	v_mov_b32_e32 v23, 0
	v_mov_b32_e32 v24, 0
	v_mov_b32_e32 v25, 0
	v_mov_b32_e32 v18, 0
	v_mov_b32_e32 v19, 0
	v_mov_b32_e32 v20, 0
	v_mov_b32_e32 v21, 0
	v_mov_b32_e32 v14, 0
	v_mov_b32_e32 v15, 0
	v_mov_b32_e32 v16, 0
	v_mov_b32_e32 v17, 0
	v_mov_b32_e32 v10, 0
	v_mov_b32_e32 v11, 0
	v_mov_b32_e32 v12, 0
	v_mov_b32_e32 v13, 0
	v_mov_b32_e32 v34, 0
	v_mov_b32_e32 v35, 0
	v_mov_b32_e32 v36, 0
	v_mov_b32_e32 v37, 0
	v_mov_b32_e32 v30, 0
	v_mov_b32_e32 v31, 0
	v_mov_b32_e32 v32, 0
	v_mov_b32_e32 v33, 0
	v_mov_b32_e32 v26, 0
	v_mov_b32_e32 v27, 0
	v_mov_b32_e32 v28, 0
	v_mov_b32_e32 v29, 0
	v_mov_b32_e32 v134, 0
	v_mov_b32_e32 v135, 0
	v_mov_b32_e32 v136, 0
	v_mov_b32_e32 v137, 0
	v_mov_b32_e32 v178, 0
	v_mov_b32_e32 v179, 0
	v_mov_b32_e32 v180, 0
	v_mov_b32_e32 v181, 0
	v_mov_b32_e32 v182, 0
	v_mov_b32_e32 v183, 0
	v_mov_b32_e32 v184, 0
	v_mov_b32_e32 v185, 0
	v_mov_b32_e32 v186, 0
	v_mov_b32_e32 v187, 0
	v_mov_b32_e32 v188, 0
	v_mov_b32_e32 v189, 0
	v_mov_b32_e32 v190, 0
	v_mov_b32_e32 v191, 0
	v_mov_b32_e32 v192, 0
	v_mov_b32_e32 v193, 0
	v_mov_b32_e32 v194, 0
	v_mov_b32_e32 v195, 0
	v_mov_b32_e32 v196, 0
	v_mov_b32_e32 v197, 0
	v_mov_b32_e32 v198, 0
	v_mov_b32_e32 v199, 0
	v_mov_b32_e32 v200, 0
	v_mov_b32_e32 v201, 0
	v_mov_b32_e32 v202, 0
	v_mov_b32_e32 v203, 0
	v_mov_b32_e32 v204, 0
	v_mov_b32_e32 v205, 0
	s_waitcnt lgkmcnt(0)
	s_barrier
	v_readlane_b32 s46, v255, 16
	s_and_b32 s46, s46, 7
	s_lshl_b32 s46, s46, 1
	s_lshl_b32 s51, s46, 7
	s_add_u32 s98, s98, s51
	s_addc_u32 s99, s99, 0
	s_add_u32 s52, s52, s51
	s_addc_u32 s53, s53, 0
	s_add_u32 m0, s101, 0
	s_nop 0
	global_load_lds_dwordx4 v208, s[98:99] offset:0
	global_load_lds_dwordx4 v209, s[98:99] offset:1024
	global_load_lds_dwordx4 v210, s[98:99] offset:2048
	global_load_lds_dwordx4 v211, s[98:99] offset:3072
	s_add_u32 m0, s101, 16384
	s_nop 0
	global_load_lds_dwordx4 v208, s[52:53] offset:0
	global_load_lds_dwordx4 v209, s[52:53] offset:1024
	global_load_lds_dwordx4 v210, s[52:53] offset:2048
	global_load_lds_dwordx4 v211, s[52:53] offset:3072
	s_add_u32 s46, s46, 1
	s_and_b32 s46, s46, 15
	s_cmp_eq_u32 s46, 0
	s_cselect_b32 s51, 0x800, 0
	s_add_u32 s98, s98, 0x80
	s_addc_u32 s99, s99, 0
	s_sub_u32 s98, s98, s51
	s_subb_u32 s99, s99, 0
	s_add_u32 s52, s52, 0x80
	s_addc_u32 s53, s53, 0
	s_sub_u32 s52, s52, s51
	s_subb_u32 s53, s53, 0
	s_mov_b32 s100, 0
	s_waitcnt vmcnt(0)
	s_setprio 1
.Lk_pq1_loop:
	s_barrier
	s_add_u32 m0, s101, 32768
	v_mfma_f32_16x16x32_bf16 v[66:69], v[134:137], v[190:193], v[66:69]
	ds_read_b128 v[62:65], v138 offset:32
	global_load_lds_dwordx4 v208, s[98:99] offset:0
	v_mfma_f32_16x16x32_bf16 v[58:61], v[134:137], v[194:197], v[58:61]
	ds_read_b128 v[82:85], v206 offset:32
	global_load_lds_dwordx4 v209, s[98:99] offset:1024
	v_mfma_f32_16x16x32_bf16 v[54:57], v[134:137], v[198:201], v[54:57]
	ds_read_b128 v[86:89], v206 offset:2080
	global_load_lds_dwordx4 v210, s[98:99] offset:2048
	v_mfma_f32_16x16x32_bf16 v[50:53], v[134:137], v[202:205], v[50:53]
	ds_read_b128 v[70:73], v138 offset:2080
	global_load_lds_dwordx4 v211, s[98:99] offset:3072
	s_add_u32 m0, s101, 49152
	v_mfma_f32_16x16x32_bf16 v[46:49], v[178:181], v[190:193], v[46:49]
	ds_read_b128 v[90:93], v206 offset:4128
	global_load_lds_dwordx4 v208, s[52:53] offset:0
	v_mfma_f32_16x16x32_bf16 v[42:45], v[178:181], v[194:197], v[42:45]
	ds_read_b128 v[94:97], v206 offset:6176
	global_load_lds_dwordx4 v209, s[52:53] offset:1024
	v_mfma_f32_16x16x32_bf16 v[38:41], v[178:181], v[198:201], v[38:41]
	ds_read_b128 v[74:77], v138 offset:4128
	global_load_lds_dwordx4 v210, s[52:53] offset:2048
	v_mfma_f32_16x16x32_bf16 v[6:9], v[178:181], v[202:205], v[6:9]
	ds_read_b128 v[78:81], v138 offset:6176
	global_load_lds_dwordx4 v211, s[52:53] offset:3072
	v_mfma_f32_16x16x32_bf16 v[2:5], v[182:185], v[190:193], v[2:5]
	v_mfma_f32_16x16x32_bf16 v[22:25], v[182:185], v[194:197], v[22:25]
	v_mfma_f32_16x16x32_bf16 v[18:21], v[182:185], v[198:201], v[18:21]
	v_mfma_f32_16x16x32_bf16 v[14:17], v[182:185], v[202:205], v[14:17]
	v_mfma_f32_16x16x32_bf16 v[10:13], v[186:189], v[190:193], v[10:13]
	v_mfma_f32_16x16x32_bf16 v[34:37], v[186:189], v[194:197], v[34:37]
	v_mfma_f32_16x16x32_bf16 v[30:33], v[186:189], v[198:201], v[30:33]
	v_mfma_f32_16x16x32_bf16 v[26:29], v[186:189], v[202:205], v[26:29]
	s_add_u32 s46, s46, 1
	s_and_b32 s46, s46, 15
	s_cmp_eq_u32 s46, 0
	s_cselect_b32 s51, 0x800, 0
	s_add_u32 s98, s98, 0x80
	s_addc_u32 s99, s99, 0
	s_sub_u32 s98, s98, s51
	s_subb_u32 s99, s99, 0
	s_add_u32 s52, s52, 0x80
	s_addc_u32 s53, s53, 0
	s_sub_u32 s52, s52, s51
	s_subb_u32 s53, s53, 0
	s_waitcnt lgkmcnt(0)
	v_mfma_f32_16x16x32_bf16 v[66:69], v[62:65], v[82:85], v[66:69]
	ds_read_b128 v[134:137], v139 offset:32
	v_mfma_f32_16x16x32_bf16 v[58:61], v[62:65], v[86:89], v[58:61]
	ds_read_b128 v[190:193], v207 offset:32
	v_mfma_f32_16x16x32_bf16 v[54:57], v[62:65], v[90:93], v[54:57]
	ds_read_b128 v[194:197], v207 offset:2080
	v_mfma_f32_16x16x32_bf16 v[50:53], v[62:65], v[94:97], v[50:53]
	ds_read_b128 v[178:181], v139 offset:2080
	v_mfma_f32_16x16x32_bf16 v[46:49], v[70:73], v[82:85], v[46:49]
	ds_read_b128 v[198:201], v207 offset:4128
	v_mfma_f32_16x16x32_bf16 v[42:45], v[70:73], v[86:89], v[42:45]
	ds_read_b128 v[202:205], v207 offset:6176
	v_mfma_f32_16x16x32_bf16 v[38:41], v[70:73], v[90:93], v[38:41]
	ds_read_b128 v[182:185], v139 offset:4128
	v_mfma_f32_16x16x32_bf16 v[6:9], v[70:73], v[94:97], v[6:9]
	ds_read_b128 v[186:189], v139 offset:6176
	v_mfma_f32_16x16x32_bf16 v[2:5], v[74:77], v[82:85], v[2:5]
	v_mfma_f32_16x16x32_bf16 v[22:25], v[74:77], v[86:89], v[22:25]
	v_mfma_f32_16x16x32_bf16 v[18:21], v[74:77], v[90:93], v[18:21]
	v_mfma_f32_16x16x32_bf16 v[14:17], v[74:77], v[94:97], v[14:17]
	v_mfma_f32_16x16x32_bf16 v[10:13], v[78:81], v[82:85], v[10:13]
	v_mfma_f32_16x16x32_bf16 v[34:37], v[78:81], v[86:89], v[34:37]
	v_mfma_f32_16x16x32_bf16 v[30:33], v[78:81], v[90:93], v[30:33]
	v_mfma_f32_16x16x32_bf16 v[26:29], v[78:81], v[94:97], v[26:29]
	s_waitcnt lgkmcnt(0)
	s_waitcnt vmcnt(0)
	s_barrier
	s_add_u32 m0, s101, 0
	v_mfma_f32_16x16x32_bf16 v[66:69], v[134:137], v[190:193], v[66:69]
	ds_read_b128 v[62:65], v138 offset:32800
	global_load_lds_dwordx4 v208, s[98:99] offset:0
	v_mfma_f32_16x16x32_bf16 v[58:61], v[134:137], v[194:197], v[58:61]
	ds_read_b128 v[82:85], v206 offset:32800
	global_load_lds_dwordx4 v209, s[98:99] offset:1024
	v_mfma_f32_16x16x32_bf16 v[54:57], v[134:137], v[198:201], v[54:57]
	ds_read_b128 v[86:89], v206 offset:34848
	global_load_lds_dwordx4 v210, s[98:99] offset:2048
	v_mfma_f32_16x16x32_bf16 v[50:53], v[134:137], v[202:205], v[50:53]
	ds_read_b128 v[70:73], v138 offset:34848
	global_load_lds_dwordx4 v211, s[98:99] offset:3072
	s_add_u32 m0, s101, 16384
	v_mfma_f32_16x16x32_bf16 v[46:49], v[178:181], v[190:193], v[46:49]
	ds_read_b128 v[90:93], v206 offset:36896
	global_load_lds_dwordx4 v208, s[52:53] offset:0
	v_mfma_f32_16x16x32_bf16 v[42:45], v[178:181], v[194:197], v[42:45]
	ds_read_b128 v[94:97], v206 offset:38944
	global_load_lds_dwordx4 v209, s[52:53] offset:1024
	v_mfma_f32_16x16x32_bf16 v[38:41], v[178:181], v[198:201], v[38:41]
	ds_read_b128 v[74:77], v138 offset:36896
	global_load_lds_dwordx4 v210, s[52:53] offset:2048
	v_mfma_f32_16x16x32_bf16 v[6:9], v[178:181], v[202:205], v[6:9]
	ds_read_b128 v[78:81], v138 offset:38944
	global_load_lds_dwordx4 v211, s[52:53] offset:3072
	v_mfma_f32_16x16x32_bf16 v[2:5], v[182:185], v[190:193], v[2:5]
	v_mfma_f32_16x16x32_bf16 v[22:25], v[182:185], v[194:197], v[22:25]
	v_mfma_f32_16x16x32_bf16 v[18:21], v[182:185], v[198:201], v[18:21]
	v_mfma_f32_16x16x32_bf16 v[14:17], v[182:185], v[202:205], v[14:17]
	v_mfma_f32_16x16x32_bf16 v[10:13], v[186:189], v[190:193], v[10:13]
	v_mfma_f32_16x16x32_bf16 v[34:37], v[186:189], v[194:197], v[34:37]
	v_mfma_f32_16x16x32_bf16 v[30:33], v[186:189], v[198:201], v[30:33]
	v_mfma_f32_16x16x32_bf16 v[26:29], v[186:189], v[202:205], v[26:29]
	s_add_u32 s46, s46, 1
	s_and_b32 s46, s46, 15
	s_cmp_eq_u32 s46, 0
	s_cselect_b32 s51, 0x800, 0
	s_add_u32 s98, s98, 0x80
	s_addc_u32 s99, s99, 0
	s_sub_u32 s98, s98, s51
	s_subb_u32 s99, s99, 0
	s_add_u32 s52, s52, 0x80
	s_addc_u32 s53, s53, 0
	s_sub_u32 s52, s52, s51
	s_subb_u32 s53, s53, 0
	s_waitcnt lgkmcnt(0)
	v_mfma_f32_16x16x32_bf16 v[66:69], v[62:65], v[82:85], v[66:69]
	ds_read_b128 v[134:137], v139 offset:32800
	v_mfma_f32_16x16x32_bf16 v[58:61], v[62:65], v[86:89], v[58:61]
	ds_read_b128 v[190:193], v207 offset:32800
	v_mfma_f32_16x16x32_bf16 v[54:57], v[62:65], v[90:93], v[54:57]
	ds_read_b128 v[194:197], v207 offset:34848
	v_mfma_f32_16x16x32_bf16 v[50:53], v[62:65], v[94:97], v[50:53]
	ds_read_b128 v[178:181], v139 offset:34848
	v_mfma_f32_16x16x32_bf16 v[46:49], v[70:73], v[82:85], v[46:49]
	ds_read_b128 v[198:201], v207 offset:36896
	v_mfma_f32_16x16x32_bf16 v[42:45], v[70:73], v[86:89], v[42:45]
	ds_read_b128 v[202:205], v207 offset:38944
	v_mfma_f32_16x16x32_bf16 v[38:41], v[70:73], v[90:93], v[38:41]
	ds_read_b128 v[182:185], v139 offset:36896
	v_mfma_f32_16x16x32_bf16 v[6:9], v[70:73], v[94:97], v[6:9]
	ds_read_b128 v[186:189], v139 offset:38944
	v_mfma_f32_16x16x32_bf16 v[2:5], v[74:77], v[82:85], v[2:5]
	v_mfma_f32_16x16x32_bf16 v[22:25], v[74:77], v[86:89], v[22:25]
	v_mfma_f32_16x16x32_bf16 v[18:21], v[74:77], v[90:93], v[18:21]
	v_mfma_f32_16x16x32_bf16 v[14:17], v[74:77], v[94:97], v[14:17]
	v_mfma_f32_16x16x32_bf16 v[10:13], v[78:81], v[82:85], v[10:13]
	v_mfma_f32_16x16x32_bf16 v[34:37], v[78:81], v[86:89], v[34:37]
	v_mfma_f32_16x16x32_bf16 v[30:33], v[78:81], v[90:93], v[30:33]
	v_mfma_f32_16x16x32_bf16 v[26:29], v[78:81], v[94:97], v[26:29]
	s_waitcnt lgkmcnt(0)
	s_waitcnt vmcnt(0)
	s_add_u32 s100, s100, 1
	s_cmp_lt_u32 s100, 7
	s_cbranch_scc1 .Lk_pq1_loop
	s_barrier
	s_add_u32 m0, s101, 32768
	v_mfma_f32_16x16x32_bf16 v[66:69], v[134:137], v[190:193], v[66:69]
	ds_read_b128 v[62:65], v138 offset:32
	global_load_lds_dwordx4 v208, s[98:99] offset:0
	v_mfma_f32_16x16x32_bf16 v[58:61], v[134:137], v[194:197], v[58:61]
	ds_read_b128 v[82:85], v206 offset:32
	global_load_lds_dwordx4 v209, s[98:99] offset:1024
	v_mfma_f32_16x16x32_bf16 v[54:57], v[134:137], v[198:201], v[54:57]
	ds_read_b128 v[86:89], v206 offset:2080
	global_load_lds_dwordx4 v210, s[98:99] offset:2048
	v_mfma_f32_16x16x32_bf16 v[50:53], v[134:137], v[202:205], v[50:53]
	ds_read_b128 v[70:73], v138 offset:2080
	global_load_lds_dwordx4 v211, s[98:99] offset:3072
	s_add_u32 m0, s101, 49152
	v_mfma_f32_16x16x32_bf16 v[46:49], v[178:181], v[190:193], v[46:49]
	ds_read_b128 v[90:93], v206 offset:4128
	global_load_lds_dwordx4 v208, s[52:53] offset:0
	v_mfma_f32_16x16x32_bf16 v[42:45], v[178:181], v[194:197], v[42:45]
	ds_read_b128 v[94:97], v206 offset:6176
	global_load_lds_dwordx4 v209, s[52:53] offset:1024
	v_mfma_f32_16x16x32_bf16 v[38:41], v[178:181], v[198:201], v[38:41]
	ds_read_b128 v[74:77], v138 offset:4128
	global_load_lds_dwordx4 v210, s[52:53] offset:2048
	v_mfma_f32_16x16x32_bf16 v[6:9], v[178:181], v[202:205], v[6:9]
	ds_read_b128 v[78:81], v138 offset:6176
	global_load_lds_dwordx4 v211, s[52:53] offset:3072
	v_mfma_f32_16x16x32_bf16 v[2:5], v[182:185], v[190:193], v[2:5]
	v_mfma_f32_16x16x32_bf16 v[22:25], v[182:185], v[194:197], v[22:25]
	v_mfma_f32_16x16x32_bf16 v[18:21], v[182:185], v[198:201], v[18:21]
	v_mfma_f32_16x16x32_bf16 v[14:17], v[182:185], v[202:205], v[14:17]
	v_mfma_f32_16x16x32_bf16 v[10:13], v[186:189], v[190:193], v[10:13]
	v_mfma_f32_16x16x32_bf16 v[34:37], v[186:189], v[194:197], v[34:37]
	v_mfma_f32_16x16x32_bf16 v[30:33], v[186:189], v[198:201], v[30:33]
	v_mfma_f32_16x16x32_bf16 v[26:29], v[186:189], v[202:205], v[26:29]
	s_add_u32 s46, s46, 1
	s_and_b32 s46, s46, 15
	s_cmp_eq_u32 s46, 0
	s_cselect_b32 s51, 0x800, 0
	s_add_u32 s98, s98, 0x80
	s_addc_u32 s99, s99, 0
	s_sub_u32 s98, s98, s51
	s_subb_u32 s99, s99, 0
	s_add_u32 s52, s52, 0x80
	s_addc_u32 s53, s53, 0
	s_sub_u32 s52, s52, s51
	s_subb_u32 s53, s53, 0
	s_waitcnt lgkmcnt(0)
	v_mfma_f32_16x16x32_bf16 v[66:69], v[62:65], v[82:85], v[66:69]
	ds_read_b128 v[134:137], v139 offset:32
	v_mfma_f32_16x16x32_bf16 v[58:61], v[62:65], v[86:89], v[58:61]
	ds_read_b128 v[190:193], v207 offset:32
	v_mfma_f32_16x16x32_bf16 v[54:57], v[62:65], v[90:93], v[54:57]
	ds_read_b128 v[194:197], v207 offset:2080
	v_mfma_f32_16x16x32_bf16 v[50:53], v[62:65], v[94:97], v[50:53]
	ds_read_b128 v[178:181], v139 offset:2080
	v_mfma_f32_16x16x32_bf16 v[46:49], v[70:73], v[82:85], v[46:49]
	ds_read_b128 v[198:201], v207 offset:4128
	v_mfma_f32_16x16x32_bf16 v[42:45], v[70:73], v[86:89], v[42:45]
	ds_read_b128 v[202:205], v207 offset:6176
	v_mfma_f32_16x16x32_bf16 v[38:41], v[70:73], v[90:93], v[38:41]
	ds_read_b128 v[182:185], v139 offset:4128
	v_mfma_f32_16x16x32_bf16 v[6:9], v[70:73], v[94:97], v[6:9]
	ds_read_b128 v[186:189], v139 offset:6176
	v_mfma_f32_16x16x32_bf16 v[2:5], v[74:77], v[82:85], v[2:5]
	v_mfma_f32_16x16x32_bf16 v[22:25], v[74:77], v[86:89], v[22:25]
	v_mfma_f32_16x16x32_bf16 v[18:21], v[74:77], v[90:93], v[18:21]
	v_mfma_f32_16x16x32_bf16 v[14:17], v[74:77], v[94:97], v[14:17]
	v_mfma_f32_16x16x32_bf16 v[10:13], v[78:81], v[82:85], v[10:13]
	v_mfma_f32_16x16x32_bf16 v[34:37], v[78:81], v[86:89], v[34:37]
	v_mfma_f32_16x16x32_bf16 v[30:33], v[78:81], v[90:93], v[30:33]
	v_mfma_f32_16x16x32_bf16 v[26:29], v[78:81], v[94:97], v[26:29]
	s_waitcnt lgkmcnt(0)
	s_waitcnt vmcnt(0)
	s_barrier
	v_mfma_f32_16x16x32_bf16 v[66:69], v[134:137], v[190:193], v[66:69]
	ds_read_b128 v[62:65], v138 offset:32800
	v_mfma_f32_16x16x32_bf16 v[58:61], v[134:137], v[194:197], v[58:61]
	ds_read_b128 v[82:85], v206 offset:32800
	v_mfma_f32_16x16x32_bf16 v[54:57], v[134:137], v[198:201], v[54:57]
	ds_read_b128 v[86:89], v206 offset:34848
	v_mfma_f32_16x16x32_bf16 v[50:53], v[134:137], v[202:205], v[50:53]
	ds_read_b128 v[70:73], v138 offset:34848
	v_mfma_f32_16x16x32_bf16 v[46:49], v[178:181], v[190:193], v[46:49]
	ds_read_b128 v[90:93], v206 offset:36896
	v_mfma_f32_16x16x32_bf16 v[42:45], v[178:181], v[194:197], v[42:45]
	ds_read_b128 v[94:97], v206 offset:38944
	v_mfma_f32_16x16x32_bf16 v[38:41], v[178:181], v[198:201], v[38:41]
	ds_read_b128 v[74:77], v138 offset:36896
	v_mfma_f32_16x16x32_bf16 v[6:9], v[178:181], v[202:205], v[6:9]
	ds_read_b128 v[78:81], v138 offset:38944
	v_mfma_f32_16x16x32_bf16 v[2:5], v[182:185], v[190:193], v[2:5]
	v_mfma_f32_16x16x32_bf16 v[22:25], v[182:185], v[194:197], v[22:25]
	v_mfma_f32_16x16x32_bf16 v[18:21], v[182:185], v[198:201], v[18:21]
	v_mfma_f32_16x16x32_bf16 v[14:17], v[182:185], v[202:205], v[14:17]
	v_mfma_f32_16x16x32_bf16 v[10:13], v[186:189], v[190:193], v[10:13]
	v_mfma_f32_16x16x32_bf16 v[34:37], v[186:189], v[194:197], v[34:37]
	v_mfma_f32_16x16x32_bf16 v[30:33], v[186:189], v[198:201], v[30:33]
	v_mfma_f32_16x16x32_bf16 v[26:29], v[186:189], v[202:205], v[26:29]
	s_waitcnt lgkmcnt(0)
	v_mfma_f32_16x16x32_bf16 v[66:69], v[62:65], v[82:85], v[66:69]
	ds_read_b128 v[134:137], v139 offset:32800
	v_mfma_f32_16x16x32_bf16 v[58:61], v[62:65], v[86:89], v[58:61]
	ds_read_b128 v[190:193], v207 offset:32800
	v_mfma_f32_16x16x32_bf16 v[54:57], v[62:65], v[90:93], v[54:57]
	ds_read_b128 v[194:197], v207 offset:34848
	v_mfma_f32_16x16x32_bf16 v[50:53], v[62:65], v[94:97], v[50:53]
	ds_read_b128 v[178:181], v139 offset:34848
	v_mfma_f32_16x16x32_bf16 v[46:49], v[70:73], v[82:85], v[46:49]
	ds_read_b128 v[198:201], v207 offset:36896
	v_mfma_f32_16x16x32_bf16 v[42:45], v[70:73], v[86:89], v[42:45]
	ds_read_b128 v[202:205], v207 offset:38944
	v_mfma_f32_16x16x32_bf16 v[38:41], v[70:73], v[90:93], v[38:41]
	ds_read_b128 v[182:185], v139 offset:36896
	v_mfma_f32_16x16x32_bf16 v[6:9], v[70:73], v[94:97], v[6:9]
	ds_read_b128 v[186:189], v139 offset:38944
	v_mfma_f32_16x16x32_bf16 v[2:5], v[74:77], v[82:85], v[2:5]
	v_mfma_f32_16x16x32_bf16 v[22:25], v[74:77], v[86:89], v[22:25]
	v_mfma_f32_16x16x32_bf16 v[18:21], v[74:77], v[90:93], v[18:21]
	v_mfma_f32_16x16x32_bf16 v[14:17], v[74:77], v[94:97], v[14:17]
	v_mfma_f32_16x16x32_bf16 v[10:13], v[78:81], v[82:85], v[10:13]
	v_mfma_f32_16x16x32_bf16 v[34:37], v[78:81], v[86:89], v[34:37]
	v_mfma_f32_16x16x32_bf16 v[30:33], v[78:81], v[90:93], v[30:33]
	v_mfma_f32_16x16x32_bf16 v[26:29], v[78:81], v[94:97], v[26:29]
	s_waitcnt lgkmcnt(0)
	v_mfma_f32_16x16x32_bf16 v[66:69], v[134:137], v[190:193], v[66:69]
	v_mfma_f32_16x16x32_bf16 v[58:61], v[134:137], v[194:197], v[58:61]
	v_mfma_f32_16x16x32_bf16 v[54:57], v[134:137], v[198:201], v[54:57]
	v_mfma_f32_16x16x32_bf16 v[50:53], v[134:137], v[202:205], v[50:53]
	v_mfma_f32_16x16x32_bf16 v[46:49], v[178:181], v[190:193], v[46:49]
	v_mfma_f32_16x16x32_bf16 v[42:45], v[178:181], v[194:197], v[42:45]
	v_mfma_f32_16x16x32_bf16 v[38:41], v[178:181], v[198:201], v[38:41]
	v_mfma_f32_16x16x32_bf16 v[6:9], v[178:181], v[202:205], v[6:9]
	v_mfma_f32_16x16x32_bf16 v[2:5], v[182:185], v[190:193], v[2:5]
	v_mfma_f32_16x16x32_bf16 v[22:25], v[182:185], v[194:197], v[22:25]
	v_mfma_f32_16x16x32_bf16 v[18:21], v[182:185], v[198:201], v[18:21]
	v_mfma_f32_16x16x32_bf16 v[14:17], v[182:185], v[202:205], v[14:17]
	v_mfma_f32_16x16x32_bf16 v[10:13], v[186:189], v[190:193], v[10:13]
	v_mfma_f32_16x16x32_bf16 v[34:37], v[186:189], v[194:197], v[34:37]
	v_mfma_f32_16x16x32_bf16 v[30:33], v[186:189], v[198:201], v[30:33]
	v_mfma_f32_16x16x32_bf16 v[26:29], v[186:189], v[202:205], v[26:29]
	s_setprio 0
	s_waitcnt vmcnt(2)
	v_cvt_pk_bf16_f32 v62, v66, s0
	s_barrier
	ds_write_b16 v146, v62
	v_cvt_pk_bf16_f32 v62, v67, s0
	v_cvt_pk_bf16_f32 v58, v58, s0
	v_cvt_pk_bf16_f32 v54, v54, s0
	v_cvt_pk_bf16_f32 v50, v50, s0
	v_cvt_pk_bf16_f32 v46, v46, s0
	v_cvt_pk_bf16_f32 v42, v42, s0
	v_cvt_pk_bf16_f32 v38, v38, s0
	ds_write_b16 v146, v62 offset:272
	v_cvt_pk_bf16_f32 v62, v68, s0
	ds_write_b16 v146, v58 offset:32
	v_cvt_pk_bf16_f32 v58, v59, s0
	ds_write_b16 v146, v54 offset:64
	v_cvt_pk_bf16_f32 v54, v55, s0
	ds_write_b16 v146, v50 offset:96
	v_cvt_pk_bf16_f32 v50, v51, s0
	ds_write_b16 v146, v46 offset:4352
	v_cvt_pk_bf16_f32 v46, v47, s0
	ds_write_b16 v146, v42 offset:4384
	v_cvt_pk_bf16_f32 v42, v43, s0
	ds_write_b16 v146, v38 offset:4416
	v_cvt_pk_bf16_f32 v38, v39, s0
	s_mov_b32 s51, s11
	ds_write_b16 v146, v62 offset:544
	v_cvt_pk_bf16_f32 v62, v69, s0
	ds_write_b16 v146, v58 offset:304
	v_cvt_pk_bf16_f32 v58, v60, s0
	ds_write_b16 v146, v54 offset:336
	v_cvt_pk_bf16_f32 v54, v56, s0
	ds_write_b16 v146, v50 offset:368
	v_cvt_pk_bf16_f32 v50, v52, s0
	ds_write_b16 v146, v46 offset:4624
	v_cvt_pk_bf16_f32 v46, v48, s0
	ds_write_b16 v146, v42 offset:4656
	v_cvt_pk_bf16_f32 v42, v44, s0
	ds_write_b16 v146, v38 offset:4688
	v_cvt_pk_bf16_f32 v38, v40, s0
	s_lshl_b64 s[52:53], s[50:51], 15
	ds_write_b16 v146, v62 offset:816
	ds_write_b16 v146, v58 offset:576
	v_cvt_pk_bf16_f32 v58, v61, s0
	ds_write_b16 v146, v54 offset:608
	v_cvt_pk_bf16_f32 v54, v57, s0
	ds_write_b16 v146, v50 offset:640
	v_cvt_pk_bf16_f32 v50, v53, s0
	ds_write_b16 v146, v46 offset:4896
	v_cvt_pk_bf16_f32 v46, v49, s0
	ds_write_b16 v146, v42 offset:4928
	v_cvt_pk_bf16_f32 v42, v45, s0
	ds_write_b16 v146, v38 offset:4960
	v_cvt_pk_bf16_f32 v38, v41, s0
	v_lshl_add_u64 v[62:63], v[100:101], 0, s[52:53]
	v_mov_b32_e32 v105, v99
	v_mov_b32_e32 v107, v99
	v_mov_b32_e32 v109, v99
	v_mov_b32_e32 v111, v99
	v_mov_b32_e32 v113, v99
	v_mov_b32_e32 v115, v99
	v_mov_b32_e32 v117, v99
	ds_write_b16 v146, v58 offset:848
	ds_write_b16 v146, v54 offset:880
	ds_write_b16 v146, v50 offset:912
	ds_write_b16 v146, v46 offset:5168
	ds_write_b16 v146, v42 offset:5200
	ds_write_b16 v146, v38 offset:5232
	v_lshl_add_u64 v[38:39], v[62:63], 0, v[98:99]
	v_lshl_add_u64 v[42:43], v[62:63], 0, v[104:105]
	v_lshl_add_u64 v[46:47], v[62:63], 0, v[106:107]
	v_lshl_add_u64 v[50:51], v[62:63], 0, v[108:109]
	v_lshl_add_u64 v[54:55], v[62:63], 0, v[110:111]
	v_lshl_add_u64 v[58:59], v[62:63], 0, v[112:113]
	v_lshl_add_u64 v[64:65], v[62:63], 0, v[114:115]
	v_lshl_add_u64 v[66:67], v[62:63], 0, v[116:117]
	global_load_dwordx4 v[38:41], v[38:39], off
	s_nop 0
	global_load_dwordx4 v[42:45], v[42:43], off
	s_nop 0
	global_load_dwordx4 v[46:49], v[46:47], off
	s_nop 0
	global_load_dwordx4 v[50:53], v[50:51], off
	s_nop 0
	global_load_dwordx4 v[54:57], v[54:55], off
	s_nop 0
	global_load_dwordx4 v[58:61], v[58:59], off
	s_nop 0
	global_load_dwordx4 v[62:65], v[64:65], off
	s_nop 0
	global_load_dwordx4 v[66:69], v[66:67], off
	v_cvt_pk_bf16_f32 v2, v2, s0
	ds_write_b16 v146, v2 offset:8704
	v_cvt_pk_bf16_f32 v2, v3, s0
	ds_write_b16 v146, v2 offset:8976
	v_cvt_pk_bf16_f32 v2, v4, s0
	ds_write_b16 v146, v2 offset:9248
	v_cvt_pk_bf16_f32 v2, v5, s0
	ds_write_b16 v146, v2 offset:9520
	v_cvt_pk_bf16_f32 v2, v22, s0
	ds_write_b16 v146, v2 offset:8736
	v_cvt_pk_bf16_f32 v2, v23, s0
	ds_write_b16 v146, v2 offset:9008
	v_cvt_pk_bf16_f32 v2, v24, s0
	ds_write_b16 v146, v2 offset:9280
	v_cvt_pk_bf16_f32 v2, v25, s0
	ds_write_b16 v146, v2 offset:9552
	v_cvt_pk_bf16_f32 v2, v18, s0
	ds_write_b16 v146, v2 offset:8768
	v_cvt_pk_bf16_f32 v2, v19, s0
	ds_write_b16 v146, v2 offset:9040
	v_cvt_pk_bf16_f32 v2, v20, s0
	ds_write_b16 v146, v2 offset:9312
	v_cvt_pk_bf16_f32 v2, v21, s0
	ds_write_b16 v146, v2 offset:9584
	v_cvt_pk_bf16_f32 v2, v14, s0
	ds_write_b16 v146, v2 offset:8800
	v_cvt_pk_bf16_f32 v2, v15, s0
	ds_write_b16 v146, v2 offset:9072
	v_cvt_pk_bf16_f32 v2, v16, s0
	ds_write_b16 v146, v2 offset:9344
	v_cvt_pk_bf16_f32 v2, v17, s0
	ds_write_b16 v146, v2 offset:9616
	v_cvt_pk_bf16_f32 v2, v10, s0
	ds_write_b16 v146, v2 offset:13056
	v_cvt_pk_bf16_f32 v2, v11, s0
	ds_write_b16 v146, v2 offset:13328
	v_cvt_pk_bf16_f32 v2, v12, s0
	ds_write_b16 v146, v2 offset:13600
	v_cvt_pk_bf16_f32 v2, v13, s0
	ds_write_b16 v146, v2 offset:13872
	v_cvt_pk_bf16_f32 v2, v34, s0
	ds_write_b16 v146, v2 offset:13088
	v_cvt_pk_bf16_f32 v2, v35, s0
	ds_write_b16 v146, v2 offset:13360
	v_cvt_pk_bf16_f32 v2, v36, s0
	ds_write_b16 v146, v2 offset:13632
	v_cvt_pk_bf16_f32 v2, v37, s0
	ds_write_b16 v146, v2 offset:13904
	v_cvt_pk_bf16_f32 v2, v30, s0
	ds_write_b16 v146, v2 offset:13120
	v_cvt_pk_bf16_f32 v2, v31, s0
	ds_write_b16 v146, v2 offset:13392
	v_cvt_pk_bf16_f32 v2, v32, s0
	ds_write_b16 v146, v2 offset:13664
	v_cvt_pk_bf16_f32 v2, v33, s0
	v_cvt_pk_bf16_f32 v6, v6, s0
	ds_write_b16 v146, v2 offset:13936
	v_cvt_pk_bf16_f32 v2, v26, s0
	ds_write_b16 v146, v6 offset:4448
	v_cvt_pk_bf16_f32 v6, v7, s0
	ds_write_b16 v146, v2 offset:13152
	v_cvt_pk_bf16_f32 v2, v27, s0
	ds_write_b16 v146, v6 offset:4720
	v_cvt_pk_bf16_f32 v6, v8, s0
	ds_write_b16 v146, v2 offset:13424
	v_cvt_pk_bf16_f32 v2, v28, s0
	ds_write_b16 v146, v6 offset:4992
	v_cvt_pk_bf16_f32 v6, v9, s0
	ds_write_b16 v146, v2 offset:13696
	v_cvt_pk_bf16_f32 v2, v29, s0
	ds_write_b16 v146, v6 offset:5264
	ds_write_b16 v146, v2 offset:13968
	s_waitcnt vmcnt(7)
	ds_write_b128 v147, v[38:41]
	s_waitcnt vmcnt(6)
	ds_write_b128 v148, v[42:45]
	s_waitcnt vmcnt(5)
	ds_write_b128 v149, v[46:49]
	s_waitcnt vmcnt(4)
	ds_write_b128 v150, v[50:53]
	s_waitcnt vmcnt(3)
	ds_write_b128 v151, v[54:57]
	s_waitcnt vmcnt(2)
	ds_write_b128 v152, v[58:61]
	s_waitcnt vmcnt(1)
	ds_write_b128 v153, v[62:65]
	s_waitcnt vmcnt(0)
	ds_write_b128 v154, v[66:69]
	s_waitcnt lgkmcnt(0)
	s_barrier
	ds_read_b128 v[2:5], v175
	ds_read_b128 v[6:9], v176 offset:34816
	ds_read_b128 v[10:13], v175 offset:64
	ds_read_b128 v[14:17], v176 offset:34880
	ds_read_b128 v[22:25], v176 offset:39168
	ds_read_b128 v[26:29], v176 offset:39232
	ds_read_b128 v[34:37], v176 offset:43520
	ds_read_b128 v[38:41], v176 offset:43584
	ds_read_b128 v[46:49], v176 offset:47872
	ds_read_b128 v[50:53], v176 offset:47936
	ds_read_b128 v[54:57], v175 offset:4352
	ds_read_b128 v[58:61], v175 offset:4416
	ds_read_b128 v[74:77], v175 offset:8704
	ds_read_b128 v[78:81], v175 offset:8768
	ds_read_b128 v[94:97], v175 offset:13056
	ds_read_b128 v[134:137], v175 offset:13120
	s_waitcnt lgkmcnt(14)
	v_mfma_f32_16x16x32_bf16 v[18:21], v[2:5], v[6:9], 0
	s_lshl_b64 s[50:51], s[50:51], 6
	s_add_u32 s50, s35, s50
	s_addc_u32 s51, s79, s51
	s_waitcnt lgkmcnt(11)
	v_mfma_f32_16x16x32_bf16 v[30:33], v[2:5], v[22:25], 0
	s_mov_b32 s10, 0
	s_waitcnt lgkmcnt(9)
	v_mfma_f32_16x16x32_bf16 v[42:45], v[2:5], v[34:37], 0
	s_waitcnt lgkmcnt(7)
	v_mfma_f32_16x16x32_bf16 v[2:5], v[2:5], v[46:49], 0
	s_waitcnt lgkmcnt(5)
	v_mfma_f32_16x16x32_bf16 v[62:65], v[54:57], v[6:9], 0
	v_mfma_f32_16x16x32_bf16 v[66:69], v[54:57], v[22:25], 0
	v_mfma_f32_16x16x32_bf16 v[70:73], v[54:57], v[34:37], 0
	v_mfma_f32_16x16x32_bf16 v[54:57], v[54:57], v[46:49], 0
	s_waitcnt lgkmcnt(3)
	v_mfma_f32_16x16x32_bf16 v[82:85], v[74:77], v[6:9], 0
	v_mfma_f32_16x16x32_bf16 v[86:89], v[74:77], v[22:25], 0
	s_waitcnt lgkmcnt(1)
	v_mfma_f32_16x16x32_bf16 v[6:9], v[94:97], v[6:9], 0
	v_mfma_f32_16x16x32_bf16 v[22:25], v[94:97], v[22:25], 0
	v_mfma_f32_16x16x32_bf16 v[18:21], v[10:13], v[14:17], v[18:21]
	v_mfma_f32_16x16x32_bf16 v[30:33], v[10:13], v[26:29], v[30:33]
	v_mfma_f32_16x16x32_bf16 v[42:45], v[10:13], v[38:41], v[42:45]
	v_mfma_f32_16x16x32_bf16 v[2:5], v[10:13], v[50:53], v[2:5]
	v_mfma_f32_16x16x32_bf16 v[10:13], v[58:61], v[14:17], v[62:65]
	v_mfma_f32_16x16x32_bf16 v[62:65], v[58:61], v[26:29], v[66:69]
	v_mfma_f32_16x16x32_bf16 v[66:69], v[58:61], v[38:41], v[70:73]
	v_mfma_f32_16x16x32_bf16 v[54:57], v[58:61], v[50:53], v[54:57]
	v_mfma_f32_16x16x32_bf16 v[58:61], v[78:81], v[14:17], v[82:85]
	v_mfma_f32_16x16x32_bf16 v[70:73], v[78:81], v[26:29], v[86:89]
	s_waitcnt lgkmcnt(0)
	v_mfma_f32_16x16x32_bf16 v[6:9], v[134:137], v[14:17], v[6:9]
	v_mfma_f32_16x16x32_bf16 v[14:17], v[134:137], v[26:29], v[22:25]
	ds_read_b128 v[26:29], v175 offset:128
	v_mfma_f32_16x16x32_bf16 v[90:93], v[74:77], v[34:37], 0
	v_mfma_f32_16x16x32_bf16 v[74:77], v[74:77], v[46:49], 0
	v_mfma_f32_16x16x32_bf16 v[34:37], v[94:97], v[34:37], 0
	v_mfma_f32_16x16x32_bf16 v[46:49], v[94:97], v[46:49], 0
	v_mfma_f32_16x16x32_bf16 v[82:85], v[78:81], v[38:41], v[90:93]
	v_mfma_f32_16x16x32_bf16 v[74:77], v[78:81], v[50:53], v[74:77]
	v_mfma_f32_16x16x32_bf16 v[22:25], v[134:137], v[38:41], v[34:37]
	v_mfma_f32_16x16x32_bf16 v[34:37], v[134:137], v[50:53], v[46:49]
	ds_read_b128 v[38:41], v176 offset:34944
	s_nop 2
	ds_read_b128 v[46:49], v175 offset:192
	ds_read_b128 v[50:53], v176 offset:35008
	ds_read_b128 v[78:81], v176 offset:39296
	ds_read_b128 v[86:89], v176 offset:39360
	ds_read_b128 v[90:93], v176 offset:43648
	ds_read_b128 v[94:97], v176 offset:43712
	ds_read_b128 v[134:137], v176 offset:48000
	ds_read_b128 v[178:181], v176 offset:48064
	s_waitcnt lgkmcnt(8)
	v_mfma_f32_16x16x32_bf16 v[18:21], v[26:29], v[38:41], v[18:21]
	s_waitcnt lgkmcnt(5)
	v_mfma_f32_16x16x32_bf16 v[30:33], v[26:29], v[78:81], v[30:33]
	s_waitcnt lgkmcnt(3)
	v_mfma_f32_16x16x32_bf16 v[42:45], v[26:29], v[90:93], v[42:45]
	s_waitcnt lgkmcnt(1)
	v_mfma_f32_16x16x32_bf16 v[2:5], v[26:29], v[134:137], v[2:5]
	ds_read_b128 v[26:29], v175 offset:4480
	ds_read_b128 v[182:185], v175 offset:4544
	s_waitcnt lgkmcnt(1)
	v_mfma_f32_16x16x32_bf16 v[10:13], v[26:29], v[38:41], v[10:13]
	v_mfma_f32_16x16x32_bf16 v[62:65], v[26:29], v[78:81], v[62:65]
	v_mfma_f32_16x16x32_bf16 v[66:69], v[26:29], v[90:93], v[66:69]
	v_mfma_f32_16x16x32_bf16 v[26:29], v[26:29], v[134:137], v[54:57]
	s_nop 2
	ds_read_b128 v[54:57], v175 offset:8832
	ds_read_b128 v[186:189], v175 offset:8896
	s_waitcnt lgkmcnt(1)
	v_mfma_f32_16x16x32_bf16 v[58:61], v[54:57], v[38:41], v[58:61]
	v_mfma_f32_16x16x32_bf16 v[70:73], v[54:57], v[78:81], v[70:73]
	v_mfma_f32_16x16x32_bf16 v[82:85], v[54:57], v[90:93], v[82:85]
	v_mfma_f32_16x16x32_bf16 v[54:57], v[54:57], v[134:137], v[74:77]
	s_nop 2
	ds_read_b128 v[74:77], v175 offset:13184
	ds_read_b128 v[190:193], v175 offset:13248
	s_waitcnt lgkmcnt(0)
	s_barrier
	v_mfma_f32_16x16x32_bf16 v[6:9], v[74:77], v[38:41], v[6:9]
	v_mfma_f32_16x16x32_bf16 v[14:17], v[74:77], v[78:81], v[14:17]
	v_mfma_f32_16x16x32_bf16 v[18:21], v[46:49], v[50:53], v[18:21]
	v_mfma_f32_16x16x32_bf16 v[30:33], v[46:49], v[86:89], v[30:33]
	s_nop 7
	ds_write2_b32 v145, v18, v30 offset1:16
	ds_write2_b32 v145, v19, v31 offset0:132 offset1:148
	v_mfma_f32_16x16x32_bf16 v[22:25], v[74:77], v[90:93], v[22:25]
	v_add_u32_e32 v18, 0x400, v145
	v_mfma_f32_16x16x32_bf16 v[34:37], v[74:77], v[134:137], v[34:37]
	v_mfma_f32_16x16x32_bf16 v[38:41], v[46:49], v[94:97], v[42:45]
	v_mfma_f32_16x16x32_bf16 v[10:13], v[182:185], v[50:53], v[10:13]
	v_mfma_f32_16x16x32_bf16 v[42:45], v[182:185], v[86:89], v[62:65]
	v_mfma_f32_16x16x32_bf16 v[2:5], v[46:49], v[178:181], v[2:5]
	ds_write2_b32 v18, v20, v32 offset0:8 offset1:24
	ds_write2_b32 v18, v21, v33 offset0:140 offset1:156
	s_nop 5
	ds_write2_b32 v145, v38, v2 offset0:32 offset1:48
	ds_write2_b32 v145, v39, v3 offset0:164 offset1:180
	ds_write2_b32 v18, v40, v4 offset0:40 offset1:56
	ds_write2_b32 v18, v41, v5 offset0:172 offset1:188
	v_add_u32_e32 v2, 0x2000, v145
	v_mfma_f32_16x16x32_bf16 v[58:61], v[186:189], v[50:53], v[58:61]
	v_add_u32_e32 v3, 0x2400, v145
	ds_write2_b32 v2, v10, v42 offset0:64 offset1:80
	ds_write2_b32 v2, v11, v43 offset0:196 offset1:212
	v_add_u32_e32 v4, 0x4800, v145
	v_mfma_f32_16x16x32_bf16 v[62:65], v[186:189], v[86:89], v[70:73]
	v_mfma_f32_16x16x32_bf16 v[46:49], v[182:185], v[94:97], v[66:69]
	v_mfma_f32_16x16x32_bf16 v[26:29], v[182:185], v[178:181], v[26:29]
	ds_write2_b32 v3, v12, v44 offset0:72 offset1:88
	ds_write2_b32 v3, v13, v45 offset0:204 offset1:220
	s_nop 5
	ds_write2_b32 v2, v46, v26 offset0:96 offset1:112
	ds_write2_b32 v2, v47, v27 offset0:228 offset1:244
	ds_write2_b32 v3, v48, v28 offset0:104 offset1:120
	ds_write2_b32 v3, v49, v29 offset0:236 offset1:252
	v_add_u32_e32 v2, 0x4000, v145
	v_mfma_f32_16x16x32_bf16 v[66:69], v[186:189], v[94:97], v[82:85]
	v_add_u32_e32 v3, 0x4400, v145
	ds_write2_b32 v2, v58, v62 offset0:128 offset1:144
	ds_write2_b32 v3, v59, v63 offset0:4 offset1:20
	ds_write2_b32 v3, v60, v64 offset0:136 offset1:152
	v_mfma_f32_16x16x32_bf16 v[54:57], v[186:189], v[178:181], v[54:57]
	ds_write2_b32 v4, v61, v65 offset0:12 offset1:28
	s_nop 6
	ds_write2_b32 v2, v66, v54 offset0:160 offset1:176
	ds_write2_b32 v3, v67, v55 offset0:36 offset1:52
	ds_write2_b32 v3, v68, v56 offset0:168 offset1:184
	ds_write2_b32 v4, v69, v57 offset0:44 offset1:60
	v_mfma_f32_16x16x32_bf16 v[6:9], v[190:193], v[50:53], v[6:9]
	v_add_u32_e32 v2, 0x6000, v145
	v_add_u32_e32 v3, 0x6400, v145
	v_add_u32_e32 v4, 0x6800, v145
	v_mfma_f32_16x16x32_bf16 v[14:17], v[190:193], v[86:89], v[14:17]
	v_mfma_f32_16x16x32_bf16 v[22:25], v[190:193], v[94:97], v[22:25]
	v_mfma_f32_16x16x32_bf16 v[34:37], v[190:193], v[178:181], v[34:37]
	s_nop 5
	ds_write2_b32 v2, v6, v14 offset0:192 offset1:208
	ds_write2_b32 v3, v7, v15 offset0:68 offset1:84
	ds_write2_b32 v3, v8, v16 offset0:200 offset1:216
	ds_write2_b32 v4, v9, v17 offset0:76 offset1:92
	ds_write2_b32 v2, v22, v34 offset0:224 offset1:240
	ds_write2_b32 v3, v23, v35 offset0:100 offset1:116
	ds_write2_b32 v3, v24, v36 offset0:232 offset1:248
	ds_write2_b32 v4, v25, v37 offset0:108 offset1:124
	v_mov_b32_e32 v2, v177
	s_waitcnt lgkmcnt(0)
	s_barrier
	s_branch .LBB0_1500
